# 8-phase GEMM K-loops: all per-segment s_setprio flips removed (segments run at the default priority), A/B against the previous version
# speedup vs baseline: 1.0087x; 1.0004x over previous
; #define PG8_STAGE(bufoff, gbase, voff) do { _Pragma("unroll") for (int _i = 0; _i < 2; ++_i) \
;         __builtin_amdgcn_global_load_lds((const unsigned*)((const char*)(gbase) + (voff)[_i]), (LAS unsigned*)(lds + (bufoff) + ldsw + _i * 8192), 16, 0, 0); } while (0)
; #define PG8_LDA(dst, b, h) do { _Pragma("unroll") for (int m = 0; m < 4; ++m) _Pragma("unroll") for (int k = 0; k < 2; ++k) dst[m][k] = *(const LAS bf16x8*)(lds + PG8_SA(b, h) + aoff + m * 2048 + k * 1024); } while (0)
; #define PG8_LDB(dst, b, h) do { _Pragma("unroll") for (int n = 0; n < 2; ++n) _Pragma("unroll") for (int k = 0; k < 2; ++k) dst[n][k] = *(const LAS bf16x8*)(lds + PG8_SB(b, h) + boff + n * 2048 + k * 1024); } while (0)
; #define PG8_MMA(ai, bj, At, Bt) do { __builtin_amdgcn_s_setprio(1); _Pragma("unroll") for (int m = 0; m < 4; ++m) _Pragma("unroll") for (int n = 0; n < 2; ++n) _Pragma("unroll") for (int k = 0; k < 2; ++k) \
;         acc[ai][bj][m][n] = __builtin_amdgcn_mfma_f32_16x16x32_bf16(Bt[n][k], At[m][k], acc[ai][bj][m][n], 0, 0, 0); __builtin_amdgcn_s_setprio(0); } while (0)
; #define PG8_WAIT_V(n) asm volatile("s_waitcnt vmcnt(" #n ")" ::: "memory")
; #define PG8_WAIT_L(n) asm volatile("s_waitcnt lgkmcnt(" #n ")" ::: "memory")
; #define PG8_BAR __builtin_amdgcn_s_barrier()
; #define PG8_SCHED __builtin_amdgcn_sched_barrier(0)
; template <class Desc, class Epi>
; DI void gemm_phase(LAS unsigned char* lds, const Desc& D, const Epi& E, int wv) {
;     ...
;         for (int t = 0; t < nt; t += 2) {
;             const bool last = (t == nt - 2);
;             const char* a1 = cA + (size_t)(t + 1) * kstep;
;             const char* a2 = last ? nA : cA + (size_t)(t + 2) * kstep; const char* b2 = last ? nB : cB + (size_t)(t + 2) * kstep;
;             const char* a3 = a2 + kstep; const char* b3 = b2 + kstep;
;             PG8_LDB(B0, 0, 0); PG8_LDB(B1, 0, 1); PG8_SCHED; PG8_LDA(At, 0, 0); PG8_STAGE(PG8_SA(1, 1), a1 + hstepA, voffA);
;             PG8_WAIT_V(8); PG8_WAIT_L(0); PG8_BAR; PG8_MMA(0, 0, At, B0); PG8_MMA(0, 1, At, B1); PG8_BAR; PG8_SCHED;
;             PG8_LDA(At, 0, 1); PG8_STAGE(PG8_SB(0, 0), b2, voffB); PG8_STAGE(PG8_SB(0, 1), b2 + hstepB, voffB); PG8_STAGE(PG8_SA(0, 0), a2, voffA);
.LBB0_292:
	ds_read_b128 v[152:155], v149
	ds_read_b128 v[156:159], v149 offset:1024
	ds_read_b128 v[160:163], v149 offset:2048
	ds_read_b128 v[164:167], v149 offset:3072
	ds_read_b128 v[168:171], v150
	ds_read_b128 v[172:175], v150 offset:1024
	ds_read_b128 v[176:179], v150 offset:2048
	ds_read_b128 v[180:183], v150 offset:3072
	s_add_u32 s66, s64, 0xfff80080
	s_addc_u32 s67, s65, -1
	s_cmp_eq_u32 s63, 28
	s_cselect_b32 s69, s39, s67
	s_cselect_b32 s68, s38, s66
	s_cselect_b32 s67, s47, s61
	s_cselect_b32 s66, s46, s53
	v_lshl_add_u64 v[146:147], s[64:65], 0, v[138:139]
	s_add_i32 m0, s31, 0xc000
	ds_read_b128 v[184:187], v151
	ds_read_b128 v[188:191], v151 offset:1024
	ds_read_b128 v[192:195], v151 offset:2048
	ds_read_b128 v[196:199], v151 offset:3072
	ds_read_b128 v[200:203], v151 offset:4096
	ds_read_b128 v[204:207], v151 offset:5120
	ds_read_b128 v[208:211], v151 offset:6144
	ds_read_b128 v[212:215], v151 offset:7168
	global_load_lds_dwordx4 v[146:147], off
	v_lshl_add_u64 v[146:147], s[64:65], 0, v[140:141]
	s_add_i32 m0, s31, 0xe000
	s_nop 0
	global_load_lds_dwordx4 v[146:147], off
	s_waitcnt vmcnt(8)
	s_waitcnt lgkmcnt(0)
	s_barrier
	v_mfma_f32_16x16x32_bf16 v[124:127], v[152:155], v[184:187], v[124:127]
	v_mfma_f32_16x16x32_bf16 v[120:123], v[160:163], v[184:187], v[120:123]
	v_mfma_f32_16x16x32_bf16 v[108:111], v[152:155], v[192:195], v[108:111]
	v_mfma_f32_16x16x32_bf16 v[104:107], v[160:163], v[192:195], v[104:107]
	v_mfma_f32_16x16x32_bf16 v[92:95], v[152:155], v[200:203], v[92:95]
	v_mfma_f32_16x16x32_bf16 v[88:91], v[160:163], v[200:203], v[88:91]
	v_mfma_f32_16x16x32_bf16 v[76:79], v[152:155], v[208:211], v[76:79]
	v_mfma_f32_16x16x32_bf16 v[72:75], v[160:163], v[208:211], v[72:75]
	v_mfma_f32_16x16x32_bf16 v[124:127], v[156:159], v[188:191], v[124:127]
	v_mfma_f32_16x16x32_bf16 v[120:123], v[164:167], v[188:191], v[120:123]
	v_mfma_f32_16x16x32_bf16 v[108:111], v[156:159], v[196:199], v[108:111]
	v_mfma_f32_16x16x32_bf16 v[104:107], v[164:167], v[196:199], v[104:107]
	v_mfma_f32_16x16x32_bf16 v[92:95], v[156:159], v[204:207], v[92:95]
	v_mfma_f32_16x16x32_bf16 v[88:91], v[164:167], v[204:207], v[88:91]
	v_mfma_f32_16x16x32_bf16 v[76:79], v[156:159], v[212:215], v[76:79]
	v_mfma_f32_16x16x32_bf16 v[72:75], v[164:167], v[212:215], v[72:75]
	v_mfma_f32_16x16x32_bf16 v[116:119], v[168:171], v[184:187], v[116:119]
	v_mfma_f32_16x16x32_bf16 v[112:115], v[176:179], v[184:187], v[112:115]
	v_mfma_f32_16x16x32_bf16 v[100:103], v[168:171], v[192:195], v[100:103]
	v_mfma_f32_16x16x32_bf16 v[96:99], v[176:179], v[192:195], v[96:99]
	v_mfma_f32_16x16x32_bf16 v[84:87], v[168:171], v[200:203], v[84:87]
	v_mfma_f32_16x16x32_bf16 v[80:83], v[176:179], v[200:203], v[80:83]
	v_mfma_f32_16x16x32_bf16 v[68:71], v[168:171], v[208:211], v[68:71]
	v_mfma_f32_16x16x32_bf16 v[64:67], v[176:179], v[208:211], v[64:67]
	v_mfma_f32_16x16x32_bf16 v[116:119], v[172:175], v[188:191], v[116:119]
	v_mfma_f32_16x16x32_bf16 v[112:115], v[180:183], v[188:191], v[112:115]
	v_mfma_f32_16x16x32_bf16 v[100:103], v[172:175], v[196:199], v[100:103]
	v_mfma_f32_16x16x32_bf16 v[96:99], v[180:183], v[196:199], v[96:99]
	v_mfma_f32_16x16x32_bf16 v[84:87], v[172:175], v[204:207], v[84:87]
	v_mfma_f32_16x16x32_bf16 v[80:83], v[180:183], v[204:207], v[80:83]
	v_mfma_f32_16x16x32_bf16 v[68:71], v[172:175], v[212:215], v[68:71]
	v_mfma_f32_16x16x32_bf16 v[64:67], v[180:183], v[212:215], v[64:67]
	s_barrier
	s_add_i32 s76, s51, s28
	v_lshl_add_u64 v[146:147], s[66:67], 0, v[132:133]
	s_mov_b32 m0, s76
	ds_read_b128 v[184:187], v151 offset:16384
	ds_read_b128 v[188:191], v151 offset:17408
	ds_read_b128 v[192:195], v151 offset:18432
	ds_read_b128 v[196:199], v151 offset:19456
	ds_read_b128 v[200:203], v151 offset:20480
	ds_read_b128 v[204:207], v151 offset:21504
	ds_read_b128 v[208:211], v151 offset:22528
	ds_read_b128 v[212:215], v151 offset:23552
	global_load_lds_dwordx4 v[146:147], off
	s_add_i32 m0, s76, 0x2000
	s_add_u32 s76, s66, 0x80000
	v_lshl_add_u64 v[216:217], s[66:67], 0, v[128:129]
	s_addc_u32 s77, s67, 0
	s_add_i32 s78, s70, s28
	global_load_lds_dwordx4 v[216:217], off
	v_lshl_add_u64 v[218:219], s[76:77], 0, v[132:133]
	s_mov_b32 m0, s78
	v_lshl_add_u64 v[220:221], s[68:69], 0, v[130:131]
	global_load_lds_dwordx4 v[218:219], off
	v_lshl_add_u64 v[218:219], s[76:77], 0, v[128:129]
	s_add_i32 m0, s78, 0x2000
	s_nop 0
	global_load_lds_dwordx4 v[218:219], off
	v_lshl_add_u64 v[218:219], s[68:69], 0, v[134:135]
	s_mov_b32 m0, s31
	s_nop 0
	global_load_lds_dwordx4 v[218:219], off
	s_mov_b32 m0, s34
	s_nop 0
	global_load_lds_dwordx4 v[220:221], off
	s_waitcnt vmcnt(8)
	s_waitcnt lgkmcnt(0)
	s_barrier
; #define PG8_STAGE(bufoff, gbase, voff) do { _Pragma("unroll") for (int _i = 0; _i < 2; ++_i) \
;         __builtin_amdgcn_global_load_lds((const unsigned*)((const char*)(gbase) + (voff)[_i]), (LAS unsigned*)(lds + (bufoff) + ldsw + _i * 8192), 16, 0, 0); } while (0)
; #define PG8_LDA(dst, b, h) do { _Pragma("unroll") for (int m = 0; m < 4; ++m) _Pragma("unroll") for (int k = 0; k < 2; ++k) dst[m][k] = *(const LAS bf16x8*)(lds + PG8_SA(b, h) + aoff + m * 2048 + k * 1024); } while (0)
; #define PG8_LDB(dst, b, h) do { _Pragma("unroll") for (int n = 0; n < 2; ++n) _Pragma("unroll") for (int k = 0; k < 2; ++k) dst[n][k] = *(const LAS bf16x8*)(lds + PG8_SB(b, h) + boff + n * 2048 + k * 1024); } while (0)
; #define PG8_MMA(ai, bj, At, Bt) do { __builtin_amdgcn_s_setprio(1); _Pragma("unroll") for (int m = 0; m < 4; ++m) _Pragma("unroll") for (int n = 0; n < 2; ++n) _Pragma("unroll") for (int k = 0; k < 2; ++k) \
;         acc[ai][bj][m][n] = __builtin_amdgcn_mfma_f32_16x16x32_bf16(Bt[n][k], At[m][k], acc[ai][bj][m][n], 0, 0, 0); __builtin_amdgcn_s_setprio(0); } while (0)
; #define PG8_WAIT_V(n) asm volatile("s_waitcnt vmcnt(" #n ")" ::: "memory")
; #define PG8_WAIT_L(n) asm volatile("s_waitcnt lgkmcnt(" #n ")" ::: "memory")
; #define PG8_BAR __builtin_amdgcn_s_barrier()
; #define PG8_SCHED __builtin_amdgcn_sched_barrier(0)
; template <class Desc, class Epi>
; DI void gemm_phase(LAS unsigned char* lds, const Desc& D, const Epi& E, int wv) {
;     ...
;             PG8_WAIT_V(8); PG8_WAIT_L(0); PG8_BAR; PG8_MMA(1, 0, At, B0); PG8_MMA(1, 1, At, B1); PG8_BAR; PG8_SCHED;
;             PG8_LDB(B0, 1, 0); PG8_LDB(B1, 1, 1); PG8_SCHED; PG8_LDA(At, 1, 0); PG8_STAGE(PG8_SA(0, 1), a2 + hstepA, voffA);
;             PG8_WAIT_V(8); PG8_WAIT_L(0); PG8_BAR; PG8_MMA(0, 0, At, B0); PG8_MMA(0, 1, At, B1); PG8_BAR; PG8_SCHED;
	v_mfma_f32_16x16x32_bf16 v[60:63], v[152:155], v[184:187], v[60:63]
	v_mfma_f32_16x16x32_bf16 v[56:59], v[160:163], v[184:187], v[56:59]
	v_mfma_f32_16x16x32_bf16 v[44:47], v[152:155], v[192:195], v[44:47]
	v_mfma_f32_16x16x32_bf16 v[40:43], v[160:163], v[192:195], v[40:43]
	v_mfma_f32_16x16x32_bf16 v[28:31], v[152:155], v[200:203], v[28:31]
	v_mfma_f32_16x16x32_bf16 v[24:27], v[160:163], v[200:203], v[24:27]
	v_mfma_f32_16x16x32_bf16 v[12:15], v[152:155], v[208:211], v[12:15]
	v_mfma_f32_16x16x32_bf16 v[8:11], v[160:163], v[208:211], v[8:11]
	v_mfma_f32_16x16x32_bf16 v[60:63], v[156:159], v[188:191], v[60:63]
	v_mfma_f32_16x16x32_bf16 v[56:59], v[164:167], v[188:191], v[56:59]
	v_mfma_f32_16x16x32_bf16 v[44:47], v[156:159], v[196:199], v[44:47]
	v_mfma_f32_16x16x32_bf16 v[40:43], v[164:167], v[196:199], v[40:43]
	v_mfma_f32_16x16x32_bf16 v[28:31], v[156:159], v[204:207], v[28:31]
	v_mfma_f32_16x16x32_bf16 v[24:27], v[164:167], v[204:207], v[24:27]
	v_mfma_f32_16x16x32_bf16 v[12:15], v[156:159], v[212:215], v[12:15]
	v_mfma_f32_16x16x32_bf16 v[8:11], v[164:167], v[212:215], v[8:11]
	v_mfma_f32_16x16x32_bf16 v[52:55], v[168:171], v[184:187], v[52:55]
	v_mfma_f32_16x16x32_bf16 v[48:51], v[176:179], v[184:187], v[48:51]
	v_mfma_f32_16x16x32_bf16 v[36:39], v[168:171], v[192:195], v[36:39]
	v_mfma_f32_16x16x32_bf16 v[32:35], v[176:179], v[192:195], v[32:35]
	v_mfma_f32_16x16x32_bf16 v[20:23], v[168:171], v[200:203], v[20:23]
	v_mfma_f32_16x16x32_bf16 v[16:19], v[176:179], v[200:203], v[16:19]
	v_mfma_f32_16x16x32_bf16 v[4:7], v[168:171], v[208:211], v[4:7]
	v_mfma_f32_16x16x32_bf16 v[0:3], v[176:179], v[208:211], v[0:3]
	v_mfma_f32_16x16x32_bf16 v[52:55], v[172:175], v[188:191], v[52:55]
	v_mfma_f32_16x16x32_bf16 v[48:51], v[180:183], v[188:191], v[48:51]
	v_mfma_f32_16x16x32_bf16 v[36:39], v[172:175], v[196:199], v[36:39]
	v_mfma_f32_16x16x32_bf16 v[32:35], v[180:183], v[196:199], v[32:35]
	v_mfma_f32_16x16x32_bf16 v[20:23], v[172:175], v[204:207], v[20:23]
	v_mfma_f32_16x16x32_bf16 v[16:19], v[180:183], v[204:207], v[16:19]
	v_mfma_f32_16x16x32_bf16 v[4:7], v[172:175], v[212:215], v[4:7]
	v_mfma_f32_16x16x32_bf16 v[0:3], v[180:183], v[212:215], v[0:3]
	s_barrier
	s_add_i32 s76, 0, 0x18000
	v_add_u32_e32 v136, s76, v148
	s_add_i32 s77, 0, 0x1c000
	ds_read_b128 v[152:155], v136
	ds_read_b128 v[156:159], v136 offset:1024
	ds_read_b128 v[160:163], v136 offset:2048
	ds_read_b128 v[164:167], v136 offset:3072
	v_add_u32_e32 v136, s77, v148
	ds_read_b128 v[168:171], v136
	ds_read_b128 v[172:175], v136 offset:1024
	ds_read_b128 v[176:179], v136 offset:2048
	ds_read_b128 v[180:183], v136 offset:3072
	s_add_u32 s68, s68, 0x80000
	s_addc_u32 s69, s69, 0
	s_mov_b32 m0, s35
	v_lshl_add_u64 v[222:223], s[68:69], 0, v[134:135]
	ds_read_b128 v[184:187], v151 offset:32768
	ds_read_b128 v[188:191], v151 offset:33792
	ds_read_b128 v[192:195], v151 offset:34816
	ds_read_b128 v[196:199], v151 offset:35840
	ds_read_b128 v[200:203], v151 offset:36864
	ds_read_b128 v[204:207], v151 offset:37888
	ds_read_b128 v[208:211], v151 offset:38912
	ds_read_b128 v[212:215], v151 offset:39936
	global_load_lds_dwordx4 v[222:223], off
	v_lshl_add_u64 v[222:223], s[68:69], 0, v[130:131]
	s_mov_b32 m0, s40
	s_nop 0
	global_load_lds_dwordx4 v[222:223], off
	s_waitcnt vmcnt(8)
	s_waitcnt lgkmcnt(0)
	s_barrier
	v_mfma_f32_16x16x32_bf16 v[124:127], v[152:155], v[184:187], v[124:127]
	v_mfma_f32_16x16x32_bf16 v[120:123], v[160:163], v[184:187], v[120:123]
	v_mfma_f32_16x16x32_bf16 v[108:111], v[152:155], v[192:195], v[108:111]
	v_mfma_f32_16x16x32_bf16 v[104:107], v[160:163], v[192:195], v[104:107]
	v_mfma_f32_16x16x32_bf16 v[92:95], v[152:155], v[200:203], v[92:95]
	v_mfma_f32_16x16x32_bf16 v[88:91], v[160:163], v[200:203], v[88:91]
	v_mfma_f32_16x16x32_bf16 v[76:79], v[152:155], v[208:211], v[76:79]
	v_mfma_f32_16x16x32_bf16 v[72:75], v[160:163], v[208:211], v[72:75]
	v_mfma_f32_16x16x32_bf16 v[124:127], v[156:159], v[188:191], v[124:127]
	v_mfma_f32_16x16x32_bf16 v[120:123], v[164:167], v[188:191], v[120:123]
	v_mfma_f32_16x16x32_bf16 v[108:111], v[156:159], v[196:199], v[108:111]
	v_mfma_f32_16x16x32_bf16 v[104:107], v[164:167], v[196:199], v[104:107]
	v_mfma_f32_16x16x32_bf16 v[92:95], v[156:159], v[204:207], v[92:95]
	v_mfma_f32_16x16x32_bf16 v[88:91], v[164:167], v[204:207], v[88:91]
	v_mfma_f32_16x16x32_bf16 v[76:79], v[156:159], v[212:215], v[76:79]
	v_mfma_f32_16x16x32_bf16 v[72:75], v[164:167], v[212:215], v[72:75]
	v_mfma_f32_16x16x32_bf16 v[116:119], v[168:171], v[184:187], v[116:119]
	v_mfma_f32_16x16x32_bf16 v[112:115], v[176:179], v[184:187], v[112:115]
	v_mfma_f32_16x16x32_bf16 v[100:103], v[168:171], v[192:195], v[100:103]
	v_mfma_f32_16x16x32_bf16 v[96:99], v[176:179], v[192:195], v[96:99]
	v_mfma_f32_16x16x32_bf16 v[84:87], v[168:171], v[200:203], v[84:87]
	v_mfma_f32_16x16x32_bf16 v[80:83], v[176:179], v[200:203], v[80:83]
	v_mfma_f32_16x16x32_bf16 v[68:71], v[168:171], v[208:211], v[68:71]
	v_mfma_f32_16x16x32_bf16 v[64:67], v[176:179], v[208:211], v[64:67]
	v_mfma_f32_16x16x32_bf16 v[116:119], v[172:175], v[188:191], v[116:119]
	v_mfma_f32_16x16x32_bf16 v[112:115], v[180:183], v[188:191], v[112:115]
	v_mfma_f32_16x16x32_bf16 v[100:103], v[172:175], v[196:199], v[100:103]
	v_mfma_f32_16x16x32_bf16 v[96:99], v[180:183], v[196:199], v[96:99]
	v_mfma_f32_16x16x32_bf16 v[84:87], v[172:175], v[204:207], v[84:87]
	v_mfma_f32_16x16x32_bf16 v[80:83], v[180:183], v[204:207], v[80:83]
	v_mfma_f32_16x16x32_bf16 v[68:71], v[172:175], v[212:215], v[68:71]
	v_mfma_f32_16x16x32_bf16 v[64:67], v[180:183], v[212:215], v[64:67]
	s_barrier
; #define PG8_STAGE(bufoff, gbase, voff) do { _Pragma("unroll") for (int _i = 0; _i < 2; ++_i) \
;         __builtin_amdgcn_global_load_lds((const unsigned*)((const char*)(gbase) + (voff)[_i]), (LAS unsigned*)(lds + (bufoff) + ldsw + _i * 8192), 16, 0, 0); } while (0)
; #define PG8_LDA(dst, b, h) do { _Pragma("unroll") for (int m = 0; m < 4; ++m) _Pragma("unroll") for (int k = 0; k < 2; ++k) dst[m][k] = *(const LAS bf16x8*)(lds + PG8_SA(b, h) + aoff + m * 2048 + k * 1024); } while (0)
; #define PG8_MMA(ai, bj, At, Bt) do { __builtin_amdgcn_s_setprio(1); _Pragma("unroll") for (int m = 0; m < 4; ++m) _Pragma("unroll") for (int n = 0; n < 2; ++n) _Pragma("unroll") for (int k = 0; k < 2; ++k) \
;         acc[ai][bj][m][n] = __builtin_amdgcn_mfma_f32_16x16x32_bf16(Bt[n][k], At[m][k], acc[ai][bj][m][n], 0, 0, 0); __builtin_amdgcn_s_setprio(0); } while (0)
; #define PG8_WAIT_V(n) asm volatile("s_waitcnt vmcnt(" #n ")" ::: "memory")
; #define PG8_WAIT_L(n) asm volatile("s_waitcnt lgkmcnt(" #n ")" ::: "memory")
; #define PG8_BAR __builtin_amdgcn_s_barrier()
; #define PG8_SCHED __builtin_amdgcn_sched_barrier(0)
; template <class Desc, class Epi>
; DI void gemm_phase(LAS unsigned char* lds, const Desc& D, const Epi& E, int wv) {
;     ...
;             PG8_LDA(At, 1, 1); PG8_STAGE(PG8_SB(1, 0), b3, voffB); PG8_STAGE(PG8_SB(1, 1), b3 + hstepB, voffB); PG8_STAGE(PG8_SA(1, 0), a3, voffA);
;             PG8_WAIT_V(8); PG8_WAIT_L(0); PG8_BAR; PG8_MMA(1, 0, At, B0); PG8_MMA(1, 1, At, B1); PG8_BAR; PG8_SCHED;
;         }
;         if (wr == 0) PG8_BAR;
	s_add_i32 s68, s76, s28
	v_lshl_add_u64 v[146:147], v[146:147], 0, s[8:9]
	s_mov_b32 m0, s68
	ds_read_b128 v[184:187], v151 offset:49152
	ds_read_b128 v[188:191], v151 offset:50176
	ds_read_b128 v[192:195], v151 offset:51200
	ds_read_b128 v[196:199], v151 offset:52224
	ds_read_b128 v[200:203], v151 offset:53248
	ds_read_b128 v[204:207], v151 offset:54272
	ds_read_b128 v[208:211], v151 offset:55296
	ds_read_b128 v[212:215], v151 offset:56320
	global_load_lds_dwordx4 v[146:147], off
	s_add_i32 m0, s68, 0x2000
	s_add_u32 s66, s66, 0x80080
	v_lshl_add_u64 v[146:147], v[216:217], 0, s[8:9]
	s_addc_u32 s67, s67, 0
	s_add_i32 s68, s77, s28
	global_load_lds_dwordx4 v[146:147], off
	v_lshl_add_u64 v[146:147], s[66:67], 0, v[132:133]
	s_mov_b32 m0, s68
	s_nop 0
	global_load_lds_dwordx4 v[146:147], off
	v_lshl_add_u64 v[146:147], s[66:67], 0, v[128:129]
	s_add_i32 m0, s68, 0x2000
	s_nop 0
	global_load_lds_dwordx4 v[146:147], off
	v_lshl_add_u64 v[146:147], v[218:219], 0, s[8:9]
	s_mov_b32 m0, s48
	s_nop 0
	global_load_lds_dwordx4 v[146:147], off
	v_lshl_add_u64 v[146:147], v[220:221], 0, s[8:9]
	s_mov_b32 m0, s49
	s_nop 0
	global_load_lds_dwordx4 v[146:147], off
	s_waitcnt vmcnt(8)
	s_waitcnt lgkmcnt(0)
	s_barrier
	v_mfma_f32_16x16x32_bf16 v[60:63], v[152:155], v[184:187], v[60:63]
	v_mfma_f32_16x16x32_bf16 v[56:59], v[160:163], v[184:187], v[56:59]
	v_mfma_f32_16x16x32_bf16 v[44:47], v[152:155], v[192:195], v[44:47]
	v_mfma_f32_16x16x32_bf16 v[40:43], v[160:163], v[192:195], v[40:43]
	v_mfma_f32_16x16x32_bf16 v[28:31], v[152:155], v[200:203], v[28:31]
	v_mfma_f32_16x16x32_bf16 v[24:27], v[160:163], v[200:203], v[24:27]
	v_mfma_f32_16x16x32_bf16 v[12:15], v[152:155], v[208:211], v[12:15]
	v_mfma_f32_16x16x32_bf16 v[8:11], v[160:163], v[208:211], v[8:11]
	v_mfma_f32_16x16x32_bf16 v[60:63], v[156:159], v[188:191], v[60:63]
	v_mfma_f32_16x16x32_bf16 v[56:59], v[164:167], v[188:191], v[56:59]
	v_mfma_f32_16x16x32_bf16 v[44:47], v[156:159], v[196:199], v[44:47]
	v_mfma_f32_16x16x32_bf16 v[40:43], v[164:167], v[196:199], v[40:43]
	v_mfma_f32_16x16x32_bf16 v[28:31], v[156:159], v[204:207], v[28:31]
	v_mfma_f32_16x16x32_bf16 v[24:27], v[164:167], v[204:207], v[24:27]
	v_mfma_f32_16x16x32_bf16 v[12:15], v[156:159], v[212:215], v[12:15]
	v_mfma_f32_16x16x32_bf16 v[8:11], v[164:167], v[212:215], v[8:11]
	v_mfma_f32_16x16x32_bf16 v[52:55], v[168:171], v[184:187], v[52:55]
	v_mfma_f32_16x16x32_bf16 v[48:51], v[176:179], v[184:187], v[48:51]
	v_mfma_f32_16x16x32_bf16 v[36:39], v[168:171], v[192:195], v[36:39]
	v_mfma_f32_16x16x32_bf16 v[32:35], v[176:179], v[192:195], v[32:35]
	v_mfma_f32_16x16x32_bf16 v[20:23], v[168:171], v[200:203], v[20:23]
	v_mfma_f32_16x16x32_bf16 v[16:19], v[176:179], v[200:203], v[16:19]
	v_mfma_f32_16x16x32_bf16 v[4:7], v[168:171], v[208:211], v[4:7]
	v_mfma_f32_16x16x32_bf16 v[0:3], v[176:179], v[208:211], v[0:3]
	v_mfma_f32_16x16x32_bf16 v[52:55], v[172:175], v[188:191], v[52:55]
	v_mfma_f32_16x16x32_bf16 v[48:51], v[180:183], v[188:191], v[48:51]
	v_mfma_f32_16x16x32_bf16 v[36:39], v[172:175], v[196:199], v[36:39]
	v_mfma_f32_16x16x32_bf16 v[32:35], v[180:183], v[196:199], v[32:35]
	v_mfma_f32_16x16x32_bf16 v[20:23], v[172:175], v[204:207], v[20:23]
	v_mfma_f32_16x16x32_bf16 v[16:19], v[180:183], v[204:207], v[16:19]
	v_mfma_f32_16x16x32_bf16 v[4:7], v[172:175], v[212:215], v[4:7]
	v_mfma_f32_16x16x32_bf16 v[0:3], v[180:183], v[212:215], v[0:3]
	s_barrier
	s_add_i32 s63, s63, 2
	s_add_u32 s64, s64, 0x100
	s_addc_u32 s65, s65, 0
	s_add_u32 s53, s53, 0x100
	s_addc_u32 s61, s61, 0
	s_cmp_gt_u32 s63, 29
	s_cbranch_scc0 .LBB0_292
	s_and_b64 vcc, exec, s[14:15]
	s_cbranch_vccz .LBB0_295
	s_barrier

; #define PG8_STAGE(bufoff, gbase, voff) do { _Pragma("unroll") for (int _i = 0; _i < 2; ++_i) \
;         __builtin_amdgcn_global_load_lds((const unsigned*)((const char*)(gbase) + (voff)[_i]), (LAS unsigned*)(lds + (bufoff) + ldsw + _i * 8192), 16, 0, 0); } while (0)
; #define PG8_LDA(dst, b, h) do { _Pragma("unroll") for (int m = 0; m < 4; ++m) _Pragma("unroll") for (int k = 0; k < 2; ++k) dst[m][k] = *(const LAS bf16x8*)(lds + PG8_SA(b, h) + aoff + m * 2048 + k * 1024); } while (0)
; #define PG8_LDB(dst, b, h) do { _Pragma("unroll") for (int n = 0; n < 2; ++n) _Pragma("unroll") for (int k = 0; k < 2; ++k) dst[n][k] = *(const LAS bf16x8*)(lds + PG8_SB(b, h) + boff + n * 2048 + k * 1024); } while (0)
; #define PG8_MMA(ai, bj, At, Bt) do { __builtin_amdgcn_s_setprio(1); _Pragma("unroll") for (int m = 0; m < 4; ++m) _Pragma("unroll") for (int n = 0; n < 2; ++n) _Pragma("unroll") for (int k = 0; k < 2; ++k) \
;         acc[ai][bj][m][n] = __builtin_amdgcn_mfma_f32_16x16x32_bf16(Bt[n][k], At[m][k], acc[ai][bj][m][n], 0, 0, 0); __builtin_amdgcn_s_setprio(0); } while (0)
; #define PG8_WAIT_V(n) asm volatile("s_waitcnt vmcnt(" #n ")" ::: "memory")
; #define PG8_WAIT_L(n) asm volatile("s_waitcnt lgkmcnt(" #n ")" ::: "memory")
; #define PG8_BAR __builtin_amdgcn_s_barrier()
; #define PG8_SCHED __builtin_amdgcn_sched_barrier(0)
; template <class Desc, class Epi>
; DI void gemm_phase(LAS unsigned char* lds, const Desc& D, const Epi& E, int wv) {
;     ...
;         for (int t = 0; t < nt; t += 2) {
;             const bool last = (t == nt - 2);
;             const char* a1 = cA + (size_t)(t + 1) * kstep;
;             const char* a2 = last ? nA : cA + (size_t)(t + 2) * kstep; const char* b2 = last ? nB : cB + (size_t)(t + 2) * kstep;
;             const char* a3 = a2 + kstep; const char* b3 = b2 + kstep;
;             PG8_LDB(B0, 0, 0); PG8_LDB(B1, 0, 1); PG8_SCHED; PG8_LDA(At, 0, 0); PG8_STAGE(PG8_SA(1, 1), a1 + hstepA, voffA);
;             PG8_WAIT_V(8); PG8_WAIT_L(0); PG8_BAR; PG8_MMA(0, 0, At, B0); PG8_MMA(0, 1, At, B1); PG8_BAR; PG8_SCHED;
;             PG8_LDA(At, 0, 1); PG8_STAGE(PG8_SB(0, 0), b2, voffB); PG8_STAGE(PG8_SB(0, 1), b2 + hstepB, voffB); PG8_STAGE(PG8_SA(0, 0), a2, voffA);
.LBB0_339:
	ds_read_b128 v[142:145], v151
	ds_read_b128 v[146:149], v151 offset:1024
	ds_read_b128 v[158:161], v151 offset:2048
	ds_read_b128 v[162:165], v151 offset:3072
	ds_read_b128 v[166:169], v152
	ds_read_b128 v[170:173], v152 offset:1024
	ds_read_b128 v[174:177], v152 offset:2048
	ds_read_b128 v[178:181], v152 offset:3072
	s_add_u32 s8, s6, 0xfffe0080
	s_addc_u32 s9, s7, -1
	s_cmp_eq_u32 s67, 4
	s_cselect_b32 s65, s61, s9
	s_cselect_b32 s64, s60, s8
	s_cselect_b32 s9, s63, s66
	s_cselect_b32 s8, s62, s53
	v_lshl_add_u64 v[214:215], s[6:7], 0, v[138:139]
	s_add_i32 m0, s3, 0xc000
	ds_read_b128 v[182:185], v153
	ds_read_b128 v[186:189], v153 offset:1024
	ds_read_b128 v[190:193], v153 offset:2048
	ds_read_b128 v[194:197], v153 offset:3072
	ds_read_b128 v[198:201], v153 offset:4096
	ds_read_b128 v[202:205], v153 offset:5120
	ds_read_b128 v[206:209], v153 offset:6144
	ds_read_b128 v[210:213], v153 offset:7168
	global_load_lds_dwordx4 v[214:215], off
	v_lshl_add_u64 v[214:215], s[6:7], 0, v[140:141]
	s_add_i32 m0, s3, 0xe000
	s_nop 0
	global_load_lds_dwordx4 v[214:215], off
	s_waitcnt vmcnt(8)
	s_waitcnt lgkmcnt(0)
	s_barrier
	v_mfma_f32_16x16x32_bf16 v[124:127], v[142:145], v[182:185], v[124:127]
	v_mfma_f32_16x16x32_bf16 v[120:123], v[158:161], v[182:185], v[120:123]
	v_mfma_f32_16x16x32_bf16 v[108:111], v[142:145], v[190:193], v[108:111]
	v_mfma_f32_16x16x32_bf16 v[104:107], v[158:161], v[190:193], v[104:107]
	v_mfma_f32_16x16x32_bf16 v[92:95], v[142:145], v[198:201], v[92:95]
	v_mfma_f32_16x16x32_bf16 v[88:91], v[158:161], v[198:201], v[88:91]
	v_mfma_f32_16x16x32_bf16 v[76:79], v[142:145], v[206:209], v[76:79]
	v_mfma_f32_16x16x32_bf16 v[72:75], v[158:161], v[206:209], v[72:75]
	v_mfma_f32_16x16x32_bf16 v[124:127], v[146:149], v[186:189], v[124:127]
	v_mfma_f32_16x16x32_bf16 v[120:123], v[162:165], v[186:189], v[120:123]
	v_mfma_f32_16x16x32_bf16 v[108:111], v[146:149], v[194:197], v[108:111]
	v_mfma_f32_16x16x32_bf16 v[104:107], v[162:165], v[194:197], v[104:107]
	v_mfma_f32_16x16x32_bf16 v[92:95], v[146:149], v[202:205], v[92:95]
	v_mfma_f32_16x16x32_bf16 v[88:91], v[162:165], v[202:205], v[88:91]
	v_mfma_f32_16x16x32_bf16 v[76:79], v[146:149], v[210:213], v[76:79]
	v_mfma_f32_16x16x32_bf16 v[72:75], v[162:165], v[210:213], v[72:75]
	v_mfma_f32_16x16x32_bf16 v[116:119], v[166:169], v[182:185], v[116:119]
	v_mfma_f32_16x16x32_bf16 v[112:115], v[174:177], v[182:185], v[112:115]
	v_mfma_f32_16x16x32_bf16 v[100:103], v[166:169], v[190:193], v[100:103]
	v_mfma_f32_16x16x32_bf16 v[96:99], v[174:177], v[190:193], v[96:99]
	v_mfma_f32_16x16x32_bf16 v[84:87], v[166:169], v[198:201], v[84:87]
	v_mfma_f32_16x16x32_bf16 v[80:83], v[174:177], v[198:201], v[80:83]
	v_mfma_f32_16x16x32_bf16 v[68:71], v[166:169], v[206:209], v[68:71]
	v_mfma_f32_16x16x32_bf16 v[64:67], v[174:177], v[206:209], v[64:67]
	v_mfma_f32_16x16x32_bf16 v[116:119], v[170:173], v[186:189], v[116:119]
	v_mfma_f32_16x16x32_bf16 v[112:115], v[178:181], v[186:189], v[112:115]
	v_mfma_f32_16x16x32_bf16 v[100:103], v[170:173], v[194:197], v[100:103]
	v_mfma_f32_16x16x32_bf16 v[96:99], v[178:181], v[194:197], v[96:99]
	v_mfma_f32_16x16x32_bf16 v[84:87], v[170:173], v[202:205], v[84:87]
	v_mfma_f32_16x16x32_bf16 v[80:83], v[178:181], v[202:205], v[80:83]
	v_mfma_f32_16x16x32_bf16 v[68:71], v[170:173], v[210:213], v[68:71]
	v_mfma_f32_16x16x32_bf16 v[64:67], v[178:181], v[210:213], v[64:67]
	s_barrier
	s_add_i32 s68, s41, s2
	v_lshl_add_u64 v[214:215], s[8:9], 0, v[130:131]
	s_mov_b32 m0, s68
	ds_read_b128 v[182:185], v153 offset:16384
	ds_read_b128 v[186:189], v153 offset:17408
	ds_read_b128 v[190:193], v153 offset:18432
	ds_read_b128 v[194:197], v153 offset:19456
	ds_read_b128 v[198:201], v153 offset:20480
	ds_read_b128 v[202:205], v153 offset:21504
	ds_read_b128 v[206:209], v153 offset:22528
	ds_read_b128 v[210:213], v153 offset:23552
	global_load_lds_dwordx4 v[214:215], off
	s_add_i32 m0, s68, 0x2000
	s_add_u32 s68, s8, 0x80000
	v_lshl_add_u64 v[216:217], s[8:9], 0, v[134:135]
	s_addc_u32 s69, s9, 0
	s_add_i32 s70, s42, s2
	global_load_lds_dwordx4 v[216:217], off
	v_lshl_add_u64 v[218:219], s[68:69], 0, v[130:131]
	s_mov_b32 m0, s70
	v_lshl_add_u64 v[220:221], s[64:65], 0, v[132:133]
	global_load_lds_dwordx4 v[218:219], off
	v_lshl_add_u64 v[218:219], s[68:69], 0, v[134:135]
	s_add_i32 m0, s70, 0x2000
	s_nop 0
	global_load_lds_dwordx4 v[218:219], off
	v_lshl_add_u64 v[218:219], s[64:65], 0, v[128:129]
	s_mov_b32 m0, s3
	s_nop 0
	global_load_lds_dwordx4 v[218:219], off
	s_mov_b32 m0, s28
	s_nop 0
	global_load_lds_dwordx4 v[220:221], off
	s_waitcnt vmcnt(8)
	s_waitcnt lgkmcnt(0)
	s_barrier
; #define PG8_STAGE(bufoff, gbase, voff) do { _Pragma("unroll") for (int _i = 0; _i < 2; ++_i) \
;         __builtin_amdgcn_global_load_lds((const unsigned*)((const char*)(gbase) + (voff)[_i]), (LAS unsigned*)(lds + (bufoff) + ldsw + _i * 8192), 16, 0, 0); } while (0)
; #define PG8_LDA(dst, b, h) do { _Pragma("unroll") for (int m = 0; m < 4; ++m) _Pragma("unroll") for (int k = 0; k < 2; ++k) dst[m][k] = *(const LAS bf16x8*)(lds + PG8_SA(b, h) + aoff + m * 2048 + k * 1024); } while (0)
; #define PG8_LDB(dst, b, h) do { _Pragma("unroll") for (int n = 0; n < 2; ++n) _Pragma("unroll") for (int k = 0; k < 2; ++k) dst[n][k] = *(const LAS bf16x8*)(lds + PG8_SB(b, h) + boff + n * 2048 + k * 1024); } while (0)
; #define PG8_MMA(ai, bj, At, Bt) do { __builtin_amdgcn_s_setprio(1); _Pragma("unroll") for (int m = 0; m < 4; ++m) _Pragma("unroll") for (int n = 0; n < 2; ++n) _Pragma("unroll") for (int k = 0; k < 2; ++k) \
;         acc[ai][bj][m][n] = __builtin_amdgcn_mfma_f32_16x16x32_bf16(Bt[n][k], At[m][k], acc[ai][bj][m][n], 0, 0, 0); __builtin_amdgcn_s_setprio(0); } while (0)
; #define PG8_WAIT_V(n) asm volatile("s_waitcnt vmcnt(" #n ")" ::: "memory")
; #define PG8_WAIT_L(n) asm volatile("s_waitcnt lgkmcnt(" #n ")" ::: "memory")
; #define PG8_BAR __builtin_amdgcn_s_barrier()
; #define PG8_SCHED __builtin_amdgcn_sched_barrier(0)
; template <class Desc, class Epi>
; DI void gemm_phase(LAS unsigned char* lds, const Desc& D, const Epi& E, int wv) {
;     ...
;             PG8_WAIT_V(8); PG8_WAIT_L(0); PG8_BAR; PG8_MMA(1, 0, At, B0); PG8_MMA(1, 1, At, B1); PG8_BAR; PG8_SCHED;
;             PG8_LDB(B0, 1, 0); PG8_LDB(B1, 1, 1); PG8_SCHED; PG8_LDA(At, 1, 0); PG8_STAGE(PG8_SA(0, 1), a2 + hstepA, voffA);
;             PG8_WAIT_V(8); PG8_WAIT_L(0); PG8_BAR; PG8_MMA(0, 0, At, B0); PG8_MMA(0, 1, At, B1); PG8_BAR; PG8_SCHED;
	v_mfma_f32_16x16x32_bf16 v[60:63], v[142:145], v[182:185], v[60:63]
	v_mfma_f32_16x16x32_bf16 v[56:59], v[158:161], v[182:185], v[56:59]
	v_mfma_f32_16x16x32_bf16 v[44:47], v[142:145], v[190:193], v[44:47]
	v_mfma_f32_16x16x32_bf16 v[40:43], v[158:161], v[190:193], v[40:43]
	v_mfma_f32_16x16x32_bf16 v[28:31], v[142:145], v[198:201], v[28:31]
	v_mfma_f32_16x16x32_bf16 v[24:27], v[158:161], v[198:201], v[24:27]
	v_mfma_f32_16x16x32_bf16 v[12:15], v[142:145], v[206:209], v[12:15]
	v_mfma_f32_16x16x32_bf16 v[8:11], v[158:161], v[206:209], v[8:11]
	v_mfma_f32_16x16x32_bf16 v[60:63], v[146:149], v[186:189], v[60:63]
	v_mfma_f32_16x16x32_bf16 v[56:59], v[162:165], v[186:189], v[56:59]
	v_mfma_f32_16x16x32_bf16 v[44:47], v[146:149], v[194:197], v[44:47]
	v_mfma_f32_16x16x32_bf16 v[40:43], v[162:165], v[194:197], v[40:43]
	v_mfma_f32_16x16x32_bf16 v[28:31], v[146:149], v[202:205], v[28:31]
	v_mfma_f32_16x16x32_bf16 v[24:27], v[162:165], v[202:205], v[24:27]
	v_mfma_f32_16x16x32_bf16 v[12:15], v[146:149], v[210:213], v[12:15]
	v_mfma_f32_16x16x32_bf16 v[8:11], v[162:165], v[210:213], v[8:11]
	v_mfma_f32_16x16x32_bf16 v[52:55], v[166:169], v[182:185], v[52:55]
	v_mfma_f32_16x16x32_bf16 v[48:51], v[174:177], v[182:185], v[48:51]
	v_mfma_f32_16x16x32_bf16 v[36:39], v[166:169], v[190:193], v[36:39]
	v_mfma_f32_16x16x32_bf16 v[32:35], v[174:177], v[190:193], v[32:35]
	v_mfma_f32_16x16x32_bf16 v[20:23], v[166:169], v[198:201], v[20:23]
	v_mfma_f32_16x16x32_bf16 v[16:19], v[174:177], v[198:201], v[16:19]
	v_mfma_f32_16x16x32_bf16 v[4:7], v[166:169], v[206:209], v[4:7]
	v_mfma_f32_16x16x32_bf16 v[0:3], v[174:177], v[206:209], v[0:3]
	v_mfma_f32_16x16x32_bf16 v[52:55], v[170:173], v[186:189], v[52:55]
	v_mfma_f32_16x16x32_bf16 v[48:51], v[178:181], v[186:189], v[48:51]
	v_mfma_f32_16x16x32_bf16 v[36:39], v[170:173], v[194:197], v[36:39]
	v_mfma_f32_16x16x32_bf16 v[32:35], v[178:181], v[194:197], v[32:35]
	v_mfma_f32_16x16x32_bf16 v[20:23], v[170:173], v[202:205], v[20:23]
	v_mfma_f32_16x16x32_bf16 v[16:19], v[178:181], v[202:205], v[16:19]
	v_mfma_f32_16x16x32_bf16 v[4:7], v[170:173], v[210:213], v[4:7]
	v_mfma_f32_16x16x32_bf16 v[0:3], v[178:181], v[210:213], v[0:3]
	s_barrier
	s_add_i32 s68, 0, 0x18000
	v_add_u32_e32 v136, s68, v150
	s_add_i32 s69, 0, 0x1c000
	ds_read_b128 v[142:145], v136
	ds_read_b128 v[146:149], v136 offset:1024
	ds_read_b128 v[158:161], v136 offset:2048
	ds_read_b128 v[162:165], v136 offset:3072
	v_add_u32_e32 v136, s69, v150
	ds_read_b128 v[166:169], v136
	ds_read_b128 v[170:173], v136 offset:1024
	ds_read_b128 v[174:177], v136 offset:2048
	ds_read_b128 v[178:181], v136 offset:3072
	s_add_u32 s64, s64, 0x20000
	s_addc_u32 s65, s65, 0
	s_mov_b32 m0, s29
	v_lshl_add_u64 v[222:223], s[64:65], 0, v[128:129]
	ds_read_b128 v[182:185], v153 offset:32768
	ds_read_b128 v[186:189], v153 offset:33792
	ds_read_b128 v[190:193], v153 offset:34816
	ds_read_b128 v[194:197], v153 offset:35840
	ds_read_b128 v[198:201], v153 offset:36864
	ds_read_b128 v[202:205], v153 offset:37888
	ds_read_b128 v[206:209], v153 offset:38912
	ds_read_b128 v[210:213], v153 offset:39936
	global_load_lds_dwordx4 v[222:223], off
	v_lshl_add_u64 v[222:223], s[64:65], 0, v[132:133]
	s_mov_b32 m0, s30
	s_nop 0
	global_load_lds_dwordx4 v[222:223], off
	s_waitcnt vmcnt(8)
	s_waitcnt lgkmcnt(0)
	s_barrier
	v_mfma_f32_16x16x32_bf16 v[124:127], v[142:145], v[182:185], v[124:127]
	v_mfma_f32_16x16x32_bf16 v[120:123], v[158:161], v[182:185], v[120:123]
	v_mfma_f32_16x16x32_bf16 v[108:111], v[142:145], v[190:193], v[108:111]
	v_mfma_f32_16x16x32_bf16 v[104:107], v[158:161], v[190:193], v[104:107]
	v_mfma_f32_16x16x32_bf16 v[92:95], v[142:145], v[198:201], v[92:95]
	v_mfma_f32_16x16x32_bf16 v[88:91], v[158:161], v[198:201], v[88:91]
	v_mfma_f32_16x16x32_bf16 v[76:79], v[142:145], v[206:209], v[76:79]
	v_mfma_f32_16x16x32_bf16 v[72:75], v[158:161], v[206:209], v[72:75]
	v_mfma_f32_16x16x32_bf16 v[124:127], v[146:149], v[186:189], v[124:127]
	v_mfma_f32_16x16x32_bf16 v[120:123], v[162:165], v[186:189], v[120:123]
	v_mfma_f32_16x16x32_bf16 v[108:111], v[146:149], v[194:197], v[108:111]
	v_mfma_f32_16x16x32_bf16 v[104:107], v[162:165], v[194:197], v[104:107]
	v_mfma_f32_16x16x32_bf16 v[92:95], v[146:149], v[202:205], v[92:95]
	v_mfma_f32_16x16x32_bf16 v[88:91], v[162:165], v[202:205], v[88:91]
	v_mfma_f32_16x16x32_bf16 v[76:79], v[146:149], v[210:213], v[76:79]
	v_mfma_f32_16x16x32_bf16 v[72:75], v[162:165], v[210:213], v[72:75]
	v_mfma_f32_16x16x32_bf16 v[116:119], v[166:169], v[182:185], v[116:119]
	v_mfma_f32_16x16x32_bf16 v[112:115], v[174:177], v[182:185], v[112:115]
	v_mfma_f32_16x16x32_bf16 v[100:103], v[166:169], v[190:193], v[100:103]
	v_mfma_f32_16x16x32_bf16 v[96:99], v[174:177], v[190:193], v[96:99]
	v_mfma_f32_16x16x32_bf16 v[84:87], v[166:169], v[198:201], v[84:87]
	v_mfma_f32_16x16x32_bf16 v[80:83], v[174:177], v[198:201], v[80:83]
	v_mfma_f32_16x16x32_bf16 v[68:71], v[166:169], v[206:209], v[68:71]
	v_mfma_f32_16x16x32_bf16 v[64:67], v[174:177], v[206:209], v[64:67]
	v_mfma_f32_16x16x32_bf16 v[116:119], v[170:173], v[186:189], v[116:119]
	v_mfma_f32_16x16x32_bf16 v[112:115], v[178:181], v[186:189], v[112:115]
	v_mfma_f32_16x16x32_bf16 v[100:103], v[170:173], v[194:197], v[100:103]
	v_mfma_f32_16x16x32_bf16 v[96:99], v[178:181], v[194:197], v[96:99]
	v_mfma_f32_16x16x32_bf16 v[84:87], v[170:173], v[202:205], v[84:87]
	v_mfma_f32_16x16x32_bf16 v[80:83], v[178:181], v[202:205], v[80:83]
	v_mfma_f32_16x16x32_bf16 v[68:71], v[170:173], v[210:213], v[68:71]
	v_mfma_f32_16x16x32_bf16 v[64:67], v[178:181], v[210:213], v[64:67]
	s_barrier
; #define PG8_STAGE(bufoff, gbase, voff) do { _Pragma("unroll") for (int _i = 0; _i < 2; ++_i) \
;         __builtin_amdgcn_global_load_lds((const unsigned*)((const char*)(gbase) + (voff)[_i]), (LAS unsigned*)(lds + (bufoff) + ldsw + _i * 8192), 16, 0, 0); } while (0)
; #define PG8_LDA(dst, b, h) do { _Pragma("unroll") for (int m = 0; m < 4; ++m) _Pragma("unroll") for (int k = 0; k < 2; ++k) dst[m][k] = *(const LAS bf16x8*)(lds + PG8_SA(b, h) + aoff + m * 2048 + k * 1024); } while (0)
; #define PG8_MMA(ai, bj, At, Bt) do { __builtin_amdgcn_s_setprio(1); _Pragma("unroll") for (int m = 0; m < 4; ++m) _Pragma("unroll") for (int n = 0; n < 2; ++n) _Pragma("unroll") for (int k = 0; k < 2; ++k) \
;         acc[ai][bj][m][n] = __builtin_amdgcn_mfma_f32_16x16x32_bf16(Bt[n][k], At[m][k], acc[ai][bj][m][n], 0, 0, 0); __builtin_amdgcn_s_setprio(0); } while (0)
; #define PG8_WAIT_V(n) asm volatile("s_waitcnt vmcnt(" #n ")" ::: "memory")
; #define PG8_WAIT_L(n) asm volatile("s_waitcnt lgkmcnt(" #n ")" ::: "memory")
; #define PG8_BAR __builtin_amdgcn_s_barrier()
; #define PG8_SCHED __builtin_amdgcn_sched_barrier(0)
; template <class Desc, class Epi>
; DI void gemm_phase(LAS unsigned char* lds, const Desc& D, const Epi& E, int wv) {
;     ...
;             PG8_LDA(At, 1, 1); PG8_STAGE(PG8_SB(1, 0), b3, voffB); PG8_STAGE(PG8_SB(1, 1), b3 + hstepB, voffB); PG8_STAGE(PG8_SA(1, 0), a3, voffA);
;             PG8_WAIT_V(8); PG8_WAIT_L(0); PG8_BAR; PG8_MMA(1, 0, At, B0); PG8_MMA(1, 1, At, B1); PG8_BAR; PG8_SCHED;
;         }
;         if (wr == 0) PG8_BAR;
	s_add_i32 s64, s68, s2
	v_lshl_add_u64 v[214:215], v[214:215], 0, s[20:21]
	s_mov_b32 m0, s64
	ds_read_b128 v[182:185], v153 offset:49152
	ds_read_b128 v[186:189], v153 offset:50176
	ds_read_b128 v[190:193], v153 offset:51200
	ds_read_b128 v[194:197], v153 offset:52224
	ds_read_b128 v[198:201], v153 offset:53248
	ds_read_b128 v[202:205], v153 offset:54272
	ds_read_b128 v[206:209], v153 offset:55296
	ds_read_b128 v[210:213], v153 offset:56320
	global_load_lds_dwordx4 v[214:215], off
	s_add_i32 m0, s64, 0x2000
	s_add_u32 s8, s8, 0x80080
	v_lshl_add_u64 v[214:215], v[216:217], 0, s[20:21]
	s_addc_u32 s9, s9, 0
	s_add_i32 s64, s69, s2
	global_load_lds_dwordx4 v[214:215], off
	v_lshl_add_u64 v[214:215], s[8:9], 0, v[130:131]
	s_mov_b32 m0, s64
	s_nop 0
	global_load_lds_dwordx4 v[214:215], off
	v_lshl_add_u64 v[214:215], s[8:9], 0, v[134:135]
	s_add_i32 m0, s64, 0x2000
	s_nop 0
	global_load_lds_dwordx4 v[214:215], off
	v_lshl_add_u64 v[214:215], v[218:219], 0, s[20:21]
	s_mov_b32 m0, s35
	s_nop 0
	global_load_lds_dwordx4 v[214:215], off
	v_lshl_add_u64 v[214:215], v[220:221], 0, s[20:21]
	s_mov_b32 m0, s40
	s_nop 0
	global_load_lds_dwordx4 v[214:215], off
	s_waitcnt vmcnt(8)
	s_waitcnt lgkmcnt(0)
	s_barrier
	v_mfma_f32_16x16x32_bf16 v[60:63], v[142:145], v[182:185], v[60:63]
	v_mfma_f32_16x16x32_bf16 v[56:59], v[158:161], v[182:185], v[56:59]
	v_mfma_f32_16x16x32_bf16 v[44:47], v[142:145], v[190:193], v[44:47]
	v_mfma_f32_16x16x32_bf16 v[40:43], v[158:161], v[190:193], v[40:43]
	v_mfma_f32_16x16x32_bf16 v[28:31], v[142:145], v[198:201], v[28:31]
	v_mfma_f32_16x16x32_bf16 v[24:27], v[158:161], v[198:201], v[24:27]
	v_mfma_f32_16x16x32_bf16 v[12:15], v[142:145], v[206:209], v[12:15]
	v_mfma_f32_16x16x32_bf16 v[8:11], v[158:161], v[206:209], v[8:11]
	v_mfma_f32_16x16x32_bf16 v[60:63], v[146:149], v[186:189], v[60:63]
	v_mfma_f32_16x16x32_bf16 v[56:59], v[162:165], v[186:189], v[56:59]
	v_mfma_f32_16x16x32_bf16 v[44:47], v[146:149], v[194:197], v[44:47]
	v_mfma_f32_16x16x32_bf16 v[40:43], v[162:165], v[194:197], v[40:43]
	v_mfma_f32_16x16x32_bf16 v[28:31], v[146:149], v[202:205], v[28:31]
	v_mfma_f32_16x16x32_bf16 v[24:27], v[162:165], v[202:205], v[24:27]
	v_mfma_f32_16x16x32_bf16 v[12:15], v[146:149], v[210:213], v[12:15]
	v_mfma_f32_16x16x32_bf16 v[8:11], v[162:165], v[210:213], v[8:11]
	v_mfma_f32_16x16x32_bf16 v[52:55], v[166:169], v[182:185], v[52:55]
	v_mfma_f32_16x16x32_bf16 v[48:51], v[174:177], v[182:185], v[48:51]
	v_mfma_f32_16x16x32_bf16 v[36:39], v[166:169], v[190:193], v[36:39]
	v_mfma_f32_16x16x32_bf16 v[32:35], v[174:177], v[190:193], v[32:35]
	v_mfma_f32_16x16x32_bf16 v[20:23], v[166:169], v[198:201], v[20:23]
	v_mfma_f32_16x16x32_bf16 v[16:19], v[174:177], v[198:201], v[16:19]
	v_mfma_f32_16x16x32_bf16 v[4:7], v[166:169], v[206:209], v[4:7]
	v_mfma_f32_16x16x32_bf16 v[0:3], v[174:177], v[206:209], v[0:3]
	v_mfma_f32_16x16x32_bf16 v[52:55], v[170:173], v[186:189], v[52:55]
	v_mfma_f32_16x16x32_bf16 v[48:51], v[178:181], v[186:189], v[48:51]
	v_mfma_f32_16x16x32_bf16 v[36:39], v[170:173], v[194:197], v[36:39]
	v_mfma_f32_16x16x32_bf16 v[32:35], v[178:181], v[194:197], v[32:35]
	v_mfma_f32_16x16x32_bf16 v[20:23], v[170:173], v[202:205], v[20:23]
	v_mfma_f32_16x16x32_bf16 v[16:19], v[178:181], v[202:205], v[16:19]
	v_mfma_f32_16x16x32_bf16 v[4:7], v[170:173], v[210:213], v[4:7]
	v_mfma_f32_16x16x32_bf16 v[0:3], v[178:181], v[210:213], v[0:3]
	s_barrier
	s_add_i32 s67, s67, 2
	s_add_u32 s6, s6, 0x100
	s_addc_u32 s7, s7, 0
	s_add_u32 s53, s53, 0x100
	s_addc_u32 s66, s66, 0
	s_cmp_gt_u32 s67, 5
	s_cbranch_scc0 .LBB0_339
	s_and_b64 vcc, exec, s[22:23]
	s_cbranch_vccz .LBB0_342
	s_barrier

; #define PG8_STAGE(bufoff, gbase, voff) do { _Pragma("unroll") for (int _i = 0; _i < 2; ++_i) \
;         __builtin_amdgcn_global_load_lds((const unsigned*)((const char*)(gbase) + (voff)[_i]), (LAS unsigned*)(lds + (bufoff) + ldsw + _i * 8192), 16, 0, 0); } while (0)
; #define PG8_LDA(dst, b, h) do { _Pragma("unroll") for (int m = 0; m < 4; ++m) _Pragma("unroll") for (int k = 0; k < 2; ++k) dst[m][k] = *(const LAS bf16x8*)(lds + PG8_SA(b, h) + aoff + m * 2048 + k * 1024); } while (0)
; #define PG8_LDB(dst, b, h) do { _Pragma("unroll") for (int n = 0; n < 2; ++n) _Pragma("unroll") for (int k = 0; k < 2; ++k) dst[n][k] = *(const LAS bf16x8*)(lds + PG8_SB(b, h) + boff + n * 2048 + k * 1024); } while (0)
; #define PG8_MMA(ai, bj, At, Bt) do { __builtin_amdgcn_s_setprio(1); _Pragma("unroll") for (int m = 0; m < 4; ++m) _Pragma("unroll") for (int n = 0; n < 2; ++n) _Pragma("unroll") for (int k = 0; k < 2; ++k) \
;         acc[ai][bj][m][n] = __builtin_amdgcn_mfma_f32_16x16x32_bf16(Bt[n][k], At[m][k], acc[ai][bj][m][n], 0, 0, 0); __builtin_amdgcn_s_setprio(0); } while (0)
; #define PG8_WAIT_V(n) asm volatile("s_waitcnt vmcnt(" #n ")" ::: "memory")
; #define PG8_WAIT_L(n) asm volatile("s_waitcnt lgkmcnt(" #n ")" ::: "memory")
; #define PG8_BAR __builtin_amdgcn_s_barrier()
; #define PG8_SCHED __builtin_amdgcn_sched_barrier(0)
; template <class Desc, class Epi>
; DI void gemm_phase(LAS unsigned char* lds, const Desc& D, const Epi& E, int wv) {
;     ...
;         for (int t = 0; t < nt; t += 2) {
;             const bool last = (t == nt - 2);
;             const char* a1 = cA + (size_t)(t + 1) * kstep;
;             const char* a2 = last ? nA : cA + (size_t)(t + 2) * kstep; const char* b2 = last ? nB : cB + (size_t)(t + 2) * kstep;
;             const char* a3 = a2 + kstep; const char* b3 = b2 + kstep;
;             PG8_LDB(B0, 0, 0); PG8_LDB(B1, 0, 1); PG8_SCHED; PG8_LDA(At, 0, 0); PG8_STAGE(PG8_SA(1, 1), a1 + hstepA, voffA);
;             PG8_WAIT_V(8); PG8_WAIT_L(0); PG8_BAR; PG8_MMA(0, 0, At, B0); PG8_MMA(0, 1, At, B1); PG8_BAR; PG8_SCHED;
;             PG8_LDA(At, 0, 1); PG8_STAGE(PG8_SB(0, 0), b2, voffB); PG8_STAGE(PG8_SB(0, 1), b2 + hstepB, voffB); PG8_STAGE(PG8_SA(0, 0), a2, voffA);
.LBB0_581:
	ds_read_b128 v[128:131], v185
	ds_read_b128 v[132:135], v185 offset:1024
	ds_read_b128 v[150:153], v185 offset:2048
	ds_read_b128 v[154:157], v185 offset:3072
	ds_read_b128 v[158:161], v186
	ds_read_b128 v[162:165], v186 offset:1024
	ds_read_b128 v[166:169], v186 offset:2048
	ds_read_b128 v[170:173], v186 offset:3072
	s_add_u32 s49, s66, 0xfff00080
	s_addc_u32 s50, s67, -1
	s_cmp_eq_u32 s48, 28
	s_cselect_b32 s71, s19, s50
	s_cselect_b32 s70, s18, s49
	s_cselect_b32 s69, s21, s47
	s_cselect_b32 s68, s20, s1
	v_lshl_add_u64 v[182:183], s[66:67], 0, v[146:147]
	s_add_i32 m0, s3, 0xc000
	ds_read_b128 v[174:177], v187
	ds_read_b128 v[178:181], v187 offset:1024
	ds_read_b128 v[190:193], v187 offset:2048
	ds_read_b128 v[194:197], v187 offset:3072
	ds_read_b128 v[198:201], v187 offset:4096
	ds_read_b128 v[202:205], v187 offset:5120
	ds_read_b128 v[206:209], v187 offset:6144
	ds_read_b128 v[210:213], v187 offset:7168
	global_load_lds_dwordx4 v[182:183], off
	v_lshl_add_u64 v[182:183], s[66:67], 0, v[148:149]
	s_add_i32 m0, s3, 0xe000
	s_nop 0
	global_load_lds_dwordx4 v[182:183], off
	s_waitcnt vmcnt(8)
	s_waitcnt lgkmcnt(0)
	s_barrier
	v_mfma_f32_16x16x32_bf16 v[124:127], v[128:131], v[174:177], v[124:127]
	v_mfma_f32_16x16x32_bf16 v[120:123], v[150:153], v[174:177], v[120:123]
	v_mfma_f32_16x16x32_bf16 v[108:111], v[128:131], v[190:193], v[108:111]
	v_mfma_f32_16x16x32_bf16 v[104:107], v[150:153], v[190:193], v[104:107]
	v_mfma_f32_16x16x32_bf16 v[92:95], v[128:131], v[198:201], v[92:95]
	v_mfma_f32_16x16x32_bf16 v[88:91], v[150:153], v[198:201], v[88:91]
	v_mfma_f32_16x16x32_bf16 v[76:79], v[128:131], v[206:209], v[76:79]
	v_mfma_f32_16x16x32_bf16 v[72:75], v[150:153], v[206:209], v[72:75]
	v_mfma_f32_16x16x32_bf16 v[124:127], v[132:135], v[178:181], v[124:127]
	v_mfma_f32_16x16x32_bf16 v[120:123], v[154:157], v[178:181], v[120:123]
	v_mfma_f32_16x16x32_bf16 v[108:111], v[132:135], v[194:197], v[108:111]
	v_mfma_f32_16x16x32_bf16 v[104:107], v[154:157], v[194:197], v[104:107]
	v_mfma_f32_16x16x32_bf16 v[92:95], v[132:135], v[202:205], v[92:95]
	v_mfma_f32_16x16x32_bf16 v[88:91], v[154:157], v[202:205], v[88:91]
	v_mfma_f32_16x16x32_bf16 v[76:79], v[132:135], v[210:213], v[76:79]
	v_mfma_f32_16x16x32_bf16 v[72:75], v[154:157], v[210:213], v[72:75]
	v_mfma_f32_16x16x32_bf16 v[116:119], v[158:161], v[174:177], v[116:119]
	v_mfma_f32_16x16x32_bf16 v[112:115], v[166:169], v[174:177], v[112:115]
	v_mfma_f32_16x16x32_bf16 v[100:103], v[158:161], v[190:193], v[100:103]
	v_mfma_f32_16x16x32_bf16 v[96:99], v[166:169], v[190:193], v[96:99]
	v_mfma_f32_16x16x32_bf16 v[84:87], v[158:161], v[198:201], v[84:87]
	v_mfma_f32_16x16x32_bf16 v[80:83], v[166:169], v[198:201], v[80:83]
	v_mfma_f32_16x16x32_bf16 v[68:71], v[158:161], v[206:209], v[68:71]
	v_mfma_f32_16x16x32_bf16 v[64:67], v[166:169], v[206:209], v[64:67]
	v_mfma_f32_16x16x32_bf16 v[116:119], v[162:165], v[178:181], v[116:119]
	v_mfma_f32_16x16x32_bf16 v[112:115], v[170:173], v[178:181], v[112:115]
	v_mfma_f32_16x16x32_bf16 v[100:103], v[162:165], v[194:197], v[100:103]
	v_mfma_f32_16x16x32_bf16 v[96:99], v[170:173], v[194:197], v[96:99]
	v_mfma_f32_16x16x32_bf16 v[84:87], v[162:165], v[202:205], v[84:87]
	v_mfma_f32_16x16x32_bf16 v[80:83], v[170:173], v[202:205], v[80:83]
	v_mfma_f32_16x16x32_bf16 v[68:71], v[162:165], v[210:213], v[68:71]
	v_mfma_f32_16x16x32_bf16 v[64:67], v[170:173], v[210:213], v[64:67]
	s_barrier
	s_add_i32 s49, s42, s2
	v_lshl_add_u64 v[182:183], s[68:69], 0, v[140:141]
	s_mov_b32 m0, s49
	ds_read_b128 v[174:177], v187 offset:16384
	ds_read_b128 v[178:181], v187 offset:17408
	ds_read_b128 v[190:193], v187 offset:18432
	ds_read_b128 v[194:197], v187 offset:19456
	ds_read_b128 v[198:201], v187 offset:20480
	ds_read_b128 v[202:205], v187 offset:21504
	ds_read_b128 v[206:209], v187 offset:22528
	ds_read_b128 v[210:213], v187 offset:23552
	global_load_lds_dwordx4 v[182:183], off
	s_add_i32 m0, s49, 0x2000
	s_add_u32 s50, s68, 0x100000
	v_lshl_add_u64 v[214:215], s[68:69], 0, v[136:137]
	s_addc_u32 s51, s69, 0
	s_add_i32 s49, s43, s2
	global_load_lds_dwordx4 v[214:215], off
	v_lshl_add_u64 v[216:217], s[50:51], 0, v[140:141]
	s_mov_b32 m0, s49
	v_lshl_add_u64 v[218:219], s[70:71], 0, v[138:139]
	global_load_lds_dwordx4 v[216:217], off
	v_lshl_add_u64 v[216:217], s[50:51], 0, v[136:137]
	s_add_i32 m0, s49, 0x2000
	s_nop 0
	global_load_lds_dwordx4 v[216:217], off
	v_lshl_add_u64 v[216:217], s[70:71], 0, v[142:143]
	s_mov_b32 m0, s3
	s_nop 0
	global_load_lds_dwordx4 v[216:217], off
	s_mov_b32 m0, s28
	s_nop 0
	global_load_lds_dwordx4 v[218:219], off
	s_waitcnt vmcnt(8)
	s_waitcnt lgkmcnt(0)
	s_barrier
; #define PG8_STAGE(bufoff, gbase, voff) do { _Pragma("unroll") for (int _i = 0; _i < 2; ++_i) \
;         __builtin_amdgcn_global_load_lds((const unsigned*)((const char*)(gbase) + (voff)[_i]), (LAS unsigned*)(lds + (bufoff) + ldsw + _i * 8192), 16, 0, 0); } while (0)
; #define PG8_LDA(dst, b, h) do { _Pragma("unroll") for (int m = 0; m < 4; ++m) _Pragma("unroll") for (int k = 0; k < 2; ++k) dst[m][k] = *(const LAS bf16x8*)(lds + PG8_SA(b, h) + aoff + m * 2048 + k * 1024); } while (0)
; #define PG8_LDB(dst, b, h) do { _Pragma("unroll") for (int n = 0; n < 2; ++n) _Pragma("unroll") for (int k = 0; k < 2; ++k) dst[n][k] = *(const LAS bf16x8*)(lds + PG8_SB(b, h) + boff + n * 2048 + k * 1024); } while (0)
; #define PG8_MMA(ai, bj, At, Bt) do { __builtin_amdgcn_s_setprio(1); _Pragma("unroll") for (int m = 0; m < 4; ++m) _Pragma("unroll") for (int n = 0; n < 2; ++n) _Pragma("unroll") for (int k = 0; k < 2; ++k) \
;         acc[ai][bj][m][n] = __builtin_amdgcn_mfma_f32_16x16x32_bf16(Bt[n][k], At[m][k], acc[ai][bj][m][n], 0, 0, 0); __builtin_amdgcn_s_setprio(0); } while (0)
; #define PG8_WAIT_V(n) asm volatile("s_waitcnt vmcnt(" #n ")" ::: "memory")
; #define PG8_WAIT_L(n) asm volatile("s_waitcnt lgkmcnt(" #n ")" ::: "memory")
; #define PG8_BAR __builtin_amdgcn_s_barrier()
; #define PG8_SCHED __builtin_amdgcn_sched_barrier(0)
; template <class Desc, class Epi>
; DI void gemm_phase(LAS unsigned char* lds, const Desc& D, const Epi& E, int wv) {
;     ...
;             PG8_WAIT_V(8); PG8_WAIT_L(0); PG8_BAR; PG8_MMA(1, 0, At, B0); PG8_MMA(1, 1, At, B1); PG8_BAR; PG8_SCHED;
;             PG8_LDB(B0, 1, 0); PG8_LDB(B1, 1, 1); PG8_SCHED; PG8_LDA(At, 1, 0); PG8_STAGE(PG8_SA(0, 1), a2 + hstepA, voffA);
;             PG8_WAIT_V(8); PG8_WAIT_L(0); PG8_BAR; PG8_MMA(0, 0, At, B0); PG8_MMA(0, 1, At, B1); PG8_BAR; PG8_SCHED;
	v_mfma_f32_16x16x32_bf16 v[60:63], v[128:131], v[174:177], v[60:63]
	v_mfma_f32_16x16x32_bf16 v[56:59], v[150:153], v[174:177], v[56:59]
	v_mfma_f32_16x16x32_bf16 v[44:47], v[128:131], v[190:193], v[44:47]
	v_mfma_f32_16x16x32_bf16 v[40:43], v[150:153], v[190:193], v[40:43]
	v_mfma_f32_16x16x32_bf16 v[28:31], v[128:131], v[198:201], v[28:31]
	v_mfma_f32_16x16x32_bf16 v[24:27], v[150:153], v[198:201], v[24:27]
	v_mfma_f32_16x16x32_bf16 v[12:15], v[128:131], v[206:209], v[12:15]
	v_mfma_f32_16x16x32_bf16 v[8:11], v[150:153], v[206:209], v[8:11]
	v_mfma_f32_16x16x32_bf16 v[60:63], v[132:135], v[178:181], v[60:63]
	v_mfma_f32_16x16x32_bf16 v[56:59], v[154:157], v[178:181], v[56:59]
	v_mfma_f32_16x16x32_bf16 v[44:47], v[132:135], v[194:197], v[44:47]
	v_mfma_f32_16x16x32_bf16 v[40:43], v[154:157], v[194:197], v[40:43]
	v_mfma_f32_16x16x32_bf16 v[28:31], v[132:135], v[202:205], v[28:31]
	v_mfma_f32_16x16x32_bf16 v[24:27], v[154:157], v[202:205], v[24:27]
	v_mfma_f32_16x16x32_bf16 v[12:15], v[132:135], v[210:213], v[12:15]
	v_mfma_f32_16x16x32_bf16 v[8:11], v[154:157], v[210:213], v[8:11]
	v_mfma_f32_16x16x32_bf16 v[52:55], v[158:161], v[174:177], v[52:55]
	v_mfma_f32_16x16x32_bf16 v[48:51], v[166:169], v[174:177], v[48:51]
	v_mfma_f32_16x16x32_bf16 v[36:39], v[158:161], v[190:193], v[36:39]
	v_mfma_f32_16x16x32_bf16 v[32:35], v[166:169], v[190:193], v[32:35]
	v_mfma_f32_16x16x32_bf16 v[20:23], v[158:161], v[198:201], v[20:23]
	v_mfma_f32_16x16x32_bf16 v[16:19], v[166:169], v[198:201], v[16:19]
	v_mfma_f32_16x16x32_bf16 v[4:7], v[158:161], v[206:209], v[4:7]
	v_mfma_f32_16x16x32_bf16 v[0:3], v[166:169], v[206:209], v[0:3]
	v_mfma_f32_16x16x32_bf16 v[52:55], v[162:165], v[178:181], v[52:55]
	v_mfma_f32_16x16x32_bf16 v[48:51], v[170:173], v[178:181], v[48:51]
	v_mfma_f32_16x16x32_bf16 v[36:39], v[162:165], v[194:197], v[36:39]
	v_mfma_f32_16x16x32_bf16 v[32:35], v[170:173], v[194:197], v[32:35]
	v_mfma_f32_16x16x32_bf16 v[20:23], v[162:165], v[202:205], v[20:23]
	v_mfma_f32_16x16x32_bf16 v[16:19], v[170:173], v[202:205], v[16:19]
	v_mfma_f32_16x16x32_bf16 v[4:7], v[162:165], v[210:213], v[4:7]
	v_mfma_f32_16x16x32_bf16 v[0:3], v[170:173], v[210:213], v[0:3]
	s_barrier
	s_add_i32 s49, 0, 0x18000
	v_add_u32_e32 v144, s49, v184
	s_add_i32 s52, 0, 0x1c000
	ds_read_b128 v[128:131], v144
	ds_read_b128 v[132:135], v144 offset:1024
	ds_read_b128 v[150:153], v144 offset:2048
	ds_read_b128 v[154:157], v144 offset:3072
	v_add_u32_e32 v144, s52, v184
	ds_read_b128 v[158:161], v144
	ds_read_b128 v[162:165], v144 offset:1024
	ds_read_b128 v[166:169], v144 offset:2048
	ds_read_b128 v[170:173], v144 offset:3072
	s_add_u32 s50, s70, 0x100000
	s_addc_u32 s51, s71, 0
	s_mov_b32 m0, s29
	v_lshl_add_u64 v[220:221], s[50:51], 0, v[142:143]
	ds_read_b128 v[174:177], v187 offset:32768
	ds_read_b128 v[178:181], v187 offset:33792
	ds_read_b128 v[190:193], v187 offset:34816
	ds_read_b128 v[194:197], v187 offset:35840
	ds_read_b128 v[198:201], v187 offset:36864
	ds_read_b128 v[202:205], v187 offset:37888
	ds_read_b128 v[206:209], v187 offset:38912
	ds_read_b128 v[210:213], v187 offset:39936
	global_load_lds_dwordx4 v[220:221], off
	v_lshl_add_u64 v[220:221], s[50:51], 0, v[138:139]
	s_mov_b32 m0, s30
	s_nop 0
	global_load_lds_dwordx4 v[220:221], off
	s_waitcnt vmcnt(8)
	s_waitcnt lgkmcnt(0)
	s_barrier
	v_mfma_f32_16x16x32_bf16 v[124:127], v[128:131], v[174:177], v[124:127]
	v_mfma_f32_16x16x32_bf16 v[120:123], v[150:153], v[174:177], v[120:123]
	v_mfma_f32_16x16x32_bf16 v[108:111], v[128:131], v[190:193], v[108:111]
	v_mfma_f32_16x16x32_bf16 v[104:107], v[150:153], v[190:193], v[104:107]
	v_mfma_f32_16x16x32_bf16 v[92:95], v[128:131], v[198:201], v[92:95]
	v_mfma_f32_16x16x32_bf16 v[88:91], v[150:153], v[198:201], v[88:91]
	v_mfma_f32_16x16x32_bf16 v[76:79], v[128:131], v[206:209], v[76:79]
	v_mfma_f32_16x16x32_bf16 v[72:75], v[150:153], v[206:209], v[72:75]
	v_mfma_f32_16x16x32_bf16 v[124:127], v[132:135], v[178:181], v[124:127]
	v_mfma_f32_16x16x32_bf16 v[120:123], v[154:157], v[178:181], v[120:123]
	v_mfma_f32_16x16x32_bf16 v[108:111], v[132:135], v[194:197], v[108:111]
	v_mfma_f32_16x16x32_bf16 v[104:107], v[154:157], v[194:197], v[104:107]
	v_mfma_f32_16x16x32_bf16 v[92:95], v[132:135], v[202:205], v[92:95]
	v_mfma_f32_16x16x32_bf16 v[88:91], v[154:157], v[202:205], v[88:91]
	v_mfma_f32_16x16x32_bf16 v[76:79], v[132:135], v[210:213], v[76:79]
	v_mfma_f32_16x16x32_bf16 v[72:75], v[154:157], v[210:213], v[72:75]
	v_mfma_f32_16x16x32_bf16 v[116:119], v[158:161], v[174:177], v[116:119]
	v_mfma_f32_16x16x32_bf16 v[112:115], v[166:169], v[174:177], v[112:115]
	v_mfma_f32_16x16x32_bf16 v[100:103], v[158:161], v[190:193], v[100:103]
	v_mfma_f32_16x16x32_bf16 v[96:99], v[166:169], v[190:193], v[96:99]
	v_mfma_f32_16x16x32_bf16 v[84:87], v[158:161], v[198:201], v[84:87]
	v_mfma_f32_16x16x32_bf16 v[80:83], v[166:169], v[198:201], v[80:83]
	v_mfma_f32_16x16x32_bf16 v[68:71], v[158:161], v[206:209], v[68:71]
	v_mfma_f32_16x16x32_bf16 v[64:67], v[166:169], v[206:209], v[64:67]
	v_mfma_f32_16x16x32_bf16 v[116:119], v[162:165], v[178:181], v[116:119]
	v_mfma_f32_16x16x32_bf16 v[112:115], v[170:173], v[178:181], v[112:115]
	v_mfma_f32_16x16x32_bf16 v[100:103], v[162:165], v[194:197], v[100:103]
	v_mfma_f32_16x16x32_bf16 v[96:99], v[170:173], v[194:197], v[96:99]
	v_mfma_f32_16x16x32_bf16 v[84:87], v[162:165], v[202:205], v[84:87]
	v_mfma_f32_16x16x32_bf16 v[80:83], v[170:173], v[202:205], v[80:83]
	v_mfma_f32_16x16x32_bf16 v[68:71], v[162:165], v[210:213], v[68:71]
	v_mfma_f32_16x16x32_bf16 v[64:67], v[170:173], v[210:213], v[64:67]
	s_barrier
; #define PG8_STAGE(bufoff, gbase, voff) do { _Pragma("unroll") for (int _i = 0; _i < 2; ++_i) \
;         __builtin_amdgcn_global_load_lds((const unsigned*)((const char*)(gbase) + (voff)[_i]), (LAS unsigned*)(lds + (bufoff) + ldsw + _i * 8192), 16, 0, 0); } while (0)
; #define PG8_LDA(dst, b, h) do { _Pragma("unroll") for (int m = 0; m < 4; ++m) _Pragma("unroll") for (int k = 0; k < 2; ++k) dst[m][k] = *(const LAS bf16x8*)(lds + PG8_SA(b, h) + aoff + m * 2048 + k * 1024); } while (0)
; #define PG8_MMA(ai, bj, At, Bt) do { __builtin_amdgcn_s_setprio(1); _Pragma("unroll") for (int m = 0; m < 4; ++m) _Pragma("unroll") for (int n = 0; n < 2; ++n) _Pragma("unroll") for (int k = 0; k < 2; ++k) \
;         acc[ai][bj][m][n] = __builtin_amdgcn_mfma_f32_16x16x32_bf16(Bt[n][k], At[m][k], acc[ai][bj][m][n], 0, 0, 0); __builtin_amdgcn_s_setprio(0); } while (0)
; #define PG8_WAIT_V(n) asm volatile("s_waitcnt vmcnt(" #n ")" ::: "memory")
; #define PG8_WAIT_L(n) asm volatile("s_waitcnt lgkmcnt(" #n ")" ::: "memory")
; #define PG8_BAR __builtin_amdgcn_s_barrier()
; #define PG8_SCHED __builtin_amdgcn_sched_barrier(0)
; template <class Desc, class Epi>
; DI void gemm_phase(LAS unsigned char* lds, const Desc& D, const Epi& E, int wv) {
;     ...
;             PG8_LDA(At, 1, 1); PG8_STAGE(PG8_SB(1, 0), b3, voffB); PG8_STAGE(PG8_SB(1, 1), b3 + hstepB, voffB); PG8_STAGE(PG8_SA(1, 0), a3, voffA);
;             PG8_WAIT_V(8); PG8_WAIT_L(0); PG8_BAR; PG8_MMA(1, 0, At, B0); PG8_MMA(1, 1, At, B1); PG8_BAR; PG8_SCHED;
;         }
;         if (wr == 0) PG8_BAR;
	s_add_i32 s49, s49, s2
	v_lshl_add_u64 v[182:183], v[182:183], 0, s[8:9]
	s_mov_b32 m0, s49
	ds_read_b128 v[174:177], v187 offset:49152
	ds_read_b128 v[178:181], v187 offset:50176
	ds_read_b128 v[190:193], v187 offset:51200
	ds_read_b128 v[194:197], v187 offset:52224
	ds_read_b128 v[198:201], v187 offset:53248
	ds_read_b128 v[202:205], v187 offset:54272
	ds_read_b128 v[206:209], v187 offset:55296
	ds_read_b128 v[210:213], v187 offset:56320
	global_load_lds_dwordx4 v[182:183], off
	s_add_i32 m0, s49, 0x2000
	s_add_u32 s50, s68, 0x100080
	v_lshl_add_u64 v[182:183], v[214:215], 0, s[8:9]
	s_addc_u32 s51, s69, 0
	s_add_i32 s49, s52, s2
	global_load_lds_dwordx4 v[182:183], off
	v_lshl_add_u64 v[182:183], s[50:51], 0, v[140:141]
	s_mov_b32 m0, s49
	s_nop 0
	global_load_lds_dwordx4 v[182:183], off
	v_lshl_add_u64 v[182:183], s[50:51], 0, v[136:137]
	s_add_i32 m0, s49, 0x2000
	s_nop 0
	global_load_lds_dwordx4 v[182:183], off
	v_lshl_add_u64 v[182:183], v[216:217], 0, s[8:9]
	s_mov_b32 m0, s35
	s_nop 0
	global_load_lds_dwordx4 v[182:183], off
	v_lshl_add_u64 v[182:183], v[218:219], 0, s[8:9]
	s_mov_b32 m0, s40
	s_nop 0
	global_load_lds_dwordx4 v[182:183], off
	s_waitcnt vmcnt(8)
	s_waitcnt lgkmcnt(0)
	s_barrier
	v_mfma_f32_16x16x32_bf16 v[60:63], v[128:131], v[174:177], v[60:63]
	v_mfma_f32_16x16x32_bf16 v[56:59], v[150:153], v[174:177], v[56:59]
	v_mfma_f32_16x16x32_bf16 v[44:47], v[128:131], v[190:193], v[44:47]
	v_mfma_f32_16x16x32_bf16 v[40:43], v[150:153], v[190:193], v[40:43]
	v_mfma_f32_16x16x32_bf16 v[28:31], v[128:131], v[198:201], v[28:31]
	v_mfma_f32_16x16x32_bf16 v[24:27], v[150:153], v[198:201], v[24:27]
	v_mfma_f32_16x16x32_bf16 v[12:15], v[128:131], v[206:209], v[12:15]
	v_mfma_f32_16x16x32_bf16 v[8:11], v[150:153], v[206:209], v[8:11]
	v_mfma_f32_16x16x32_bf16 v[60:63], v[132:135], v[178:181], v[60:63]
	v_mfma_f32_16x16x32_bf16 v[56:59], v[154:157], v[178:181], v[56:59]
	v_mfma_f32_16x16x32_bf16 v[44:47], v[132:135], v[194:197], v[44:47]
	v_mfma_f32_16x16x32_bf16 v[40:43], v[154:157], v[194:197], v[40:43]
	v_mfma_f32_16x16x32_bf16 v[28:31], v[132:135], v[202:205], v[28:31]
	v_mfma_f32_16x16x32_bf16 v[24:27], v[154:157], v[202:205], v[24:27]
	v_mfma_f32_16x16x32_bf16 v[12:15], v[132:135], v[210:213], v[12:15]
	v_mfma_f32_16x16x32_bf16 v[8:11], v[154:157], v[210:213], v[8:11]
	v_mfma_f32_16x16x32_bf16 v[52:55], v[158:161], v[174:177], v[52:55]
	v_mfma_f32_16x16x32_bf16 v[48:51], v[166:169], v[174:177], v[48:51]
	v_mfma_f32_16x16x32_bf16 v[36:39], v[158:161], v[190:193], v[36:39]
	v_mfma_f32_16x16x32_bf16 v[32:35], v[166:169], v[190:193], v[32:35]
	v_mfma_f32_16x16x32_bf16 v[20:23], v[158:161], v[198:201], v[20:23]
	v_mfma_f32_16x16x32_bf16 v[16:19], v[166:169], v[198:201], v[16:19]
	v_mfma_f32_16x16x32_bf16 v[4:7], v[158:161], v[206:209], v[4:7]
	v_mfma_f32_16x16x32_bf16 v[0:3], v[166:169], v[206:209], v[0:3]
	v_mfma_f32_16x16x32_bf16 v[52:55], v[162:165], v[178:181], v[52:55]
	v_mfma_f32_16x16x32_bf16 v[48:51], v[170:173], v[178:181], v[48:51]
	v_mfma_f32_16x16x32_bf16 v[36:39], v[162:165], v[194:197], v[36:39]
	v_mfma_f32_16x16x32_bf16 v[32:35], v[170:173], v[194:197], v[32:35]
	v_mfma_f32_16x16x32_bf16 v[20:23], v[162:165], v[202:205], v[20:23]
	v_mfma_f32_16x16x32_bf16 v[16:19], v[170:173], v[202:205], v[16:19]
	v_mfma_f32_16x16x32_bf16 v[4:7], v[162:165], v[210:213], v[4:7]
	v_mfma_f32_16x16x32_bf16 v[0:3], v[170:173], v[210:213], v[0:3]
	s_barrier
	s_add_i32 s48, s48, 2
	s_add_u32 s66, s66, 0x100
	s_addc_u32 s67, s67, 0
	s_add_u32 s1, s1, 0x100
	s_addc_u32 s47, s47, 0
	s_cmp_gt_u32 s48, 29
	s_cbranch_scc0 .LBB0_581
	s_and_b64 vcc, exec, s[14:15]
	s_cbranch_vccz .LBB0_584
	s_barrier

; #define PG8_STAGE(bufoff, gbase, voff) do { _Pragma("unroll") for (int _i = 0; _i < 2; ++_i) \
;         __builtin_amdgcn_global_load_lds((const unsigned*)((const char*)(gbase) + (voff)[_i]), (LAS unsigned*)(lds + (bufoff) + ldsw + _i * 8192), 16, 0, 0); } while (0)
; #define PG8_LDA(dst, b, h) do { _Pragma("unroll") for (int m = 0; m < 4; ++m) _Pragma("unroll") for (int k = 0; k < 2; ++k) dst[m][k] = *(const LAS bf16x8*)(lds + PG8_SA(b, h) + aoff + m * 2048 + k * 1024); } while (0)
; #define PG8_LDB(dst, b, h) do { _Pragma("unroll") for (int n = 0; n < 2; ++n) _Pragma("unroll") for (int k = 0; k < 2; ++k) dst[n][k] = *(const LAS bf16x8*)(lds + PG8_SB(b, h) + boff + n * 2048 + k * 1024); } while (0)
; #define PG8_MMA(ai, bj, At, Bt) do { __builtin_amdgcn_s_setprio(1); _Pragma("unroll") for (int m = 0; m < 4; ++m) _Pragma("unroll") for (int n = 0; n < 2; ++n) _Pragma("unroll") for (int k = 0; k < 2; ++k) \
;         acc[ai][bj][m][n] = __builtin_amdgcn_mfma_f32_16x16x32_bf16(Bt[n][k], At[m][k], acc[ai][bj][m][n], 0, 0, 0); __builtin_amdgcn_s_setprio(0); } while (0)
; #define PG8_WAIT_V(n) asm volatile("s_waitcnt vmcnt(" #n ")" ::: "memory")
; #define PG8_WAIT_L(n) asm volatile("s_waitcnt lgkmcnt(" #n ")" ::: "memory")
; #define PG8_BAR __builtin_amdgcn_s_barrier()
; #define PG8_SCHED __builtin_amdgcn_sched_barrier(0)
; template <class Desc, class Epi>
; DI void gemm_phase(LAS unsigned char* lds, const Desc& D, const Epi& E, int wv) {
;     ...
;         for (int t = 0; t < nt; t += 2) {
;             const bool last = (t == nt - 2);
;             const char* a1 = cA + (size_t)(t + 1) * kstep;
;             const char* a2 = last ? nA : cA + (size_t)(t + 2) * kstep; const char* b2 = last ? nB : cB + (size_t)(t + 2) * kstep;
;             const char* a3 = a2 + kstep; const char* b3 = b2 + kstep;
;             PG8_LDB(B0, 0, 0); PG8_LDB(B1, 0, 1); PG8_SCHED; PG8_LDA(At, 0, 0); PG8_STAGE(PG8_SA(1, 1), a1 + hstepA, voffA);
;             PG8_WAIT_V(8); PG8_WAIT_L(0); PG8_BAR; PG8_MMA(0, 0, At, B0); PG8_MMA(0, 1, At, B1); PG8_BAR; PG8_SCHED;
;             PG8_LDA(At, 0, 1); PG8_STAGE(PG8_SB(0, 0), b2, voffB); PG8_STAGE(PG8_SB(0, 1), b2 + hstepB, voffB); PG8_STAGE(PG8_SA(0, 0), a2, voffA);
.LBB0_763:
	ds_read_b128 v[150:153], v147
	ds_read_b128 v[154:157], v147 offset:1024
	ds_read_b128 v[158:161], v147 offset:2048
	ds_read_b128 v[162:165], v147 offset:3072
	ds_read_b128 v[166:169], v148
	ds_read_b128 v[170:173], v148 offset:1024
	ds_read_b128 v[174:177], v148 offset:2048
	ds_read_b128 v[178:181], v148 offset:3072
	s_add_u32 s64, s62, 0x100
	s_addc_u32 s65, s63, 0
	s_add_u32 s50, s21, s62
	s_addc_u32 s51, s23, s63
	s_cmp_eq_u32 s49, 4
	s_cselect_b32 s53, 0, s64
	s_cselect_b32 s52, 0, s65
	s_cselect_b32 s66, s18, s50
	s_cselect_b32 s67, s19, s51
	s_add_u32 s68, s4, s53
	s_addc_u32 s69, s5, s52
	v_lshl_add_u64 v[144:145], v[136:137], 0, s[62:63]
	s_add_i32 m0, s3, 0xc000
	ds_read_b128 v[182:185], v149
	ds_read_b128 v[186:189], v149 offset:1024
	ds_read_b128 v[190:193], v149 offset:2048
	ds_read_b128 v[194:197], v149 offset:3072
	ds_read_b128 v[198:201], v149 offset:4096
	ds_read_b128 v[202:205], v149 offset:5120
	ds_read_b128 v[206:209], v149 offset:6144
	ds_read_b128 v[210:213], v149 offset:7168
	global_load_lds_dwordx4 v[144:145], off
	v_lshl_add_u64 v[144:145], v[138:139], 0, s[62:63]
	s_add_i32 m0, s3, 0xe000
	s_nop 0
	global_load_lds_dwordx4 v[144:145], off
	s_waitcnt vmcnt(8)
	s_waitcnt lgkmcnt(0)
	s_barrier
	v_mfma_f32_16x16x32_bf16 v[124:127], v[150:153], v[182:185], v[124:127]
	v_mfma_f32_16x16x32_bf16 v[120:123], v[158:161], v[182:185], v[120:123]
	v_mfma_f32_16x16x32_bf16 v[108:111], v[150:153], v[190:193], v[108:111]
	v_mfma_f32_16x16x32_bf16 v[104:107], v[158:161], v[190:193], v[104:107]
	v_mfma_f32_16x16x32_bf16 v[92:95], v[150:153], v[198:201], v[92:95]
	v_mfma_f32_16x16x32_bf16 v[88:91], v[158:161], v[198:201], v[88:91]
	v_mfma_f32_16x16x32_bf16 v[76:79], v[150:153], v[206:209], v[76:79]
	v_mfma_f32_16x16x32_bf16 v[72:75], v[158:161], v[206:209], v[72:75]
	v_mfma_f32_16x16x32_bf16 v[124:127], v[154:157], v[186:189], v[124:127]
	v_mfma_f32_16x16x32_bf16 v[120:123], v[162:165], v[186:189], v[120:123]
	v_mfma_f32_16x16x32_bf16 v[108:111], v[154:157], v[194:197], v[108:111]
	v_mfma_f32_16x16x32_bf16 v[104:107], v[162:165], v[194:197], v[104:107]
	v_mfma_f32_16x16x32_bf16 v[92:95], v[154:157], v[202:205], v[92:95]
	v_mfma_f32_16x16x32_bf16 v[88:91], v[162:165], v[202:205], v[88:91]
	v_mfma_f32_16x16x32_bf16 v[76:79], v[154:157], v[210:213], v[76:79]
	v_mfma_f32_16x16x32_bf16 v[72:75], v[162:165], v[210:213], v[72:75]
	v_mfma_f32_16x16x32_bf16 v[116:119], v[166:169], v[182:185], v[116:119]
	v_mfma_f32_16x16x32_bf16 v[112:115], v[174:177], v[182:185], v[112:115]
	v_mfma_f32_16x16x32_bf16 v[100:103], v[166:169], v[190:193], v[100:103]
	v_mfma_f32_16x16x32_bf16 v[96:99], v[174:177], v[190:193], v[96:99]
	v_mfma_f32_16x16x32_bf16 v[84:87], v[166:169], v[198:201], v[84:87]
	v_mfma_f32_16x16x32_bf16 v[80:83], v[174:177], v[198:201], v[80:83]
	v_mfma_f32_16x16x32_bf16 v[68:71], v[166:169], v[206:209], v[68:71]
	v_mfma_f32_16x16x32_bf16 v[64:67], v[174:177], v[206:209], v[64:67]
	v_mfma_f32_16x16x32_bf16 v[116:119], v[170:173], v[186:189], v[116:119]
	v_mfma_f32_16x16x32_bf16 v[112:115], v[178:181], v[186:189], v[112:115]
	v_mfma_f32_16x16x32_bf16 v[100:103], v[170:173], v[194:197], v[100:103]
	v_mfma_f32_16x16x32_bf16 v[96:99], v[178:181], v[194:197], v[96:99]
	v_mfma_f32_16x16x32_bf16 v[84:87], v[170:173], v[202:205], v[84:87]
	v_mfma_f32_16x16x32_bf16 v[80:83], v[178:181], v[202:205], v[80:83]
	v_mfma_f32_16x16x32_bf16 v[68:71], v[170:173], v[210:213], v[68:71]
	v_mfma_f32_16x16x32_bf16 v[64:67], v[178:181], v[210:213], v[64:67]
	s_barrier
	s_add_i32 s50, s43, s2
	v_lshl_add_u64 v[144:145], s[66:67], 0, v[130:131]
	s_mov_b32 m0, s50
	ds_read_b128 v[182:185], v149 offset:16384
	ds_read_b128 v[186:189], v149 offset:17408
	ds_read_b128 v[190:193], v149 offset:18432
	ds_read_b128 v[194:197], v149 offset:19456
	ds_read_b128 v[198:201], v149 offset:20480
	ds_read_b128 v[202:205], v149 offset:21504
	ds_read_b128 v[206:209], v149 offset:22528
	ds_read_b128 v[210:213], v149 offset:23552
	global_load_lds_dwordx4 v[144:145], off
	s_add_i32 m0, s50, 0x2000
	s_add_u32 s50, s66, 0x20000
	v_lshl_add_u64 v[214:215], s[66:67], 0, v[134:135]
	s_addc_u32 s51, s67, 0
	s_add_i32 s52, s46, s2
	global_load_lds_dwordx4 v[214:215], off
	v_lshl_add_u64 v[216:217], s[50:51], 0, v[130:131]
	s_mov_b32 m0, s52
	v_lshl_add_u64 v[218:219], s[68:69], 0, v[132:133]
	global_load_lds_dwordx4 v[216:217], off
	v_lshl_add_u64 v[216:217], s[50:51], 0, v[134:135]
	s_add_i32 m0, s52, 0x2000
	s_nop 0
	global_load_lds_dwordx4 v[216:217], off
	v_lshl_add_u64 v[216:217], s[68:69], 0, v[128:129]
	s_mov_b32 m0, s3
	s_nop 0
	global_load_lds_dwordx4 v[216:217], off
	s_mov_b32 m0, s28
	s_nop 0
	global_load_lds_dwordx4 v[218:219], off
	s_waitcnt vmcnt(8)
	s_waitcnt lgkmcnt(0)
	s_barrier
; #define PG8_STAGE(bufoff, gbase, voff) do { _Pragma("unroll") for (int _i = 0; _i < 2; ++_i) \
;         __builtin_amdgcn_global_load_lds((const unsigned*)((const char*)(gbase) + (voff)[_i]), (LAS unsigned*)(lds + (bufoff) + ldsw + _i * 8192), 16, 0, 0); } while (0)
; #define PG8_LDA(dst, b, h) do { _Pragma("unroll") for (int m = 0; m < 4; ++m) _Pragma("unroll") for (int k = 0; k < 2; ++k) dst[m][k] = *(const LAS bf16x8*)(lds + PG8_SA(b, h) + aoff + m * 2048 + k * 1024); } while (0)
; #define PG8_LDB(dst, b, h) do { _Pragma("unroll") for (int n = 0; n < 2; ++n) _Pragma("unroll") for (int k = 0; k < 2; ++k) dst[n][k] = *(const LAS bf16x8*)(lds + PG8_SB(b, h) + boff + n * 2048 + k * 1024); } while (0)
; #define PG8_MMA(ai, bj, At, Bt) do { __builtin_amdgcn_s_setprio(1); _Pragma("unroll") for (int m = 0; m < 4; ++m) _Pragma("unroll") for (int n = 0; n < 2; ++n) _Pragma("unroll") for (int k = 0; k < 2; ++k) \
;         acc[ai][bj][m][n] = __builtin_amdgcn_mfma_f32_16x16x32_bf16(Bt[n][k], At[m][k], acc[ai][bj][m][n], 0, 0, 0); __builtin_amdgcn_s_setprio(0); } while (0)
; #define PG8_WAIT_V(n) asm volatile("s_waitcnt vmcnt(" #n ")" ::: "memory")
; #define PG8_WAIT_L(n) asm volatile("s_waitcnt lgkmcnt(" #n ")" ::: "memory")
; #define PG8_BAR __builtin_amdgcn_s_barrier()
; #define PG8_SCHED __builtin_amdgcn_sched_barrier(0)
; template <class Desc, class Epi>
; DI void gemm_phase(LAS unsigned char* lds, const Desc& D, const Epi& E, int wv) {
;     ...
;             PG8_WAIT_V(8); PG8_WAIT_L(0); PG8_BAR; PG8_MMA(1, 0, At, B0); PG8_MMA(1, 1, At, B1); PG8_BAR; PG8_SCHED;
;             PG8_LDB(B0, 1, 0); PG8_LDB(B1, 1, 1); PG8_SCHED; PG8_LDA(At, 1, 0); PG8_STAGE(PG8_SA(0, 1), a2 + hstepA, voffA);
;             PG8_WAIT_V(8); PG8_WAIT_L(0); PG8_BAR; PG8_MMA(0, 0, At, B0); PG8_MMA(0, 1, At, B1); PG8_BAR; PG8_SCHED;
	v_mfma_f32_16x16x32_bf16 v[60:63], v[150:153], v[182:185], v[60:63]
	v_mfma_f32_16x16x32_bf16 v[56:59], v[158:161], v[182:185], v[56:59]
	v_mfma_f32_16x16x32_bf16 v[44:47], v[150:153], v[190:193], v[44:47]
	v_mfma_f32_16x16x32_bf16 v[40:43], v[158:161], v[190:193], v[40:43]
	v_mfma_f32_16x16x32_bf16 v[28:31], v[150:153], v[198:201], v[28:31]
	v_mfma_f32_16x16x32_bf16 v[24:27], v[158:161], v[198:201], v[24:27]
	v_mfma_f32_16x16x32_bf16 v[12:15], v[150:153], v[206:209], v[12:15]
	v_mfma_f32_16x16x32_bf16 v[8:11], v[158:161], v[206:209], v[8:11]
	v_mfma_f32_16x16x32_bf16 v[60:63], v[154:157], v[186:189], v[60:63]
	v_mfma_f32_16x16x32_bf16 v[56:59], v[162:165], v[186:189], v[56:59]
	v_mfma_f32_16x16x32_bf16 v[44:47], v[154:157], v[194:197], v[44:47]
	v_mfma_f32_16x16x32_bf16 v[40:43], v[162:165], v[194:197], v[40:43]
	v_mfma_f32_16x16x32_bf16 v[28:31], v[154:157], v[202:205], v[28:31]
	v_mfma_f32_16x16x32_bf16 v[24:27], v[162:165], v[202:205], v[24:27]
	v_mfma_f32_16x16x32_bf16 v[12:15], v[154:157], v[210:213], v[12:15]
	v_mfma_f32_16x16x32_bf16 v[8:11], v[162:165], v[210:213], v[8:11]
	v_mfma_f32_16x16x32_bf16 v[52:55], v[166:169], v[182:185], v[52:55]
	v_mfma_f32_16x16x32_bf16 v[48:51], v[174:177], v[182:185], v[48:51]
	v_mfma_f32_16x16x32_bf16 v[36:39], v[166:169], v[190:193], v[36:39]
	v_mfma_f32_16x16x32_bf16 v[32:35], v[174:177], v[190:193], v[32:35]
	v_mfma_f32_16x16x32_bf16 v[20:23], v[166:169], v[198:201], v[20:23]
	v_mfma_f32_16x16x32_bf16 v[16:19], v[174:177], v[198:201], v[16:19]
	v_mfma_f32_16x16x32_bf16 v[4:7], v[166:169], v[206:209], v[4:7]
	v_mfma_f32_16x16x32_bf16 v[0:3], v[174:177], v[206:209], v[0:3]
	v_mfma_f32_16x16x32_bf16 v[52:55], v[170:173], v[186:189], v[52:55]
	v_mfma_f32_16x16x32_bf16 v[48:51], v[178:181], v[186:189], v[48:51]
	v_mfma_f32_16x16x32_bf16 v[36:39], v[170:173], v[194:197], v[36:39]
	v_mfma_f32_16x16x32_bf16 v[32:35], v[178:181], v[194:197], v[32:35]
	v_mfma_f32_16x16x32_bf16 v[20:23], v[170:173], v[202:205], v[20:23]
	v_mfma_f32_16x16x32_bf16 v[16:19], v[178:181], v[202:205], v[16:19]
	v_mfma_f32_16x16x32_bf16 v[4:7], v[170:173], v[210:213], v[4:7]
	v_mfma_f32_16x16x32_bf16 v[0:3], v[178:181], v[210:213], v[0:3]
	s_barrier
	s_add_i32 s52, 0, 0x18000
	s_add_i32 s53, 0, 0x1c000
	v_add_u32_e32 v162, s52, v146
	v_add_u32_e32 v178, s53, v146
	ds_read_b128 v[150:153], v162
	ds_read_b128 v[154:157], v162 offset:1024
	ds_read_b128 v[158:161], v162 offset:2048
	ds_read_b128 v[162:165], v162 offset:3072
	ds_read_b128 v[166:169], v178
	ds_read_b128 v[170:173], v178 offset:1024
	ds_read_b128 v[174:177], v178 offset:2048
	ds_read_b128 v[178:181], v178 offset:3072
	s_add_u32 s50, s68, 0x20000
	s_addc_u32 s51, s69, 0
	s_mov_b32 m0, s29
	v_lshl_add_u64 v[220:221], s[50:51], 0, v[128:129]
	ds_read_b128 v[182:185], v149 offset:32768
	ds_read_b128 v[186:189], v149 offset:33792
	ds_read_b128 v[190:193], v149 offset:34816
	ds_read_b128 v[194:197], v149 offset:35840
	ds_read_b128 v[198:201], v149 offset:36864
	ds_read_b128 v[202:205], v149 offset:37888
	ds_read_b128 v[206:209], v149 offset:38912
	ds_read_b128 v[210:213], v149 offset:39936
	global_load_lds_dwordx4 v[220:221], off
	v_lshl_add_u64 v[220:221], s[50:51], 0, v[132:133]
	s_mov_b32 m0, s30
	s_nop 0
	global_load_lds_dwordx4 v[220:221], off
	s_waitcnt vmcnt(8)
	s_waitcnt lgkmcnt(0)
	s_barrier
	v_mfma_f32_16x16x32_bf16 v[124:127], v[150:153], v[182:185], v[124:127]
	v_mfma_f32_16x16x32_bf16 v[120:123], v[158:161], v[182:185], v[120:123]
	v_mfma_f32_16x16x32_bf16 v[108:111], v[150:153], v[190:193], v[108:111]
	v_mfma_f32_16x16x32_bf16 v[104:107], v[158:161], v[190:193], v[104:107]
	v_mfma_f32_16x16x32_bf16 v[92:95], v[150:153], v[198:201], v[92:95]
	v_mfma_f32_16x16x32_bf16 v[88:91], v[158:161], v[198:201], v[88:91]
	v_mfma_f32_16x16x32_bf16 v[76:79], v[150:153], v[206:209], v[76:79]
	v_mfma_f32_16x16x32_bf16 v[72:75], v[158:161], v[206:209], v[72:75]
	v_mfma_f32_16x16x32_bf16 v[124:127], v[154:157], v[186:189], v[124:127]
	v_mfma_f32_16x16x32_bf16 v[120:123], v[162:165], v[186:189], v[120:123]
	v_mfma_f32_16x16x32_bf16 v[108:111], v[154:157], v[194:197], v[108:111]
	v_mfma_f32_16x16x32_bf16 v[104:107], v[162:165], v[194:197], v[104:107]
	v_mfma_f32_16x16x32_bf16 v[92:95], v[154:157], v[202:205], v[92:95]
	v_mfma_f32_16x16x32_bf16 v[88:91], v[162:165], v[202:205], v[88:91]
	v_mfma_f32_16x16x32_bf16 v[76:79], v[154:157], v[210:213], v[76:79]
	v_mfma_f32_16x16x32_bf16 v[72:75], v[162:165], v[210:213], v[72:75]
	v_mfma_f32_16x16x32_bf16 v[116:119], v[166:169], v[182:185], v[116:119]
	v_mfma_f32_16x16x32_bf16 v[112:115], v[174:177], v[182:185], v[112:115]
	v_mfma_f32_16x16x32_bf16 v[100:103], v[166:169], v[190:193], v[100:103]
	v_mfma_f32_16x16x32_bf16 v[96:99], v[174:177], v[190:193], v[96:99]
	v_mfma_f32_16x16x32_bf16 v[84:87], v[166:169], v[198:201], v[84:87]
	v_mfma_f32_16x16x32_bf16 v[80:83], v[174:177], v[198:201], v[80:83]
	v_mfma_f32_16x16x32_bf16 v[68:71], v[166:169], v[206:209], v[68:71]
	v_mfma_f32_16x16x32_bf16 v[64:67], v[174:177], v[206:209], v[64:67]
	v_mfma_f32_16x16x32_bf16 v[116:119], v[170:173], v[186:189], v[116:119]
	v_mfma_f32_16x16x32_bf16 v[112:115], v[178:181], v[186:189], v[112:115]
	v_mfma_f32_16x16x32_bf16 v[100:103], v[170:173], v[194:197], v[100:103]
	v_mfma_f32_16x16x32_bf16 v[96:99], v[178:181], v[194:197], v[96:99]
	v_mfma_f32_16x16x32_bf16 v[84:87], v[170:173], v[202:205], v[84:87]
	v_mfma_f32_16x16x32_bf16 v[80:83], v[178:181], v[202:205], v[80:83]
	v_mfma_f32_16x16x32_bf16 v[68:71], v[170:173], v[210:213], v[68:71]
	v_mfma_f32_16x16x32_bf16 v[64:67], v[178:181], v[210:213], v[64:67]
	s_barrier
; #define PG8_STAGE(bufoff, gbase, voff) do { _Pragma("unroll") for (int _i = 0; _i < 2; ++_i) \
;         __builtin_amdgcn_global_load_lds((const unsigned*)((const char*)(gbase) + (voff)[_i]), (LAS unsigned*)(lds + (bufoff) + ldsw + _i * 8192), 16, 0, 0); } while (0)
; #define PG8_LDA(dst, b, h) do { _Pragma("unroll") for (int m = 0; m < 4; ++m) _Pragma("unroll") for (int k = 0; k < 2; ++k) dst[m][k] = *(const LAS bf16x8*)(lds + PG8_SA(b, h) + aoff + m * 2048 + k * 1024); } while (0)
; #define PG8_MMA(ai, bj, At, Bt) do { __builtin_amdgcn_s_setprio(1); _Pragma("unroll") for (int m = 0; m < 4; ++m) _Pragma("unroll") for (int n = 0; n < 2; ++n) _Pragma("unroll") for (int k = 0; k < 2; ++k) \
;         acc[ai][bj][m][n] = __builtin_amdgcn_mfma_f32_16x16x32_bf16(Bt[n][k], At[m][k], acc[ai][bj][m][n], 0, 0, 0); __builtin_amdgcn_s_setprio(0); } while (0)
; #define PG8_WAIT_V(n) asm volatile("s_waitcnt vmcnt(" #n ")" ::: "memory")
; #define PG8_WAIT_L(n) asm volatile("s_waitcnt lgkmcnt(" #n ")" ::: "memory")
; #define PG8_BAR __builtin_amdgcn_s_barrier()
; #define PG8_SCHED __builtin_amdgcn_sched_barrier(0)
; template <class Desc, class Epi>
; DI void gemm_phase(LAS unsigned char* lds, const Desc& D, const Epi& E, int wv) {
;     ...
;             PG8_LDA(At, 1, 1); PG8_STAGE(PG8_SB(1, 0), b3, voffB); PG8_STAGE(PG8_SB(1, 1), b3 + hstepB, voffB); PG8_STAGE(PG8_SA(1, 0), a3, voffA);
;             PG8_WAIT_V(8); PG8_WAIT_L(0); PG8_BAR; PG8_MMA(1, 0, At, B0); PG8_MMA(1, 1, At, B1); PG8_BAR; PG8_SCHED;
;         }
;         if (wr == 0) PG8_BAR;
	s_add_i32 s50, s52, s2
	v_lshl_add_u64 v[144:145], v[144:145], 0, s[8:9]
	s_mov_b32 m0, s50
	ds_read_b128 v[182:185], v149 offset:49152
	ds_read_b128 v[186:189], v149 offset:50176
	ds_read_b128 v[190:193], v149 offset:51200
	ds_read_b128 v[194:197], v149 offset:52224
	ds_read_b128 v[198:201], v149 offset:53248
	ds_read_b128 v[202:205], v149 offset:54272
	ds_read_b128 v[206:209], v149 offset:55296
	ds_read_b128 v[210:213], v149 offset:56320
	global_load_lds_dwordx4 v[144:145], off
	s_add_i32 m0, s50, 0x2000
	s_add_u32 s50, s66, 0x20080
	v_lshl_add_u64 v[144:145], v[214:215], 0, s[8:9]
	s_addc_u32 s51, s67, 0
	s_add_i32 s52, s53, s2
	global_load_lds_dwordx4 v[144:145], off
	v_lshl_add_u64 v[144:145], s[50:51], 0, v[130:131]
	s_mov_b32 m0, s52
	s_nop 0
	global_load_lds_dwordx4 v[144:145], off
	v_lshl_add_u64 v[144:145], s[50:51], 0, v[134:135]
	s_add_i32 m0, s52, 0x2000
	s_nop 0
	global_load_lds_dwordx4 v[144:145], off
	v_lshl_add_u64 v[144:145], v[216:217], 0, s[8:9]
	s_mov_b32 m0, s40
	s_nop 0
	global_load_lds_dwordx4 v[144:145], off
	v_lshl_add_u64 v[144:145], v[218:219], 0, s[8:9]
	s_mov_b32 m0, s41
	s_nop 0
	global_load_lds_dwordx4 v[144:145], off
	s_waitcnt vmcnt(8)
	s_waitcnt lgkmcnt(0)
	s_barrier
	v_mfma_f32_16x16x32_bf16 v[60:63], v[150:153], v[182:185], v[60:63]
	v_mfma_f32_16x16x32_bf16 v[56:59], v[158:161], v[182:185], v[56:59]
	v_mfma_f32_16x16x32_bf16 v[44:47], v[150:153], v[190:193], v[44:47]
	v_mfma_f32_16x16x32_bf16 v[40:43], v[158:161], v[190:193], v[40:43]
	v_mfma_f32_16x16x32_bf16 v[28:31], v[150:153], v[198:201], v[28:31]
	v_mfma_f32_16x16x32_bf16 v[24:27], v[158:161], v[198:201], v[24:27]
	v_mfma_f32_16x16x32_bf16 v[12:15], v[150:153], v[206:209], v[12:15]
	v_mfma_f32_16x16x32_bf16 v[8:11], v[158:161], v[206:209], v[8:11]
	v_mfma_f32_16x16x32_bf16 v[60:63], v[154:157], v[186:189], v[60:63]
	v_mfma_f32_16x16x32_bf16 v[56:59], v[162:165], v[186:189], v[56:59]
	v_mfma_f32_16x16x32_bf16 v[44:47], v[154:157], v[194:197], v[44:47]
	v_mfma_f32_16x16x32_bf16 v[40:43], v[162:165], v[194:197], v[40:43]
	v_mfma_f32_16x16x32_bf16 v[28:31], v[154:157], v[202:205], v[28:31]
	v_mfma_f32_16x16x32_bf16 v[24:27], v[162:165], v[202:205], v[24:27]
	v_mfma_f32_16x16x32_bf16 v[12:15], v[154:157], v[210:213], v[12:15]
	v_mfma_f32_16x16x32_bf16 v[8:11], v[162:165], v[210:213], v[8:11]
	v_mfma_f32_16x16x32_bf16 v[52:55], v[166:169], v[182:185], v[52:55]
	v_mfma_f32_16x16x32_bf16 v[48:51], v[174:177], v[182:185], v[48:51]
	v_mfma_f32_16x16x32_bf16 v[36:39], v[166:169], v[190:193], v[36:39]
	v_mfma_f32_16x16x32_bf16 v[32:35], v[174:177], v[190:193], v[32:35]
	v_mfma_f32_16x16x32_bf16 v[20:23], v[166:169], v[198:201], v[20:23]
	v_mfma_f32_16x16x32_bf16 v[16:19], v[174:177], v[198:201], v[16:19]
	v_mfma_f32_16x16x32_bf16 v[4:7], v[166:169], v[206:209], v[4:7]
	v_mfma_f32_16x16x32_bf16 v[0:3], v[174:177], v[206:209], v[0:3]
	v_mfma_f32_16x16x32_bf16 v[52:55], v[170:173], v[186:189], v[52:55]
	v_mfma_f32_16x16x32_bf16 v[48:51], v[178:181], v[186:189], v[48:51]
	v_mfma_f32_16x16x32_bf16 v[36:39], v[170:173], v[194:197], v[36:39]
	v_mfma_f32_16x16x32_bf16 v[32:35], v[178:181], v[194:197], v[32:35]
	v_mfma_f32_16x16x32_bf16 v[20:23], v[170:173], v[202:205], v[20:23]
	v_mfma_f32_16x16x32_bf16 v[16:19], v[178:181], v[202:205], v[16:19]
	v_mfma_f32_16x16x32_bf16 v[4:7], v[170:173], v[210:213], v[4:7]
	v_mfma_f32_16x16x32_bf16 v[0:3], v[178:181], v[210:213], v[0:3]
	s_barrier
	s_add_i32 s49, s49, 2
	s_cmp_gt_u32 s49, 5
	s_mov_b64 s[62:63], s[64:65]
	s_cbranch_scc0 .LBB0_763
	s_and_b64 vcc, exec, s[14:15]
	s_cbranch_vccz .LBB0_766
	s_barrier

; #define PG8_STAGE(bufoff, gbase, voff) do { _Pragma("unroll") for (int _i = 0; _i < 2; ++_i) \
;         __builtin_amdgcn_global_load_lds((const unsigned*)((const char*)(gbase) + (voff)[_i]), (LAS unsigned*)(lds + (bufoff) + ldsw + _i * 8192), 16, 0, 0); } while (0)
; #define PG8_LDA(dst, b, h) do { _Pragma("unroll") for (int m = 0; m < 4; ++m) _Pragma("unroll") for (int k = 0; k < 2; ++k) dst[m][k] = *(const LAS bf16x8*)(lds + PG8_SA(b, h) + aoff + m * 2048 + k * 1024); } while (0)
; #define PG8_LDB(dst, b, h) do { _Pragma("unroll") for (int n = 0; n < 2; ++n) _Pragma("unroll") for (int k = 0; k < 2; ++k) dst[n][k] = *(const LAS bf16x8*)(lds + PG8_SB(b, h) + boff + n * 2048 + k * 1024); } while (0)
; #define PG8_MMA(ai, bj, At, Bt) do { __builtin_amdgcn_s_setprio(1); _Pragma("unroll") for (int m = 0; m < 4; ++m) _Pragma("unroll") for (int n = 0; n < 2; ++n) _Pragma("unroll") for (int k = 0; k < 2; ++k) \
;         acc[ai][bj][m][n] = __builtin_amdgcn_mfma_f32_16x16x32_bf16(Bt[n][k], At[m][k], acc[ai][bj][m][n], 0, 0, 0); __builtin_amdgcn_s_setprio(0); } while (0)
; #define PG8_WAIT_V(n) asm volatile("s_waitcnt vmcnt(" #n ")" ::: "memory")
; #define PG8_WAIT_L(n) asm volatile("s_waitcnt lgkmcnt(" #n ")" ::: "memory")
; #define PG8_BAR __builtin_amdgcn_s_barrier()
; #define PG8_SCHED __builtin_amdgcn_sched_barrier(0)
; template <class Desc, class Epi>
; DI void gemm_phase(LAS unsigned char* lds, const Desc& D, const Epi& E, int wv) {
;     ...
;             const bool last = (t == nt - 2);
;             const char* a1 = cA + (size_t)(t + 1) * kstep;
;             const char* a2 = last ? nA : cA + (size_t)(t + 2) * kstep; const char* b2 = last ? nB : cB + (size_t)(t + 2) * kstep;
;             const char* a3 = a2 + kstep; const char* b3 = b2 + kstep;
;             PG8_LDB(B0, 0, 0); PG8_LDB(B1, 0, 1); PG8_SCHED; PG8_LDA(At, 0, 0); PG8_STAGE(PG8_SA(1, 1), a1 + hstepA, voffA);
;             PG8_WAIT_V(8); PG8_WAIT_L(0); PG8_BAR; PG8_MMA(0, 0, At, B0); PG8_MMA(0, 1, At, B1); PG8_BAR; PG8_SCHED;
;             PG8_LDA(At, 0, 1); PG8_STAGE(PG8_SB(0, 0), b2, voffB); PG8_STAGE(PG8_SB(0, 1), b2 + hstepB, voffB); PG8_STAGE(PG8_SA(0, 0), a2, voffA);
;             PG8_WAIT_V(8); PG8_WAIT_L(0); PG8_BAR; PG8_MMA(1, 0, At, B0); PG8_MMA(1, 1, At, B1); PG8_BAR; PG8_SCHED;
.LBB0_831:
	ds_read_b128 v[128:131], v169
	ds_read_b128 v[132:135], v169 offset:1024
	ds_read_b128 v[136:139], v169 offset:2048
	ds_read_b128 v[140:143], v169 offset:3072
	ds_read_b128 v[160:163], v170
	ds_read_b128 v[164:167], v170 offset:1024
	ds_read_b128 v[172:175], v170 offset:2048
	ds_read_b128 v[176:179], v170 offset:3072
	s_add_u32 s51, s6, 0xfff80080
	s_addc_u32 s52, s7, -1
	s_cmp_eq_u32 s50, 28
	s_cselect_b32 s69, s19, s52
	s_cselect_b32 s68, s18, s51
	s_cselect_b32 s67, s21, s49
	s_cselect_b32 s66, s20, s23
	v_lshl_add_u64 v[212:213], s[6:7], 0, v[152:153]
	s_add_i32 m0, s28, 0xc000
	ds_read_b128 v[180:183], v171
	ds_read_b128 v[184:187], v171 offset:1024
	ds_read_b128 v[188:191], v171 offset:2048
	ds_read_b128 v[192:195], v171 offset:3072
	ds_read_b128 v[196:199], v171 offset:4096
	ds_read_b128 v[200:203], v171 offset:5120
	ds_read_b128 v[204:207], v171 offset:6144
	ds_read_b128 v[208:211], v171 offset:7168
	global_load_lds_dwordx4 v[212:213], off
	v_lshl_add_u64 v[212:213], s[6:7], 0, v[154:155]
	s_add_i32 m0, s28, 0xe000
	s_nop 0
	global_load_lds_dwordx4 v[212:213], off
	s_waitcnt vmcnt(8)
	s_waitcnt lgkmcnt(0)
	s_barrier
	v_mfma_f32_16x16x32_bf16 v[124:127], v[128:131], v[180:183], v[124:127]
	v_mfma_f32_16x16x32_bf16 v[120:123], v[136:139], v[180:183], v[120:123]
	v_mfma_f32_16x16x32_bf16 v[112:115], v[128:131], v[188:191], v[112:115]
	v_mfma_f32_16x16x32_bf16 v[108:111], v[136:139], v[188:191], v[108:111]
	v_mfma_f32_16x16x32_bf16 v[100:103], v[128:131], v[196:199], v[100:103]
	v_mfma_f32_16x16x32_bf16 v[92:95], v[136:139], v[196:199], v[92:95]
	v_mfma_f32_16x16x32_bf16 v[84:87], v[128:131], v[204:207], v[84:87]
	v_mfma_f32_16x16x32_bf16 v[76:79], v[136:139], v[204:207], v[76:79]
	v_mfma_f32_16x16x32_bf16 v[124:127], v[132:135], v[184:187], v[124:127]
	v_mfma_f32_16x16x32_bf16 v[120:123], v[140:143], v[184:187], v[120:123]
	v_mfma_f32_16x16x32_bf16 v[112:115], v[132:135], v[192:195], v[112:115]
	v_mfma_f32_16x16x32_bf16 v[108:111], v[140:143], v[192:195], v[108:111]
	v_mfma_f32_16x16x32_bf16 v[100:103], v[132:135], v[200:203], v[100:103]
	v_mfma_f32_16x16x32_bf16 v[92:95], v[140:143], v[200:203], v[92:95]
	v_mfma_f32_16x16x32_bf16 v[84:87], v[132:135], v[208:211], v[84:87]
	v_mfma_f32_16x16x32_bf16 v[76:79], v[140:143], v[208:211], v[76:79]
	v_mfma_f32_16x16x32_bf16 v[116:119], v[160:163], v[180:183], v[116:119]
	v_mfma_f32_16x16x32_bf16 v[104:107], v[172:175], v[180:183], v[104:107]
	v_mfma_f32_16x16x32_bf16 v[96:99], v[160:163], v[188:191], v[96:99]
	v_mfma_f32_16x16x32_bf16 v[88:91], v[172:175], v[188:191], v[88:91]
	v_mfma_f32_16x16x32_bf16 v[80:83], v[160:163], v[196:199], v[80:83]
	v_mfma_f32_16x16x32_bf16 v[72:75], v[172:175], v[196:199], v[72:75]
	v_mfma_f32_16x16x32_bf16 v[68:71], v[160:163], v[204:207], v[68:71]
	v_mfma_f32_16x16x32_bf16 v[64:67], v[172:175], v[204:207], v[64:67]
	v_mfma_f32_16x16x32_bf16 v[116:119], v[164:167], v[184:187], v[116:119]
	v_mfma_f32_16x16x32_bf16 v[104:107], v[176:179], v[184:187], v[104:107]
	v_mfma_f32_16x16x32_bf16 v[96:99], v[164:167], v[192:195], v[96:99]
	v_mfma_f32_16x16x32_bf16 v[88:91], v[176:179], v[192:195], v[88:91]
	v_mfma_f32_16x16x32_bf16 v[80:83], v[164:167], v[200:203], v[80:83]
	v_mfma_f32_16x16x32_bf16 v[72:75], v[176:179], v[200:203], v[72:75]
	v_mfma_f32_16x16x32_bf16 v[68:71], v[164:167], v[208:211], v[68:71]
	v_mfma_f32_16x16x32_bf16 v[64:67], v[176:179], v[208:211], v[64:67]
	s_barrier
	s_add_i32 s51, s46, s2
	v_lshl_add_u64 v[212:213], s[66:67], 0, v[148:149]
	s_mov_b32 m0, s51
	ds_read_b128 v[180:183], v171 offset:16384
	ds_read_b128 v[184:187], v171 offset:17408
	ds_read_b128 v[188:191], v171 offset:18432
	ds_read_b128 v[192:195], v171 offset:19456
	ds_read_b128 v[196:199], v171 offset:20480
	ds_read_b128 v[200:203], v171 offset:21504
	ds_read_b128 v[204:207], v171 offset:22528
	ds_read_b128 v[208:211], v171 offset:23552
	global_load_lds_dwordx4 v[212:213], off
	s_add_i32 m0, s51, 0x2000
	s_add_u32 s52, s66, 0x80000
	v_lshl_add_u64 v[214:215], s[66:67], 0, v[144:145]
	s_addc_u32 s53, s67, 0
	s_add_i32 s51, s47, s2
	global_load_lds_dwordx4 v[214:215], off
	v_lshl_add_u64 v[216:217], s[52:53], 0, v[148:149]
	s_mov_b32 m0, s51
	v_lshl_add_u64 v[218:219], s[68:69], 0, v[146:147]
	global_load_lds_dwordx4 v[216:217], off
	v_lshl_add_u64 v[216:217], s[52:53], 0, v[144:145]
	s_add_i32 m0, s51, 0x2000
	s_nop 0
	global_load_lds_dwordx4 v[216:217], off
	v_lshl_add_u64 v[216:217], s[68:69], 0, v[150:151]
	s_mov_b32 m0, s28
	s_nop 0
	global_load_lds_dwordx4 v[216:217], off
	s_mov_b32 m0, s29
	s_nop 0
	global_load_lds_dwordx4 v[218:219], off
	s_waitcnt vmcnt(8)
	s_waitcnt lgkmcnt(0)
	s_barrier
; #define PG8_STAGE(bufoff, gbase, voff) do { _Pragma("unroll") for (int _i = 0; _i < 2; ++_i) \
;         __builtin_amdgcn_global_load_lds((const unsigned*)((const char*)(gbase) + (voff)[_i]), (LAS unsigned*)(lds + (bufoff) + ldsw + _i * 8192), 16, 0, 0); } while (0)
; #define PG8_LDA(dst, b, h) do { _Pragma("unroll") for (int m = 0; m < 4; ++m) _Pragma("unroll") for (int k = 0; k < 2; ++k) dst[m][k] = *(const LAS bf16x8*)(lds + PG8_SA(b, h) + aoff + m * 2048 + k * 1024); } while (0)
; #define PG8_LDB(dst, b, h) do { _Pragma("unroll") for (int n = 0; n < 2; ++n) _Pragma("unroll") for (int k = 0; k < 2; ++k) dst[n][k] = *(const LAS bf16x8*)(lds + PG8_SB(b, h) + boff + n * 2048 + k * 1024); } while (0)
; #define PG8_MMA(ai, bj, At, Bt) do { __builtin_amdgcn_s_setprio(1); _Pragma("unroll") for (int m = 0; m < 4; ++m) _Pragma("unroll") for (int n = 0; n < 2; ++n) _Pragma("unroll") for (int k = 0; k < 2; ++k) \
;         acc[ai][bj][m][n] = __builtin_amdgcn_mfma_f32_16x16x32_bf16(Bt[n][k], At[m][k], acc[ai][bj][m][n], 0, 0, 0); __builtin_amdgcn_s_setprio(0); } while (0)
; #define PG8_WAIT_V(n) asm volatile("s_waitcnt vmcnt(" #n ")" ::: "memory")
; #define PG8_WAIT_L(n) asm volatile("s_waitcnt lgkmcnt(" #n ")" ::: "memory")
; #define PG8_BAR __builtin_amdgcn_s_barrier()
; #define PG8_SCHED __builtin_amdgcn_sched_barrier(0)
; template <class Desc, class Epi>
; DI void gemm_phase(LAS unsigned char* lds, const Desc& D, const Epi& E, int wv) {
;     ...
;             PG8_WAIT_V(8); PG8_WAIT_L(0); PG8_BAR; PG8_MMA(1, 0, At, B0); PG8_MMA(1, 1, At, B1); PG8_BAR; PG8_SCHED;
;             PG8_LDB(B0, 1, 0); PG8_LDB(B1, 1, 1); PG8_SCHED; PG8_LDA(At, 1, 0); PG8_STAGE(PG8_SA(0, 1), a2 + hstepA, voffA);
;             PG8_WAIT_V(8); PG8_WAIT_L(0); PG8_BAR; PG8_MMA(0, 0, At, B0); PG8_MMA(0, 1, At, B1); PG8_BAR; PG8_SCHED;
	v_mfma_f32_16x16x32_bf16 v[60:63], v[128:131], v[180:183], v[60:63]
	v_mfma_f32_16x16x32_bf16 v[56:59], v[136:139], v[180:183], v[56:59]
	v_mfma_f32_16x16x32_bf16 v[52:55], v[128:131], v[188:191], v[52:55]
	v_mfma_f32_16x16x32_bf16 v[44:47], v[136:139], v[188:191], v[44:47]
	v_mfma_f32_16x16x32_bf16 v[36:39], v[128:131], v[196:199], v[36:39]
	v_mfma_f32_16x16x32_bf16 v[28:31], v[136:139], v[196:199], v[28:31]
	v_mfma_f32_16x16x32_bf16 v[20:23], v[128:131], v[204:207], v[20:23]
	v_mfma_f32_16x16x32_bf16 v[12:15], v[136:139], v[204:207], v[12:15]
	v_mfma_f32_16x16x32_bf16 v[60:63], v[132:135], v[184:187], v[60:63]
	v_mfma_f32_16x16x32_bf16 v[56:59], v[140:143], v[184:187], v[56:59]
	v_mfma_f32_16x16x32_bf16 v[52:55], v[132:135], v[192:195], v[52:55]
	v_mfma_f32_16x16x32_bf16 v[44:47], v[140:143], v[192:195], v[44:47]
	v_mfma_f32_16x16x32_bf16 v[36:39], v[132:135], v[200:203], v[36:39]
	v_mfma_f32_16x16x32_bf16 v[28:31], v[140:143], v[200:203], v[28:31]
	v_mfma_f32_16x16x32_bf16 v[20:23], v[132:135], v[208:211], v[20:23]
	v_mfma_f32_16x16x32_bf16 v[12:15], v[140:143], v[208:211], v[12:15]
	v_mfma_f32_16x16x32_bf16 v[48:51], v[160:163], v[180:183], v[48:51]
	v_mfma_f32_16x16x32_bf16 v[40:43], v[172:175], v[180:183], v[40:43]
	v_mfma_f32_16x16x32_bf16 v[32:35], v[160:163], v[188:191], v[32:35]
	v_mfma_f32_16x16x32_bf16 v[24:27], v[172:175], v[188:191], v[24:27]
	v_mfma_f32_16x16x32_bf16 v[16:19], v[160:163], v[196:199], v[16:19]
	v_mfma_f32_16x16x32_bf16 v[8:11], v[172:175], v[196:199], v[8:11]
	v_mfma_f32_16x16x32_bf16 v[4:7], v[160:163], v[204:207], v[4:7]
	v_mfma_f32_16x16x32_bf16 v[0:3], v[172:175], v[204:207], v[0:3]
	v_mfma_f32_16x16x32_bf16 v[48:51], v[164:167], v[184:187], v[48:51]
	v_mfma_f32_16x16x32_bf16 v[40:43], v[176:179], v[184:187], v[40:43]
	v_mfma_f32_16x16x32_bf16 v[32:35], v[164:167], v[192:195], v[32:35]
	v_mfma_f32_16x16x32_bf16 v[24:27], v[176:179], v[192:195], v[24:27]
	v_mfma_f32_16x16x32_bf16 v[16:19], v[164:167], v[200:203], v[16:19]
	v_mfma_f32_16x16x32_bf16 v[8:11], v[176:179], v[200:203], v[8:11]
	v_mfma_f32_16x16x32_bf16 v[4:7], v[164:167], v[208:211], v[4:7]
	v_mfma_f32_16x16x32_bf16 v[0:3], v[176:179], v[208:211], v[0:3]
	s_barrier
	s_add_i32 s51, 0, 0x18000
	s_add_i32 s60, 0, 0x1c000
	v_add_u32_e32 v140, s51, v168
	v_add_u32_e32 v176, s60, v168
	ds_read_b128 v[128:131], v140
	ds_read_b128 v[132:135], v140 offset:1024
	ds_read_b128 v[136:139], v140 offset:2048
	ds_read_b128 v[140:143], v140 offset:3072
	ds_read_b128 v[160:163], v176
	ds_read_b128 v[164:167], v176 offset:1024
	ds_read_b128 v[172:175], v176 offset:2048
	ds_read_b128 v[176:179], v176 offset:3072
	s_add_u32 s52, s68, 0x80000
	s_addc_u32 s53, s69, 0
	s_mov_b32 m0, s30
	v_lshl_add_u64 v[220:221], s[52:53], 0, v[150:151]
	ds_read_b128 v[180:183], v171 offset:32768
	ds_read_b128 v[184:187], v171 offset:33792
	ds_read_b128 v[188:191], v171 offset:34816
	ds_read_b128 v[192:195], v171 offset:35840
	ds_read_b128 v[196:199], v171 offset:36864
	ds_read_b128 v[200:203], v171 offset:37888
	ds_read_b128 v[204:207], v171 offset:38912
	ds_read_b128 v[208:211], v171 offset:39936
	global_load_lds_dwordx4 v[220:221], off
	v_lshl_add_u64 v[220:221], s[52:53], 0, v[146:147]
	s_mov_b32 m0, s31
	s_nop 0
	global_load_lds_dwordx4 v[220:221], off
	s_waitcnt vmcnt(8)
	s_waitcnt lgkmcnt(0)
	s_barrier
	v_mfma_f32_16x16x32_bf16 v[124:127], v[128:131], v[180:183], v[124:127]
	v_mfma_f32_16x16x32_bf16 v[120:123], v[136:139], v[180:183], v[120:123]
	v_mfma_f32_16x16x32_bf16 v[112:115], v[128:131], v[188:191], v[112:115]
	v_mfma_f32_16x16x32_bf16 v[108:111], v[136:139], v[188:191], v[108:111]
	v_mfma_f32_16x16x32_bf16 v[100:103], v[128:131], v[196:199], v[100:103]
	v_mfma_f32_16x16x32_bf16 v[92:95], v[136:139], v[196:199], v[92:95]
	v_mfma_f32_16x16x32_bf16 v[84:87], v[128:131], v[204:207], v[84:87]
	v_mfma_f32_16x16x32_bf16 v[76:79], v[136:139], v[204:207], v[76:79]
	v_mfma_f32_16x16x32_bf16 v[124:127], v[132:135], v[184:187], v[124:127]
	v_mfma_f32_16x16x32_bf16 v[120:123], v[140:143], v[184:187], v[120:123]
	v_mfma_f32_16x16x32_bf16 v[112:115], v[132:135], v[192:195], v[112:115]
	v_mfma_f32_16x16x32_bf16 v[108:111], v[140:143], v[192:195], v[108:111]
	v_mfma_f32_16x16x32_bf16 v[100:103], v[132:135], v[200:203], v[100:103]
	v_mfma_f32_16x16x32_bf16 v[92:95], v[140:143], v[200:203], v[92:95]
	v_mfma_f32_16x16x32_bf16 v[84:87], v[132:135], v[208:211], v[84:87]
	v_mfma_f32_16x16x32_bf16 v[76:79], v[140:143], v[208:211], v[76:79]
	v_mfma_f32_16x16x32_bf16 v[116:119], v[160:163], v[180:183], v[116:119]
	v_mfma_f32_16x16x32_bf16 v[104:107], v[172:175], v[180:183], v[104:107]
	v_mfma_f32_16x16x32_bf16 v[96:99], v[160:163], v[188:191], v[96:99]
	v_mfma_f32_16x16x32_bf16 v[88:91], v[172:175], v[188:191], v[88:91]
	v_mfma_f32_16x16x32_bf16 v[80:83], v[160:163], v[196:199], v[80:83]
	v_mfma_f32_16x16x32_bf16 v[72:75], v[172:175], v[196:199], v[72:75]
	v_mfma_f32_16x16x32_bf16 v[68:71], v[160:163], v[204:207], v[68:71]
	v_mfma_f32_16x16x32_bf16 v[64:67], v[172:175], v[204:207], v[64:67]
	v_mfma_f32_16x16x32_bf16 v[116:119], v[164:167], v[184:187], v[116:119]
	v_mfma_f32_16x16x32_bf16 v[104:107], v[176:179], v[184:187], v[104:107]
	v_mfma_f32_16x16x32_bf16 v[96:99], v[164:167], v[192:195], v[96:99]
	v_mfma_f32_16x16x32_bf16 v[88:91], v[176:179], v[192:195], v[88:91]
	v_mfma_f32_16x16x32_bf16 v[80:83], v[164:167], v[200:203], v[80:83]
	v_mfma_f32_16x16x32_bf16 v[72:75], v[176:179], v[200:203], v[72:75]
	v_mfma_f32_16x16x32_bf16 v[68:71], v[164:167], v[208:211], v[68:71]
	v_mfma_f32_16x16x32_bf16 v[64:67], v[176:179], v[208:211], v[64:67]
	s_barrier
; #define PG8_STAGE(bufoff, gbase, voff) do { _Pragma("unroll") for (int _i = 0; _i < 2; ++_i) \
;         __builtin_amdgcn_global_load_lds((const unsigned*)((const char*)(gbase) + (voff)[_i]), (LAS unsigned*)(lds + (bufoff) + ldsw + _i * 8192), 16, 0, 0); } while (0)
; #define PG8_LDA(dst, b, h) do { _Pragma("unroll") for (int m = 0; m < 4; ++m) _Pragma("unroll") for (int k = 0; k < 2; ++k) dst[m][k] = *(const LAS bf16x8*)(lds + PG8_SA(b, h) + aoff + m * 2048 + k * 1024); } while (0)
; #define PG8_MMA(ai, bj, At, Bt) do { __builtin_amdgcn_s_setprio(1); _Pragma("unroll") for (int m = 0; m < 4; ++m) _Pragma("unroll") for (int n = 0; n < 2; ++n) _Pragma("unroll") for (int k = 0; k < 2; ++k) \
;         acc[ai][bj][m][n] = __builtin_amdgcn_mfma_f32_16x16x32_bf16(Bt[n][k], At[m][k], acc[ai][bj][m][n], 0, 0, 0); __builtin_amdgcn_s_setprio(0); } while (0)
; #define PG8_WAIT_V(n) asm volatile("s_waitcnt vmcnt(" #n ")" ::: "memory")
; #define PG8_WAIT_L(n) asm volatile("s_waitcnt lgkmcnt(" #n ")" ::: "memory")
; #define PG8_BAR __builtin_amdgcn_s_barrier()
; #define PG8_SCHED __builtin_amdgcn_sched_barrier(0)
; template <class Desc, class Epi>
; DI void gemm_phase(LAS unsigned char* lds, const Desc& D, const Epi& E, int wv) {
;     ...
;         for (int t = 0; t < nt; t += 2) {
;     ...
;             PG8_LDA(At, 1, 1); PG8_STAGE(PG8_SB(1, 0), b3, voffB); PG8_STAGE(PG8_SB(1, 1), b3 + hstepB, voffB); PG8_STAGE(PG8_SA(1, 0), a3, voffA);
;             PG8_WAIT_V(8); PG8_WAIT_L(0); PG8_BAR; PG8_MMA(1, 0, At, B0); PG8_MMA(1, 1, At, B1); PG8_BAR; PG8_SCHED;
;         }
	s_add_i32 s51, s51, s2
	v_lshl_add_u64 v[212:213], v[212:213], 0, s[10:11]
	s_mov_b32 m0, s51
	ds_read_b128 v[180:183], v171 offset:49152
	ds_read_b128 v[184:187], v171 offset:50176
	ds_read_b128 v[188:191], v171 offset:51200
	ds_read_b128 v[192:195], v171 offset:52224
	ds_read_b128 v[196:199], v171 offset:53248
	ds_read_b128 v[200:203], v171 offset:54272
	ds_read_b128 v[204:207], v171 offset:55296
	ds_read_b128 v[208:211], v171 offset:56320
	global_load_lds_dwordx4 v[212:213], off
	s_add_i32 m0, s51, 0x2000
	s_add_u32 s52, s66, 0x80080
	v_lshl_add_u64 v[212:213], v[214:215], 0, s[10:11]
	s_addc_u32 s53, s67, 0
	s_add_i32 s51, s60, s2
	global_load_lds_dwordx4 v[212:213], off
	v_lshl_add_u64 v[212:213], s[52:53], 0, v[148:149]
	s_mov_b32 m0, s51
	s_nop 0
	global_load_lds_dwordx4 v[212:213], off
	v_lshl_add_u64 v[212:213], s[52:53], 0, v[144:145]
	s_add_i32 m0, s51, 0x2000
	s_nop 0
	global_load_lds_dwordx4 v[212:213], off
	v_lshl_add_u64 v[212:213], v[216:217], 0, s[10:11]
	s_mov_b32 m0, s41
	s_nop 0
	global_load_lds_dwordx4 v[212:213], off
	v_lshl_add_u64 v[212:213], v[218:219], 0, s[10:11]
	s_mov_b32 m0, s42
	s_nop 0
	global_load_lds_dwordx4 v[212:213], off
	s_waitcnt vmcnt(8)
	s_waitcnt lgkmcnt(0)
	s_barrier
	v_mfma_f32_16x16x32_bf16 v[60:63], v[128:131], v[180:183], v[60:63]
	v_mfma_f32_16x16x32_bf16 v[56:59], v[136:139], v[180:183], v[56:59]
	v_mfma_f32_16x16x32_bf16 v[52:55], v[128:131], v[188:191], v[52:55]
	v_mfma_f32_16x16x32_bf16 v[44:47], v[136:139], v[188:191], v[44:47]
	v_mfma_f32_16x16x32_bf16 v[36:39], v[128:131], v[196:199], v[36:39]
	v_mfma_f32_16x16x32_bf16 v[28:31], v[136:139], v[196:199], v[28:31]
	v_mfma_f32_16x16x32_bf16 v[20:23], v[128:131], v[204:207], v[20:23]
	v_mfma_f32_16x16x32_bf16 v[12:15], v[136:139], v[204:207], v[12:15]
	v_mfma_f32_16x16x32_bf16 v[60:63], v[132:135], v[184:187], v[60:63]
	v_mfma_f32_16x16x32_bf16 v[56:59], v[140:143], v[184:187], v[56:59]
	v_mfma_f32_16x16x32_bf16 v[52:55], v[132:135], v[192:195], v[52:55]
	v_mfma_f32_16x16x32_bf16 v[44:47], v[140:143], v[192:195], v[44:47]
	v_mfma_f32_16x16x32_bf16 v[36:39], v[132:135], v[200:203], v[36:39]
	v_mfma_f32_16x16x32_bf16 v[28:31], v[140:143], v[200:203], v[28:31]
	v_mfma_f32_16x16x32_bf16 v[20:23], v[132:135], v[208:211], v[20:23]
	v_mfma_f32_16x16x32_bf16 v[12:15], v[140:143], v[208:211], v[12:15]
	v_mfma_f32_16x16x32_bf16 v[48:51], v[160:163], v[180:183], v[48:51]
	v_mfma_f32_16x16x32_bf16 v[40:43], v[172:175], v[180:183], v[40:43]
	v_mfma_f32_16x16x32_bf16 v[32:35], v[160:163], v[188:191], v[32:35]
	v_mfma_f32_16x16x32_bf16 v[24:27], v[172:175], v[188:191], v[24:27]
	v_mfma_f32_16x16x32_bf16 v[16:19], v[160:163], v[196:199], v[16:19]
	v_mfma_f32_16x16x32_bf16 v[8:11], v[172:175], v[196:199], v[8:11]
	v_mfma_f32_16x16x32_bf16 v[4:7], v[160:163], v[204:207], v[4:7]
	v_mfma_f32_16x16x32_bf16 v[0:3], v[172:175], v[204:207], v[0:3]
	v_mfma_f32_16x16x32_bf16 v[48:51], v[164:167], v[184:187], v[48:51]
	v_mfma_f32_16x16x32_bf16 v[40:43], v[176:179], v[184:187], v[40:43]
	v_mfma_f32_16x16x32_bf16 v[32:35], v[164:167], v[192:195], v[32:35]
	v_mfma_f32_16x16x32_bf16 v[24:27], v[176:179], v[192:195], v[24:27]
	v_mfma_f32_16x16x32_bf16 v[16:19], v[164:167], v[200:203], v[16:19]
	v_mfma_f32_16x16x32_bf16 v[8:11], v[176:179], v[200:203], v[8:11]
	v_mfma_f32_16x16x32_bf16 v[4:7], v[164:167], v[208:211], v[4:7]
	v_mfma_f32_16x16x32_bf16 v[0:3], v[176:179], v[208:211], v[0:3]
	s_barrier
	s_add_i32 s50, s50, 2
	s_add_u32 s6, s6, 0x100
	s_addc_u32 s7, s7, 0
	s_add_u32 s23, s23, 0x100
	s_addc_u32 s49, s49, 0
	s_cmp_gt_u32 s50, 29
	s_cbranch_scc0 .LBB0_831
	s_and_b64 vcc, exec, s[14:15]
	s_cbranch_vccz .LBB0_834
	s_barrier

; #define PG8_STAGE(bufoff, gbase, voff) do { _Pragma("unroll") for (int _i = 0; _i < 2; ++_i) \
;         __builtin_amdgcn_global_load_lds((const unsigned*)((const char*)(gbase) + (voff)[_i]), (LAS unsigned*)(lds + (bufoff) + ldsw + _i * 8192), 16, 0, 0); } while (0)
; #define PG8_LDA(dst, b, h) do { _Pragma("unroll") for (int m = 0; m < 4; ++m) _Pragma("unroll") for (int k = 0; k < 2; ++k) dst[m][k] = *(const LAS bf16x8*)(lds + PG8_SA(b, h) + aoff + m * 2048 + k * 1024); } while (0)
; #define PG8_LDB(dst, b, h) do { _Pragma("unroll") for (int n = 0; n < 2; ++n) _Pragma("unroll") for (int k = 0; k < 2; ++k) dst[n][k] = *(const LAS bf16x8*)(lds + PG8_SB(b, h) + boff + n * 2048 + k * 1024); } while (0)
; #define PG8_MMA(ai, bj, At, Bt) do { __builtin_amdgcn_s_setprio(1); _Pragma("unroll") for (int m = 0; m < 4; ++m) _Pragma("unroll") for (int n = 0; n < 2; ++n) _Pragma("unroll") for (int k = 0; k < 2; ++k) \
;         acc[ai][bj][m][n] = __builtin_amdgcn_mfma_f32_16x16x32_bf16(Bt[n][k], At[m][k], acc[ai][bj][m][n], 0, 0, 0); __builtin_amdgcn_s_setprio(0); } while (0)
; #define PG8_WAIT_V(n) asm volatile("s_waitcnt vmcnt(" #n ")" ::: "memory")
; #define PG8_WAIT_L(n) asm volatile("s_waitcnt lgkmcnt(" #n ")" ::: "memory")
; #define PG8_BAR __builtin_amdgcn_s_barrier()
; #define PG8_SCHED __builtin_amdgcn_sched_barrier(0)
; template <class Desc, class Epi>
; DI void gemm_phase(LAS unsigned char* lds, const Desc& D, const Epi& E, int wv) {
;     ...
;             const bool last = (t == nt - 2);
;             const char* a1 = cA + (size_t)(t + 1) * kstep;
;             const char* a2 = last ? nA : cA + (size_t)(t + 2) * kstep; const char* b2 = last ? nB : cB + (size_t)(t + 2) * kstep;
;             const char* a3 = a2 + kstep; const char* b3 = b2 + kstep;
;             PG8_LDB(B0, 0, 0); PG8_LDB(B1, 0, 1); PG8_SCHED; PG8_LDA(At, 0, 0); PG8_STAGE(PG8_SA(1, 1), a1 + hstepA, voffA);
;             PG8_WAIT_V(8); PG8_WAIT_L(0); PG8_BAR; PG8_MMA(0, 0, At, B0); PG8_MMA(0, 1, At, B1); PG8_BAR; PG8_SCHED;
;             PG8_LDA(At, 0, 1); PG8_STAGE(PG8_SB(0, 0), b2, voffB); PG8_STAGE(PG8_SB(0, 1), b2 + hstepB, voffB); PG8_STAGE(PG8_SA(0, 0), a2, voffA);
;             PG8_WAIT_V(8); PG8_WAIT_L(0); PG8_BAR; PG8_MMA(1, 0, At, B0); PG8_MMA(1, 1, At, B1); PG8_BAR; PG8_SCHED;
.LBB0_962:
	ds_read_b128 v[146:149], v157
	ds_read_b128 v[150:153], v157 offset:1024
	ds_read_b128 v[160:163], v157 offset:2048
	ds_read_b128 v[164:167], v157 offset:3072
	ds_read_b128 v[168:171], v158
	ds_read_b128 v[172:175], v158 offset:1024
	ds_read_b128 v[176:179], v158 offset:2048
	ds_read_b128 v[180:183], v158 offset:3072
	s_add_u32 s60, s70, 0xfff80080
	s_addc_u32 s63, s71, -1
	s_cmp_eq_u32 s53, 28
	s_cselect_b32 s75, s65, s63
	s_cselect_b32 s74, s64, s60
	s_cselect_b32 s73, s69, s10
	s_cselect_b32 s72, s68, s9
	v_lshl_add_u64 v[154:155], s[70:71], 0, v[138:139]
	s_add_i32 m0, s3, 0xc000
	ds_read_b128 v[184:187], v159
	ds_read_b128 v[188:191], v159 offset:1024
	ds_read_b128 v[192:195], v159 offset:2048
	ds_read_b128 v[196:199], v159 offset:3072
	ds_read_b128 v[200:203], v159 offset:4096
	ds_read_b128 v[204:207], v159 offset:5120
	ds_read_b128 v[208:211], v159 offset:6144
	ds_read_b128 v[212:215], v159 offset:7168
	global_load_lds_dwordx4 v[154:155], off
	v_lshl_add_u64 v[154:155], s[70:71], 0, v[140:141]
	s_add_i32 m0, s3, 0xe000
	s_nop 0
	global_load_lds_dwordx4 v[154:155], off
	s_waitcnt vmcnt(8)
	s_waitcnt lgkmcnt(0)
	s_barrier
	v_mfma_f32_16x16x32_bf16 v[124:127], v[146:149], v[184:187], v[124:127]
	v_mfma_f32_16x16x32_bf16 v[120:123], v[160:163], v[184:187], v[120:123]
	v_mfma_f32_16x16x32_bf16 v[108:111], v[146:149], v[192:195], v[108:111]
	v_mfma_f32_16x16x32_bf16 v[104:107], v[160:163], v[192:195], v[104:107]
	v_mfma_f32_16x16x32_bf16 v[92:95], v[146:149], v[200:203], v[92:95]
	v_mfma_f32_16x16x32_bf16 v[88:91], v[160:163], v[200:203], v[88:91]
	v_mfma_f32_16x16x32_bf16 v[76:79], v[146:149], v[208:211], v[76:79]
	v_mfma_f32_16x16x32_bf16 v[72:75], v[160:163], v[208:211], v[72:75]
	v_mfma_f32_16x16x32_bf16 v[124:127], v[150:153], v[188:191], v[124:127]
	v_mfma_f32_16x16x32_bf16 v[120:123], v[164:167], v[188:191], v[120:123]
	v_mfma_f32_16x16x32_bf16 v[108:111], v[150:153], v[196:199], v[108:111]
	v_mfma_f32_16x16x32_bf16 v[104:107], v[164:167], v[196:199], v[104:107]
	v_mfma_f32_16x16x32_bf16 v[92:95], v[150:153], v[204:207], v[92:95]
	v_mfma_f32_16x16x32_bf16 v[88:91], v[164:167], v[204:207], v[88:91]
	v_mfma_f32_16x16x32_bf16 v[76:79], v[150:153], v[212:215], v[76:79]
	v_mfma_f32_16x16x32_bf16 v[72:75], v[164:167], v[212:215], v[72:75]
	v_mfma_f32_16x16x32_bf16 v[116:119], v[168:171], v[184:187], v[116:119]
	v_mfma_f32_16x16x32_bf16 v[112:115], v[176:179], v[184:187], v[112:115]
	v_mfma_f32_16x16x32_bf16 v[100:103], v[168:171], v[192:195], v[100:103]
	v_mfma_f32_16x16x32_bf16 v[96:99], v[176:179], v[192:195], v[96:99]
	v_mfma_f32_16x16x32_bf16 v[84:87], v[168:171], v[200:203], v[84:87]
	v_mfma_f32_16x16x32_bf16 v[80:83], v[176:179], v[200:203], v[80:83]
	v_mfma_f32_16x16x32_bf16 v[68:71], v[168:171], v[208:211], v[68:71]
	v_mfma_f32_16x16x32_bf16 v[64:67], v[176:179], v[208:211], v[64:67]
	v_mfma_f32_16x16x32_bf16 v[116:119], v[172:175], v[188:191], v[116:119]
	v_mfma_f32_16x16x32_bf16 v[112:115], v[180:183], v[188:191], v[112:115]
	v_mfma_f32_16x16x32_bf16 v[100:103], v[172:175], v[196:199], v[100:103]
	v_mfma_f32_16x16x32_bf16 v[96:99], v[180:183], v[196:199], v[96:99]
	v_mfma_f32_16x16x32_bf16 v[84:87], v[172:175], v[204:207], v[84:87]
	v_mfma_f32_16x16x32_bf16 v[80:83], v[180:183], v[204:207], v[80:83]
	v_mfma_f32_16x16x32_bf16 v[68:71], v[172:175], v[212:215], v[68:71]
	v_mfma_f32_16x16x32_bf16 v[64:67], v[180:183], v[212:215], v[64:67]
	s_barrier
	s_add_i32 s60, s46, s2
	v_lshl_add_u64 v[154:155], s[72:73], 0, v[130:131]
	s_mov_b32 m0, s60
	ds_read_b128 v[184:187], v159 offset:16384
	ds_read_b128 v[188:191], v159 offset:17408
	ds_read_b128 v[192:195], v159 offset:18432
	ds_read_b128 v[196:199], v159 offset:19456
	ds_read_b128 v[200:203], v159 offset:20480
	ds_read_b128 v[204:207], v159 offset:21504
	ds_read_b128 v[208:211], v159 offset:22528
	ds_read_b128 v[212:215], v159 offset:23552
	global_load_lds_dwordx4 v[154:155], off
	s_add_i32 m0, s60, 0x2000
	s_add_u32 s76, s72, 0x80000
	v_lshl_add_u64 v[216:217], s[72:73], 0, v[134:135]
	s_addc_u32 s77, s73, 0
	s_add_i32 s60, s47, s2
	global_load_lds_dwordx4 v[216:217], off
	v_lshl_add_u64 v[218:219], s[76:77], 0, v[130:131]
	s_mov_b32 m0, s60
	v_lshl_add_u64 v[220:221], s[74:75], 0, v[132:133]
	global_load_lds_dwordx4 v[218:219], off
	v_lshl_add_u64 v[218:219], s[76:77], 0, v[134:135]
	s_add_i32 m0, s60, 0x2000
	s_nop 0
	global_load_lds_dwordx4 v[218:219], off
	v_lshl_add_u64 v[218:219], s[74:75], 0, v[128:129]
	s_mov_b32 m0, s3
	s_nop 0
	global_load_lds_dwordx4 v[218:219], off
	s_mov_b32 m0, s28
	s_nop 0
	global_load_lds_dwordx4 v[220:221], off
	s_waitcnt vmcnt(8)
	s_waitcnt lgkmcnt(0)
	s_barrier
; #define PG8_STAGE(bufoff, gbase, voff) do { _Pragma("unroll") for (int _i = 0; _i < 2; ++_i) \
;         __builtin_amdgcn_global_load_lds((const unsigned*)((const char*)(gbase) + (voff)[_i]), (LAS unsigned*)(lds + (bufoff) + ldsw + _i * 8192), 16, 0, 0); } while (0)
; #define PG8_LDA(dst, b, h) do { _Pragma("unroll") for (int m = 0; m < 4; ++m) _Pragma("unroll") for (int k = 0; k < 2; ++k) dst[m][k] = *(const LAS bf16x8*)(lds + PG8_SA(b, h) + aoff + m * 2048 + k * 1024); } while (0)
; #define PG8_LDB(dst, b, h) do { _Pragma("unroll") for (int n = 0; n < 2; ++n) _Pragma("unroll") for (int k = 0; k < 2; ++k) dst[n][k] = *(const LAS bf16x8*)(lds + PG8_SB(b, h) + boff + n * 2048 + k * 1024); } while (0)
; #define PG8_MMA(ai, bj, At, Bt) do { __builtin_amdgcn_s_setprio(1); _Pragma("unroll") for (int m = 0; m < 4; ++m) _Pragma("unroll") for (int n = 0; n < 2; ++n) _Pragma("unroll") for (int k = 0; k < 2; ++k) \
;         acc[ai][bj][m][n] = __builtin_amdgcn_mfma_f32_16x16x32_bf16(Bt[n][k], At[m][k], acc[ai][bj][m][n], 0, 0, 0); __builtin_amdgcn_s_setprio(0); } while (0)
; #define PG8_WAIT_V(n) asm volatile("s_waitcnt vmcnt(" #n ")" ::: "memory")
; #define PG8_WAIT_L(n) asm volatile("s_waitcnt lgkmcnt(" #n ")" ::: "memory")
; #define PG8_BAR __builtin_amdgcn_s_barrier()
; #define PG8_SCHED __builtin_amdgcn_sched_barrier(0)
; template <class Desc, class Epi>
; DI void gemm_phase(LAS unsigned char* lds, const Desc& D, const Epi& E, int wv) {
;     ...
;             PG8_WAIT_V(8); PG8_WAIT_L(0); PG8_BAR; PG8_MMA(1, 0, At, B0); PG8_MMA(1, 1, At, B1); PG8_BAR; PG8_SCHED;
;             PG8_LDB(B0, 1, 0); PG8_LDB(B1, 1, 1); PG8_SCHED; PG8_LDA(At, 1, 0); PG8_STAGE(PG8_SA(0, 1), a2 + hstepA, voffA);
;             PG8_WAIT_V(8); PG8_WAIT_L(0); PG8_BAR; PG8_MMA(0, 0, At, B0); PG8_MMA(0, 1, At, B1); PG8_BAR; PG8_SCHED;
	v_mfma_f32_16x16x32_bf16 v[60:63], v[146:149], v[184:187], v[60:63]
	v_mfma_f32_16x16x32_bf16 v[56:59], v[160:163], v[184:187], v[56:59]
	v_mfma_f32_16x16x32_bf16 v[44:47], v[146:149], v[192:195], v[44:47]
	v_mfma_f32_16x16x32_bf16 v[40:43], v[160:163], v[192:195], v[40:43]
	v_mfma_f32_16x16x32_bf16 v[28:31], v[146:149], v[200:203], v[28:31]
	v_mfma_f32_16x16x32_bf16 v[24:27], v[160:163], v[200:203], v[24:27]
	v_mfma_f32_16x16x32_bf16 v[12:15], v[146:149], v[208:211], v[12:15]
	v_mfma_f32_16x16x32_bf16 v[8:11], v[160:163], v[208:211], v[8:11]
	v_mfma_f32_16x16x32_bf16 v[60:63], v[150:153], v[188:191], v[60:63]
	v_mfma_f32_16x16x32_bf16 v[56:59], v[164:167], v[188:191], v[56:59]
	v_mfma_f32_16x16x32_bf16 v[44:47], v[150:153], v[196:199], v[44:47]
	v_mfma_f32_16x16x32_bf16 v[40:43], v[164:167], v[196:199], v[40:43]
	v_mfma_f32_16x16x32_bf16 v[28:31], v[150:153], v[204:207], v[28:31]
	v_mfma_f32_16x16x32_bf16 v[24:27], v[164:167], v[204:207], v[24:27]
	v_mfma_f32_16x16x32_bf16 v[12:15], v[150:153], v[212:215], v[12:15]
	v_mfma_f32_16x16x32_bf16 v[8:11], v[164:167], v[212:215], v[8:11]
	v_mfma_f32_16x16x32_bf16 v[52:55], v[168:171], v[184:187], v[52:55]
	v_mfma_f32_16x16x32_bf16 v[48:51], v[176:179], v[184:187], v[48:51]
	v_mfma_f32_16x16x32_bf16 v[36:39], v[168:171], v[192:195], v[36:39]
	v_mfma_f32_16x16x32_bf16 v[32:35], v[176:179], v[192:195], v[32:35]
	v_mfma_f32_16x16x32_bf16 v[20:23], v[168:171], v[200:203], v[20:23]
	v_mfma_f32_16x16x32_bf16 v[16:19], v[176:179], v[200:203], v[16:19]
	v_mfma_f32_16x16x32_bf16 v[4:7], v[168:171], v[208:211], v[4:7]
	v_mfma_f32_16x16x32_bf16 v[0:3], v[176:179], v[208:211], v[0:3]
	v_mfma_f32_16x16x32_bf16 v[52:55], v[172:175], v[188:191], v[52:55]
	v_mfma_f32_16x16x32_bf16 v[48:51], v[180:183], v[188:191], v[48:51]
	v_mfma_f32_16x16x32_bf16 v[36:39], v[172:175], v[196:199], v[36:39]
	v_mfma_f32_16x16x32_bf16 v[32:35], v[180:183], v[196:199], v[32:35]
	v_mfma_f32_16x16x32_bf16 v[20:23], v[172:175], v[204:207], v[20:23]
	v_mfma_f32_16x16x32_bf16 v[16:19], v[180:183], v[204:207], v[16:19]
	v_mfma_f32_16x16x32_bf16 v[4:7], v[172:175], v[212:215], v[4:7]
	v_mfma_f32_16x16x32_bf16 v[0:3], v[180:183], v[212:215], v[0:3]
	s_barrier
	s_add_i32 s60, 0, 0x18000
	v_add_u32_e32 v136, s60, v156
	s_add_i32 s63, 0, 0x1c000
	ds_read_b128 v[146:149], v136
	ds_read_b128 v[150:153], v136 offset:1024
	ds_read_b128 v[160:163], v136 offset:2048
	ds_read_b128 v[164:167], v136 offset:3072
	v_add_u32_e32 v136, s63, v156
	ds_read_b128 v[168:171], v136
	ds_read_b128 v[172:175], v136 offset:1024
	ds_read_b128 v[176:179], v136 offset:2048
	ds_read_b128 v[180:183], v136 offset:3072
	s_add_u32 s74, s74, 0x80000
	s_addc_u32 s75, s75, 0
	s_mov_b32 m0, s29
	v_lshl_add_u64 v[222:223], s[74:75], 0, v[128:129]
	ds_read_b128 v[184:187], v159 offset:32768
	ds_read_b128 v[188:191], v159 offset:33792
	ds_read_b128 v[192:195], v159 offset:34816
	ds_read_b128 v[196:199], v159 offset:35840
	ds_read_b128 v[200:203], v159 offset:36864
	ds_read_b128 v[204:207], v159 offset:37888
	ds_read_b128 v[208:211], v159 offset:38912
	ds_read_b128 v[212:215], v159 offset:39936
	global_load_lds_dwordx4 v[222:223], off
	v_lshl_add_u64 v[222:223], s[74:75], 0, v[132:133]
	s_mov_b32 m0, s30
	s_nop 0
	global_load_lds_dwordx4 v[222:223], off
	s_waitcnt vmcnt(8)
	s_waitcnt lgkmcnt(0)
	s_barrier
	v_mfma_f32_16x16x32_bf16 v[124:127], v[146:149], v[184:187], v[124:127]
	v_mfma_f32_16x16x32_bf16 v[120:123], v[160:163], v[184:187], v[120:123]
	v_mfma_f32_16x16x32_bf16 v[108:111], v[146:149], v[192:195], v[108:111]
	v_mfma_f32_16x16x32_bf16 v[104:107], v[160:163], v[192:195], v[104:107]
	v_mfma_f32_16x16x32_bf16 v[92:95], v[146:149], v[200:203], v[92:95]
	v_mfma_f32_16x16x32_bf16 v[88:91], v[160:163], v[200:203], v[88:91]
	v_mfma_f32_16x16x32_bf16 v[76:79], v[146:149], v[208:211], v[76:79]
	v_mfma_f32_16x16x32_bf16 v[72:75], v[160:163], v[208:211], v[72:75]
	v_mfma_f32_16x16x32_bf16 v[124:127], v[150:153], v[188:191], v[124:127]
	v_mfma_f32_16x16x32_bf16 v[120:123], v[164:167], v[188:191], v[120:123]
	v_mfma_f32_16x16x32_bf16 v[108:111], v[150:153], v[196:199], v[108:111]
	v_mfma_f32_16x16x32_bf16 v[104:107], v[164:167], v[196:199], v[104:107]
	v_mfma_f32_16x16x32_bf16 v[92:95], v[150:153], v[204:207], v[92:95]
	v_mfma_f32_16x16x32_bf16 v[88:91], v[164:167], v[204:207], v[88:91]
	v_mfma_f32_16x16x32_bf16 v[76:79], v[150:153], v[212:215], v[76:79]
	v_mfma_f32_16x16x32_bf16 v[72:75], v[164:167], v[212:215], v[72:75]
	v_mfma_f32_16x16x32_bf16 v[116:119], v[168:171], v[184:187], v[116:119]
	v_mfma_f32_16x16x32_bf16 v[112:115], v[176:179], v[184:187], v[112:115]
	v_mfma_f32_16x16x32_bf16 v[100:103], v[168:171], v[192:195], v[100:103]
	v_mfma_f32_16x16x32_bf16 v[96:99], v[176:179], v[192:195], v[96:99]
	v_mfma_f32_16x16x32_bf16 v[84:87], v[168:171], v[200:203], v[84:87]
	v_mfma_f32_16x16x32_bf16 v[80:83], v[176:179], v[200:203], v[80:83]
	v_mfma_f32_16x16x32_bf16 v[68:71], v[168:171], v[208:211], v[68:71]
	v_mfma_f32_16x16x32_bf16 v[64:67], v[176:179], v[208:211], v[64:67]
	v_mfma_f32_16x16x32_bf16 v[116:119], v[172:175], v[188:191], v[116:119]
	v_mfma_f32_16x16x32_bf16 v[112:115], v[180:183], v[188:191], v[112:115]
	v_mfma_f32_16x16x32_bf16 v[100:103], v[172:175], v[196:199], v[100:103]
	v_mfma_f32_16x16x32_bf16 v[96:99], v[180:183], v[196:199], v[96:99]
	v_mfma_f32_16x16x32_bf16 v[84:87], v[172:175], v[204:207], v[84:87]
	v_mfma_f32_16x16x32_bf16 v[80:83], v[180:183], v[204:207], v[80:83]
	v_mfma_f32_16x16x32_bf16 v[68:71], v[172:175], v[212:215], v[68:71]
	v_mfma_f32_16x16x32_bf16 v[64:67], v[180:183], v[212:215], v[64:67]
	s_barrier
; #define PG8_STAGE(bufoff, gbase, voff) do { _Pragma("unroll") for (int _i = 0; _i < 2; ++_i) \
;         __builtin_amdgcn_global_load_lds((const unsigned*)((const char*)(gbase) + (voff)[_i]), (LAS unsigned*)(lds + (bufoff) + ldsw + _i * 8192), 16, 0, 0); } while (0)
; #define PG8_LDA(dst, b, h) do { _Pragma("unroll") for (int m = 0; m < 4; ++m) _Pragma("unroll") for (int k = 0; k < 2; ++k) dst[m][k] = *(const LAS bf16x8*)(lds + PG8_SA(b, h) + aoff + m * 2048 + k * 1024); } while (0)
; #define PG8_MMA(ai, bj, At, Bt) do { __builtin_amdgcn_s_setprio(1); _Pragma("unroll") for (int m = 0; m < 4; ++m) _Pragma("unroll") for (int n = 0; n < 2; ++n) _Pragma("unroll") for (int k = 0; k < 2; ++k) \
;         acc[ai][bj][m][n] = __builtin_amdgcn_mfma_f32_16x16x32_bf16(Bt[n][k], At[m][k], acc[ai][bj][m][n], 0, 0, 0); __builtin_amdgcn_s_setprio(0); } while (0)
; #define PG8_WAIT_V(n) asm volatile("s_waitcnt vmcnt(" #n ")" ::: "memory")
; #define PG8_WAIT_L(n) asm volatile("s_waitcnt lgkmcnt(" #n ")" ::: "memory")
; #define PG8_BAR __builtin_amdgcn_s_barrier()
; #define PG8_SCHED __builtin_amdgcn_sched_barrier(0)
; template <class Desc, class Epi>
; DI void gemm_phase(LAS unsigned char* lds, const Desc& D, const Epi& E, int wv) {
;     ...
;         for (int t = 0; t < nt; t += 2) {
;     ...
;             PG8_LDA(At, 1, 1); PG8_STAGE(PG8_SB(1, 0), b3, voffB); PG8_STAGE(PG8_SB(1, 1), b3 + hstepB, voffB); PG8_STAGE(PG8_SA(1, 0), a3, voffA);
;             PG8_WAIT_V(8); PG8_WAIT_L(0); PG8_BAR; PG8_MMA(1, 0, At, B0); PG8_MMA(1, 1, At, B1); PG8_BAR; PG8_SCHED;
;         }
	s_add_i32 s60, s60, s2
	v_lshl_add_u64 v[154:155], v[154:155], 0, s[14:15]
	s_mov_b32 m0, s60
	ds_read_b128 v[184:187], v159 offset:49152
	ds_read_b128 v[188:191], v159 offset:50176
	ds_read_b128 v[192:195], v159 offset:51200
	ds_read_b128 v[196:199], v159 offset:52224
	ds_read_b128 v[200:203], v159 offset:53248
	ds_read_b128 v[204:207], v159 offset:54272
	ds_read_b128 v[208:211], v159 offset:55296
	ds_read_b128 v[212:215], v159 offset:56320
	global_load_lds_dwordx4 v[154:155], off
	s_add_i32 m0, s60, 0x2000
	s_add_u32 s72, s72, 0x80080
	v_lshl_add_u64 v[154:155], v[216:217], 0, s[14:15]
	s_addc_u32 s73, s73, 0
	s_add_i32 s60, s63, s2
	global_load_lds_dwordx4 v[154:155], off
	v_lshl_add_u64 v[154:155], s[72:73], 0, v[130:131]
	s_mov_b32 m0, s60
	s_nop 0
	global_load_lds_dwordx4 v[154:155], off
	v_lshl_add_u64 v[154:155], s[72:73], 0, v[134:135]
	s_add_i32 m0, s60, 0x2000
	s_nop 0
	global_load_lds_dwordx4 v[154:155], off
	v_lshl_add_u64 v[154:155], v[218:219], 0, s[14:15]
	s_mov_b32 m0, s41
	s_nop 0
	global_load_lds_dwordx4 v[154:155], off
	v_lshl_add_u64 v[154:155], v[220:221], 0, s[14:15]
	s_mov_b32 m0, s42
	s_nop 0
	global_load_lds_dwordx4 v[154:155], off
	s_waitcnt vmcnt(8)
	s_waitcnt lgkmcnt(0)
	s_barrier
	v_mfma_f32_16x16x32_bf16 v[60:63], v[146:149], v[184:187], v[60:63]
	v_mfma_f32_16x16x32_bf16 v[56:59], v[160:163], v[184:187], v[56:59]
	v_mfma_f32_16x16x32_bf16 v[44:47], v[146:149], v[192:195], v[44:47]
	v_mfma_f32_16x16x32_bf16 v[40:43], v[160:163], v[192:195], v[40:43]
	v_mfma_f32_16x16x32_bf16 v[28:31], v[146:149], v[200:203], v[28:31]
	v_mfma_f32_16x16x32_bf16 v[24:27], v[160:163], v[200:203], v[24:27]
	v_mfma_f32_16x16x32_bf16 v[12:15], v[146:149], v[208:211], v[12:15]
	v_mfma_f32_16x16x32_bf16 v[8:11], v[160:163], v[208:211], v[8:11]
	v_mfma_f32_16x16x32_bf16 v[60:63], v[150:153], v[188:191], v[60:63]
	v_mfma_f32_16x16x32_bf16 v[56:59], v[164:167], v[188:191], v[56:59]
	v_mfma_f32_16x16x32_bf16 v[44:47], v[150:153], v[196:199], v[44:47]
	v_mfma_f32_16x16x32_bf16 v[40:43], v[164:167], v[196:199], v[40:43]
	v_mfma_f32_16x16x32_bf16 v[28:31], v[150:153], v[204:207], v[28:31]
	v_mfma_f32_16x16x32_bf16 v[24:27], v[164:167], v[204:207], v[24:27]
	v_mfma_f32_16x16x32_bf16 v[12:15], v[150:153], v[212:215], v[12:15]
	v_mfma_f32_16x16x32_bf16 v[8:11], v[164:167], v[212:215], v[8:11]
	v_mfma_f32_16x16x32_bf16 v[52:55], v[168:171], v[184:187], v[52:55]
	v_mfma_f32_16x16x32_bf16 v[48:51], v[176:179], v[184:187], v[48:51]
	v_mfma_f32_16x16x32_bf16 v[36:39], v[168:171], v[192:195], v[36:39]
	v_mfma_f32_16x16x32_bf16 v[32:35], v[176:179], v[192:195], v[32:35]
	v_mfma_f32_16x16x32_bf16 v[20:23], v[168:171], v[200:203], v[20:23]
	v_mfma_f32_16x16x32_bf16 v[16:19], v[176:179], v[200:203], v[16:19]
	v_mfma_f32_16x16x32_bf16 v[4:7], v[168:171], v[208:211], v[4:7]
	v_mfma_f32_16x16x32_bf16 v[0:3], v[176:179], v[208:211], v[0:3]
	v_mfma_f32_16x16x32_bf16 v[52:55], v[172:175], v[188:191], v[52:55]
	v_mfma_f32_16x16x32_bf16 v[48:51], v[180:183], v[188:191], v[48:51]
	v_mfma_f32_16x16x32_bf16 v[36:39], v[172:175], v[196:199], v[36:39]
	v_mfma_f32_16x16x32_bf16 v[32:35], v[180:183], v[196:199], v[32:35]
	v_mfma_f32_16x16x32_bf16 v[20:23], v[172:175], v[204:207], v[20:23]
	v_mfma_f32_16x16x32_bf16 v[16:19], v[180:183], v[204:207], v[16:19]
	v_mfma_f32_16x16x32_bf16 v[4:7], v[172:175], v[212:215], v[4:7]
	v_mfma_f32_16x16x32_bf16 v[0:3], v[180:183], v[212:215], v[0:3]
	s_barrier
	s_add_i32 s53, s53, 2
	s_add_u32 s70, s70, 0x100
	s_addc_u32 s71, s71, 0
	s_add_u32 s9, s9, 0x100
	s_addc_u32 s10, s10, 0
	s_cmp_gt_u32 s53, 29
	s_cbranch_scc0 .LBB0_962
	s_and_b64 vcc, exec, s[20:21]
	s_cbranch_vccz .LBB0_965
	s_barrier

; #define PG8_STAGE(bufoff, gbase, voff) do { _Pragma("unroll") for (int _i = 0; _i < 2; ++_i) \
;         __builtin_amdgcn_global_load_lds((const unsigned*)((const char*)(gbase) + (voff)[_i]), (LAS unsigned*)(lds + (bufoff) + ldsw + _i * 8192), 16, 0, 0); } while (0)
; #define PG8_LDA(dst, b, h) do { _Pragma("unroll") for (int m = 0; m < 4; ++m) _Pragma("unroll") for (int k = 0; k < 2; ++k) dst[m][k] = *(const LAS bf16x8*)(lds + PG8_SA(b, h) + aoff + m * 2048 + k * 1024); } while (0)
; #define PG8_LDB(dst, b, h) do { _Pragma("unroll") for (int n = 0; n < 2; ++n) _Pragma("unroll") for (int k = 0; k < 2; ++k) dst[n][k] = *(const LAS bf16x8*)(lds + PG8_SB(b, h) + boff + n * 2048 + k * 1024); } while (0)
; #define PG8_MMA(ai, bj, At, Bt) do { __builtin_amdgcn_s_setprio(1); _Pragma("unroll") for (int m = 0; m < 4; ++m) _Pragma("unroll") for (int n = 0; n < 2; ++n) _Pragma("unroll") for (int k = 0; k < 2; ++k) \
;         acc[ai][bj][m][n] = __builtin_amdgcn_mfma_f32_16x16x32_bf16(Bt[n][k], At[m][k], acc[ai][bj][m][n], 0, 0, 0); __builtin_amdgcn_s_setprio(0); } while (0)
; #define PG8_WAIT_V(n) asm volatile("s_waitcnt vmcnt(" #n ")" ::: "memory")
; #define PG8_WAIT_L(n) asm volatile("s_waitcnt lgkmcnt(" #n ")" ::: "memory")
; #define PG8_BAR __builtin_amdgcn_s_barrier()
; #define PG8_SCHED __builtin_amdgcn_sched_barrier(0)
; template <class Desc, class Epi>
; DI void gemm_phase(LAS unsigned char* lds, const Desc& D, const Epi& E, int wv) {
;     ...
;             const bool last = (t == nt - 2);
;             const char* a1 = cA + (size_t)(t + 1) * kstep;
;             const char* a2 = last ? nA : cA + (size_t)(t + 2) * kstep; const char* b2 = last ? nB : cB + (size_t)(t + 2) * kstep;
;             const char* a3 = a2 + kstep; const char* b3 = b2 + kstep;
;             PG8_LDB(B0, 0, 0); PG8_LDB(B1, 0, 1); PG8_SCHED; PG8_LDA(At, 0, 0); PG8_STAGE(PG8_SA(1, 1), a1 + hstepA, voffA);
;             PG8_WAIT_V(8); PG8_WAIT_L(0); PG8_BAR; PG8_MMA(0, 0, At, B0); PG8_MMA(0, 1, At, B1); PG8_BAR; PG8_SCHED;
;             PG8_LDA(At, 0, 1); PG8_STAGE(PG8_SB(0, 0), b2, voffB); PG8_STAGE(PG8_SB(0, 1), b2 + hstepB, voffB); PG8_STAGE(PG8_SA(0, 0), a2, voffA);
;             PG8_WAIT_V(8); PG8_WAIT_L(0); PG8_BAR; PG8_MMA(1, 0, At, B0); PG8_MMA(1, 1, At, B1); PG8_BAR; PG8_SCHED;
.LBB0_1313:
	ds_read_b128 v[146:149], v157
	ds_read_b128 v[150:153], v157 offset:1024
	ds_read_b128 v[160:163], v157 offset:2048
	ds_read_b128 v[164:167], v157 offset:3072
	ds_read_b128 v[168:171], v158
	ds_read_b128 v[172:175], v158 offset:1024
	ds_read_b128 v[176:179], v158 offset:2048
	ds_read_b128 v[180:183], v158 offset:3072
	s_add_u32 s40, s22, 0xfff80080
	s_addc_u32 s41, s23, -1
	s_cmp_eq_u32 s50, 28
	s_cselect_b32 s63, s15, s41
	s_cselect_b32 s62, s14, s40
	s_cselect_b32 s41, s17, s21
	s_cselect_b32 s40, s16, s19
	v_lshl_add_u64 v[154:155], s[22:23], 0, v[138:139]
	s_add_i32 m0, s28, 0xc000
	ds_read_b128 v[184:187], v159
	ds_read_b128 v[188:191], v159 offset:1024
	ds_read_b128 v[192:195], v159 offset:2048
	ds_read_b128 v[196:199], v159 offset:3072
	ds_read_b128 v[200:203], v159 offset:4096
	ds_read_b128 v[204:207], v159 offset:5120
	ds_read_b128 v[208:211], v159 offset:6144
	ds_read_b128 v[212:215], v159 offset:7168
	global_load_lds_dwordx4 v[154:155], off
	v_lshl_add_u64 v[154:155], s[22:23], 0, v[140:141]
	s_add_i32 m0, s28, 0xe000
	s_nop 0
	global_load_lds_dwordx4 v[154:155], off
	s_waitcnt vmcnt(8)
	s_waitcnt lgkmcnt(0)
	s_barrier
	v_mfma_f32_16x16x32_bf16 v[124:127], v[146:149], v[184:187], v[124:127]
	v_mfma_f32_16x16x32_bf16 v[120:123], v[160:163], v[184:187], v[120:123]
	v_mfma_f32_16x16x32_bf16 v[108:111], v[146:149], v[192:195], v[108:111]
	v_mfma_f32_16x16x32_bf16 v[104:107], v[160:163], v[192:195], v[104:107]
	v_mfma_f32_16x16x32_bf16 v[92:95], v[146:149], v[200:203], v[92:95]
	v_mfma_f32_16x16x32_bf16 v[88:91], v[160:163], v[200:203], v[88:91]
	v_mfma_f32_16x16x32_bf16 v[76:79], v[146:149], v[208:211], v[76:79]
	v_mfma_f32_16x16x32_bf16 v[72:75], v[160:163], v[208:211], v[72:75]
	v_mfma_f32_16x16x32_bf16 v[124:127], v[150:153], v[188:191], v[124:127]
	v_mfma_f32_16x16x32_bf16 v[120:123], v[164:167], v[188:191], v[120:123]
	v_mfma_f32_16x16x32_bf16 v[108:111], v[150:153], v[196:199], v[108:111]
	v_mfma_f32_16x16x32_bf16 v[104:107], v[164:167], v[196:199], v[104:107]
	v_mfma_f32_16x16x32_bf16 v[92:95], v[150:153], v[204:207], v[92:95]
	v_mfma_f32_16x16x32_bf16 v[88:91], v[164:167], v[204:207], v[88:91]
	v_mfma_f32_16x16x32_bf16 v[76:79], v[150:153], v[212:215], v[76:79]
	v_mfma_f32_16x16x32_bf16 v[72:75], v[164:167], v[212:215], v[72:75]
	v_mfma_f32_16x16x32_bf16 v[116:119], v[168:171], v[184:187], v[116:119]
	v_mfma_f32_16x16x32_bf16 v[112:115], v[176:179], v[184:187], v[112:115]
	v_mfma_f32_16x16x32_bf16 v[100:103], v[168:171], v[192:195], v[100:103]
	v_mfma_f32_16x16x32_bf16 v[96:99], v[176:179], v[192:195], v[96:99]
	v_mfma_f32_16x16x32_bf16 v[84:87], v[168:171], v[200:203], v[84:87]
	v_mfma_f32_16x16x32_bf16 v[80:83], v[176:179], v[200:203], v[80:83]
	v_mfma_f32_16x16x32_bf16 v[68:71], v[168:171], v[208:211], v[68:71]
	v_mfma_f32_16x16x32_bf16 v[64:67], v[176:179], v[208:211], v[64:67]
	v_mfma_f32_16x16x32_bf16 v[116:119], v[172:175], v[188:191], v[116:119]
	v_mfma_f32_16x16x32_bf16 v[112:115], v[180:183], v[188:191], v[112:115]
	v_mfma_f32_16x16x32_bf16 v[100:103], v[172:175], v[196:199], v[100:103]
	v_mfma_f32_16x16x32_bf16 v[96:99], v[180:183], v[196:199], v[96:99]
	v_mfma_f32_16x16x32_bf16 v[84:87], v[172:175], v[204:207], v[84:87]
	v_mfma_f32_16x16x32_bf16 v[80:83], v[180:183], v[204:207], v[80:83]
	v_mfma_f32_16x16x32_bf16 v[68:71], v[172:175], v[212:215], v[68:71]
	v_mfma_f32_16x16x32_bf16 v[64:67], v[180:183], v[212:215], v[64:67]
	s_barrier
	s_add_i32 s51, s48, s2
	v_lshl_add_u64 v[154:155], s[40:41], 0, v[132:133]
	s_mov_b32 m0, s51
	ds_read_b128 v[184:187], v159 offset:16384
	ds_read_b128 v[188:191], v159 offset:17408
	ds_read_b128 v[192:195], v159 offset:18432
	ds_read_b128 v[196:199], v159 offset:19456
	ds_read_b128 v[200:203], v159 offset:20480
	ds_read_b128 v[204:207], v159 offset:21504
	ds_read_b128 v[208:211], v159 offset:22528
	ds_read_b128 v[212:215], v159 offset:23552
	global_load_lds_dwordx4 v[154:155], off
	s_add_i32 m0, s51, 0x2000
	s_add_u32 s52, s40, 0x80000
	v_lshl_add_u64 v[216:217], s[40:41], 0, v[128:129]
	s_addc_u32 s53, s41, 0
	s_add_i32 s51, s49, s2
	global_load_lds_dwordx4 v[216:217], off
	v_lshl_add_u64 v[218:219], s[52:53], 0, v[132:133]
	s_mov_b32 m0, s51
	v_lshl_add_u64 v[220:221], s[62:63], 0, v[130:131]
	global_load_lds_dwordx4 v[218:219], off
	v_lshl_add_u64 v[218:219], s[52:53], 0, v[128:129]
	s_add_i32 m0, s51, 0x2000
	s_nop 0
	global_load_lds_dwordx4 v[218:219], off
	v_lshl_add_u64 v[218:219], s[62:63], 0, v[134:135]
	s_mov_b32 m0, s28
	s_nop 0
	global_load_lds_dwordx4 v[218:219], off
	s_mov_b32 m0, s29
	s_nop 0
	global_load_lds_dwordx4 v[220:221], off
	s_waitcnt vmcnt(8)
	s_waitcnt lgkmcnt(0)
	s_barrier
; #define PG8_STAGE(bufoff, gbase, voff) do { _Pragma("unroll") for (int _i = 0; _i < 2; ++_i) \
;         __builtin_amdgcn_global_load_lds((const unsigned*)((const char*)(gbase) + (voff)[_i]), (LAS unsigned*)(lds + (bufoff) + ldsw + _i * 8192), 16, 0, 0); } while (0)
; #define PG8_LDA(dst, b, h) do { _Pragma("unroll") for (int m = 0; m < 4; ++m) _Pragma("unroll") for (int k = 0; k < 2; ++k) dst[m][k] = *(const LAS bf16x8*)(lds + PG8_SA(b, h) + aoff + m * 2048 + k * 1024); } while (0)
; #define PG8_LDB(dst, b, h) do { _Pragma("unroll") for (int n = 0; n < 2; ++n) _Pragma("unroll") for (int k = 0; k < 2; ++k) dst[n][k] = *(const LAS bf16x8*)(lds + PG8_SB(b, h) + boff + n * 2048 + k * 1024); } while (0)
; #define PG8_MMA(ai, bj, At, Bt) do { __builtin_amdgcn_s_setprio(1); _Pragma("unroll") for (int m = 0; m < 4; ++m) _Pragma("unroll") for (int n = 0; n < 2; ++n) _Pragma("unroll") for (int k = 0; k < 2; ++k) \
;         acc[ai][bj][m][n] = __builtin_amdgcn_mfma_f32_16x16x32_bf16(Bt[n][k], At[m][k], acc[ai][bj][m][n], 0, 0, 0); __builtin_amdgcn_s_setprio(0); } while (0)
; #define PG8_WAIT_V(n) asm volatile("s_waitcnt vmcnt(" #n ")" ::: "memory")
; #define PG8_WAIT_L(n) asm volatile("s_waitcnt lgkmcnt(" #n ")" ::: "memory")
; #define PG8_BAR __builtin_amdgcn_s_barrier()
; #define PG8_SCHED __builtin_amdgcn_sched_barrier(0)
; template <class Desc, class Epi>
; DI void gemm_phase(LAS unsigned char* lds, const Desc& D, const Epi& E, int wv) {
;     ...
;             PG8_WAIT_V(8); PG8_WAIT_L(0); PG8_BAR; PG8_MMA(1, 0, At, B0); PG8_MMA(1, 1, At, B1); PG8_BAR; PG8_SCHED;
;             PG8_LDB(B0, 1, 0); PG8_LDB(B1, 1, 1); PG8_SCHED; PG8_LDA(At, 1, 0); PG8_STAGE(PG8_SA(0, 1), a2 + hstepA, voffA);
;             PG8_WAIT_V(8); PG8_WAIT_L(0); PG8_BAR; PG8_MMA(0, 0, At, B0); PG8_MMA(0, 1, At, B1); PG8_BAR; PG8_SCHED;
	v_mfma_f32_16x16x32_bf16 v[60:63], v[146:149], v[184:187], v[60:63]
	v_mfma_f32_16x16x32_bf16 v[56:59], v[160:163], v[184:187], v[56:59]
	v_mfma_f32_16x16x32_bf16 v[44:47], v[146:149], v[192:195], v[44:47]
	v_mfma_f32_16x16x32_bf16 v[40:43], v[160:163], v[192:195], v[40:43]
	v_mfma_f32_16x16x32_bf16 v[28:31], v[146:149], v[200:203], v[28:31]
	v_mfma_f32_16x16x32_bf16 v[24:27], v[160:163], v[200:203], v[24:27]
	v_mfma_f32_16x16x32_bf16 v[12:15], v[146:149], v[208:211], v[12:15]
	v_mfma_f32_16x16x32_bf16 v[8:11], v[160:163], v[208:211], v[8:11]
	v_mfma_f32_16x16x32_bf16 v[60:63], v[150:153], v[188:191], v[60:63]
	v_mfma_f32_16x16x32_bf16 v[56:59], v[164:167], v[188:191], v[56:59]
	v_mfma_f32_16x16x32_bf16 v[44:47], v[150:153], v[196:199], v[44:47]
	v_mfma_f32_16x16x32_bf16 v[40:43], v[164:167], v[196:199], v[40:43]
	v_mfma_f32_16x16x32_bf16 v[28:31], v[150:153], v[204:207], v[28:31]
	v_mfma_f32_16x16x32_bf16 v[24:27], v[164:167], v[204:207], v[24:27]
	v_mfma_f32_16x16x32_bf16 v[12:15], v[150:153], v[212:215], v[12:15]
	v_mfma_f32_16x16x32_bf16 v[8:11], v[164:167], v[212:215], v[8:11]
	v_mfma_f32_16x16x32_bf16 v[52:55], v[168:171], v[184:187], v[52:55]
	v_mfma_f32_16x16x32_bf16 v[48:51], v[176:179], v[184:187], v[48:51]
	v_mfma_f32_16x16x32_bf16 v[36:39], v[168:171], v[192:195], v[36:39]
	v_mfma_f32_16x16x32_bf16 v[32:35], v[176:179], v[192:195], v[32:35]
	v_mfma_f32_16x16x32_bf16 v[20:23], v[168:171], v[200:203], v[20:23]
	v_mfma_f32_16x16x32_bf16 v[16:19], v[176:179], v[200:203], v[16:19]
	v_mfma_f32_16x16x32_bf16 v[4:7], v[168:171], v[208:211], v[4:7]
	v_mfma_f32_16x16x32_bf16 v[0:3], v[176:179], v[208:211], v[0:3]
	v_mfma_f32_16x16x32_bf16 v[52:55], v[172:175], v[188:191], v[52:55]
	v_mfma_f32_16x16x32_bf16 v[48:51], v[180:183], v[188:191], v[48:51]
	v_mfma_f32_16x16x32_bf16 v[36:39], v[172:175], v[196:199], v[36:39]
	v_mfma_f32_16x16x32_bf16 v[32:35], v[180:183], v[196:199], v[32:35]
	v_mfma_f32_16x16x32_bf16 v[20:23], v[172:175], v[204:207], v[20:23]
	v_mfma_f32_16x16x32_bf16 v[16:19], v[180:183], v[204:207], v[16:19]
	v_mfma_f32_16x16x32_bf16 v[4:7], v[172:175], v[212:215], v[4:7]
	v_mfma_f32_16x16x32_bf16 v[0:3], v[180:183], v[212:215], v[0:3]
	s_barrier
	s_add_i32 s51, 0, 0x18000
	v_add_u32_e32 v136, s51, v156
	s_add_i32 s60, 0, 0x1c000
	ds_read_b128 v[146:149], v136
	ds_read_b128 v[150:153], v136 offset:1024
	ds_read_b128 v[160:163], v136 offset:2048
	ds_read_b128 v[164:167], v136 offset:3072
	v_add_u32_e32 v136, s60, v156
	ds_read_b128 v[168:171], v136
	ds_read_b128 v[172:175], v136 offset:1024
	ds_read_b128 v[176:179], v136 offset:2048
	ds_read_b128 v[180:183], v136 offset:3072
	s_add_u32 s52, s62, 0x80000
	s_addc_u32 s53, s63, 0
	s_mov_b32 m0, s30
	v_lshl_add_u64 v[222:223], s[52:53], 0, v[134:135]
	ds_read_b128 v[184:187], v159 offset:32768
	ds_read_b128 v[188:191], v159 offset:33792
	ds_read_b128 v[192:195], v159 offset:34816
	ds_read_b128 v[196:199], v159 offset:35840
	ds_read_b128 v[200:203], v159 offset:36864
	ds_read_b128 v[204:207], v159 offset:37888
	ds_read_b128 v[208:211], v159 offset:38912
	ds_read_b128 v[212:215], v159 offset:39936
	global_load_lds_dwordx4 v[222:223], off
	v_lshl_add_u64 v[222:223], s[52:53], 0, v[130:131]
	s_mov_b32 m0, s31
	s_nop 0
	global_load_lds_dwordx4 v[222:223], off
	s_waitcnt vmcnt(8)
	s_waitcnt lgkmcnt(0)
	s_barrier
	v_mfma_f32_16x16x32_bf16 v[124:127], v[146:149], v[184:187], v[124:127]
	v_mfma_f32_16x16x32_bf16 v[120:123], v[160:163], v[184:187], v[120:123]
	v_mfma_f32_16x16x32_bf16 v[108:111], v[146:149], v[192:195], v[108:111]
	v_mfma_f32_16x16x32_bf16 v[104:107], v[160:163], v[192:195], v[104:107]
	v_mfma_f32_16x16x32_bf16 v[92:95], v[146:149], v[200:203], v[92:95]
	v_mfma_f32_16x16x32_bf16 v[88:91], v[160:163], v[200:203], v[88:91]
	v_mfma_f32_16x16x32_bf16 v[76:79], v[146:149], v[208:211], v[76:79]
	v_mfma_f32_16x16x32_bf16 v[72:75], v[160:163], v[208:211], v[72:75]
	v_mfma_f32_16x16x32_bf16 v[124:127], v[150:153], v[188:191], v[124:127]
	v_mfma_f32_16x16x32_bf16 v[120:123], v[164:167], v[188:191], v[120:123]
	v_mfma_f32_16x16x32_bf16 v[108:111], v[150:153], v[196:199], v[108:111]
	v_mfma_f32_16x16x32_bf16 v[104:107], v[164:167], v[196:199], v[104:107]
	v_mfma_f32_16x16x32_bf16 v[92:95], v[150:153], v[204:207], v[92:95]
	v_mfma_f32_16x16x32_bf16 v[88:91], v[164:167], v[204:207], v[88:91]
	v_mfma_f32_16x16x32_bf16 v[76:79], v[150:153], v[212:215], v[76:79]
	v_mfma_f32_16x16x32_bf16 v[72:75], v[164:167], v[212:215], v[72:75]
	v_mfma_f32_16x16x32_bf16 v[116:119], v[168:171], v[184:187], v[116:119]
	v_mfma_f32_16x16x32_bf16 v[112:115], v[176:179], v[184:187], v[112:115]
	v_mfma_f32_16x16x32_bf16 v[100:103], v[168:171], v[192:195], v[100:103]
	v_mfma_f32_16x16x32_bf16 v[96:99], v[176:179], v[192:195], v[96:99]
	v_mfma_f32_16x16x32_bf16 v[84:87], v[168:171], v[200:203], v[84:87]
	v_mfma_f32_16x16x32_bf16 v[80:83], v[176:179], v[200:203], v[80:83]
	v_mfma_f32_16x16x32_bf16 v[68:71], v[168:171], v[208:211], v[68:71]
	v_mfma_f32_16x16x32_bf16 v[64:67], v[176:179], v[208:211], v[64:67]
	v_mfma_f32_16x16x32_bf16 v[116:119], v[172:175], v[188:191], v[116:119]
	v_mfma_f32_16x16x32_bf16 v[112:115], v[180:183], v[188:191], v[112:115]
	v_mfma_f32_16x16x32_bf16 v[100:103], v[172:175], v[196:199], v[100:103]
	v_mfma_f32_16x16x32_bf16 v[96:99], v[180:183], v[196:199], v[96:99]
	v_mfma_f32_16x16x32_bf16 v[84:87], v[172:175], v[204:207], v[84:87]
	v_mfma_f32_16x16x32_bf16 v[80:83], v[180:183], v[204:207], v[80:83]
	v_mfma_f32_16x16x32_bf16 v[68:71], v[172:175], v[212:215], v[68:71]
	v_mfma_f32_16x16x32_bf16 v[64:67], v[180:183], v[212:215], v[64:67]
	s_barrier
; #define PG8_STAGE(bufoff, gbase, voff) do { _Pragma("unroll") for (int _i = 0; _i < 2; ++_i) \
;         __builtin_amdgcn_global_load_lds((const unsigned*)((const char*)(gbase) + (voff)[_i]), (LAS unsigned*)(lds + (bufoff) + ldsw + _i * 8192), 16, 0, 0); } while (0)
; #define PG8_LDA(dst, b, h) do { _Pragma("unroll") for (int m = 0; m < 4; ++m) _Pragma("unroll") for (int k = 0; k < 2; ++k) dst[m][k] = *(const LAS bf16x8*)(lds + PG8_SA(b, h) + aoff + m * 2048 + k * 1024); } while (0)
; #define PG8_MMA(ai, bj, At, Bt) do { __builtin_amdgcn_s_setprio(1); _Pragma("unroll") for (int m = 0; m < 4; ++m) _Pragma("unroll") for (int n = 0; n < 2; ++n) _Pragma("unroll") for (int k = 0; k < 2; ++k) \
;         acc[ai][bj][m][n] = __builtin_amdgcn_mfma_f32_16x16x32_bf16(Bt[n][k], At[m][k], acc[ai][bj][m][n], 0, 0, 0); __builtin_amdgcn_s_setprio(0); } while (0)
; #define PG8_WAIT_V(n) asm volatile("s_waitcnt vmcnt(" #n ")" ::: "memory")
; #define PG8_WAIT_L(n) asm volatile("s_waitcnt lgkmcnt(" #n ")" ::: "memory")
; #define PG8_BAR __builtin_amdgcn_s_barrier()
; #define PG8_SCHED __builtin_amdgcn_sched_barrier(0)
; template <class Desc, class Epi>
; DI void gemm_phase(LAS unsigned char* lds, const Desc& D, const Epi& E, int wv) {
;     ...
;         for (int t = 0; t < nt; t += 2) {
;     ...
;             PG8_LDA(At, 1, 1); PG8_STAGE(PG8_SB(1, 0), b3, voffB); PG8_STAGE(PG8_SB(1, 1), b3 + hstepB, voffB); PG8_STAGE(PG8_SA(1, 0), a3, voffA);
;             PG8_WAIT_V(8); PG8_WAIT_L(0); PG8_BAR; PG8_MMA(1, 0, At, B0); PG8_MMA(1, 1, At, B1); PG8_BAR; PG8_SCHED;
;         }
	s_add_i32 s51, s51, s2
	v_lshl_add_u64 v[154:155], v[154:155], 0, s[10:11]
	s_mov_b32 m0, s51
	ds_read_b128 v[184:187], v159 offset:49152
	ds_read_b128 v[188:191], v159 offset:50176
	ds_read_b128 v[192:195], v159 offset:51200
	ds_read_b128 v[196:199], v159 offset:52224
	ds_read_b128 v[200:203], v159 offset:53248
	ds_read_b128 v[204:207], v159 offset:54272
	ds_read_b128 v[208:211], v159 offset:55296
	ds_read_b128 v[212:215], v159 offset:56320
	global_load_lds_dwordx4 v[154:155], off
	s_add_i32 m0, s51, 0x2000
	s_add_u32 s40, s40, 0x80080
	v_lshl_add_u64 v[154:155], v[216:217], 0, s[10:11]
	s_addc_u32 s41, s41, 0
	s_add_i32 s51, s60, s2
	global_load_lds_dwordx4 v[154:155], off
	v_lshl_add_u64 v[154:155], s[40:41], 0, v[132:133]
	s_mov_b32 m0, s51
	s_nop 0
	global_load_lds_dwordx4 v[154:155], off
	v_lshl_add_u64 v[154:155], s[40:41], 0, v[128:129]
	s_add_i32 m0, s51, 0x2000
	s_nop 0
	global_load_lds_dwordx4 v[154:155], off
	v_lshl_add_u64 v[154:155], v[218:219], 0, s[10:11]
	s_mov_b32 m0, s43
	s_nop 0
	global_load_lds_dwordx4 v[154:155], off
	v_lshl_add_u64 v[154:155], v[220:221], 0, s[10:11]
	s_mov_b32 m0, s46
	s_nop 0
	global_load_lds_dwordx4 v[154:155], off
	s_waitcnt vmcnt(8)
	s_waitcnt lgkmcnt(0)
	s_barrier
	v_mfma_f32_16x16x32_bf16 v[60:63], v[146:149], v[184:187], v[60:63]
	v_mfma_f32_16x16x32_bf16 v[56:59], v[160:163], v[184:187], v[56:59]
	v_mfma_f32_16x16x32_bf16 v[44:47], v[146:149], v[192:195], v[44:47]
	v_mfma_f32_16x16x32_bf16 v[40:43], v[160:163], v[192:195], v[40:43]
	v_mfma_f32_16x16x32_bf16 v[28:31], v[146:149], v[200:203], v[28:31]
	v_mfma_f32_16x16x32_bf16 v[24:27], v[160:163], v[200:203], v[24:27]
	v_mfma_f32_16x16x32_bf16 v[12:15], v[146:149], v[208:211], v[12:15]
	v_mfma_f32_16x16x32_bf16 v[8:11], v[160:163], v[208:211], v[8:11]
	v_mfma_f32_16x16x32_bf16 v[60:63], v[150:153], v[188:191], v[60:63]
	v_mfma_f32_16x16x32_bf16 v[56:59], v[164:167], v[188:191], v[56:59]
	v_mfma_f32_16x16x32_bf16 v[44:47], v[150:153], v[196:199], v[44:47]
	v_mfma_f32_16x16x32_bf16 v[40:43], v[164:167], v[196:199], v[40:43]
	v_mfma_f32_16x16x32_bf16 v[28:31], v[150:153], v[204:207], v[28:31]
	v_mfma_f32_16x16x32_bf16 v[24:27], v[164:167], v[204:207], v[24:27]
	v_mfma_f32_16x16x32_bf16 v[12:15], v[150:153], v[212:215], v[12:15]
	v_mfma_f32_16x16x32_bf16 v[8:11], v[164:167], v[212:215], v[8:11]
	v_mfma_f32_16x16x32_bf16 v[52:55], v[168:171], v[184:187], v[52:55]
	v_mfma_f32_16x16x32_bf16 v[48:51], v[176:179], v[184:187], v[48:51]
	v_mfma_f32_16x16x32_bf16 v[36:39], v[168:171], v[192:195], v[36:39]
	v_mfma_f32_16x16x32_bf16 v[32:35], v[176:179], v[192:195], v[32:35]
	v_mfma_f32_16x16x32_bf16 v[20:23], v[168:171], v[200:203], v[20:23]
	v_mfma_f32_16x16x32_bf16 v[16:19], v[176:179], v[200:203], v[16:19]
	v_mfma_f32_16x16x32_bf16 v[4:7], v[168:171], v[208:211], v[4:7]
	v_mfma_f32_16x16x32_bf16 v[0:3], v[176:179], v[208:211], v[0:3]
	v_mfma_f32_16x16x32_bf16 v[52:55], v[172:175], v[188:191], v[52:55]
	v_mfma_f32_16x16x32_bf16 v[48:51], v[180:183], v[188:191], v[48:51]
	v_mfma_f32_16x16x32_bf16 v[36:39], v[172:175], v[196:199], v[36:39]
	v_mfma_f32_16x16x32_bf16 v[32:35], v[180:183], v[196:199], v[32:35]
	v_mfma_f32_16x16x32_bf16 v[20:23], v[172:175], v[204:207], v[20:23]
	v_mfma_f32_16x16x32_bf16 v[16:19], v[180:183], v[204:207], v[16:19]
	v_mfma_f32_16x16x32_bf16 v[4:7], v[172:175], v[212:215], v[4:7]
	v_mfma_f32_16x16x32_bf16 v[0:3], v[180:183], v[212:215], v[0:3]
	s_barrier
	s_add_i32 s50, s50, 2
	s_add_u32 s22, s22, 0x100
	s_addc_u32 s23, s23, 0
	s_add_u32 s19, s19, 0x100
	s_addc_u32 s21, s21, 0
	s_cmp_gt_u32 s50, 29
	s_cbranch_scc0 .LBB0_1313
	s_and_b64 vcc, exec, s[12:13]
	s_cbranch_vccz .LBB0_1316
	s_barrier

; #define PG8_STAGE(bufoff, gbase, voff) do { _Pragma("unroll") for (int _i = 0; _i < 2; ++_i) \
;         __builtin_amdgcn_global_load_lds((const unsigned*)((const char*)(gbase) + (voff)[_i]), (LAS unsigned*)(lds + (bufoff) + ldsw + _i * 8192), 16, 0, 0); } while (0)
; #define PG8_LDA(dst, b, h) do { _Pragma("unroll") for (int m = 0; m < 4; ++m) _Pragma("unroll") for (int k = 0; k < 2; ++k) dst[m][k] = *(const LAS bf16x8*)(lds + PG8_SA(b, h) + aoff + m * 2048 + k * 1024); } while (0)
; #define PG8_LDB(dst, b, h) do { _Pragma("unroll") for (int n = 0; n < 2; ++n) _Pragma("unroll") for (int k = 0; k < 2; ++k) dst[n][k] = *(const LAS bf16x8*)(lds + PG8_SB(b, h) + boff + n * 2048 + k * 1024); } while (0)
; #define PG8_MMA(ai, bj, At, Bt) do { __builtin_amdgcn_s_setprio(1); _Pragma("unroll") for (int m = 0; m < 4; ++m) _Pragma("unroll") for (int n = 0; n < 2; ++n) _Pragma("unroll") for (int k = 0; k < 2; ++k) \
;         acc[ai][bj][m][n] = __builtin_amdgcn_mfma_f32_16x16x32_bf16(Bt[n][k], At[m][k], acc[ai][bj][m][n], 0, 0, 0); __builtin_amdgcn_s_setprio(0); } while (0)
; #define PG8_WAIT_V(n) asm volatile("s_waitcnt vmcnt(" #n ")" ::: "memory")
; #define PG8_WAIT_L(n) asm volatile("s_waitcnt lgkmcnt(" #n ")" ::: "memory")
; #define PG8_BAR __builtin_amdgcn_s_barrier()
; #define PG8_SCHED __builtin_amdgcn_sched_barrier(0)
; template <class Desc, class Epi>
; DI void gemm_phase(LAS unsigned char* lds, const Desc& D, const Epi& E, int wv) {
;     ...
;             const bool last = (t == nt - 2);
;             const char* a1 = cA + (size_t)(t + 1) * kstep;
;             const char* a2 = last ? nA : cA + (size_t)(t + 2) * kstep; const char* b2 = last ? nB : cB + (size_t)(t + 2) * kstep;
;             const char* a3 = a2 + kstep; const char* b3 = b2 + kstep;
;             PG8_LDB(B0, 0, 0); PG8_LDB(B1, 0, 1); PG8_SCHED; PG8_LDA(At, 0, 0); PG8_STAGE(PG8_SA(1, 1), a1 + hstepA, voffA);
;             PG8_WAIT_V(8); PG8_WAIT_L(0); PG8_BAR; PG8_MMA(0, 0, At, B0); PG8_MMA(0, 1, At, B1); PG8_BAR; PG8_SCHED;
;             PG8_LDA(At, 0, 1); PG8_STAGE(PG8_SB(0, 0), b2, voffB); PG8_STAGE(PG8_SB(0, 1), b2 + hstepB, voffB); PG8_STAGE(PG8_SA(0, 0), a2, voffA);
;             PG8_WAIT_V(8); PG8_WAIT_L(0); PG8_BAR; PG8_MMA(1, 0, At, B0); PG8_MMA(1, 1, At, B1); PG8_BAR; PG8_SCHED;
.LBB0_1501:
	ds_read_b128 v[128:131], v230
	ds_read_b128 v[132:135], v230 offset:1024
	ds_read_b128 v[136:139], v230 offset:2048
	ds_read_b128 v[140:143], v230 offset:3072
	ds_read_b128 v[144:147], v231
	ds_read_b128 v[148:151], v231 offset:1024
	ds_read_b128 v[152:155], v231 offset:2048
	ds_read_b128 v[156:159], v231 offset:3072
	s_add_u32 s22, s20, 0xfff80080
	s_addc_u32 s23, s21, -1
	s_cmp_eq_u32 s64, 28
	s_cselect_b32 s41, s11, s23
	s_cselect_b32 s40, s10, s22
	s_cselect_b32 s23, s13, s17
	s_cselect_b32 s22, s12, s15
	v_lshl_add_u64 v[192:193], s[20:21], 0, v[216:217]
	s_add_i32 m0, s30, 0xc000
	ds_read_b128 v[160:163], v232
	ds_read_b128 v[164:167], v232 offset:1024
	ds_read_b128 v[168:171], v232 offset:2048
	ds_read_b128 v[172:175], v232 offset:3072
	ds_read_b128 v[176:179], v232 offset:4096
	ds_read_b128 v[180:183], v232 offset:5120
	ds_read_b128 v[184:187], v232 offset:6144
	ds_read_b128 v[188:191], v232 offset:7168
	global_load_lds_dwordx4 v[192:193], off
	v_lshl_add_u64 v[192:193], s[20:21], 0, v[218:219]
	s_add_i32 m0, s30, 0xe000
	s_nop 0
	global_load_lds_dwordx4 v[192:193], off
	s_waitcnt vmcnt(8)
	s_waitcnt lgkmcnt(0)
	s_barrier
	v_mfma_f32_16x16x32_bf16 v[124:127], v[128:131], v[160:163], v[124:127]
	v_mfma_f32_16x16x32_bf16 v[120:123], v[136:139], v[160:163], v[120:123]
	v_mfma_f32_16x16x32_bf16 v[112:115], v[128:131], v[168:171], v[112:115]
	v_mfma_f32_16x16x32_bf16 v[104:107], v[136:139], v[168:171], v[104:107]
	v_mfma_f32_16x16x32_bf16 v[96:99], v[128:131], v[176:179], v[96:99]
	v_mfma_f32_16x16x32_bf16 v[88:91], v[136:139], v[176:179], v[88:91]
	v_mfma_f32_16x16x32_bf16 v[80:83], v[128:131], v[184:187], v[80:83]
	v_mfma_f32_16x16x32_bf16 v[72:75], v[136:139], v[184:187], v[72:75]
	v_mfma_f32_16x16x32_bf16 v[124:127], v[132:135], v[164:167], v[124:127]
	v_mfma_f32_16x16x32_bf16 v[120:123], v[140:143], v[164:167], v[120:123]
	v_mfma_f32_16x16x32_bf16 v[112:115], v[132:135], v[172:175], v[112:115]
	v_mfma_f32_16x16x32_bf16 v[104:107], v[140:143], v[172:175], v[104:107]
	v_mfma_f32_16x16x32_bf16 v[96:99], v[132:135], v[180:183], v[96:99]
	v_mfma_f32_16x16x32_bf16 v[88:91], v[140:143], v[180:183], v[88:91]
	v_mfma_f32_16x16x32_bf16 v[80:83], v[132:135], v[188:191], v[80:83]
	v_mfma_f32_16x16x32_bf16 v[72:75], v[140:143], v[188:191], v[72:75]
	v_mfma_f32_16x16x32_bf16 v[116:119], v[144:147], v[160:163], v[116:119]
	v_mfma_f32_16x16x32_bf16 v[108:111], v[152:155], v[160:163], v[108:111]
	v_mfma_f32_16x16x32_bf16 v[100:103], v[144:147], v[168:171], v[100:103]
	v_mfma_f32_16x16x32_bf16 v[92:95], v[152:155], v[168:171], v[92:95]
	v_mfma_f32_16x16x32_bf16 v[84:87], v[144:147], v[176:179], v[84:87]
	v_mfma_f32_16x16x32_bf16 v[76:79], v[152:155], v[176:179], v[76:79]
	v_mfma_f32_16x16x32_bf16 v[68:71], v[144:147], v[184:187], v[68:71]
	v_mfma_f32_16x16x32_bf16 v[64:67], v[152:155], v[184:187], v[64:67]
	v_mfma_f32_16x16x32_bf16 v[116:119], v[148:151], v[164:167], v[116:119]
	v_mfma_f32_16x16x32_bf16 v[108:111], v[156:159], v[164:167], v[108:111]
	v_mfma_f32_16x16x32_bf16 v[100:103], v[148:151], v[172:175], v[100:103]
	v_mfma_f32_16x16x32_bf16 v[92:95], v[156:159], v[172:175], v[92:95]
	v_mfma_f32_16x16x32_bf16 v[84:87], v[148:151], v[180:183], v[84:87]
	v_mfma_f32_16x16x32_bf16 v[76:79], v[156:159], v[180:183], v[76:79]
	v_mfma_f32_16x16x32_bf16 v[68:71], v[148:151], v[188:191], v[68:71]
	v_mfma_f32_16x16x32_bf16 v[64:67], v[156:159], v[188:191], v[64:67]
	s_barrier
	s_add_i32 s65, s51, s28
	v_lshl_add_u64 v[192:193], s[22:23], 0, v[212:213]
	s_mov_b32 m0, s65
	ds_read_b128 v[160:163], v232 offset:16384
	ds_read_b128 v[164:167], v232 offset:17408
	ds_read_b128 v[168:171], v232 offset:18432
	ds_read_b128 v[172:175], v232 offset:19456
	ds_read_b128 v[176:179], v232 offset:20480
	ds_read_b128 v[180:183], v232 offset:21504
	ds_read_b128 v[184:187], v232 offset:22528
	ds_read_b128 v[188:191], v232 offset:23552
	global_load_lds_dwordx4 v[192:193], off
	s_add_i32 m0, s65, 0x2000
	s_add_u32 s66, s22, 0x80000
	v_lshl_add_u64 v[194:195], s[22:23], 0, v[208:209]
	s_addc_u32 s67, s23, 0
	s_add_i32 s65, s52, s28
	global_load_lds_dwordx4 v[194:195], off
	v_lshl_add_u64 v[196:197], s[66:67], 0, v[212:213]
	s_mov_b32 m0, s65
	v_lshl_add_u64 v[198:199], s[40:41], 0, v[210:211]
	global_load_lds_dwordx4 v[196:197], off
	v_lshl_add_u64 v[196:197], s[66:67], 0, v[208:209]
	s_add_i32 m0, s65, 0x2000
	s_nop 0
	global_load_lds_dwordx4 v[196:197], off
	v_lshl_add_u64 v[196:197], s[40:41], 0, v[214:215]
	s_mov_b32 m0, s30
	s_nop 0
	global_load_lds_dwordx4 v[196:197], off
	s_mov_b32 m0, s31
	s_nop 0
	global_load_lds_dwordx4 v[198:199], off
	s_waitcnt vmcnt(8)
	s_waitcnt lgkmcnt(0)
	s_barrier
; #define PG8_STAGE(bufoff, gbase, voff) do { _Pragma("unroll") for (int _i = 0; _i < 2; ++_i) \
;         __builtin_amdgcn_global_load_lds((const unsigned*)((const char*)(gbase) + (voff)[_i]), (LAS unsigned*)(lds + (bufoff) + ldsw + _i * 8192), 16, 0, 0); } while (0)
; #define PG8_LDA(dst, b, h) do { _Pragma("unroll") for (int m = 0; m < 4; ++m) _Pragma("unroll") for (int k = 0; k < 2; ++k) dst[m][k] = *(const LAS bf16x8*)(lds + PG8_SA(b, h) + aoff + m * 2048 + k * 1024); } while (0)
; #define PG8_LDB(dst, b, h) do { _Pragma("unroll") for (int n = 0; n < 2; ++n) _Pragma("unroll") for (int k = 0; k < 2; ++k) dst[n][k] = *(const LAS bf16x8*)(lds + PG8_SB(b, h) + boff + n * 2048 + k * 1024); } while (0)
; #define PG8_MMA(ai, bj, At, Bt) do { __builtin_amdgcn_s_setprio(1); _Pragma("unroll") for (int m = 0; m < 4; ++m) _Pragma("unroll") for (int n = 0; n < 2; ++n) _Pragma("unroll") for (int k = 0; k < 2; ++k) \
;         acc[ai][bj][m][n] = __builtin_amdgcn_mfma_f32_16x16x32_bf16(Bt[n][k], At[m][k], acc[ai][bj][m][n], 0, 0, 0); __builtin_amdgcn_s_setprio(0); } while (0)
; #define PG8_WAIT_V(n) asm volatile("s_waitcnt vmcnt(" #n ")" ::: "memory")
; #define PG8_WAIT_L(n) asm volatile("s_waitcnt lgkmcnt(" #n ")" ::: "memory")
; #define PG8_BAR __builtin_amdgcn_s_barrier()
; #define PG8_SCHED __builtin_amdgcn_sched_barrier(0)
; template <class Desc, class Epi>
; DI void gemm_phase(LAS unsigned char* lds, const Desc& D, const Epi& E, int wv) {
;     ...
;             PG8_WAIT_V(8); PG8_WAIT_L(0); PG8_BAR; PG8_MMA(1, 0, At, B0); PG8_MMA(1, 1, At, B1); PG8_BAR; PG8_SCHED;
;             PG8_LDB(B0, 1, 0); PG8_LDB(B1, 1, 1); PG8_SCHED; PG8_LDA(At, 1, 0); PG8_STAGE(PG8_SA(0, 1), a2 + hstepA, voffA);
;             PG8_WAIT_V(8); PG8_WAIT_L(0); PG8_BAR; PG8_MMA(0, 0, At, B0); PG8_MMA(0, 1, At, B1); PG8_BAR; PG8_SCHED;
	v_mfma_f32_16x16x32_bf16 v[60:63], v[128:131], v[160:163], v[60:63]
	v_mfma_f32_16x16x32_bf16 v[56:59], v[136:139], v[160:163], v[56:59]
	v_mfma_f32_16x16x32_bf16 v[48:51], v[128:131], v[168:171], v[48:51]
	v_mfma_f32_16x16x32_bf16 v[40:43], v[136:139], v[168:171], v[40:43]
	v_mfma_f32_16x16x32_bf16 v[32:35], v[128:131], v[176:179], v[32:35]
	v_mfma_f32_16x16x32_bf16 v[24:27], v[136:139], v[176:179], v[24:27]
	v_mfma_f32_16x16x32_bf16 v[16:19], v[128:131], v[184:187], v[16:19]
	v_mfma_f32_16x16x32_bf16 v[8:11], v[136:139], v[184:187], v[8:11]
	v_mfma_f32_16x16x32_bf16 v[60:63], v[132:135], v[164:167], v[60:63]
	v_mfma_f32_16x16x32_bf16 v[56:59], v[140:143], v[164:167], v[56:59]
	v_mfma_f32_16x16x32_bf16 v[48:51], v[132:135], v[172:175], v[48:51]
	v_mfma_f32_16x16x32_bf16 v[40:43], v[140:143], v[172:175], v[40:43]
	v_mfma_f32_16x16x32_bf16 v[32:35], v[132:135], v[180:183], v[32:35]
	v_mfma_f32_16x16x32_bf16 v[24:27], v[140:143], v[180:183], v[24:27]
	v_mfma_f32_16x16x32_bf16 v[16:19], v[132:135], v[188:191], v[16:19]
	v_mfma_f32_16x16x32_bf16 v[8:11], v[140:143], v[188:191], v[8:11]
	v_mfma_f32_16x16x32_bf16 v[52:55], v[144:147], v[160:163], v[52:55]
	v_mfma_f32_16x16x32_bf16 v[44:47], v[152:155], v[160:163], v[44:47]
	v_mfma_f32_16x16x32_bf16 v[36:39], v[144:147], v[168:171], v[36:39]
	v_mfma_f32_16x16x32_bf16 v[28:31], v[152:155], v[168:171], v[28:31]
	v_mfma_f32_16x16x32_bf16 v[20:23], v[144:147], v[176:179], v[20:23]
	v_mfma_f32_16x16x32_bf16 v[12:15], v[152:155], v[176:179], v[12:15]
	v_mfma_f32_16x16x32_bf16 v[4:7], v[144:147], v[184:187], v[4:7]
	v_mfma_f32_16x16x32_bf16 v[0:3], v[152:155], v[184:187], v[0:3]
	v_mfma_f32_16x16x32_bf16 v[52:55], v[148:151], v[164:167], v[52:55]
	v_mfma_f32_16x16x32_bf16 v[44:47], v[156:159], v[164:167], v[44:47]
	v_mfma_f32_16x16x32_bf16 v[36:39], v[148:151], v[172:175], v[36:39]
	v_mfma_f32_16x16x32_bf16 v[28:31], v[156:159], v[172:175], v[28:31]
	v_mfma_f32_16x16x32_bf16 v[20:23], v[148:151], v[180:183], v[20:23]
	v_mfma_f32_16x16x32_bf16 v[12:15], v[156:159], v[180:183], v[12:15]
	v_mfma_f32_16x16x32_bf16 v[4:7], v[148:151], v[188:191], v[4:7]
	v_mfma_f32_16x16x32_bf16 v[0:3], v[156:159], v[188:191], v[0:3]
	s_barrier
	s_add_i32 s65, 0, 0x18000
	s_add_i32 s66, 0, 0x1c000
	v_add_u32_e32 v140, s65, v229
	v_add_u32_e32 v156, s66, v229
	ds_read_b128 v[128:131], v140
	ds_read_b128 v[132:135], v140 offset:1024
	ds_read_b128 v[136:139], v140 offset:2048
	ds_read_b128 v[140:143], v140 offset:3072
	ds_read_b128 v[144:147], v156
	ds_read_b128 v[148:151], v156 offset:1024
	ds_read_b128 v[152:155], v156 offset:2048
	ds_read_b128 v[156:159], v156 offset:3072
	s_add_u32 s40, s40, 0x80000
	s_addc_u32 s41, s41, 0
	s_mov_b32 m0, s34
	v_lshl_add_u64 v[200:201], s[40:41], 0, v[214:215]
	ds_read_b128 v[160:163], v232 offset:32768
	ds_read_b128 v[164:167], v232 offset:33792
	ds_read_b128 v[168:171], v232 offset:34816
	ds_read_b128 v[172:175], v232 offset:35840
	ds_read_b128 v[176:179], v232 offset:36864
	ds_read_b128 v[180:183], v232 offset:37888
	ds_read_b128 v[184:187], v232 offset:38912
	ds_read_b128 v[188:191], v232 offset:39936
	global_load_lds_dwordx4 v[200:201], off
	v_lshl_add_u64 v[200:201], s[40:41], 0, v[210:211]
	s_mov_b32 m0, s35
	s_nop 0
	global_load_lds_dwordx4 v[200:201], off
	s_waitcnt vmcnt(8)
	s_waitcnt lgkmcnt(0)
	s_barrier
	v_mfma_f32_16x16x32_bf16 v[124:127], v[128:131], v[160:163], v[124:127]
	v_mfma_f32_16x16x32_bf16 v[120:123], v[136:139], v[160:163], v[120:123]
	v_mfma_f32_16x16x32_bf16 v[112:115], v[128:131], v[168:171], v[112:115]
	v_mfma_f32_16x16x32_bf16 v[104:107], v[136:139], v[168:171], v[104:107]
	v_mfma_f32_16x16x32_bf16 v[96:99], v[128:131], v[176:179], v[96:99]
	v_mfma_f32_16x16x32_bf16 v[88:91], v[136:139], v[176:179], v[88:91]
	v_mfma_f32_16x16x32_bf16 v[80:83], v[128:131], v[184:187], v[80:83]
	v_mfma_f32_16x16x32_bf16 v[72:75], v[136:139], v[184:187], v[72:75]
	v_mfma_f32_16x16x32_bf16 v[124:127], v[132:135], v[164:167], v[124:127]
	v_mfma_f32_16x16x32_bf16 v[120:123], v[140:143], v[164:167], v[120:123]
	v_mfma_f32_16x16x32_bf16 v[112:115], v[132:135], v[172:175], v[112:115]
	v_mfma_f32_16x16x32_bf16 v[104:107], v[140:143], v[172:175], v[104:107]
	v_mfma_f32_16x16x32_bf16 v[96:99], v[132:135], v[180:183], v[96:99]
	v_mfma_f32_16x16x32_bf16 v[88:91], v[140:143], v[180:183], v[88:91]
	v_mfma_f32_16x16x32_bf16 v[80:83], v[132:135], v[188:191], v[80:83]
	v_mfma_f32_16x16x32_bf16 v[72:75], v[140:143], v[188:191], v[72:75]
	v_mfma_f32_16x16x32_bf16 v[116:119], v[144:147], v[160:163], v[116:119]
	v_mfma_f32_16x16x32_bf16 v[108:111], v[152:155], v[160:163], v[108:111]
	v_mfma_f32_16x16x32_bf16 v[100:103], v[144:147], v[168:171], v[100:103]
	v_mfma_f32_16x16x32_bf16 v[92:95], v[152:155], v[168:171], v[92:95]
	v_mfma_f32_16x16x32_bf16 v[84:87], v[144:147], v[176:179], v[84:87]
	v_mfma_f32_16x16x32_bf16 v[76:79], v[152:155], v[176:179], v[76:79]
	v_mfma_f32_16x16x32_bf16 v[68:71], v[144:147], v[184:187], v[68:71]
	v_mfma_f32_16x16x32_bf16 v[64:67], v[152:155], v[184:187], v[64:67]
	v_mfma_f32_16x16x32_bf16 v[116:119], v[148:151], v[164:167], v[116:119]
	v_mfma_f32_16x16x32_bf16 v[108:111], v[156:159], v[164:167], v[108:111]
	v_mfma_f32_16x16x32_bf16 v[100:103], v[148:151], v[172:175], v[100:103]
	v_mfma_f32_16x16x32_bf16 v[92:95], v[156:159], v[172:175], v[92:95]
	v_mfma_f32_16x16x32_bf16 v[84:87], v[148:151], v[180:183], v[84:87]
	v_mfma_f32_16x16x32_bf16 v[76:79], v[156:159], v[180:183], v[76:79]
	v_mfma_f32_16x16x32_bf16 v[68:71], v[148:151], v[188:191], v[68:71]
	v_mfma_f32_16x16x32_bf16 v[64:67], v[156:159], v[188:191], v[64:67]
	s_barrier
; #define PG8_STAGE(bufoff, gbase, voff) do { _Pragma("unroll") for (int _i = 0; _i < 2; ++_i) \
;         __builtin_amdgcn_global_load_lds((const unsigned*)((const char*)(gbase) + (voff)[_i]), (LAS unsigned*)(lds + (bufoff) + ldsw + _i * 8192), 16, 0, 0); } while (0)
; #define PG8_LDA(dst, b, h) do { _Pragma("unroll") for (int m = 0; m < 4; ++m) _Pragma("unroll") for (int k = 0; k < 2; ++k) dst[m][k] = *(const LAS bf16x8*)(lds + PG8_SA(b, h) + aoff + m * 2048 + k * 1024); } while (0)
; #define PG8_MMA(ai, bj, At, Bt) do { __builtin_amdgcn_s_setprio(1); _Pragma("unroll") for (int m = 0; m < 4; ++m) _Pragma("unroll") for (int n = 0; n < 2; ++n) _Pragma("unroll") for (int k = 0; k < 2; ++k) \
;         acc[ai][bj][m][n] = __builtin_amdgcn_mfma_f32_16x16x32_bf16(Bt[n][k], At[m][k], acc[ai][bj][m][n], 0, 0, 0); __builtin_amdgcn_s_setprio(0); } while (0)
; #define PG8_WAIT_V(n) asm volatile("s_waitcnt vmcnt(" #n ")" ::: "memory")
; #define PG8_WAIT_L(n) asm volatile("s_waitcnt lgkmcnt(" #n ")" ::: "memory")
; #define PG8_BAR __builtin_amdgcn_s_barrier()
; #define PG8_SCHED __builtin_amdgcn_sched_barrier(0)
; template <class Desc, class Epi>
; DI void gemm_phase(LAS unsigned char* lds, const Desc& D, const Epi& E, int wv) {
;     ...
;         for (int t = 0; t < nt; t += 2) {
;     ...
;             PG8_LDA(At, 1, 1); PG8_STAGE(PG8_SB(1, 0), b3, voffB); PG8_STAGE(PG8_SB(1, 1), b3 + hstepB, voffB); PG8_STAGE(PG8_SA(1, 0), a3, voffA);
;             PG8_WAIT_V(8); PG8_WAIT_L(0); PG8_BAR; PG8_MMA(1, 0, At, B0); PG8_MMA(1, 1, At, B1); PG8_BAR; PG8_SCHED;
;         }
	s_add_i32 s40, s65, s28
	v_lshl_add_u64 v[192:193], v[192:193], 0, s[6:7]
	s_mov_b32 m0, s40
	ds_read_b128 v[160:163], v232 offset:49152
	ds_read_b128 v[164:167], v232 offset:50176
	ds_read_b128 v[168:171], v232 offset:51200
	ds_read_b128 v[172:175], v232 offset:52224
	ds_read_b128 v[176:179], v232 offset:53248
	ds_read_b128 v[180:183], v232 offset:54272
	ds_read_b128 v[184:187], v232 offset:55296
	ds_read_b128 v[188:191], v232 offset:56320
	global_load_lds_dwordx4 v[192:193], off
	s_add_i32 m0, s40, 0x2000
	s_add_u32 s22, s22, 0x80080
	v_lshl_add_u64 v[192:193], v[194:195], 0, s[6:7]
	s_addc_u32 s23, s23, 0
	s_add_i32 s40, s66, s28
	global_load_lds_dwordx4 v[192:193], off
	v_lshl_add_u64 v[192:193], s[22:23], 0, v[212:213]
	s_mov_b32 m0, s40
	s_nop 0
	global_load_lds_dwordx4 v[192:193], off
	v_lshl_add_u64 v[192:193], s[22:23], 0, v[208:209]
	s_add_i32 m0, s40, 0x2000
	s_nop 0
	global_load_lds_dwordx4 v[192:193], off
	v_lshl_add_u64 v[192:193], v[196:197], 0, s[6:7]
	s_mov_b32 m0, s47
	s_nop 0
	global_load_lds_dwordx4 v[192:193], off
	v_lshl_add_u64 v[192:193], v[198:199], 0, s[6:7]
	s_mov_b32 m0, s48
	s_nop 0
	global_load_lds_dwordx4 v[192:193], off
	s_waitcnt vmcnt(8)
	s_waitcnt lgkmcnt(0)
	s_barrier
	v_mfma_f32_16x16x32_bf16 v[60:63], v[128:131], v[160:163], v[60:63]
	v_mfma_f32_16x16x32_bf16 v[56:59], v[136:139], v[160:163], v[56:59]
	v_mfma_f32_16x16x32_bf16 v[48:51], v[128:131], v[168:171], v[48:51]
	v_mfma_f32_16x16x32_bf16 v[40:43], v[136:139], v[168:171], v[40:43]
	v_mfma_f32_16x16x32_bf16 v[32:35], v[128:131], v[176:179], v[32:35]
	v_mfma_f32_16x16x32_bf16 v[24:27], v[136:139], v[176:179], v[24:27]
	v_mfma_f32_16x16x32_bf16 v[16:19], v[128:131], v[184:187], v[16:19]
	v_mfma_f32_16x16x32_bf16 v[8:11], v[136:139], v[184:187], v[8:11]
	v_mfma_f32_16x16x32_bf16 v[60:63], v[132:135], v[164:167], v[60:63]
	v_mfma_f32_16x16x32_bf16 v[56:59], v[140:143], v[164:167], v[56:59]
	v_mfma_f32_16x16x32_bf16 v[48:51], v[132:135], v[172:175], v[48:51]
	v_mfma_f32_16x16x32_bf16 v[40:43], v[140:143], v[172:175], v[40:43]
	v_mfma_f32_16x16x32_bf16 v[32:35], v[132:135], v[180:183], v[32:35]
	v_mfma_f32_16x16x32_bf16 v[24:27], v[140:143], v[180:183], v[24:27]
	v_mfma_f32_16x16x32_bf16 v[16:19], v[132:135], v[188:191], v[16:19]
	v_mfma_f32_16x16x32_bf16 v[8:11], v[140:143], v[188:191], v[8:11]
	v_mfma_f32_16x16x32_bf16 v[52:55], v[144:147], v[160:163], v[52:55]
	v_mfma_f32_16x16x32_bf16 v[44:47], v[152:155], v[160:163], v[44:47]
	v_mfma_f32_16x16x32_bf16 v[36:39], v[144:147], v[168:171], v[36:39]
	v_mfma_f32_16x16x32_bf16 v[28:31], v[152:155], v[168:171], v[28:31]
	v_mfma_f32_16x16x32_bf16 v[20:23], v[144:147], v[176:179], v[20:23]
	v_mfma_f32_16x16x32_bf16 v[12:15], v[152:155], v[176:179], v[12:15]
	v_mfma_f32_16x16x32_bf16 v[4:7], v[144:147], v[184:187], v[4:7]
	v_mfma_f32_16x16x32_bf16 v[0:3], v[152:155], v[184:187], v[0:3]
	v_mfma_f32_16x16x32_bf16 v[52:55], v[148:151], v[164:167], v[52:55]
	v_mfma_f32_16x16x32_bf16 v[44:47], v[156:159], v[164:167], v[44:47]
	v_mfma_f32_16x16x32_bf16 v[36:39], v[148:151], v[172:175], v[36:39]
	v_mfma_f32_16x16x32_bf16 v[28:31], v[156:159], v[172:175], v[28:31]
	v_mfma_f32_16x16x32_bf16 v[20:23], v[148:151], v[180:183], v[20:23]
	v_mfma_f32_16x16x32_bf16 v[12:15], v[156:159], v[180:183], v[12:15]
	v_mfma_f32_16x16x32_bf16 v[4:7], v[148:151], v[188:191], v[4:7]
	v_mfma_f32_16x16x32_bf16 v[0:3], v[156:159], v[188:191], v[0:3]
	s_barrier
	s_add_i32 s64, s64, 2
	s_add_u32 s20, s20, 0x100
	s_addc_u32 s21, s21, 0
	s_add_u32 s15, s15, 0x100
	s_addc_u32 s17, s17, 0
	s_cmp_gt_u32 s64, 29
	s_cbranch_scc0 .LBB0_1501
	s_and_b64 vcc, exec, s[8:9]
	s_cbranch_vccz .LBB0_1504
	s_barrier

; #define PG8_STAGE(bufoff, gbase, voff) do { _Pragma("unroll") for (int _i = 0; _i < 2; ++_i) \
;         __builtin_amdgcn_global_load_lds((const unsigned*)((const char*)(gbase) + (voff)[_i]), (LAS unsigned*)(lds + (bufoff) + ldsw + _i * 8192), 16, 0, 0); } while (0)
; #define PG8_LDA(dst, b, h) do { _Pragma("unroll") for (int m = 0; m < 4; ++m) _Pragma("unroll") for (int k = 0; k < 2; ++k) dst[m][k] = *(const LAS bf16x8*)(lds + PG8_SA(b, h) + aoff + m * 2048 + k * 1024); } while (0)
; #define PG8_LDB(dst, b, h) do { _Pragma("unroll") for (int n = 0; n < 2; ++n) _Pragma("unroll") for (int k = 0; k < 2; ++k) dst[n][k] = *(const LAS bf16x8*)(lds + PG8_SB(b, h) + boff + n * 2048 + k * 1024); } while (0)
; #define PG8_MMA(ai, bj, At, Bt) do { __builtin_amdgcn_s_setprio(1); _Pragma("unroll") for (int m = 0; m < 4; ++m) _Pragma("unroll") for (int n = 0; n < 2; ++n) _Pragma("unroll") for (int k = 0; k < 2; ++k) \
;         acc[ai][bj][m][n] = __builtin_amdgcn_mfma_f32_16x16x32_bf16(Bt[n][k], At[m][k], acc[ai][bj][m][n], 0, 0, 0); __builtin_amdgcn_s_setprio(0); } while (0)
; #define PG8_WAIT_V(n) asm volatile("s_waitcnt vmcnt(" #n ")" ::: "memory")
; #define PG8_WAIT_L(n) asm volatile("s_waitcnt lgkmcnt(" #n ")" ::: "memory")
; #define PG8_BAR __builtin_amdgcn_s_barrier()
; #define PG8_SCHED __builtin_amdgcn_sched_barrier(0)
; template <class Desc, class Epi>
; DI void gemm_phase(LAS unsigned char* lds, const Desc& D, const Epi& E, int wv) {
;     ...
;             const bool last = (t == nt - 2);
;             const char* a1 = cA + (size_t)(t + 1) * kstep;
;             const char* a2 = last ? nA : cA + (size_t)(t + 2) * kstep; const char* b2 = last ? nB : cB + (size_t)(t + 2) * kstep;
;             const char* a3 = a2 + kstep; const char* b3 = b2 + kstep;
;             PG8_LDB(B0, 0, 0); PG8_LDB(B1, 0, 1); PG8_SCHED; PG8_LDA(At, 0, 0); PG8_STAGE(PG8_SA(1, 1), a1 + hstepA, voffA);
;             PG8_WAIT_V(8); PG8_WAIT_L(0); PG8_BAR; PG8_MMA(0, 0, At, B0); PG8_MMA(0, 1, At, B1); PG8_BAR; PG8_SCHED;
;             PG8_LDA(At, 0, 1); PG8_STAGE(PG8_SB(0, 0), b2, voffB); PG8_STAGE(PG8_SB(0, 1), b2 + hstepB, voffB); PG8_STAGE(PG8_SA(0, 0), a2, voffA);
;             PG8_WAIT_V(8); PG8_WAIT_L(0); PG8_BAR; PG8_MMA(1, 0, At, B0); PG8_MMA(1, 1, At, B1); PG8_BAR; PG8_SCHED;
.LBB0_1632:
	ds_read_b128 v[146:149], v155
	ds_read_b128 v[150:153], v155 offset:1024
	ds_read_b128 v[158:161], v155 offset:2048
	ds_read_b128 v[162:165], v155 offset:3072
	ds_read_b128 v[166:169], v156
	ds_read_b128 v[170:173], v156 offset:1024
	ds_read_b128 v[174:177], v156 offset:2048
	ds_read_b128 v[178:181], v156 offset:3072
	s_add_u32 s17, s62, 0xfff80080
	s_addc_u32 s19, s63, -1
	s_cmp_eq_u32 s8, 28
	s_cselect_b32 s67, s21, s19
	s_cselect_b32 s66, s20, s17
	s_cselect_b32 s65, s23, s7
	s_cselect_b32 s64, s22, s5
	v_lshl_add_u64 v[214:215], s[62:63], 0, v[138:139]
	s_add_i32 m0, s29, 0xc000
	ds_read_b128 v[182:185], v157
	ds_read_b128 v[186:189], v157 offset:1024
	ds_read_b128 v[190:193], v157 offset:2048
	ds_read_b128 v[194:197], v157 offset:3072
	ds_read_b128 v[198:201], v157 offset:4096
	ds_read_b128 v[202:205], v157 offset:5120
	ds_read_b128 v[206:209], v157 offset:6144
	ds_read_b128 v[210:213], v157 offset:7168
	global_load_lds_dwordx4 v[214:215], off
	v_lshl_add_u64 v[214:215], s[62:63], 0, v[140:141]
	s_add_i32 m0, s29, 0xe000
	s_nop 0
	global_load_lds_dwordx4 v[214:215], off
	s_waitcnt vmcnt(8)
	s_waitcnt lgkmcnt(0)
	s_barrier
	v_mfma_f32_16x16x32_bf16 v[124:127], v[146:149], v[182:185], v[124:127]
	v_mfma_f32_16x16x32_bf16 v[120:123], v[158:161], v[182:185], v[120:123]
	v_mfma_f32_16x16x32_bf16 v[108:111], v[146:149], v[190:193], v[108:111]
	v_mfma_f32_16x16x32_bf16 v[104:107], v[158:161], v[190:193], v[104:107]
	v_mfma_f32_16x16x32_bf16 v[92:95], v[146:149], v[198:201], v[92:95]
	v_mfma_f32_16x16x32_bf16 v[88:91], v[158:161], v[198:201], v[88:91]
	v_mfma_f32_16x16x32_bf16 v[76:79], v[146:149], v[206:209], v[76:79]
	v_mfma_f32_16x16x32_bf16 v[72:75], v[158:161], v[206:209], v[72:75]
	v_mfma_f32_16x16x32_bf16 v[124:127], v[150:153], v[186:189], v[124:127]
	v_mfma_f32_16x16x32_bf16 v[120:123], v[162:165], v[186:189], v[120:123]
	v_mfma_f32_16x16x32_bf16 v[108:111], v[150:153], v[194:197], v[108:111]
	v_mfma_f32_16x16x32_bf16 v[104:107], v[162:165], v[194:197], v[104:107]
	v_mfma_f32_16x16x32_bf16 v[92:95], v[150:153], v[202:205], v[92:95]
	v_mfma_f32_16x16x32_bf16 v[88:91], v[162:165], v[202:205], v[88:91]
	v_mfma_f32_16x16x32_bf16 v[76:79], v[150:153], v[210:213], v[76:79]
	v_mfma_f32_16x16x32_bf16 v[72:75], v[162:165], v[210:213], v[72:75]
	v_mfma_f32_16x16x32_bf16 v[116:119], v[166:169], v[182:185], v[116:119]
	v_mfma_f32_16x16x32_bf16 v[112:115], v[174:177], v[182:185], v[112:115]
	v_mfma_f32_16x16x32_bf16 v[100:103], v[166:169], v[190:193], v[100:103]
	v_mfma_f32_16x16x32_bf16 v[96:99], v[174:177], v[190:193], v[96:99]
	v_mfma_f32_16x16x32_bf16 v[84:87], v[166:169], v[198:201], v[84:87]
	v_mfma_f32_16x16x32_bf16 v[80:83], v[174:177], v[198:201], v[80:83]
	v_mfma_f32_16x16x32_bf16 v[68:71], v[166:169], v[206:209], v[68:71]
	v_mfma_f32_16x16x32_bf16 v[64:67], v[174:177], v[206:209], v[64:67]
	v_mfma_f32_16x16x32_bf16 v[116:119], v[170:173], v[186:189], v[116:119]
	v_mfma_f32_16x16x32_bf16 v[112:115], v[178:181], v[186:189], v[112:115]
	v_mfma_f32_16x16x32_bf16 v[100:103], v[170:173], v[194:197], v[100:103]
	v_mfma_f32_16x16x32_bf16 v[96:99], v[178:181], v[194:197], v[96:99]
	v_mfma_f32_16x16x32_bf16 v[84:87], v[170:173], v[202:205], v[84:87]
	v_mfma_f32_16x16x32_bf16 v[80:83], v[178:181], v[202:205], v[80:83]
	v_mfma_f32_16x16x32_bf16 v[68:71], v[170:173], v[210:213], v[68:71]
	v_mfma_f32_16x16x32_bf16 v[64:67], v[178:181], v[210:213], v[64:67]
	s_barrier
	s_add_i32 s17, s50, s28
	v_lshl_add_u64 v[214:215], s[64:65], 0, v[130:131]
	s_mov_b32 m0, s17
	ds_read_b128 v[182:185], v157 offset:16384
	ds_read_b128 v[186:189], v157 offset:17408
	ds_read_b128 v[190:193], v157 offset:18432
	ds_read_b128 v[194:197], v157 offset:19456
	ds_read_b128 v[198:201], v157 offset:20480
	ds_read_b128 v[202:205], v157 offset:21504
	ds_read_b128 v[206:209], v157 offset:22528
	ds_read_b128 v[210:213], v157 offset:23552
	global_load_lds_dwordx4 v[214:215], off
	s_add_i32 m0, s17, 0x2000
	s_add_u32 s68, s64, 0x80000
	v_lshl_add_u64 v[216:217], s[64:65], 0, v[134:135]
	s_addc_u32 s69, s65, 0
	s_add_i32 s17, s51, s28
	global_load_lds_dwordx4 v[216:217], off
	v_lshl_add_u64 v[218:219], s[68:69], 0, v[130:131]
	s_mov_b32 m0, s17
	v_lshl_add_u64 v[220:221], s[66:67], 0, v[132:133]
	global_load_lds_dwordx4 v[218:219], off
	v_lshl_add_u64 v[218:219], s[68:69], 0, v[134:135]
	s_add_i32 m0, s17, 0x2000
	s_nop 0
	global_load_lds_dwordx4 v[218:219], off
	v_lshl_add_u64 v[218:219], s[66:67], 0, v[128:129]
	s_mov_b32 m0, s29
	s_nop 0
	global_load_lds_dwordx4 v[218:219], off
	s_mov_b32 m0, s30
	s_nop 0
	global_load_lds_dwordx4 v[220:221], off
	s_waitcnt vmcnt(8)
	s_waitcnt lgkmcnt(0)
	s_barrier
; #define PG8_STAGE(bufoff, gbase, voff) do { _Pragma("unroll") for (int _i = 0; _i < 2; ++_i) \
;         __builtin_amdgcn_global_load_lds((const unsigned*)((const char*)(gbase) + (voff)[_i]), (LAS unsigned*)(lds + (bufoff) + ldsw + _i * 8192), 16, 0, 0); } while (0)
; #define PG8_LDA(dst, b, h) do { _Pragma("unroll") for (int m = 0; m < 4; ++m) _Pragma("unroll") for (int k = 0; k < 2; ++k) dst[m][k] = *(const LAS bf16x8*)(lds + PG8_SA(b, h) + aoff + m * 2048 + k * 1024); } while (0)
; #define PG8_LDB(dst, b, h) do { _Pragma("unroll") for (int n = 0; n < 2; ++n) _Pragma("unroll") for (int k = 0; k < 2; ++k) dst[n][k] = *(const LAS bf16x8*)(lds + PG8_SB(b, h) + boff + n * 2048 + k * 1024); } while (0)
; #define PG8_MMA(ai, bj, At, Bt) do { __builtin_amdgcn_s_setprio(1); _Pragma("unroll") for (int m = 0; m < 4; ++m) _Pragma("unroll") for (int n = 0; n < 2; ++n) _Pragma("unroll") for (int k = 0; k < 2; ++k) \
;         acc[ai][bj][m][n] = __builtin_amdgcn_mfma_f32_16x16x32_bf16(Bt[n][k], At[m][k], acc[ai][bj][m][n], 0, 0, 0); __builtin_amdgcn_s_setprio(0); } while (0)
; #define PG8_WAIT_V(n) asm volatile("s_waitcnt vmcnt(" #n ")" ::: "memory")
; #define PG8_WAIT_L(n) asm volatile("s_waitcnt lgkmcnt(" #n ")" ::: "memory")
; #define PG8_BAR __builtin_amdgcn_s_barrier()
; #define PG8_SCHED __builtin_amdgcn_sched_barrier(0)
; template <class Desc, class Epi>
; DI void gemm_phase(LAS unsigned char* lds, const Desc& D, const Epi& E, int wv) {
;     ...
;             PG8_WAIT_V(8); PG8_WAIT_L(0); PG8_BAR; PG8_MMA(1, 0, At, B0); PG8_MMA(1, 1, At, B1); PG8_BAR; PG8_SCHED;
;             PG8_LDB(B0, 1, 0); PG8_LDB(B1, 1, 1); PG8_SCHED; PG8_LDA(At, 1, 0); PG8_STAGE(PG8_SA(0, 1), a2 + hstepA, voffA);
;             PG8_WAIT_V(8); PG8_WAIT_L(0); PG8_BAR; PG8_MMA(0, 0, At, B0); PG8_MMA(0, 1, At, B1); PG8_BAR; PG8_SCHED;
	v_mfma_f32_16x16x32_bf16 v[60:63], v[146:149], v[182:185], v[60:63]
	v_mfma_f32_16x16x32_bf16 v[56:59], v[158:161], v[182:185], v[56:59]
	v_mfma_f32_16x16x32_bf16 v[44:47], v[146:149], v[190:193], v[44:47]
	v_mfma_f32_16x16x32_bf16 v[40:43], v[158:161], v[190:193], v[40:43]
	v_mfma_f32_16x16x32_bf16 v[28:31], v[146:149], v[198:201], v[28:31]
	v_mfma_f32_16x16x32_bf16 v[24:27], v[158:161], v[198:201], v[24:27]
	v_mfma_f32_16x16x32_bf16 v[12:15], v[146:149], v[206:209], v[12:15]
	v_mfma_f32_16x16x32_bf16 v[8:11], v[158:161], v[206:209], v[8:11]
	v_mfma_f32_16x16x32_bf16 v[60:63], v[150:153], v[186:189], v[60:63]
	v_mfma_f32_16x16x32_bf16 v[56:59], v[162:165], v[186:189], v[56:59]
	v_mfma_f32_16x16x32_bf16 v[44:47], v[150:153], v[194:197], v[44:47]
	v_mfma_f32_16x16x32_bf16 v[40:43], v[162:165], v[194:197], v[40:43]
	v_mfma_f32_16x16x32_bf16 v[28:31], v[150:153], v[202:205], v[28:31]
	v_mfma_f32_16x16x32_bf16 v[24:27], v[162:165], v[202:205], v[24:27]
	v_mfma_f32_16x16x32_bf16 v[12:15], v[150:153], v[210:213], v[12:15]
	v_mfma_f32_16x16x32_bf16 v[8:11], v[162:165], v[210:213], v[8:11]
	v_mfma_f32_16x16x32_bf16 v[52:55], v[166:169], v[182:185], v[52:55]
	v_mfma_f32_16x16x32_bf16 v[48:51], v[174:177], v[182:185], v[48:51]
	v_mfma_f32_16x16x32_bf16 v[36:39], v[166:169], v[190:193], v[36:39]
	v_mfma_f32_16x16x32_bf16 v[32:35], v[174:177], v[190:193], v[32:35]
	v_mfma_f32_16x16x32_bf16 v[20:23], v[166:169], v[198:201], v[20:23]
	v_mfma_f32_16x16x32_bf16 v[16:19], v[174:177], v[198:201], v[16:19]
	v_mfma_f32_16x16x32_bf16 v[4:7], v[166:169], v[206:209], v[4:7]
	v_mfma_f32_16x16x32_bf16 v[0:3], v[174:177], v[206:209], v[0:3]
	v_mfma_f32_16x16x32_bf16 v[52:55], v[170:173], v[186:189], v[52:55]
	v_mfma_f32_16x16x32_bf16 v[48:51], v[178:181], v[186:189], v[48:51]
	v_mfma_f32_16x16x32_bf16 v[36:39], v[170:173], v[194:197], v[36:39]
	v_mfma_f32_16x16x32_bf16 v[32:35], v[178:181], v[194:197], v[32:35]
	v_mfma_f32_16x16x32_bf16 v[20:23], v[170:173], v[202:205], v[20:23]
	v_mfma_f32_16x16x32_bf16 v[16:19], v[178:181], v[202:205], v[16:19]
	v_mfma_f32_16x16x32_bf16 v[4:7], v[170:173], v[210:213], v[4:7]
	v_mfma_f32_16x16x32_bf16 v[0:3], v[178:181], v[210:213], v[0:3]
	s_barrier
	s_add_i32 s17, 0, 0x18000
	v_add_u32_e32 v136, s17, v154
	s_add_i32 s19, 0, 0x1c000
	ds_read_b128 v[146:149], v136
	ds_read_b128 v[150:153], v136 offset:1024
	ds_read_b128 v[158:161], v136 offset:2048
	ds_read_b128 v[162:165], v136 offset:3072
	v_add_u32_e32 v136, s19, v154
	ds_read_b128 v[166:169], v136
	ds_read_b128 v[170:173], v136 offset:1024
	ds_read_b128 v[174:177], v136 offset:2048
	ds_read_b128 v[178:181], v136 offset:3072
	s_add_u32 s66, s66, 0x80000
	s_addc_u32 s67, s67, 0
	s_mov_b32 m0, s31
	v_lshl_add_u64 v[222:223], s[66:67], 0, v[128:129]
	ds_read_b128 v[182:185], v157 offset:32768
	ds_read_b128 v[186:189], v157 offset:33792
	ds_read_b128 v[190:193], v157 offset:34816
	ds_read_b128 v[194:197], v157 offset:35840
	ds_read_b128 v[198:201], v157 offset:36864
	ds_read_b128 v[202:205], v157 offset:37888
	ds_read_b128 v[206:209], v157 offset:38912
	ds_read_b128 v[210:213], v157 offset:39936
	global_load_lds_dwordx4 v[222:223], off
	v_lshl_add_u64 v[222:223], s[66:67], 0, v[132:133]
	s_mov_b32 m0, s34
	s_nop 0
	global_load_lds_dwordx4 v[222:223], off
	s_waitcnt vmcnt(8)
	s_waitcnt lgkmcnt(0)
	s_barrier
	v_mfma_f32_16x16x32_bf16 v[124:127], v[146:149], v[182:185], v[124:127]
	v_mfma_f32_16x16x32_bf16 v[120:123], v[158:161], v[182:185], v[120:123]
	v_mfma_f32_16x16x32_bf16 v[108:111], v[146:149], v[190:193], v[108:111]
	v_mfma_f32_16x16x32_bf16 v[104:107], v[158:161], v[190:193], v[104:107]
	v_mfma_f32_16x16x32_bf16 v[92:95], v[146:149], v[198:201], v[92:95]
	v_mfma_f32_16x16x32_bf16 v[88:91], v[158:161], v[198:201], v[88:91]
	v_mfma_f32_16x16x32_bf16 v[76:79], v[146:149], v[206:209], v[76:79]
	v_mfma_f32_16x16x32_bf16 v[72:75], v[158:161], v[206:209], v[72:75]
	v_mfma_f32_16x16x32_bf16 v[124:127], v[150:153], v[186:189], v[124:127]
	v_mfma_f32_16x16x32_bf16 v[120:123], v[162:165], v[186:189], v[120:123]
	v_mfma_f32_16x16x32_bf16 v[108:111], v[150:153], v[194:197], v[108:111]
	v_mfma_f32_16x16x32_bf16 v[104:107], v[162:165], v[194:197], v[104:107]
	v_mfma_f32_16x16x32_bf16 v[92:95], v[150:153], v[202:205], v[92:95]
	v_mfma_f32_16x16x32_bf16 v[88:91], v[162:165], v[202:205], v[88:91]
	v_mfma_f32_16x16x32_bf16 v[76:79], v[150:153], v[210:213], v[76:79]
	v_mfma_f32_16x16x32_bf16 v[72:75], v[162:165], v[210:213], v[72:75]
	v_mfma_f32_16x16x32_bf16 v[116:119], v[166:169], v[182:185], v[116:119]
	v_mfma_f32_16x16x32_bf16 v[112:115], v[174:177], v[182:185], v[112:115]
	v_mfma_f32_16x16x32_bf16 v[100:103], v[166:169], v[190:193], v[100:103]
	v_mfma_f32_16x16x32_bf16 v[96:99], v[174:177], v[190:193], v[96:99]
	v_mfma_f32_16x16x32_bf16 v[84:87], v[166:169], v[198:201], v[84:87]
	v_mfma_f32_16x16x32_bf16 v[80:83], v[174:177], v[198:201], v[80:83]
	v_mfma_f32_16x16x32_bf16 v[68:71], v[166:169], v[206:209], v[68:71]
	v_mfma_f32_16x16x32_bf16 v[64:67], v[174:177], v[206:209], v[64:67]
	v_mfma_f32_16x16x32_bf16 v[116:119], v[170:173], v[186:189], v[116:119]
	v_mfma_f32_16x16x32_bf16 v[112:115], v[178:181], v[186:189], v[112:115]
	v_mfma_f32_16x16x32_bf16 v[100:103], v[170:173], v[194:197], v[100:103]
	v_mfma_f32_16x16x32_bf16 v[96:99], v[178:181], v[194:197], v[96:99]
	v_mfma_f32_16x16x32_bf16 v[84:87], v[170:173], v[202:205], v[84:87]
	v_mfma_f32_16x16x32_bf16 v[80:83], v[178:181], v[202:205], v[80:83]
	v_mfma_f32_16x16x32_bf16 v[68:71], v[170:173], v[210:213], v[68:71]
	v_mfma_f32_16x16x32_bf16 v[64:67], v[178:181], v[210:213], v[64:67]
	s_barrier
; #define PG8_STAGE(bufoff, gbase, voff) do { _Pragma("unroll") for (int _i = 0; _i < 2; ++_i) \
;         __builtin_amdgcn_global_load_lds((const unsigned*)((const char*)(gbase) + (voff)[_i]), (LAS unsigned*)(lds + (bufoff) + ldsw + _i * 8192), 16, 0, 0); } while (0)
; #define PG8_LDA(dst, b, h) do { _Pragma("unroll") for (int m = 0; m < 4; ++m) _Pragma("unroll") for (int k = 0; k < 2; ++k) dst[m][k] = *(const LAS bf16x8*)(lds + PG8_SA(b, h) + aoff + m * 2048 + k * 1024); } while (0)
; #define PG8_MMA(ai, bj, At, Bt) do { __builtin_amdgcn_s_setprio(1); _Pragma("unroll") for (int m = 0; m < 4; ++m) _Pragma("unroll") for (int n = 0; n < 2; ++n) _Pragma("unroll") for (int k = 0; k < 2; ++k) \
;         acc[ai][bj][m][n] = __builtin_amdgcn_mfma_f32_16x16x32_bf16(Bt[n][k], At[m][k], acc[ai][bj][m][n], 0, 0, 0); __builtin_amdgcn_s_setprio(0); } while (0)
; #define PG8_WAIT_V(n) asm volatile("s_waitcnt vmcnt(" #n ")" ::: "memory")
; #define PG8_WAIT_L(n) asm volatile("s_waitcnt lgkmcnt(" #n ")" ::: "memory")
; #define PG8_BAR __builtin_amdgcn_s_barrier()
; #define PG8_SCHED __builtin_amdgcn_sched_barrier(0)
; template <class Desc, class Epi>
; DI void gemm_phase(LAS unsigned char* lds, const Desc& D, const Epi& E, int wv) {
;     ...
;         for (int t = 0; t < nt; t += 2) {
;     ...
;             PG8_LDA(At, 1, 1); PG8_STAGE(PG8_SB(1, 0), b3, voffB); PG8_STAGE(PG8_SB(1, 1), b3 + hstepB, voffB); PG8_STAGE(PG8_SA(1, 0), a3, voffA);
;             PG8_WAIT_V(8); PG8_WAIT_L(0); PG8_BAR; PG8_MMA(1, 0, At, B0); PG8_MMA(1, 1, At, B1); PG8_BAR; PG8_SCHED;
;         }
	s_add_i32 s17, s17, s28
	v_lshl_add_u64 v[214:215], v[214:215], 0, s[12:13]
	s_mov_b32 m0, s17
	ds_read_b128 v[182:185], v157 offset:49152
	ds_read_b128 v[186:189], v157 offset:50176
	ds_read_b128 v[190:193], v157 offset:51200
	ds_read_b128 v[194:197], v157 offset:52224
	ds_read_b128 v[198:201], v157 offset:53248
	ds_read_b128 v[202:205], v157 offset:54272
	ds_read_b128 v[206:209], v157 offset:55296
	ds_read_b128 v[210:213], v157 offset:56320
	global_load_lds_dwordx4 v[214:215], off
	s_add_i32 m0, s17, 0x2000
	s_add_u32 s64, s64, 0x80080
	v_lshl_add_u64 v[214:215], v[216:217], 0, s[12:13]
	s_addc_u32 s65, s65, 0
	s_add_i32 s17, s19, s28
	global_load_lds_dwordx4 v[214:215], off
	v_lshl_add_u64 v[214:215], s[64:65], 0, v[130:131]
	s_mov_b32 m0, s17
	s_nop 0
	global_load_lds_dwordx4 v[214:215], off
	v_lshl_add_u64 v[214:215], s[64:65], 0, v[134:135]
	s_add_i32 m0, s17, 0x2000
	s_nop 0
	global_load_lds_dwordx4 v[214:215], off
	v_lshl_add_u64 v[214:215], v[218:219], 0, s[12:13]
	s_mov_b32 m0, s47
	s_nop 0
	global_load_lds_dwordx4 v[214:215], off
	v_lshl_add_u64 v[214:215], v[220:221], 0, s[12:13]
	s_mov_b32 m0, s48
	s_nop 0
	global_load_lds_dwordx4 v[214:215], off
	s_waitcnt vmcnt(8)
	s_waitcnt lgkmcnt(0)
	s_barrier
	v_mfma_f32_16x16x32_bf16 v[60:63], v[146:149], v[182:185], v[60:63]
	v_mfma_f32_16x16x32_bf16 v[56:59], v[158:161], v[182:185], v[56:59]
	v_mfma_f32_16x16x32_bf16 v[44:47], v[146:149], v[190:193], v[44:47]
	v_mfma_f32_16x16x32_bf16 v[40:43], v[158:161], v[190:193], v[40:43]
	v_mfma_f32_16x16x32_bf16 v[28:31], v[146:149], v[198:201], v[28:31]
	v_mfma_f32_16x16x32_bf16 v[24:27], v[158:161], v[198:201], v[24:27]
	v_mfma_f32_16x16x32_bf16 v[12:15], v[146:149], v[206:209], v[12:15]
	v_mfma_f32_16x16x32_bf16 v[8:11], v[158:161], v[206:209], v[8:11]
	v_mfma_f32_16x16x32_bf16 v[60:63], v[150:153], v[186:189], v[60:63]
	v_mfma_f32_16x16x32_bf16 v[56:59], v[162:165], v[186:189], v[56:59]
	v_mfma_f32_16x16x32_bf16 v[44:47], v[150:153], v[194:197], v[44:47]
	v_mfma_f32_16x16x32_bf16 v[40:43], v[162:165], v[194:197], v[40:43]
	v_mfma_f32_16x16x32_bf16 v[28:31], v[150:153], v[202:205], v[28:31]
	v_mfma_f32_16x16x32_bf16 v[24:27], v[162:165], v[202:205], v[24:27]
	v_mfma_f32_16x16x32_bf16 v[12:15], v[150:153], v[210:213], v[12:15]
	v_mfma_f32_16x16x32_bf16 v[8:11], v[162:165], v[210:213], v[8:11]
	v_mfma_f32_16x16x32_bf16 v[52:55], v[166:169], v[182:185], v[52:55]
	v_mfma_f32_16x16x32_bf16 v[48:51], v[174:177], v[182:185], v[48:51]
	v_mfma_f32_16x16x32_bf16 v[36:39], v[166:169], v[190:193], v[36:39]
	v_mfma_f32_16x16x32_bf16 v[32:35], v[174:177], v[190:193], v[32:35]
	v_mfma_f32_16x16x32_bf16 v[20:23], v[166:169], v[198:201], v[20:23]
	v_mfma_f32_16x16x32_bf16 v[16:19], v[174:177], v[198:201], v[16:19]
	v_mfma_f32_16x16x32_bf16 v[4:7], v[166:169], v[206:209], v[4:7]
	v_mfma_f32_16x16x32_bf16 v[0:3], v[174:177], v[206:209], v[0:3]
	v_mfma_f32_16x16x32_bf16 v[52:55], v[170:173], v[186:189], v[52:55]
	v_mfma_f32_16x16x32_bf16 v[48:51], v[178:181], v[186:189], v[48:51]
	v_mfma_f32_16x16x32_bf16 v[36:39], v[170:173], v[194:197], v[36:39]
	v_mfma_f32_16x16x32_bf16 v[32:35], v[178:181], v[194:197], v[32:35]
	v_mfma_f32_16x16x32_bf16 v[20:23], v[170:173], v[202:205], v[20:23]
	v_mfma_f32_16x16x32_bf16 v[16:19], v[178:181], v[202:205], v[16:19]
	v_mfma_f32_16x16x32_bf16 v[4:7], v[170:173], v[210:213], v[4:7]
	v_mfma_f32_16x16x32_bf16 v[0:3], v[178:181], v[210:213], v[0:3]
	s_barrier
	s_add_i32 s8, s8, 2
	s_add_u32 s62, s62, 0x100
	s_addc_u32 s63, s63, 0
	s_add_u32 s5, s5, 0x100
	s_addc_u32 s7, s7, 0
	s_cmp_gt_u32 s8, 29
	s_cbranch_scc0 .LBB0_1632
	s_and_b64 vcc, exec, s[14:15]
	s_cbranch_vccz .LBB0_1635
	s_barrier

; #define PG8_STAGE(bufoff, gbase, voff) do { _Pragma("unroll") for (int _i = 0; _i < 2; ++_i) \
;         __builtin_amdgcn_global_load_lds((const unsigned*)((const char*)(gbase) + (voff)[_i]), (LAS unsigned*)(lds + (bufoff) + ldsw + _i * 8192), 16, 0, 0); } while (0)
; #define PG8_LDA(dst, b, h) do { _Pragma("unroll") for (int m = 0; m < 4; ++m) _Pragma("unroll") for (int k = 0; k < 2; ++k) dst[m][k] = *(const LAS bf16x8*)(lds + PG8_SA(b, h) + aoff + m * 2048 + k * 1024); } while (0)
; #define PG8_LDB(dst, b, h) do { _Pragma("unroll") for (int n = 0; n < 2; ++n) _Pragma("unroll") for (int k = 0; k < 2; ++k) dst[n][k] = *(const LAS bf16x8*)(lds + PG8_SB(b, h) + boff + n * 2048 + k * 1024); } while (0)
; #define PG8_MMA(ai, bj, At, Bt) do { __builtin_amdgcn_s_setprio(1); _Pragma("unroll") for (int m = 0; m < 4; ++m) _Pragma("unroll") for (int n = 0; n < 2; ++n) _Pragma("unroll") for (int k = 0; k < 2; ++k) \
;         acc[ai][bj][m][n] = __builtin_amdgcn_mfma_f32_16x16x32_bf16(Bt[n][k], At[m][k], acc[ai][bj][m][n], 0, 0, 0); __builtin_amdgcn_s_setprio(0); } while (0)
; #define PG8_WAIT_V(n) asm volatile("s_waitcnt vmcnt(" #n ")" ::: "memory")
; #define PG8_WAIT_L(n) asm volatile("s_waitcnt lgkmcnt(" #n ")" ::: "memory")
; #define PG8_BAR __builtin_amdgcn_s_barrier()
; #define PG8_SCHED __builtin_amdgcn_sched_barrier(0)
; template <class Desc, class Epi>
; DI void gemm_phase(LAS unsigned char* lds, const Desc& D, const Epi& E, int wv) {
;     ...
;             const bool last = (t == nt - 2);
;             const char* a1 = cA + (size_t)(t + 1) * kstep;
;             const char* a2 = last ? nA : cA + (size_t)(t + 2) * kstep; const char* b2 = last ? nB : cB + (size_t)(t + 2) * kstep;
;             const char* a3 = a2 + kstep; const char* b3 = b2 + kstep;
;             PG8_LDB(B0, 0, 0); PG8_LDB(B1, 0, 1); PG8_SCHED; PG8_LDA(At, 0, 0); PG8_STAGE(PG8_SA(1, 1), a1 + hstepA, voffA);
;             PG8_WAIT_V(8); PG8_WAIT_L(0); PG8_BAR; PG8_MMA(0, 0, At, B0); PG8_MMA(0, 1, At, B1); PG8_BAR; PG8_SCHED;
;             PG8_LDA(At, 0, 1); PG8_STAGE(PG8_SB(0, 0), b2, voffB); PG8_STAGE(PG8_SB(0, 1), b2 + hstepB, voffB); PG8_STAGE(PG8_SA(0, 0), a2, voffA);
;             PG8_WAIT_V(8); PG8_WAIT_L(0); PG8_BAR; PG8_MMA(1, 0, At, B0); PG8_MMA(1, 1, At, B1); PG8_BAR; PG8_SCHED;
.LBB0_2088:
	ds_read_b128 v[128:131], v221
	ds_read_b128 v[132:135], v221 offset:1024
	ds_read_b128 v[136:139], v221 offset:2048
	ds_read_b128 v[140:143], v221 offset:3072
	ds_read_b128 v[144:147], v222
	ds_read_b128 v[148:151], v222 offset:1024
	ds_read_b128 v[152:155], v222 offset:2048
	ds_read_b128 v[156:159], v222 offset:3072
	s_add_u32 s42, s40, 0xfff80080
	s_addc_u32 s43, s41, -1
	s_cmp_eq_u32 s66, 28
	s_cselect_b32 s49, s15, s43
	s_cselect_b32 s48, s14, s42
	s_cselect_b32 s43, s17, s21
	s_cselect_b32 s42, s16, s19
	v_lshl_add_u64 v[192:193], s[40:41], 0, v[208:209]
	s_add_i32 m0, s29, 0xc000
	ds_read_b128 v[160:163], v223
	ds_read_b128 v[164:167], v223 offset:1024
	ds_read_b128 v[168:171], v223 offset:2048
	ds_read_b128 v[172:175], v223 offset:3072
	ds_read_b128 v[176:179], v223 offset:4096
	ds_read_b128 v[180:183], v223 offset:5120
	ds_read_b128 v[184:187], v223 offset:6144
	ds_read_b128 v[188:191], v223 offset:7168
	global_load_lds_dwordx4 v[192:193], off
	v_lshl_add_u64 v[192:193], s[40:41], 0, v[210:211]
	s_add_i32 m0, s29, 0xe000
	s_nop 0
	global_load_lds_dwordx4 v[192:193], off
	s_waitcnt vmcnt(8)
	s_waitcnt lgkmcnt(0)
	s_barrier
	v_mfma_f32_16x16x32_bf16 v[124:127], v[128:131], v[160:163], v[124:127]
	v_mfma_f32_16x16x32_bf16 v[120:123], v[136:139], v[160:163], v[120:123]
	v_mfma_f32_16x16x32_bf16 v[112:115], v[128:131], v[168:171], v[112:115]
	v_mfma_f32_16x16x32_bf16 v[104:107], v[136:139], v[168:171], v[104:107]
	v_mfma_f32_16x16x32_bf16 v[96:99], v[128:131], v[176:179], v[96:99]
	v_mfma_f32_16x16x32_bf16 v[88:91], v[136:139], v[176:179], v[88:91]
	v_mfma_f32_16x16x32_bf16 v[80:83], v[128:131], v[184:187], v[80:83]
	v_mfma_f32_16x16x32_bf16 v[72:75], v[136:139], v[184:187], v[72:75]
	v_mfma_f32_16x16x32_bf16 v[124:127], v[132:135], v[164:167], v[124:127]
	v_mfma_f32_16x16x32_bf16 v[120:123], v[140:143], v[164:167], v[120:123]
	v_mfma_f32_16x16x32_bf16 v[112:115], v[132:135], v[172:175], v[112:115]
	v_mfma_f32_16x16x32_bf16 v[104:107], v[140:143], v[172:175], v[104:107]
	v_mfma_f32_16x16x32_bf16 v[96:99], v[132:135], v[180:183], v[96:99]
	v_mfma_f32_16x16x32_bf16 v[88:91], v[140:143], v[180:183], v[88:91]
	v_mfma_f32_16x16x32_bf16 v[80:83], v[132:135], v[188:191], v[80:83]
	v_mfma_f32_16x16x32_bf16 v[72:75], v[140:143], v[188:191], v[72:75]
	v_mfma_f32_16x16x32_bf16 v[116:119], v[144:147], v[160:163], v[116:119]
	v_mfma_f32_16x16x32_bf16 v[108:111], v[152:155], v[160:163], v[108:111]
	v_mfma_f32_16x16x32_bf16 v[100:103], v[144:147], v[168:171], v[100:103]
	v_mfma_f32_16x16x32_bf16 v[92:95], v[152:155], v[168:171], v[92:95]
	v_mfma_f32_16x16x32_bf16 v[84:87], v[144:147], v[176:179], v[84:87]
	v_mfma_f32_16x16x32_bf16 v[76:79], v[152:155], v[176:179], v[76:79]
	v_mfma_f32_16x16x32_bf16 v[68:71], v[144:147], v[184:187], v[68:71]
	v_mfma_f32_16x16x32_bf16 v[64:67], v[152:155], v[184:187], v[64:67]
	v_mfma_f32_16x16x32_bf16 v[116:119], v[148:151], v[164:167], v[116:119]
	v_mfma_f32_16x16x32_bf16 v[108:111], v[156:159], v[164:167], v[108:111]
	v_mfma_f32_16x16x32_bf16 v[100:103], v[148:151], v[172:175], v[100:103]
	v_mfma_f32_16x16x32_bf16 v[92:95], v[156:159], v[172:175], v[92:95]
	v_mfma_f32_16x16x32_bf16 v[84:87], v[148:151], v[180:183], v[84:87]
	v_mfma_f32_16x16x32_bf16 v[76:79], v[156:159], v[180:183], v[76:79]
	v_mfma_f32_16x16x32_bf16 v[68:71], v[148:151], v[188:191], v[68:71]
	v_mfma_f32_16x16x32_bf16 v[64:67], v[156:159], v[188:191], v[64:67]
	s_barrier
	s_add_i32 s67, s53, s28
	v_lshl_add_u64 v[192:193], s[42:43], 0, v[202:203]
	s_mov_b32 m0, s67
	ds_read_b128 v[160:163], v223 offset:16384
	ds_read_b128 v[164:167], v223 offset:17408
	ds_read_b128 v[168:171], v223 offset:18432
	ds_read_b128 v[172:175], v223 offset:19456
	ds_read_b128 v[176:179], v223 offset:20480
	ds_read_b128 v[180:183], v223 offset:21504
	ds_read_b128 v[184:187], v223 offset:22528
	ds_read_b128 v[188:191], v223 offset:23552
	global_load_lds_dwordx4 v[192:193], off
	s_add_i32 m0, s67, 0x2000
	s_add_u32 s68, s42, 0x80000
	v_lshl_add_u64 v[194:195], s[42:43], 0, v[206:207]
	s_addc_u32 s69, s43, 0
	s_add_i32 s67, s60, s28
	global_load_lds_dwordx4 v[194:195], off
	v_lshl_add_u64 v[196:197], s[68:69], 0, v[202:203]
	s_mov_b32 m0, s67
	v_lshl_add_u64 v[198:199], s[48:49], 0, v[204:205]
	global_load_lds_dwordx4 v[196:197], off
	v_lshl_add_u64 v[196:197], s[68:69], 0, v[206:207]
	s_add_i32 m0, s67, 0x2000
	s_nop 0
	global_load_lds_dwordx4 v[196:197], off
	v_lshl_add_u64 v[196:197], s[48:49], 0, v[200:201]
	s_mov_b32 m0, s29
	s_nop 0
	global_load_lds_dwordx4 v[196:197], off
	s_mov_b32 m0, s30
	s_nop 0
	global_load_lds_dwordx4 v[198:199], off
	s_waitcnt vmcnt(8)
	s_waitcnt lgkmcnt(0)
	s_barrier
; #define PG8_STAGE(bufoff, gbase, voff) do { _Pragma("unroll") for (int _i = 0; _i < 2; ++_i) \
;         __builtin_amdgcn_global_load_lds((const unsigned*)((const char*)(gbase) + (voff)[_i]), (LAS unsigned*)(lds + (bufoff) + ldsw + _i * 8192), 16, 0, 0); } while (0)
; #define PG8_LDA(dst, b, h) do { _Pragma("unroll") for (int m = 0; m < 4; ++m) _Pragma("unroll") for (int k = 0; k < 2; ++k) dst[m][k] = *(const LAS bf16x8*)(lds + PG8_SA(b, h) + aoff + m * 2048 + k * 1024); } while (0)
; #define PG8_LDB(dst, b, h) do { _Pragma("unroll") for (int n = 0; n < 2; ++n) _Pragma("unroll") for (int k = 0; k < 2; ++k) dst[n][k] = *(const LAS bf16x8*)(lds + PG8_SB(b, h) + boff + n * 2048 + k * 1024); } while (0)
; #define PG8_MMA(ai, bj, At, Bt) do { __builtin_amdgcn_s_setprio(1); _Pragma("unroll") for (int m = 0; m < 4; ++m) _Pragma("unroll") for (int n = 0; n < 2; ++n) _Pragma("unroll") for (int k = 0; k < 2; ++k) \
;         acc[ai][bj][m][n] = __builtin_amdgcn_mfma_f32_16x16x32_bf16(Bt[n][k], At[m][k], acc[ai][bj][m][n], 0, 0, 0); __builtin_amdgcn_s_setprio(0); } while (0)
; #define PG8_WAIT_V(n) asm volatile("s_waitcnt vmcnt(" #n ")" ::: "memory")
; #define PG8_WAIT_L(n) asm volatile("s_waitcnt lgkmcnt(" #n ")" ::: "memory")
; #define PG8_BAR __builtin_amdgcn_s_barrier()
; #define PG8_SCHED __builtin_amdgcn_sched_barrier(0)
; template <class Desc, class Epi>
; DI void gemm_phase(LAS unsigned char* lds, const Desc& D, const Epi& E, int wv) {
;     ...
;             PG8_WAIT_V(8); PG8_WAIT_L(0); PG8_BAR; PG8_MMA(1, 0, At, B0); PG8_MMA(1, 1, At, B1); PG8_BAR; PG8_SCHED;
;             PG8_LDB(B0, 1, 0); PG8_LDB(B1, 1, 1); PG8_SCHED; PG8_LDA(At, 1, 0); PG8_STAGE(PG8_SA(0, 1), a2 + hstepA, voffA);
;             PG8_WAIT_V(8); PG8_WAIT_L(0); PG8_BAR; PG8_MMA(0, 0, At, B0); PG8_MMA(0, 1, At, B1); PG8_BAR; PG8_SCHED;
	v_mfma_f32_16x16x32_bf16 v[60:63], v[128:131], v[160:163], v[60:63]
	v_mfma_f32_16x16x32_bf16 v[56:59], v[136:139], v[160:163], v[56:59]
	v_mfma_f32_16x16x32_bf16 v[48:51], v[128:131], v[168:171], v[48:51]
	v_mfma_f32_16x16x32_bf16 v[40:43], v[136:139], v[168:171], v[40:43]
	v_mfma_f32_16x16x32_bf16 v[32:35], v[128:131], v[176:179], v[32:35]
	v_mfma_f32_16x16x32_bf16 v[24:27], v[136:139], v[176:179], v[24:27]
	v_mfma_f32_16x16x32_bf16 v[16:19], v[128:131], v[184:187], v[16:19]
	v_mfma_f32_16x16x32_bf16 v[8:11], v[136:139], v[184:187], v[8:11]
	v_mfma_f32_16x16x32_bf16 v[60:63], v[132:135], v[164:167], v[60:63]
	v_mfma_f32_16x16x32_bf16 v[56:59], v[140:143], v[164:167], v[56:59]
	v_mfma_f32_16x16x32_bf16 v[48:51], v[132:135], v[172:175], v[48:51]
	v_mfma_f32_16x16x32_bf16 v[40:43], v[140:143], v[172:175], v[40:43]
	v_mfma_f32_16x16x32_bf16 v[32:35], v[132:135], v[180:183], v[32:35]
	v_mfma_f32_16x16x32_bf16 v[24:27], v[140:143], v[180:183], v[24:27]
	v_mfma_f32_16x16x32_bf16 v[16:19], v[132:135], v[188:191], v[16:19]
	v_mfma_f32_16x16x32_bf16 v[8:11], v[140:143], v[188:191], v[8:11]
	v_mfma_f32_16x16x32_bf16 v[52:55], v[144:147], v[160:163], v[52:55]
	v_mfma_f32_16x16x32_bf16 v[44:47], v[152:155], v[160:163], v[44:47]
	v_mfma_f32_16x16x32_bf16 v[36:39], v[144:147], v[168:171], v[36:39]
	v_mfma_f32_16x16x32_bf16 v[28:31], v[152:155], v[168:171], v[28:31]
	v_mfma_f32_16x16x32_bf16 v[20:23], v[144:147], v[176:179], v[20:23]
	v_mfma_f32_16x16x32_bf16 v[12:15], v[152:155], v[176:179], v[12:15]
	v_mfma_f32_16x16x32_bf16 v[4:7], v[144:147], v[184:187], v[4:7]
	v_mfma_f32_16x16x32_bf16 v[0:3], v[152:155], v[184:187], v[0:3]
	v_mfma_f32_16x16x32_bf16 v[52:55], v[148:151], v[164:167], v[52:55]
	v_mfma_f32_16x16x32_bf16 v[44:47], v[156:159], v[164:167], v[44:47]
	v_mfma_f32_16x16x32_bf16 v[36:39], v[148:151], v[172:175], v[36:39]
	v_mfma_f32_16x16x32_bf16 v[28:31], v[156:159], v[172:175], v[28:31]
	v_mfma_f32_16x16x32_bf16 v[20:23], v[148:151], v[180:183], v[20:23]
	v_mfma_f32_16x16x32_bf16 v[12:15], v[156:159], v[180:183], v[12:15]
	v_mfma_f32_16x16x32_bf16 v[4:7], v[148:151], v[188:191], v[4:7]
	v_mfma_f32_16x16x32_bf16 v[0:3], v[156:159], v[188:191], v[0:3]
	s_barrier
	s_add_i32 s67, 0, 0x18000
	s_add_i32 s68, 0, 0x1c000
	v_add_u32_e32 v140, s67, v220
	v_add_u32_e32 v156, s68, v220
	ds_read_b128 v[128:131], v140
	ds_read_b128 v[132:135], v140 offset:1024
	ds_read_b128 v[136:139], v140 offset:2048
	ds_read_b128 v[140:143], v140 offset:3072
	ds_read_b128 v[144:147], v156
	ds_read_b128 v[148:151], v156 offset:1024
	ds_read_b128 v[152:155], v156 offset:2048
	ds_read_b128 v[156:159], v156 offset:3072
	s_add_u32 s48, s48, 0x80000
	s_addc_u32 s49, s49, 0
	s_mov_b32 m0, s31
	v_lshl_add_u64 v[216:217], s[48:49], 0, v[200:201]
	ds_read_b128 v[160:163], v223 offset:32768
	ds_read_b128 v[164:167], v223 offset:33792
	ds_read_b128 v[168:171], v223 offset:34816
	ds_read_b128 v[172:175], v223 offset:35840
	ds_read_b128 v[176:179], v223 offset:36864
	ds_read_b128 v[180:183], v223 offset:37888
	ds_read_b128 v[184:187], v223 offset:38912
	ds_read_b128 v[188:191], v223 offset:39936
	global_load_lds_dwordx4 v[216:217], off
	v_lshl_add_u64 v[216:217], s[48:49], 0, v[204:205]
	s_mov_b32 m0, s34
	s_nop 0
	global_load_lds_dwordx4 v[216:217], off
	s_waitcnt vmcnt(8)
	s_waitcnt lgkmcnt(0)
	s_barrier
	v_mfma_f32_16x16x32_bf16 v[124:127], v[128:131], v[160:163], v[124:127]
	v_mfma_f32_16x16x32_bf16 v[120:123], v[136:139], v[160:163], v[120:123]
	v_mfma_f32_16x16x32_bf16 v[112:115], v[128:131], v[168:171], v[112:115]
	v_mfma_f32_16x16x32_bf16 v[104:107], v[136:139], v[168:171], v[104:107]
	v_mfma_f32_16x16x32_bf16 v[96:99], v[128:131], v[176:179], v[96:99]
	v_mfma_f32_16x16x32_bf16 v[88:91], v[136:139], v[176:179], v[88:91]
	v_mfma_f32_16x16x32_bf16 v[80:83], v[128:131], v[184:187], v[80:83]
	v_mfma_f32_16x16x32_bf16 v[72:75], v[136:139], v[184:187], v[72:75]
	v_mfma_f32_16x16x32_bf16 v[124:127], v[132:135], v[164:167], v[124:127]
	v_mfma_f32_16x16x32_bf16 v[120:123], v[140:143], v[164:167], v[120:123]
	v_mfma_f32_16x16x32_bf16 v[112:115], v[132:135], v[172:175], v[112:115]
	v_mfma_f32_16x16x32_bf16 v[104:107], v[140:143], v[172:175], v[104:107]
	v_mfma_f32_16x16x32_bf16 v[96:99], v[132:135], v[180:183], v[96:99]
	v_mfma_f32_16x16x32_bf16 v[88:91], v[140:143], v[180:183], v[88:91]
	v_mfma_f32_16x16x32_bf16 v[80:83], v[132:135], v[188:191], v[80:83]
	v_mfma_f32_16x16x32_bf16 v[72:75], v[140:143], v[188:191], v[72:75]
	v_mfma_f32_16x16x32_bf16 v[116:119], v[144:147], v[160:163], v[116:119]
	v_mfma_f32_16x16x32_bf16 v[108:111], v[152:155], v[160:163], v[108:111]
	v_mfma_f32_16x16x32_bf16 v[100:103], v[144:147], v[168:171], v[100:103]
	v_mfma_f32_16x16x32_bf16 v[92:95], v[152:155], v[168:171], v[92:95]
	v_mfma_f32_16x16x32_bf16 v[84:87], v[144:147], v[176:179], v[84:87]
	v_mfma_f32_16x16x32_bf16 v[76:79], v[152:155], v[176:179], v[76:79]
	v_mfma_f32_16x16x32_bf16 v[68:71], v[144:147], v[184:187], v[68:71]
	v_mfma_f32_16x16x32_bf16 v[64:67], v[152:155], v[184:187], v[64:67]
	v_mfma_f32_16x16x32_bf16 v[116:119], v[148:151], v[164:167], v[116:119]
	v_mfma_f32_16x16x32_bf16 v[108:111], v[156:159], v[164:167], v[108:111]
	v_mfma_f32_16x16x32_bf16 v[100:103], v[148:151], v[172:175], v[100:103]
	v_mfma_f32_16x16x32_bf16 v[92:95], v[156:159], v[172:175], v[92:95]
	v_mfma_f32_16x16x32_bf16 v[84:87], v[148:151], v[180:183], v[84:87]
	v_mfma_f32_16x16x32_bf16 v[76:79], v[156:159], v[180:183], v[76:79]
	v_mfma_f32_16x16x32_bf16 v[68:71], v[148:151], v[188:191], v[68:71]
	v_mfma_f32_16x16x32_bf16 v[64:67], v[156:159], v[188:191], v[64:67]
	s_barrier
; #define PG8_STAGE(bufoff, gbase, voff) do { _Pragma("unroll") for (int _i = 0; _i < 2; ++_i) \
;         __builtin_amdgcn_global_load_lds((const unsigned*)((const char*)(gbase) + (voff)[_i]), (LAS unsigned*)(lds + (bufoff) + ldsw + _i * 8192), 16, 0, 0); } while (0)
; #define PG8_LDA(dst, b, h) do { _Pragma("unroll") for (int m = 0; m < 4; ++m) _Pragma("unroll") for (int k = 0; k < 2; ++k) dst[m][k] = *(const LAS bf16x8*)(lds + PG8_SA(b, h) + aoff + m * 2048 + k * 1024); } while (0)
; #define PG8_MMA(ai, bj, At, Bt) do { __builtin_amdgcn_s_setprio(1); _Pragma("unroll") for (int m = 0; m < 4; ++m) _Pragma("unroll") for (int n = 0; n < 2; ++n) _Pragma("unroll") for (int k = 0; k < 2; ++k) \
;         acc[ai][bj][m][n] = __builtin_amdgcn_mfma_f32_16x16x32_bf16(Bt[n][k], At[m][k], acc[ai][bj][m][n], 0, 0, 0); __builtin_amdgcn_s_setprio(0); } while (0)
; #define PG8_WAIT_V(n) asm volatile("s_waitcnt vmcnt(" #n ")" ::: "memory")
; #define PG8_WAIT_L(n) asm volatile("s_waitcnt lgkmcnt(" #n ")" ::: "memory")
; #define PG8_BAR __builtin_amdgcn_s_barrier()
; #define PG8_SCHED __builtin_amdgcn_sched_barrier(0)
; template <class Desc, class Epi>
; DI void gemm_phase(LAS unsigned char* lds, const Desc& D, const Epi& E, int wv) {
;     ...
;         for (int t = 0; t < nt; t += 2) {
;     ...
;             PG8_LDA(At, 1, 1); PG8_STAGE(PG8_SB(1, 0), b3, voffB); PG8_STAGE(PG8_SB(1, 1), b3 + hstepB, voffB); PG8_STAGE(PG8_SA(1, 0), a3, voffA);
;             PG8_WAIT_V(8); PG8_WAIT_L(0); PG8_BAR; PG8_MMA(1, 0, At, B0); PG8_MMA(1, 1, At, B1); PG8_BAR; PG8_SCHED;
;         }
	s_add_i32 s48, s67, s28
	v_lshl_add_u64 v[192:193], v[192:193], 0, s[8:9]
	s_mov_b32 m0, s48
	ds_read_b128 v[160:163], v223 offset:49152
	ds_read_b128 v[164:167], v223 offset:50176
	ds_read_b128 v[168:171], v223 offset:51200
	ds_read_b128 v[172:175], v223 offset:52224
	ds_read_b128 v[176:179], v223 offset:53248
	ds_read_b128 v[180:183], v223 offset:54272
	ds_read_b128 v[184:187], v223 offset:55296
	ds_read_b128 v[188:191], v223 offset:56320
	global_load_lds_dwordx4 v[192:193], off
	s_add_i32 m0, s48, 0x2000
	s_add_u32 s42, s42, 0x80080
	v_lshl_add_u64 v[192:193], v[194:195], 0, s[8:9]
	s_addc_u32 s43, s43, 0
	s_add_i32 s48, s68, s28
	global_load_lds_dwordx4 v[192:193], off
	v_lshl_add_u64 v[192:193], s[42:43], 0, v[202:203]
	s_mov_b32 m0, s48
	s_nop 0
	global_load_lds_dwordx4 v[192:193], off
	v_lshl_add_u64 v[192:193], s[42:43], 0, v[206:207]
	s_add_i32 m0, s48, 0x2000
	s_nop 0
	global_load_lds_dwordx4 v[192:193], off
	v_lshl_add_u64 v[192:193], v[196:197], 0, s[8:9]
	s_mov_b32 m0, s50
	s_nop 0
	global_load_lds_dwordx4 v[192:193], off
	v_lshl_add_u64 v[192:193], v[198:199], 0, s[8:9]
	s_mov_b32 m0, s51
	s_nop 0
	global_load_lds_dwordx4 v[192:193], off
	s_waitcnt vmcnt(8)
	s_waitcnt lgkmcnt(0)
	s_barrier
	v_mfma_f32_16x16x32_bf16 v[60:63], v[128:131], v[160:163], v[60:63]
	v_mfma_f32_16x16x32_bf16 v[56:59], v[136:139], v[160:163], v[56:59]
	v_mfma_f32_16x16x32_bf16 v[48:51], v[128:131], v[168:171], v[48:51]
	v_mfma_f32_16x16x32_bf16 v[40:43], v[136:139], v[168:171], v[40:43]
	v_mfma_f32_16x16x32_bf16 v[32:35], v[128:131], v[176:179], v[32:35]
	v_mfma_f32_16x16x32_bf16 v[24:27], v[136:139], v[176:179], v[24:27]
	v_mfma_f32_16x16x32_bf16 v[16:19], v[128:131], v[184:187], v[16:19]
	v_mfma_f32_16x16x32_bf16 v[8:11], v[136:139], v[184:187], v[8:11]
	v_mfma_f32_16x16x32_bf16 v[60:63], v[132:135], v[164:167], v[60:63]
	v_mfma_f32_16x16x32_bf16 v[56:59], v[140:143], v[164:167], v[56:59]
	v_mfma_f32_16x16x32_bf16 v[48:51], v[132:135], v[172:175], v[48:51]
	v_mfma_f32_16x16x32_bf16 v[40:43], v[140:143], v[172:175], v[40:43]
	v_mfma_f32_16x16x32_bf16 v[32:35], v[132:135], v[180:183], v[32:35]
	v_mfma_f32_16x16x32_bf16 v[24:27], v[140:143], v[180:183], v[24:27]
	v_mfma_f32_16x16x32_bf16 v[16:19], v[132:135], v[188:191], v[16:19]
	v_mfma_f32_16x16x32_bf16 v[8:11], v[140:143], v[188:191], v[8:11]
	v_mfma_f32_16x16x32_bf16 v[52:55], v[144:147], v[160:163], v[52:55]
	v_mfma_f32_16x16x32_bf16 v[44:47], v[152:155], v[160:163], v[44:47]
	v_mfma_f32_16x16x32_bf16 v[36:39], v[144:147], v[168:171], v[36:39]
	v_mfma_f32_16x16x32_bf16 v[28:31], v[152:155], v[168:171], v[28:31]
	v_mfma_f32_16x16x32_bf16 v[20:23], v[144:147], v[176:179], v[20:23]
	v_mfma_f32_16x16x32_bf16 v[12:15], v[152:155], v[176:179], v[12:15]
	v_mfma_f32_16x16x32_bf16 v[4:7], v[144:147], v[184:187], v[4:7]
	v_mfma_f32_16x16x32_bf16 v[0:3], v[152:155], v[184:187], v[0:3]
	v_mfma_f32_16x16x32_bf16 v[52:55], v[148:151], v[164:167], v[52:55]
	v_mfma_f32_16x16x32_bf16 v[44:47], v[156:159], v[164:167], v[44:47]
	v_mfma_f32_16x16x32_bf16 v[36:39], v[148:151], v[172:175], v[36:39]
	v_mfma_f32_16x16x32_bf16 v[28:31], v[156:159], v[172:175], v[28:31]
	v_mfma_f32_16x16x32_bf16 v[20:23], v[148:151], v[180:183], v[20:23]
	v_mfma_f32_16x16x32_bf16 v[12:15], v[156:159], v[180:183], v[12:15]
	v_mfma_f32_16x16x32_bf16 v[4:7], v[148:151], v[188:191], v[4:7]
	v_mfma_f32_16x16x32_bf16 v[0:3], v[156:159], v[188:191], v[0:3]
	s_barrier
	s_add_i32 s66, s66, 2
	s_add_u32 s40, s40, 0x100
	s_addc_u32 s41, s41, 0
	s_add_u32 s19, s19, 0x100
	s_addc_u32 s21, s21, 0
	s_cmp_gt_u32 s66, 29
	s_cbranch_scc0 .LBB0_2088
	s_and_b64 vcc, exec, s[10:11]
	s_cbranch_vccz .LBB0_2091
	s_barrier

; #define PG8_STAGE(bufoff, gbase, voff) do { _Pragma("unroll") for (int _i = 0; _i < 2; ++_i) \
;         __builtin_amdgcn_global_load_lds((const unsigned*)((const char*)(gbase) + (voff)[_i]), (LAS unsigned*)(lds + (bufoff) + ldsw + _i * 8192), 16, 0, 0); } while (0)
; #define PG8_LDA(dst, b, h) do { _Pragma("unroll") for (int m = 0; m < 4; ++m) _Pragma("unroll") for (int k = 0; k < 2; ++k) dst[m][k] = *(const LAS bf16x8*)(lds + PG8_SA(b, h) + aoff + m * 2048 + k * 1024); } while (0)
; #define PG8_LDB(dst, b, h) do { _Pragma("unroll") for (int n = 0; n < 2; ++n) _Pragma("unroll") for (int k = 0; k < 2; ++k) dst[n][k] = *(const LAS bf16x8*)(lds + PG8_SB(b, h) + boff + n * 2048 + k * 1024); } while (0)
; #define PG8_MMA(ai, bj, At, Bt) do { __builtin_amdgcn_s_setprio(1); _Pragma("unroll") for (int m = 0; m < 4; ++m) _Pragma("unroll") for (int n = 0; n < 2; ++n) _Pragma("unroll") for (int k = 0; k < 2; ++k) \
;         acc[ai][bj][m][n] = __builtin_amdgcn_mfma_f32_16x16x32_bf16(Bt[n][k], At[m][k], acc[ai][bj][m][n], 0, 0, 0); __builtin_amdgcn_s_setprio(0); } while (0)
; #define PG8_WAIT_V(n) asm volatile("s_waitcnt vmcnt(" #n ")" ::: "memory")
; #define PG8_WAIT_L(n) asm volatile("s_waitcnt lgkmcnt(" #n ")" ::: "memory")
; #define PG8_BAR __builtin_amdgcn_s_barrier()
; #define PG8_SCHED __builtin_amdgcn_sched_barrier(0)
; template <class Desc, class Epi>
; DI void gemm_phase(LAS unsigned char* lds, const Desc& D, const Epi& E, int wv) {
;     ...
;             const bool last = (t == nt - 2);
;             const char* a1 = cA + (size_t)(t + 1) * kstep;
;             const char* a2 = last ? nA : cA + (size_t)(t + 2) * kstep; const char* b2 = last ? nB : cB + (size_t)(t + 2) * kstep;
;             const char* a3 = a2 + kstep; const char* b3 = b2 + kstep;
;             PG8_LDB(B0, 0, 0); PG8_LDB(B1, 0, 1); PG8_SCHED; PG8_LDA(At, 0, 0); PG8_STAGE(PG8_SA(1, 1), a1 + hstepA, voffA);
;             PG8_WAIT_V(8); PG8_WAIT_L(0); PG8_BAR; PG8_MMA(0, 0, At, B0); PG8_MMA(0, 1, At, B1); PG8_BAR; PG8_SCHED;
;             PG8_LDA(At, 0, 1); PG8_STAGE(PG8_SB(0, 0), b2, voffB); PG8_STAGE(PG8_SB(0, 1), b2 + hstepB, voffB); PG8_STAGE(PG8_SA(0, 0), a2, voffA);
;             PG8_WAIT_V(8); PG8_WAIT_L(0); PG8_BAR; PG8_MMA(1, 0, At, B0); PG8_MMA(1, 1, At, B1); PG8_BAR; PG8_SCHED;
.LBB0_2213:
	ds_read_b128 v[152:155], v149
	ds_read_b128 v[156:159], v149 offset:1024
	ds_read_b128 v[160:163], v149 offset:2048
	ds_read_b128 v[164:167], v149 offset:3072
	ds_read_b128 v[168:171], v150
	ds_read_b128 v[172:175], v150 offset:1024
	ds_read_b128 v[176:179], v150 offset:2048
	ds_read_b128 v[180:183], v150 offset:3072
	s_add_u32 s48, s42, 0xfff80080
	s_addc_u32 s49, s43, -1
	s_cmp_eq_u32 s41, 28
	s_cselect_b32 s51, s19, s49
	s_cselect_b32 s50, s18, s48
	s_cselect_b32 s49, s21, s25
	s_cselect_b32 s48, s20, s23
	v_lshl_add_u64 v[146:147], s[42:43], 0, v[138:139]
	s_add_i32 m0, s30, 0xc000
	ds_read_b128 v[184:187], v151
	ds_read_b128 v[188:191], v151 offset:1024
	ds_read_b128 v[192:195], v151 offset:2048
	ds_read_b128 v[196:199], v151 offset:3072
	ds_read_b128 v[200:203], v151 offset:4096
	ds_read_b128 v[204:207], v151 offset:5120
	ds_read_b128 v[208:211], v151 offset:6144
	ds_read_b128 v[212:215], v151 offset:7168
	global_load_lds_dwordx4 v[146:147], off
	v_lshl_add_u64 v[146:147], s[42:43], 0, v[140:141]
	s_add_i32 m0, s30, 0xe000
	s_nop 0
	global_load_lds_dwordx4 v[146:147], off
	s_waitcnt vmcnt(8)
	s_waitcnt lgkmcnt(0)
	s_barrier
	v_mfma_f32_16x16x32_bf16 v[124:127], v[152:155], v[184:187], v[124:127]
	v_mfma_f32_16x16x32_bf16 v[120:123], v[160:163], v[184:187], v[120:123]
	v_mfma_f32_16x16x32_bf16 v[108:111], v[152:155], v[192:195], v[108:111]
	v_mfma_f32_16x16x32_bf16 v[104:107], v[160:163], v[192:195], v[104:107]
	v_mfma_f32_16x16x32_bf16 v[92:95], v[152:155], v[200:203], v[92:95]
	v_mfma_f32_16x16x32_bf16 v[88:91], v[160:163], v[200:203], v[88:91]
	v_mfma_f32_16x16x32_bf16 v[76:79], v[152:155], v[208:211], v[76:79]
	v_mfma_f32_16x16x32_bf16 v[72:75], v[160:163], v[208:211], v[72:75]
	v_mfma_f32_16x16x32_bf16 v[124:127], v[156:159], v[188:191], v[124:127]
	v_mfma_f32_16x16x32_bf16 v[120:123], v[164:167], v[188:191], v[120:123]
	v_mfma_f32_16x16x32_bf16 v[108:111], v[156:159], v[196:199], v[108:111]
	v_mfma_f32_16x16x32_bf16 v[104:107], v[164:167], v[196:199], v[104:107]
	v_mfma_f32_16x16x32_bf16 v[92:95], v[156:159], v[204:207], v[92:95]
	v_mfma_f32_16x16x32_bf16 v[88:91], v[164:167], v[204:207], v[88:91]
	v_mfma_f32_16x16x32_bf16 v[76:79], v[156:159], v[212:215], v[76:79]
	v_mfma_f32_16x16x32_bf16 v[72:75], v[164:167], v[212:215], v[72:75]
	v_mfma_f32_16x16x32_bf16 v[116:119], v[168:171], v[184:187], v[116:119]
	v_mfma_f32_16x16x32_bf16 v[112:115], v[176:179], v[184:187], v[112:115]
	v_mfma_f32_16x16x32_bf16 v[100:103], v[168:171], v[192:195], v[100:103]
	v_mfma_f32_16x16x32_bf16 v[96:99], v[176:179], v[192:195], v[96:99]
	v_mfma_f32_16x16x32_bf16 v[84:87], v[168:171], v[200:203], v[84:87]
	v_mfma_f32_16x16x32_bf16 v[80:83], v[176:179], v[200:203], v[80:83]
	v_mfma_f32_16x16x32_bf16 v[68:71], v[168:171], v[208:211], v[68:71]
	v_mfma_f32_16x16x32_bf16 v[64:67], v[176:179], v[208:211], v[64:67]
	v_mfma_f32_16x16x32_bf16 v[116:119], v[172:175], v[188:191], v[116:119]
	v_mfma_f32_16x16x32_bf16 v[112:115], v[180:183], v[188:191], v[112:115]
	v_mfma_f32_16x16x32_bf16 v[100:103], v[172:175], v[196:199], v[100:103]
	v_mfma_f32_16x16x32_bf16 v[96:99], v[180:183], v[196:199], v[96:99]
	v_mfma_f32_16x16x32_bf16 v[84:87], v[172:175], v[204:207], v[84:87]
	v_mfma_f32_16x16x32_bf16 v[80:83], v[180:183], v[204:207], v[80:83]
	v_mfma_f32_16x16x32_bf16 v[68:71], v[172:175], v[212:215], v[68:71]
	v_mfma_f32_16x16x32_bf16 v[64:67], v[180:183], v[212:215], v[64:67]
	s_barrier
	s_add_i32 s67, s62, s28
	v_lshl_add_u64 v[146:147], s[48:49], 0, v[132:133]
	s_mov_b32 m0, s67
	ds_read_b128 v[184:187], v151 offset:16384
	ds_read_b128 v[188:191], v151 offset:17408
	ds_read_b128 v[192:195], v151 offset:18432
	ds_read_b128 v[196:199], v151 offset:19456
	ds_read_b128 v[200:203], v151 offset:20480
	ds_read_b128 v[204:207], v151 offset:21504
	ds_read_b128 v[208:211], v151 offset:22528
	ds_read_b128 v[212:215], v151 offset:23552
	global_load_lds_dwordx4 v[146:147], off
	s_add_i32 m0, s67, 0x2000
	s_add_u32 s68, s48, 0x80000
	v_lshl_add_u64 v[216:217], s[48:49], 0, v[128:129]
	s_addc_u32 s69, s49, 0
	s_add_i32 s67, s63, s28
	global_load_lds_dwordx4 v[216:217], off
	v_lshl_add_u64 v[218:219], s[68:69], 0, v[132:133]
	s_mov_b32 m0, s67
	v_lshl_add_u64 v[220:221], s[50:51], 0, v[130:131]
	global_load_lds_dwordx4 v[218:219], off
	v_lshl_add_u64 v[218:219], s[68:69], 0, v[128:129]
	s_add_i32 m0, s67, 0x2000
	s_nop 0
	global_load_lds_dwordx4 v[218:219], off
	v_lshl_add_u64 v[218:219], s[50:51], 0, v[134:135]
	s_mov_b32 m0, s30
	s_nop 0
	global_load_lds_dwordx4 v[218:219], off
	s_mov_b32 m0, s31
	s_nop 0
	global_load_lds_dwordx4 v[220:221], off
	s_waitcnt vmcnt(8)
	s_waitcnt lgkmcnt(0)
	s_barrier
; #define PG8_STAGE(bufoff, gbase, voff) do { _Pragma("unroll") for (int _i = 0; _i < 2; ++_i) \
;         __builtin_amdgcn_global_load_lds((const unsigned*)((const char*)(gbase) + (voff)[_i]), (LAS unsigned*)(lds + (bufoff) + ldsw + _i * 8192), 16, 0, 0); } while (0)
; #define PG8_LDA(dst, b, h) do { _Pragma("unroll") for (int m = 0; m < 4; ++m) _Pragma("unroll") for (int k = 0; k < 2; ++k) dst[m][k] = *(const LAS bf16x8*)(lds + PG8_SA(b, h) + aoff + m * 2048 + k * 1024); } while (0)
; #define PG8_LDB(dst, b, h) do { _Pragma("unroll") for (int n = 0; n < 2; ++n) _Pragma("unroll") for (int k = 0; k < 2; ++k) dst[n][k] = *(const LAS bf16x8*)(lds + PG8_SB(b, h) + boff + n * 2048 + k * 1024); } while (0)
; #define PG8_MMA(ai, bj, At, Bt) do { __builtin_amdgcn_s_setprio(1); _Pragma("unroll") for (int m = 0; m < 4; ++m) _Pragma("unroll") for (int n = 0; n < 2; ++n) _Pragma("unroll") for (int k = 0; k < 2; ++k) \
;         acc[ai][bj][m][n] = __builtin_amdgcn_mfma_f32_16x16x32_bf16(Bt[n][k], At[m][k], acc[ai][bj][m][n], 0, 0, 0); __builtin_amdgcn_s_setprio(0); } while (0)
; #define PG8_WAIT_V(n) asm volatile("s_waitcnt vmcnt(" #n ")" ::: "memory")
; #define PG8_WAIT_L(n) asm volatile("s_waitcnt lgkmcnt(" #n ")" ::: "memory")
; #define PG8_BAR __builtin_amdgcn_s_barrier()
; #define PG8_SCHED __builtin_amdgcn_sched_barrier(0)
; template <class Desc, class Epi>
; DI void gemm_phase(LAS unsigned char* lds, const Desc& D, const Epi& E, int wv) {
;     ...
;             PG8_WAIT_V(8); PG8_WAIT_L(0); PG8_BAR; PG8_MMA(1, 0, At, B0); PG8_MMA(1, 1, At, B1); PG8_BAR; PG8_SCHED;
;             PG8_LDB(B0, 1, 0); PG8_LDB(B1, 1, 1); PG8_SCHED; PG8_LDA(At, 1, 0); PG8_STAGE(PG8_SA(0, 1), a2 + hstepA, voffA);
;             PG8_WAIT_V(8); PG8_WAIT_L(0); PG8_BAR; PG8_MMA(0, 0, At, B0); PG8_MMA(0, 1, At, B1); PG8_BAR; PG8_SCHED;
	v_mfma_f32_16x16x32_bf16 v[60:63], v[152:155], v[184:187], v[60:63]
	v_mfma_f32_16x16x32_bf16 v[56:59], v[160:163], v[184:187], v[56:59]
	v_mfma_f32_16x16x32_bf16 v[44:47], v[152:155], v[192:195], v[44:47]
	v_mfma_f32_16x16x32_bf16 v[40:43], v[160:163], v[192:195], v[40:43]
	v_mfma_f32_16x16x32_bf16 v[28:31], v[152:155], v[200:203], v[28:31]
	v_mfma_f32_16x16x32_bf16 v[24:27], v[160:163], v[200:203], v[24:27]
	v_mfma_f32_16x16x32_bf16 v[12:15], v[152:155], v[208:211], v[12:15]
	v_mfma_f32_16x16x32_bf16 v[8:11], v[160:163], v[208:211], v[8:11]
	v_mfma_f32_16x16x32_bf16 v[60:63], v[156:159], v[188:191], v[60:63]
	v_mfma_f32_16x16x32_bf16 v[56:59], v[164:167], v[188:191], v[56:59]
	v_mfma_f32_16x16x32_bf16 v[44:47], v[156:159], v[196:199], v[44:47]
	v_mfma_f32_16x16x32_bf16 v[40:43], v[164:167], v[196:199], v[40:43]
	v_mfma_f32_16x16x32_bf16 v[28:31], v[156:159], v[204:207], v[28:31]
	v_mfma_f32_16x16x32_bf16 v[24:27], v[164:167], v[204:207], v[24:27]
	v_mfma_f32_16x16x32_bf16 v[12:15], v[156:159], v[212:215], v[12:15]
	v_mfma_f32_16x16x32_bf16 v[8:11], v[164:167], v[212:215], v[8:11]
	v_mfma_f32_16x16x32_bf16 v[52:55], v[168:171], v[184:187], v[52:55]
	v_mfma_f32_16x16x32_bf16 v[48:51], v[176:179], v[184:187], v[48:51]
	v_mfma_f32_16x16x32_bf16 v[36:39], v[168:171], v[192:195], v[36:39]
	v_mfma_f32_16x16x32_bf16 v[32:35], v[176:179], v[192:195], v[32:35]
	v_mfma_f32_16x16x32_bf16 v[20:23], v[168:171], v[200:203], v[20:23]
	v_mfma_f32_16x16x32_bf16 v[16:19], v[176:179], v[200:203], v[16:19]
	v_mfma_f32_16x16x32_bf16 v[4:7], v[168:171], v[208:211], v[4:7]
	v_mfma_f32_16x16x32_bf16 v[0:3], v[176:179], v[208:211], v[0:3]
	v_mfma_f32_16x16x32_bf16 v[52:55], v[172:175], v[188:191], v[52:55]
	v_mfma_f32_16x16x32_bf16 v[48:51], v[180:183], v[188:191], v[48:51]
	v_mfma_f32_16x16x32_bf16 v[36:39], v[172:175], v[196:199], v[36:39]
	v_mfma_f32_16x16x32_bf16 v[32:35], v[180:183], v[196:199], v[32:35]
	v_mfma_f32_16x16x32_bf16 v[20:23], v[172:175], v[204:207], v[20:23]
	v_mfma_f32_16x16x32_bf16 v[16:19], v[180:183], v[204:207], v[16:19]
	v_mfma_f32_16x16x32_bf16 v[4:7], v[172:175], v[212:215], v[4:7]
	v_mfma_f32_16x16x32_bf16 v[0:3], v[180:183], v[212:215], v[0:3]
	s_barrier
	s_add_i32 s67, 0, 0x18000
	v_add_u32_e32 v136, s67, v148
	s_add_i32 s68, 0, 0x1c000
	ds_read_b128 v[152:155], v136
	ds_read_b128 v[156:159], v136 offset:1024
	ds_read_b128 v[160:163], v136 offset:2048
	ds_read_b128 v[164:167], v136 offset:3072
	v_add_u32_e32 v136, s68, v148
	ds_read_b128 v[168:171], v136
	ds_read_b128 v[172:175], v136 offset:1024
	ds_read_b128 v[176:179], v136 offset:2048
	ds_read_b128 v[180:183], v136 offset:3072
	s_add_u32 s50, s50, 0x80000
	s_addc_u32 s51, s51, 0
	s_mov_b32 m0, s34
	v_lshl_add_u64 v[222:223], s[50:51], 0, v[134:135]
	ds_read_b128 v[184:187], v151 offset:32768
	ds_read_b128 v[188:191], v151 offset:33792
	ds_read_b128 v[192:195], v151 offset:34816
	ds_read_b128 v[196:199], v151 offset:35840
	ds_read_b128 v[200:203], v151 offset:36864
	ds_read_b128 v[204:207], v151 offset:37888
	ds_read_b128 v[208:211], v151 offset:38912
	ds_read_b128 v[212:215], v151 offset:39936
	global_load_lds_dwordx4 v[222:223], off
	v_lshl_add_u64 v[222:223], s[50:51], 0, v[130:131]
	s_mov_b32 m0, s35
	s_nop 0
	global_load_lds_dwordx4 v[222:223], off
	s_waitcnt vmcnt(8)
	s_waitcnt lgkmcnt(0)
	s_barrier
	v_mfma_f32_16x16x32_bf16 v[124:127], v[152:155], v[184:187], v[124:127]
	v_mfma_f32_16x16x32_bf16 v[120:123], v[160:163], v[184:187], v[120:123]
	v_mfma_f32_16x16x32_bf16 v[108:111], v[152:155], v[192:195], v[108:111]
	v_mfma_f32_16x16x32_bf16 v[104:107], v[160:163], v[192:195], v[104:107]
	v_mfma_f32_16x16x32_bf16 v[92:95], v[152:155], v[200:203], v[92:95]
	v_mfma_f32_16x16x32_bf16 v[88:91], v[160:163], v[200:203], v[88:91]
	v_mfma_f32_16x16x32_bf16 v[76:79], v[152:155], v[208:211], v[76:79]
	v_mfma_f32_16x16x32_bf16 v[72:75], v[160:163], v[208:211], v[72:75]
	v_mfma_f32_16x16x32_bf16 v[124:127], v[156:159], v[188:191], v[124:127]
	v_mfma_f32_16x16x32_bf16 v[120:123], v[164:167], v[188:191], v[120:123]
	v_mfma_f32_16x16x32_bf16 v[108:111], v[156:159], v[196:199], v[108:111]
	v_mfma_f32_16x16x32_bf16 v[104:107], v[164:167], v[196:199], v[104:107]
	v_mfma_f32_16x16x32_bf16 v[92:95], v[156:159], v[204:207], v[92:95]
	v_mfma_f32_16x16x32_bf16 v[88:91], v[164:167], v[204:207], v[88:91]
	v_mfma_f32_16x16x32_bf16 v[76:79], v[156:159], v[212:215], v[76:79]
	v_mfma_f32_16x16x32_bf16 v[72:75], v[164:167], v[212:215], v[72:75]
	v_mfma_f32_16x16x32_bf16 v[116:119], v[168:171], v[184:187], v[116:119]
	v_mfma_f32_16x16x32_bf16 v[112:115], v[176:179], v[184:187], v[112:115]
	v_mfma_f32_16x16x32_bf16 v[100:103], v[168:171], v[192:195], v[100:103]
	v_mfma_f32_16x16x32_bf16 v[96:99], v[176:179], v[192:195], v[96:99]
	v_mfma_f32_16x16x32_bf16 v[84:87], v[168:171], v[200:203], v[84:87]
	v_mfma_f32_16x16x32_bf16 v[80:83], v[176:179], v[200:203], v[80:83]
	v_mfma_f32_16x16x32_bf16 v[68:71], v[168:171], v[208:211], v[68:71]
	v_mfma_f32_16x16x32_bf16 v[64:67], v[176:179], v[208:211], v[64:67]
	v_mfma_f32_16x16x32_bf16 v[116:119], v[172:175], v[188:191], v[116:119]
	v_mfma_f32_16x16x32_bf16 v[112:115], v[180:183], v[188:191], v[112:115]
	v_mfma_f32_16x16x32_bf16 v[100:103], v[172:175], v[196:199], v[100:103]
	v_mfma_f32_16x16x32_bf16 v[96:99], v[180:183], v[196:199], v[96:99]
	v_mfma_f32_16x16x32_bf16 v[84:87], v[172:175], v[204:207], v[84:87]
	v_mfma_f32_16x16x32_bf16 v[80:83], v[180:183], v[204:207], v[80:83]
	v_mfma_f32_16x16x32_bf16 v[68:71], v[172:175], v[212:215], v[68:71]
	v_mfma_f32_16x16x32_bf16 v[64:67], v[180:183], v[212:215], v[64:67]
	s_barrier
; #define PG8_STAGE(bufoff, gbase, voff) do { _Pragma("unroll") for (int _i = 0; _i < 2; ++_i) \
;         __builtin_amdgcn_global_load_lds((const unsigned*)((const char*)(gbase) + (voff)[_i]), (LAS unsigned*)(lds + (bufoff) + ldsw + _i * 8192), 16, 0, 0); } while (0)
; #define PG8_LDA(dst, b, h) do { _Pragma("unroll") for (int m = 0; m < 4; ++m) _Pragma("unroll") for (int k = 0; k < 2; ++k) dst[m][k] = *(const LAS bf16x8*)(lds + PG8_SA(b, h) + aoff + m * 2048 + k * 1024); } while (0)
; #define PG8_MMA(ai, bj, At, Bt) do { __builtin_amdgcn_s_setprio(1); _Pragma("unroll") for (int m = 0; m < 4; ++m) _Pragma("unroll") for (int n = 0; n < 2; ++n) _Pragma("unroll") for (int k = 0; k < 2; ++k) \
;         acc[ai][bj][m][n] = __builtin_amdgcn_mfma_f32_16x16x32_bf16(Bt[n][k], At[m][k], acc[ai][bj][m][n], 0, 0, 0); __builtin_amdgcn_s_setprio(0); } while (0)
; #define PG8_WAIT_V(n) asm volatile("s_waitcnt vmcnt(" #n ")" ::: "memory")
; #define PG8_WAIT_L(n) asm volatile("s_waitcnt lgkmcnt(" #n ")" ::: "memory")
; #define PG8_BAR __builtin_amdgcn_s_barrier()
; #define PG8_SCHED __builtin_amdgcn_sched_barrier(0)
; template <class Desc, class Epi>
; DI void gemm_phase(LAS unsigned char* lds, const Desc& D, const Epi& E, int wv) {
;     ...
;         for (int t = 0; t < nt; t += 2) {
;     ...
;             PG8_LDA(At, 1, 1); PG8_STAGE(PG8_SB(1, 0), b3, voffB); PG8_STAGE(PG8_SB(1, 1), b3 + hstepB, voffB); PG8_STAGE(PG8_SA(1, 0), a3, voffA);
;             PG8_WAIT_V(8); PG8_WAIT_L(0); PG8_BAR; PG8_MMA(1, 0, At, B0); PG8_MMA(1, 1, At, B1); PG8_BAR; PG8_SCHED;
;         }
	s_add_i32 s50, s67, s28
	v_lshl_add_u64 v[146:147], v[146:147], 0, s[8:9]
	s_mov_b32 m0, s50
	ds_read_b128 v[184:187], v151 offset:49152
	ds_read_b128 v[188:191], v151 offset:50176
	ds_read_b128 v[192:195], v151 offset:51200
	ds_read_b128 v[196:199], v151 offset:52224
	ds_read_b128 v[200:203], v151 offset:53248
	ds_read_b128 v[204:207], v151 offset:54272
	ds_read_b128 v[208:211], v151 offset:55296
	ds_read_b128 v[212:215], v151 offset:56320
	global_load_lds_dwordx4 v[146:147], off
	s_add_i32 m0, s50, 0x2000
	s_add_u32 s48, s48, 0x80080
	v_lshl_add_u64 v[146:147], v[216:217], 0, s[8:9]
	s_addc_u32 s49, s49, 0
	s_add_i32 s50, s68, s28
	global_load_lds_dwordx4 v[146:147], off
	v_lshl_add_u64 v[146:147], s[48:49], 0, v[132:133]
	s_mov_b32 m0, s50
	s_nop 0
	global_load_lds_dwordx4 v[146:147], off
	v_lshl_add_u64 v[146:147], s[48:49], 0, v[128:129]
	s_add_i32 m0, s50, 0x2000
	s_nop 0
	global_load_lds_dwordx4 v[146:147], off
	v_lshl_add_u64 v[146:147], v[218:219], 0, s[8:9]
	s_mov_b32 m0, s53
	s_nop 0
	global_load_lds_dwordx4 v[146:147], off
	v_lshl_add_u64 v[146:147], v[220:221], 0, s[8:9]
	s_mov_b32 m0, s60
	s_nop 0
	global_load_lds_dwordx4 v[146:147], off
	s_waitcnt vmcnt(8)
	s_waitcnt lgkmcnt(0)
	s_barrier
	v_mfma_f32_16x16x32_bf16 v[60:63], v[152:155], v[184:187], v[60:63]
	v_mfma_f32_16x16x32_bf16 v[56:59], v[160:163], v[184:187], v[56:59]
	v_mfma_f32_16x16x32_bf16 v[44:47], v[152:155], v[192:195], v[44:47]
	v_mfma_f32_16x16x32_bf16 v[40:43], v[160:163], v[192:195], v[40:43]
	v_mfma_f32_16x16x32_bf16 v[28:31], v[152:155], v[200:203], v[28:31]
	v_mfma_f32_16x16x32_bf16 v[24:27], v[160:163], v[200:203], v[24:27]
	v_mfma_f32_16x16x32_bf16 v[12:15], v[152:155], v[208:211], v[12:15]
	v_mfma_f32_16x16x32_bf16 v[8:11], v[160:163], v[208:211], v[8:11]
	v_mfma_f32_16x16x32_bf16 v[60:63], v[156:159], v[188:191], v[60:63]
	v_mfma_f32_16x16x32_bf16 v[56:59], v[164:167], v[188:191], v[56:59]
	v_mfma_f32_16x16x32_bf16 v[44:47], v[156:159], v[196:199], v[44:47]
	v_mfma_f32_16x16x32_bf16 v[40:43], v[164:167], v[196:199], v[40:43]
	v_mfma_f32_16x16x32_bf16 v[28:31], v[156:159], v[204:207], v[28:31]
	v_mfma_f32_16x16x32_bf16 v[24:27], v[164:167], v[204:207], v[24:27]
	v_mfma_f32_16x16x32_bf16 v[12:15], v[156:159], v[212:215], v[12:15]
	v_mfma_f32_16x16x32_bf16 v[8:11], v[164:167], v[212:215], v[8:11]
	v_mfma_f32_16x16x32_bf16 v[52:55], v[168:171], v[184:187], v[52:55]
	v_mfma_f32_16x16x32_bf16 v[48:51], v[176:179], v[184:187], v[48:51]
	v_mfma_f32_16x16x32_bf16 v[36:39], v[168:171], v[192:195], v[36:39]
	v_mfma_f32_16x16x32_bf16 v[32:35], v[176:179], v[192:195], v[32:35]
	v_mfma_f32_16x16x32_bf16 v[20:23], v[168:171], v[200:203], v[20:23]
	v_mfma_f32_16x16x32_bf16 v[16:19], v[176:179], v[200:203], v[16:19]
	v_mfma_f32_16x16x32_bf16 v[4:7], v[168:171], v[208:211], v[4:7]
	v_mfma_f32_16x16x32_bf16 v[0:3], v[176:179], v[208:211], v[0:3]
	v_mfma_f32_16x16x32_bf16 v[52:55], v[172:175], v[188:191], v[52:55]
	v_mfma_f32_16x16x32_bf16 v[48:51], v[180:183], v[188:191], v[48:51]
	v_mfma_f32_16x16x32_bf16 v[36:39], v[172:175], v[196:199], v[36:39]
	v_mfma_f32_16x16x32_bf16 v[32:35], v[180:183], v[196:199], v[32:35]
	v_mfma_f32_16x16x32_bf16 v[20:23], v[172:175], v[204:207], v[20:23]
	v_mfma_f32_16x16x32_bf16 v[16:19], v[180:183], v[204:207], v[16:19]
	v_mfma_f32_16x16x32_bf16 v[4:7], v[172:175], v[212:215], v[4:7]
	v_mfma_f32_16x16x32_bf16 v[0:3], v[180:183], v[212:215], v[0:3]
	s_barrier
	s_add_i32 s41, s41, 2
	s_add_u32 s42, s42, 0x100
	s_addc_u32 s43, s43, 0
	s_add_u32 s23, s23, 0x100
	s_addc_u32 s25, s25, 0
	s_cmp_gt_u32 s41, 29
	s_cbranch_scc0 .LBB0_2213
	s_and_b64 vcc, exec, s[12:13]
	s_cbranch_vccz .LBB0_2216
	s_barrier

; #define PG8_STAGE(bufoff, gbase, voff) do { _Pragma("unroll") for (int _i = 0; _i < 2; ++_i) \
;         __builtin_amdgcn_global_load_lds((const unsigned*)((const char*)(gbase) + (voff)[_i]), (LAS unsigned*)(lds + (bufoff) + ldsw + _i * 8192), 16, 0, 0); } while (0)
; #define PG8_LDA(dst, b, h) do { _Pragma("unroll") for (int m = 0; m < 4; ++m) _Pragma("unroll") for (int k = 0; k < 2; ++k) dst[m][k] = *(const LAS bf16x8*)(lds + PG8_SA(b, h) + aoff + m * 2048 + k * 1024); } while (0)
; #define PG8_LDB(dst, b, h) do { _Pragma("unroll") for (int n = 0; n < 2; ++n) _Pragma("unroll") for (int k = 0; k < 2; ++k) dst[n][k] = *(const LAS bf16x8*)(lds + PG8_SB(b, h) + boff + n * 2048 + k * 1024); } while (0)
; #define PG8_MMA(ai, bj, At, Bt) do { __builtin_amdgcn_s_setprio(1); _Pragma("unroll") for (int m = 0; m < 4; ++m) _Pragma("unroll") for (int n = 0; n < 2; ++n) _Pragma("unroll") for (int k = 0; k < 2; ++k) \
;         acc[ai][bj][m][n] = __builtin_amdgcn_mfma_f32_16x16x32_bf16(Bt[n][k], At[m][k], acc[ai][bj][m][n], 0, 0, 0); __builtin_amdgcn_s_setprio(0); } while (0)
; #define PG8_WAIT_V(n) asm volatile("s_waitcnt vmcnt(" #n ")" ::: "memory")
; #define PG8_WAIT_L(n) asm volatile("s_waitcnt lgkmcnt(" #n ")" ::: "memory")
; #define PG8_BAR __builtin_amdgcn_s_barrier()
; #define PG8_SCHED __builtin_amdgcn_sched_barrier(0)
; template <class Desc, class Epi>
; DI void gemm_phase(LAS unsigned char* lds, const Desc& D, const Epi& E, int wv) {
;     ...
;             const bool last = (t == nt - 2);
;             const char* a1 = cA + (size_t)(t + 1) * kstep;
;             const char* a2 = last ? nA : cA + (size_t)(t + 2) * kstep; const char* b2 = last ? nB : cB + (size_t)(t + 2) * kstep;
;             const char* a3 = a2 + kstep; const char* b3 = b2 + kstep;
;             PG8_LDB(B0, 0, 0); PG8_LDB(B1, 0, 1); PG8_SCHED; PG8_LDA(At, 0, 0); PG8_STAGE(PG8_SA(1, 1), a1 + hstepA, voffA);
;             PG8_WAIT_V(8); PG8_WAIT_L(0); PG8_BAR; PG8_MMA(0, 0, At, B0); PG8_MMA(0, 1, At, B1); PG8_BAR; PG8_SCHED;
;             PG8_LDA(At, 0, 1); PG8_STAGE(PG8_SB(0, 0), b2, voffB); PG8_STAGE(PG8_SB(0, 1), b2 + hstepB, voffB); PG8_STAGE(PG8_SA(0, 0), a2, voffA);
;             PG8_WAIT_V(8); PG8_WAIT_L(0); PG8_BAR; PG8_MMA(1, 0, At, B0); PG8_MMA(1, 1, At, B1); PG8_BAR; PG8_SCHED;
.LBB0_2239:
	ds_read_b128 v[142:145], v151
	ds_read_b128 v[146:149], v151 offset:1024
	ds_read_b128 v[158:161], v151 offset:2048
	ds_read_b128 v[162:165], v151 offset:3072
	ds_read_b128 v[166:169], v152
	ds_read_b128 v[170:173], v152 offset:1024
	ds_read_b128 v[174:177], v152 offset:2048
	ds_read_b128 v[178:181], v152 offset:3072
	s_add_u32 s8, s6, 0xfffe0080
	s_addc_u32 s9, s7, -1
	s_cmp_eq_u32 s50, 4
	s_cselect_b32 s43, s25, s9
	s_cselect_b32 s42, s24, s8
	s_cselect_b32 s9, s41, s49
	s_cselect_b32 s8, s40, s48
	v_lshl_add_u64 v[214:215], s[6:7], 0, v[138:139]
	s_add_i32 m0, s3, 0xc000
	ds_read_b128 v[182:185], v153
	ds_read_b128 v[186:189], v153 offset:1024
	ds_read_b128 v[190:193], v153 offset:2048
	ds_read_b128 v[194:197], v153 offset:3072
	ds_read_b128 v[198:201], v153 offset:4096
	ds_read_b128 v[202:205], v153 offset:5120
	ds_read_b128 v[206:209], v153 offset:6144
	ds_read_b128 v[210:213], v153 offset:7168
	global_load_lds_dwordx4 v[214:215], off
	v_lshl_add_u64 v[214:215], s[6:7], 0, v[140:141]
	s_add_i32 m0, s3, 0xe000
	s_nop 0
	global_load_lds_dwordx4 v[214:215], off
	s_waitcnt vmcnt(8)
	s_waitcnt lgkmcnt(0)
	s_barrier
	v_mfma_f32_16x16x32_bf16 v[124:127], v[142:145], v[182:185], v[124:127]
	v_mfma_f32_16x16x32_bf16 v[120:123], v[158:161], v[182:185], v[120:123]
	v_mfma_f32_16x16x32_bf16 v[108:111], v[142:145], v[190:193], v[108:111]
	v_mfma_f32_16x16x32_bf16 v[104:107], v[158:161], v[190:193], v[104:107]
	v_mfma_f32_16x16x32_bf16 v[92:95], v[142:145], v[198:201], v[92:95]
	v_mfma_f32_16x16x32_bf16 v[88:91], v[158:161], v[198:201], v[88:91]
	v_mfma_f32_16x16x32_bf16 v[76:79], v[142:145], v[206:209], v[76:79]
	v_mfma_f32_16x16x32_bf16 v[72:75], v[158:161], v[206:209], v[72:75]
	v_mfma_f32_16x16x32_bf16 v[124:127], v[146:149], v[186:189], v[124:127]
	v_mfma_f32_16x16x32_bf16 v[120:123], v[162:165], v[186:189], v[120:123]
	v_mfma_f32_16x16x32_bf16 v[108:111], v[146:149], v[194:197], v[108:111]
	v_mfma_f32_16x16x32_bf16 v[104:107], v[162:165], v[194:197], v[104:107]
	v_mfma_f32_16x16x32_bf16 v[92:95], v[146:149], v[202:205], v[92:95]
	v_mfma_f32_16x16x32_bf16 v[88:91], v[162:165], v[202:205], v[88:91]
	v_mfma_f32_16x16x32_bf16 v[76:79], v[146:149], v[210:213], v[76:79]
	v_mfma_f32_16x16x32_bf16 v[72:75], v[162:165], v[210:213], v[72:75]
	v_mfma_f32_16x16x32_bf16 v[116:119], v[166:169], v[182:185], v[116:119]
	v_mfma_f32_16x16x32_bf16 v[112:115], v[174:177], v[182:185], v[112:115]
	v_mfma_f32_16x16x32_bf16 v[100:103], v[166:169], v[190:193], v[100:103]
	v_mfma_f32_16x16x32_bf16 v[96:99], v[174:177], v[190:193], v[96:99]
	v_mfma_f32_16x16x32_bf16 v[84:87], v[166:169], v[198:201], v[84:87]
	v_mfma_f32_16x16x32_bf16 v[80:83], v[174:177], v[198:201], v[80:83]
	v_mfma_f32_16x16x32_bf16 v[68:71], v[166:169], v[206:209], v[68:71]
	v_mfma_f32_16x16x32_bf16 v[64:67], v[174:177], v[206:209], v[64:67]
	v_mfma_f32_16x16x32_bf16 v[116:119], v[170:173], v[186:189], v[116:119]
	v_mfma_f32_16x16x32_bf16 v[112:115], v[178:181], v[186:189], v[112:115]
	v_mfma_f32_16x16x32_bf16 v[100:103], v[170:173], v[194:197], v[100:103]
	v_mfma_f32_16x16x32_bf16 v[96:99], v[178:181], v[194:197], v[96:99]
	v_mfma_f32_16x16x32_bf16 v[84:87], v[170:173], v[202:205], v[84:87]
	v_mfma_f32_16x16x32_bf16 v[80:83], v[178:181], v[202:205], v[80:83]
	v_mfma_f32_16x16x32_bf16 v[68:71], v[170:173], v[210:213], v[68:71]
	v_mfma_f32_16x16x32_bf16 v[64:67], v[178:181], v[210:213], v[64:67]
	s_barrier
	s_add_i32 s51, s47, s2
	v_lshl_add_u64 v[214:215], s[8:9], 0, v[130:131]
	s_mov_b32 m0, s51
	ds_read_b128 v[182:185], v153 offset:16384
	ds_read_b128 v[186:189], v153 offset:17408
	ds_read_b128 v[190:193], v153 offset:18432
	ds_read_b128 v[194:197], v153 offset:19456
	ds_read_b128 v[198:201], v153 offset:20480
	ds_read_b128 v[202:205], v153 offset:21504
	ds_read_b128 v[206:209], v153 offset:22528
	ds_read_b128 v[210:213], v153 offset:23552
	global_load_lds_dwordx4 v[214:215], off
	s_add_i32 m0, s51, 0x2000
	s_add_u32 s64, s8, 0x80000
	v_lshl_add_u64 v[216:217], s[8:9], 0, v[134:135]
	s_addc_u32 s65, s9, 0
	s_add_i32 s51, s52, s2
	global_load_lds_dwordx4 v[216:217], off
	v_lshl_add_u64 v[218:219], s[64:65], 0, v[130:131]
	s_mov_b32 m0, s51
	v_lshl_add_u64 v[220:221], s[42:43], 0, v[132:133]
	global_load_lds_dwordx4 v[218:219], off
	v_lshl_add_u64 v[218:219], s[64:65], 0, v[134:135]
	s_add_i32 m0, s51, 0x2000
	s_nop 0
	global_load_lds_dwordx4 v[218:219], off
	v_lshl_add_u64 v[218:219], s[42:43], 0, v[128:129]
	s_mov_b32 m0, s3
	s_nop 0
	global_load_lds_dwordx4 v[218:219], off
	s_mov_b32 m0, s28
	s_nop 0
	global_load_lds_dwordx4 v[220:221], off
	s_waitcnt vmcnt(8)
	s_waitcnt lgkmcnt(0)
	s_barrier
; #define PG8_STAGE(bufoff, gbase, voff) do { _Pragma("unroll") for (int _i = 0; _i < 2; ++_i) \
;         __builtin_amdgcn_global_load_lds((const unsigned*)((const char*)(gbase) + (voff)[_i]), (LAS unsigned*)(lds + (bufoff) + ldsw + _i * 8192), 16, 0, 0); } while (0)
; #define PG8_LDA(dst, b, h) do { _Pragma("unroll") for (int m = 0; m < 4; ++m) _Pragma("unroll") for (int k = 0; k < 2; ++k) dst[m][k] = *(const LAS bf16x8*)(lds + PG8_SA(b, h) + aoff + m * 2048 + k * 1024); } while (0)
; #define PG8_LDB(dst, b, h) do { _Pragma("unroll") for (int n = 0; n < 2; ++n) _Pragma("unroll") for (int k = 0; k < 2; ++k) dst[n][k] = *(const LAS bf16x8*)(lds + PG8_SB(b, h) + boff + n * 2048 + k * 1024); } while (0)
; #define PG8_MMA(ai, bj, At, Bt) do { __builtin_amdgcn_s_setprio(1); _Pragma("unroll") for (int m = 0; m < 4; ++m) _Pragma("unroll") for (int n = 0; n < 2; ++n) _Pragma("unroll") for (int k = 0; k < 2; ++k) \
;         acc[ai][bj][m][n] = __builtin_amdgcn_mfma_f32_16x16x32_bf16(Bt[n][k], At[m][k], acc[ai][bj][m][n], 0, 0, 0); __builtin_amdgcn_s_setprio(0); } while (0)
; #define PG8_WAIT_V(n) asm volatile("s_waitcnt vmcnt(" #n ")" ::: "memory")
; #define PG8_WAIT_L(n) asm volatile("s_waitcnt lgkmcnt(" #n ")" ::: "memory")
; #define PG8_BAR __builtin_amdgcn_s_barrier()
; #define PG8_SCHED __builtin_amdgcn_sched_barrier(0)
; template <class Desc, class Epi>
; DI void gemm_phase(LAS unsigned char* lds, const Desc& D, const Epi& E, int wv) {
;     ...
;             PG8_WAIT_V(8); PG8_WAIT_L(0); PG8_BAR; PG8_MMA(1, 0, At, B0); PG8_MMA(1, 1, At, B1); PG8_BAR; PG8_SCHED;
;             PG8_LDB(B0, 1, 0); PG8_LDB(B1, 1, 1); PG8_SCHED; PG8_LDA(At, 1, 0); PG8_STAGE(PG8_SA(0, 1), a2 + hstepA, voffA);
;             PG8_WAIT_V(8); PG8_WAIT_L(0); PG8_BAR; PG8_MMA(0, 0, At, B0); PG8_MMA(0, 1, At, B1); PG8_BAR; PG8_SCHED;
	v_mfma_f32_16x16x32_bf16 v[60:63], v[142:145], v[182:185], v[60:63]
	v_mfma_f32_16x16x32_bf16 v[56:59], v[158:161], v[182:185], v[56:59]
	v_mfma_f32_16x16x32_bf16 v[44:47], v[142:145], v[190:193], v[44:47]
	v_mfma_f32_16x16x32_bf16 v[40:43], v[158:161], v[190:193], v[40:43]
	v_mfma_f32_16x16x32_bf16 v[28:31], v[142:145], v[198:201], v[28:31]
	v_mfma_f32_16x16x32_bf16 v[24:27], v[158:161], v[198:201], v[24:27]
	v_mfma_f32_16x16x32_bf16 v[12:15], v[142:145], v[206:209], v[12:15]
	v_mfma_f32_16x16x32_bf16 v[8:11], v[158:161], v[206:209], v[8:11]
	v_mfma_f32_16x16x32_bf16 v[60:63], v[146:149], v[186:189], v[60:63]
	v_mfma_f32_16x16x32_bf16 v[56:59], v[162:165], v[186:189], v[56:59]
	v_mfma_f32_16x16x32_bf16 v[44:47], v[146:149], v[194:197], v[44:47]
	v_mfma_f32_16x16x32_bf16 v[40:43], v[162:165], v[194:197], v[40:43]
	v_mfma_f32_16x16x32_bf16 v[28:31], v[146:149], v[202:205], v[28:31]
	v_mfma_f32_16x16x32_bf16 v[24:27], v[162:165], v[202:205], v[24:27]
	v_mfma_f32_16x16x32_bf16 v[12:15], v[146:149], v[210:213], v[12:15]
	v_mfma_f32_16x16x32_bf16 v[8:11], v[162:165], v[210:213], v[8:11]
	v_mfma_f32_16x16x32_bf16 v[52:55], v[166:169], v[182:185], v[52:55]
	v_mfma_f32_16x16x32_bf16 v[48:51], v[174:177], v[182:185], v[48:51]
	v_mfma_f32_16x16x32_bf16 v[36:39], v[166:169], v[190:193], v[36:39]
	v_mfma_f32_16x16x32_bf16 v[32:35], v[174:177], v[190:193], v[32:35]
	v_mfma_f32_16x16x32_bf16 v[20:23], v[166:169], v[198:201], v[20:23]
	v_mfma_f32_16x16x32_bf16 v[16:19], v[174:177], v[198:201], v[16:19]
	v_mfma_f32_16x16x32_bf16 v[4:7], v[166:169], v[206:209], v[4:7]
	v_mfma_f32_16x16x32_bf16 v[0:3], v[174:177], v[206:209], v[0:3]
	v_mfma_f32_16x16x32_bf16 v[52:55], v[170:173], v[186:189], v[52:55]
	v_mfma_f32_16x16x32_bf16 v[48:51], v[178:181], v[186:189], v[48:51]
	v_mfma_f32_16x16x32_bf16 v[36:39], v[170:173], v[194:197], v[36:39]
	v_mfma_f32_16x16x32_bf16 v[32:35], v[178:181], v[194:197], v[32:35]
	v_mfma_f32_16x16x32_bf16 v[20:23], v[170:173], v[202:205], v[20:23]
	v_mfma_f32_16x16x32_bf16 v[16:19], v[178:181], v[202:205], v[16:19]
	v_mfma_f32_16x16x32_bf16 v[4:7], v[170:173], v[210:213], v[4:7]
	v_mfma_f32_16x16x32_bf16 v[0:3], v[178:181], v[210:213], v[0:3]
	s_barrier
	s_add_i32 s51, 0, 0x18000
	v_add_u32_e32 v136, s51, v150
	s_add_i32 s64, 0, 0x1c000
	ds_read_b128 v[142:145], v136
	ds_read_b128 v[146:149], v136 offset:1024
	ds_read_b128 v[158:161], v136 offset:2048
	ds_read_b128 v[162:165], v136 offset:3072
	v_add_u32_e32 v136, s64, v150
	ds_read_b128 v[166:169], v136
	ds_read_b128 v[170:173], v136 offset:1024
	ds_read_b128 v[174:177], v136 offset:2048
	ds_read_b128 v[178:181], v136 offset:3072
	s_add_u32 s42, s42, 0x20000
	s_addc_u32 s43, s43, 0
	s_mov_b32 m0, s29
	v_lshl_add_u64 v[222:223], s[42:43], 0, v[128:129]
	ds_read_b128 v[182:185], v153 offset:32768
	ds_read_b128 v[186:189], v153 offset:33792
	ds_read_b128 v[190:193], v153 offset:34816
	ds_read_b128 v[194:197], v153 offset:35840
	ds_read_b128 v[198:201], v153 offset:36864
	ds_read_b128 v[202:205], v153 offset:37888
	ds_read_b128 v[206:209], v153 offset:38912
	ds_read_b128 v[210:213], v153 offset:39936
	global_load_lds_dwordx4 v[222:223], off
	v_lshl_add_u64 v[222:223], s[42:43], 0, v[132:133]
	s_mov_b32 m0, s30
	s_nop 0
	global_load_lds_dwordx4 v[222:223], off
	s_waitcnt vmcnt(8)
	s_waitcnt lgkmcnt(0)
	s_barrier
	v_mfma_f32_16x16x32_bf16 v[124:127], v[142:145], v[182:185], v[124:127]
	v_mfma_f32_16x16x32_bf16 v[120:123], v[158:161], v[182:185], v[120:123]
	v_mfma_f32_16x16x32_bf16 v[108:111], v[142:145], v[190:193], v[108:111]
	v_mfma_f32_16x16x32_bf16 v[104:107], v[158:161], v[190:193], v[104:107]
	v_mfma_f32_16x16x32_bf16 v[92:95], v[142:145], v[198:201], v[92:95]
	v_mfma_f32_16x16x32_bf16 v[88:91], v[158:161], v[198:201], v[88:91]
	v_mfma_f32_16x16x32_bf16 v[76:79], v[142:145], v[206:209], v[76:79]
	v_mfma_f32_16x16x32_bf16 v[72:75], v[158:161], v[206:209], v[72:75]
	v_mfma_f32_16x16x32_bf16 v[124:127], v[146:149], v[186:189], v[124:127]
	v_mfma_f32_16x16x32_bf16 v[120:123], v[162:165], v[186:189], v[120:123]
	v_mfma_f32_16x16x32_bf16 v[108:111], v[146:149], v[194:197], v[108:111]
	v_mfma_f32_16x16x32_bf16 v[104:107], v[162:165], v[194:197], v[104:107]
	v_mfma_f32_16x16x32_bf16 v[92:95], v[146:149], v[202:205], v[92:95]
	v_mfma_f32_16x16x32_bf16 v[88:91], v[162:165], v[202:205], v[88:91]
	v_mfma_f32_16x16x32_bf16 v[76:79], v[146:149], v[210:213], v[76:79]
	v_mfma_f32_16x16x32_bf16 v[72:75], v[162:165], v[210:213], v[72:75]
	v_mfma_f32_16x16x32_bf16 v[116:119], v[166:169], v[182:185], v[116:119]
	v_mfma_f32_16x16x32_bf16 v[112:115], v[174:177], v[182:185], v[112:115]
	v_mfma_f32_16x16x32_bf16 v[100:103], v[166:169], v[190:193], v[100:103]
	v_mfma_f32_16x16x32_bf16 v[96:99], v[174:177], v[190:193], v[96:99]
	v_mfma_f32_16x16x32_bf16 v[84:87], v[166:169], v[198:201], v[84:87]
	v_mfma_f32_16x16x32_bf16 v[80:83], v[174:177], v[198:201], v[80:83]
	v_mfma_f32_16x16x32_bf16 v[68:71], v[166:169], v[206:209], v[68:71]
	v_mfma_f32_16x16x32_bf16 v[64:67], v[174:177], v[206:209], v[64:67]
	v_mfma_f32_16x16x32_bf16 v[116:119], v[170:173], v[186:189], v[116:119]
	v_mfma_f32_16x16x32_bf16 v[112:115], v[178:181], v[186:189], v[112:115]
	v_mfma_f32_16x16x32_bf16 v[100:103], v[170:173], v[194:197], v[100:103]
	v_mfma_f32_16x16x32_bf16 v[96:99], v[178:181], v[194:197], v[96:99]
	v_mfma_f32_16x16x32_bf16 v[84:87], v[170:173], v[202:205], v[84:87]
	v_mfma_f32_16x16x32_bf16 v[80:83], v[178:181], v[202:205], v[80:83]
	v_mfma_f32_16x16x32_bf16 v[68:71], v[170:173], v[210:213], v[68:71]
	v_mfma_f32_16x16x32_bf16 v[64:67], v[178:181], v[210:213], v[64:67]
	s_barrier
; #define PG8_STAGE(bufoff, gbase, voff) do { _Pragma("unroll") for (int _i = 0; _i < 2; ++_i) \
;         __builtin_amdgcn_global_load_lds((const unsigned*)((const char*)(gbase) + (voff)[_i]), (LAS unsigned*)(lds + (bufoff) + ldsw + _i * 8192), 16, 0, 0); } while (0)
; #define PG8_LDA(dst, b, h) do { _Pragma("unroll") for (int m = 0; m < 4; ++m) _Pragma("unroll") for (int k = 0; k < 2; ++k) dst[m][k] = *(const LAS bf16x8*)(lds + PG8_SA(b, h) + aoff + m * 2048 + k * 1024); } while (0)
; #define PG8_MMA(ai, bj, At, Bt) do { __builtin_amdgcn_s_setprio(1); _Pragma("unroll") for (int m = 0; m < 4; ++m) _Pragma("unroll") for (int n = 0; n < 2; ++n) _Pragma("unroll") for (int k = 0; k < 2; ++k) \
;         acc[ai][bj][m][n] = __builtin_amdgcn_mfma_f32_16x16x32_bf16(Bt[n][k], At[m][k], acc[ai][bj][m][n], 0, 0, 0); __builtin_amdgcn_s_setprio(0); } while (0)
; #define PG8_WAIT_V(n) asm volatile("s_waitcnt vmcnt(" #n ")" ::: "memory")
; #define PG8_WAIT_L(n) asm volatile("s_waitcnt lgkmcnt(" #n ")" ::: "memory")
; #define PG8_BAR __builtin_amdgcn_s_barrier()
; #define PG8_SCHED __builtin_amdgcn_sched_barrier(0)
; template <class Desc, class Epi>
; DI void gemm_phase(LAS unsigned char* lds, const Desc& D, const Epi& E, int wv) {
;     ...
;         for (int t = 0; t < nt; t += 2) {
;     ...
;             PG8_LDA(At, 1, 1); PG8_STAGE(PG8_SB(1, 0), b3, voffB); PG8_STAGE(PG8_SB(1, 1), b3 + hstepB, voffB); PG8_STAGE(PG8_SA(1, 0), a3, voffA);
;             PG8_WAIT_V(8); PG8_WAIT_L(0); PG8_BAR; PG8_MMA(1, 0, At, B0); PG8_MMA(1, 1, At, B1); PG8_BAR; PG8_SCHED;
;         }
	s_add_i32 s42, s51, s2
	v_lshl_add_u64 v[214:215], v[214:215], 0, s[14:15]
	s_mov_b32 m0, s42
	ds_read_b128 v[182:185], v153 offset:49152
	ds_read_b128 v[186:189], v153 offset:50176
	ds_read_b128 v[190:193], v153 offset:51200
	ds_read_b128 v[194:197], v153 offset:52224
	ds_read_b128 v[198:201], v153 offset:53248
	ds_read_b128 v[202:205], v153 offset:54272
	ds_read_b128 v[206:209], v153 offset:55296
	ds_read_b128 v[210:213], v153 offset:56320
	global_load_lds_dwordx4 v[214:215], off
	s_add_i32 m0, s42, 0x2000
	s_add_u32 s8, s8, 0x80080
	v_lshl_add_u64 v[214:215], v[216:217], 0, s[14:15]
	s_addc_u32 s9, s9, 0
	s_add_i32 s42, s64, s2
	global_load_lds_dwordx4 v[214:215], off
	v_lshl_add_u64 v[214:215], s[8:9], 0, v[130:131]
	s_mov_b32 m0, s42
	s_nop 0
	global_load_lds_dwordx4 v[214:215], off
	v_lshl_add_u64 v[214:215], s[8:9], 0, v[134:135]
	s_add_i32 m0, s42, 0x2000
	s_nop 0
	global_load_lds_dwordx4 v[214:215], off
	v_lshl_add_u64 v[214:215], v[218:219], 0, s[14:15]
	s_mov_b32 m0, s35
	s_nop 0
	global_load_lds_dwordx4 v[214:215], off
	v_lshl_add_u64 v[214:215], v[220:221], 0, s[14:15]
	s_mov_b32 m0, s46
	s_nop 0
	global_load_lds_dwordx4 v[214:215], off
	s_waitcnt vmcnt(8)
	s_waitcnt lgkmcnt(0)
	s_barrier
	v_mfma_f32_16x16x32_bf16 v[60:63], v[142:145], v[182:185], v[60:63]
	v_mfma_f32_16x16x32_bf16 v[56:59], v[158:161], v[182:185], v[56:59]
	v_mfma_f32_16x16x32_bf16 v[44:47], v[142:145], v[190:193], v[44:47]
	v_mfma_f32_16x16x32_bf16 v[40:43], v[158:161], v[190:193], v[40:43]
	v_mfma_f32_16x16x32_bf16 v[28:31], v[142:145], v[198:201], v[28:31]
	v_mfma_f32_16x16x32_bf16 v[24:27], v[158:161], v[198:201], v[24:27]
	v_mfma_f32_16x16x32_bf16 v[12:15], v[142:145], v[206:209], v[12:15]
	v_mfma_f32_16x16x32_bf16 v[8:11], v[158:161], v[206:209], v[8:11]
	v_mfma_f32_16x16x32_bf16 v[60:63], v[146:149], v[186:189], v[60:63]
	v_mfma_f32_16x16x32_bf16 v[56:59], v[162:165], v[186:189], v[56:59]
	v_mfma_f32_16x16x32_bf16 v[44:47], v[146:149], v[194:197], v[44:47]
	v_mfma_f32_16x16x32_bf16 v[40:43], v[162:165], v[194:197], v[40:43]
	v_mfma_f32_16x16x32_bf16 v[28:31], v[146:149], v[202:205], v[28:31]
	v_mfma_f32_16x16x32_bf16 v[24:27], v[162:165], v[202:205], v[24:27]
	v_mfma_f32_16x16x32_bf16 v[12:15], v[146:149], v[210:213], v[12:15]
	v_mfma_f32_16x16x32_bf16 v[8:11], v[162:165], v[210:213], v[8:11]
	v_mfma_f32_16x16x32_bf16 v[52:55], v[166:169], v[182:185], v[52:55]
	v_mfma_f32_16x16x32_bf16 v[48:51], v[174:177], v[182:185], v[48:51]
	v_mfma_f32_16x16x32_bf16 v[36:39], v[166:169], v[190:193], v[36:39]
	v_mfma_f32_16x16x32_bf16 v[32:35], v[174:177], v[190:193], v[32:35]
	v_mfma_f32_16x16x32_bf16 v[20:23], v[166:169], v[198:201], v[20:23]
	v_mfma_f32_16x16x32_bf16 v[16:19], v[174:177], v[198:201], v[16:19]
	v_mfma_f32_16x16x32_bf16 v[4:7], v[166:169], v[206:209], v[4:7]
	v_mfma_f32_16x16x32_bf16 v[0:3], v[174:177], v[206:209], v[0:3]
	v_mfma_f32_16x16x32_bf16 v[52:55], v[170:173], v[186:189], v[52:55]
	v_mfma_f32_16x16x32_bf16 v[48:51], v[178:181], v[186:189], v[48:51]
	v_mfma_f32_16x16x32_bf16 v[36:39], v[170:173], v[194:197], v[36:39]
	v_mfma_f32_16x16x32_bf16 v[32:35], v[178:181], v[194:197], v[32:35]
	v_mfma_f32_16x16x32_bf16 v[20:23], v[170:173], v[202:205], v[20:23]
	v_mfma_f32_16x16x32_bf16 v[16:19], v[178:181], v[202:205], v[16:19]
	v_mfma_f32_16x16x32_bf16 v[4:7], v[170:173], v[210:213], v[4:7]
	v_mfma_f32_16x16x32_bf16 v[0:3], v[178:181], v[210:213], v[0:3]
	s_barrier
	s_add_i32 s50, s50, 2
	s_add_u32 s6, s6, 0x100
	s_addc_u32 s7, s7, 0
	s_add_u32 s48, s48, 0x100
	s_addc_u32 s49, s49, 0
	s_cmp_gt_u32 s50, 5
	s_cbranch_scc0 .LBB0_2239
	s_and_b64 vcc, exec, s[18:19]
	s_cbranch_vccz .LBB0_2242
	s_barrier

; #define PG8_STAGE(bufoff, gbase, voff) do { _Pragma("unroll") for (int _i = 0; _i < 2; ++_i) \
;         __builtin_amdgcn_global_load_lds((const unsigned*)((const char*)(gbase) + (voff)[_i]), (LAS unsigned*)(lds + (bufoff) + ldsw + _i * 8192), 16, 0, 0); } while (0)
; #define PG8_LDA(dst, b, h) do { _Pragma("unroll") for (int m = 0; m < 4; ++m) _Pragma("unroll") for (int k = 0; k < 2; ++k) dst[m][k] = *(const LAS bf16x8*)(lds + PG8_SA(b, h) + aoff + m * 2048 + k * 1024); } while (0)
; #define PG8_LDB(dst, b, h) do { _Pragma("unroll") for (int n = 0; n < 2; ++n) _Pragma("unroll") for (int k = 0; k < 2; ++k) dst[n][k] = *(const LAS bf16x8*)(lds + PG8_SB(b, h) + boff + n * 2048 + k * 1024); } while (0)
; #define PG8_MMA(ai, bj, At, Bt) do { __builtin_amdgcn_s_setprio(1); _Pragma("unroll") for (int m = 0; m < 4; ++m) _Pragma("unroll") for (int n = 0; n < 2; ++n) _Pragma("unroll") for (int k = 0; k < 2; ++k) \
;         acc[ai][bj][m][n] = __builtin_amdgcn_mfma_f32_16x16x32_bf16(Bt[n][k], At[m][k], acc[ai][bj][m][n], 0, 0, 0); __builtin_amdgcn_s_setprio(0); } while (0)
; #define PG8_WAIT_V(n) asm volatile("s_waitcnt vmcnt(" #n ")" ::: "memory")
; #define PG8_WAIT_L(n) asm volatile("s_waitcnt lgkmcnt(" #n ")" ::: "memory")
; #define PG8_BAR __builtin_amdgcn_s_barrier()
; #define PG8_SCHED __builtin_amdgcn_sched_barrier(0)
; template <class Desc, class Epi>
; DI void gemm_phase(LAS unsigned char* lds, const Desc& D, const Epi& E, int wv) {
;     ...
;             const bool last = (t == nt - 2);
;             const char* a1 = cA + (size_t)(t + 1) * kstep;
;             const char* a2 = last ? nA : cA + (size_t)(t + 2) * kstep; const char* b2 = last ? nB : cB + (size_t)(t + 2) * kstep;
;             const char* a3 = a2 + kstep; const char* b3 = b2 + kstep;
;             PG8_LDB(B0, 0, 0); PG8_LDB(B1, 0, 1); PG8_SCHED; PG8_LDA(At, 0, 0); PG8_STAGE(PG8_SA(1, 1), a1 + hstepA, voffA);
;             PG8_WAIT_V(8); PG8_WAIT_L(0); PG8_BAR; PG8_MMA(0, 0, At, B0); PG8_MMA(0, 1, At, B1); PG8_BAR; PG8_SCHED;
;             PG8_LDA(At, 0, 1); PG8_STAGE(PG8_SB(0, 0), b2, voffB); PG8_STAGE(PG8_SB(0, 1), b2 + hstepB, voffB); PG8_STAGE(PG8_SA(0, 0), a2, voffA);
;             PG8_WAIT_V(8); PG8_WAIT_L(0); PG8_BAR; PG8_MMA(1, 0, At, B0); PG8_MMA(1, 1, At, B1); PG8_BAR; PG8_SCHED;
.LBB0_2480:
	ds_read_b128 v[128:131], v185
	ds_read_b128 v[132:135], v185 offset:1024
	ds_read_b128 v[150:153], v185 offset:2048
	ds_read_b128 v[154:157], v185 offset:3072
	ds_read_b128 v[158:161], v186
	ds_read_b128 v[162:165], v186 offset:1024
	ds_read_b128 v[166:169], v186 offset:2048
	ds_read_b128 v[170:173], v186 offset:3072
	s_add_u32 s42, s40, 0xfff00080
	s_addc_u32 s43, s41, -1
	s_cmp_eq_u32 s48, 28
	s_cselect_b32 s47, s17, s43
	s_cselect_b32 s46, s16, s42
	s_cselect_b32 s43, s19, s23
	s_cselect_b32 s42, s18, s5
	v_lshl_add_u64 v[182:183], s[40:41], 0, v[146:147]
	s_add_i32 m0, s3, 0xc000
	ds_read_b128 v[174:177], v187
	ds_read_b128 v[178:181], v187 offset:1024
	ds_read_b128 v[190:193], v187 offset:2048
	ds_read_b128 v[194:197], v187 offset:3072
	ds_read_b128 v[198:201], v187 offset:4096
	ds_read_b128 v[202:205], v187 offset:5120
	ds_read_b128 v[206:209], v187 offset:6144
	ds_read_b128 v[210:213], v187 offset:7168
	global_load_lds_dwordx4 v[182:183], off
	v_lshl_add_u64 v[182:183], s[40:41], 0, v[148:149]
	s_add_i32 m0, s3, 0xe000
	s_nop 0
	global_load_lds_dwordx4 v[182:183], off
	s_waitcnt vmcnt(8)
	s_waitcnt lgkmcnt(0)
	s_barrier
	v_mfma_f32_16x16x32_bf16 v[124:127], v[128:131], v[174:177], v[124:127]
	v_mfma_f32_16x16x32_bf16 v[120:123], v[150:153], v[174:177], v[120:123]
	v_mfma_f32_16x16x32_bf16 v[108:111], v[128:131], v[190:193], v[108:111]
	v_mfma_f32_16x16x32_bf16 v[104:107], v[150:153], v[190:193], v[104:107]
	v_mfma_f32_16x16x32_bf16 v[92:95], v[128:131], v[198:201], v[92:95]
	v_mfma_f32_16x16x32_bf16 v[88:91], v[150:153], v[198:201], v[88:91]
	v_mfma_f32_16x16x32_bf16 v[76:79], v[128:131], v[206:209], v[76:79]
	v_mfma_f32_16x16x32_bf16 v[72:75], v[150:153], v[206:209], v[72:75]
	v_mfma_f32_16x16x32_bf16 v[124:127], v[132:135], v[178:181], v[124:127]
	v_mfma_f32_16x16x32_bf16 v[120:123], v[154:157], v[178:181], v[120:123]
	v_mfma_f32_16x16x32_bf16 v[108:111], v[132:135], v[194:197], v[108:111]
	v_mfma_f32_16x16x32_bf16 v[104:107], v[154:157], v[194:197], v[104:107]
	v_mfma_f32_16x16x32_bf16 v[92:95], v[132:135], v[202:205], v[92:95]
	v_mfma_f32_16x16x32_bf16 v[88:91], v[154:157], v[202:205], v[88:91]
	v_mfma_f32_16x16x32_bf16 v[76:79], v[132:135], v[210:213], v[76:79]
	v_mfma_f32_16x16x32_bf16 v[72:75], v[154:157], v[210:213], v[72:75]
	v_mfma_f32_16x16x32_bf16 v[116:119], v[158:161], v[174:177], v[116:119]
	v_mfma_f32_16x16x32_bf16 v[112:115], v[166:169], v[174:177], v[112:115]
	v_mfma_f32_16x16x32_bf16 v[100:103], v[158:161], v[190:193], v[100:103]
	v_mfma_f32_16x16x32_bf16 v[96:99], v[166:169], v[190:193], v[96:99]
	v_mfma_f32_16x16x32_bf16 v[84:87], v[158:161], v[198:201], v[84:87]
	v_mfma_f32_16x16x32_bf16 v[80:83], v[166:169], v[198:201], v[80:83]
	v_mfma_f32_16x16x32_bf16 v[68:71], v[158:161], v[206:209], v[68:71]
	v_mfma_f32_16x16x32_bf16 v[64:67], v[166:169], v[206:209], v[64:67]
	v_mfma_f32_16x16x32_bf16 v[116:119], v[162:165], v[178:181], v[116:119]
	v_mfma_f32_16x16x32_bf16 v[112:115], v[170:173], v[178:181], v[112:115]
	v_mfma_f32_16x16x32_bf16 v[100:103], v[162:165], v[194:197], v[100:103]
	v_mfma_f32_16x16x32_bf16 v[96:99], v[170:173], v[194:197], v[96:99]
	v_mfma_f32_16x16x32_bf16 v[84:87], v[162:165], v[202:205], v[84:87]
	v_mfma_f32_16x16x32_bf16 v[80:83], v[170:173], v[202:205], v[80:83]
	v_mfma_f32_16x16x32_bf16 v[68:71], v[162:165], v[210:213], v[68:71]
	v_mfma_f32_16x16x32_bf16 v[64:67], v[170:173], v[210:213], v[64:67]
	s_barrier
	s_add_i32 s49, s52, s2
	v_lshl_add_u64 v[182:183], s[42:43], 0, v[140:141]
	s_mov_b32 m0, s49
	ds_read_b128 v[174:177], v187 offset:16384
	ds_read_b128 v[178:181], v187 offset:17408
	ds_read_b128 v[190:193], v187 offset:18432
	ds_read_b128 v[194:197], v187 offset:19456
	ds_read_b128 v[198:201], v187 offset:20480
	ds_read_b128 v[202:205], v187 offset:21504
	ds_read_b128 v[206:209], v187 offset:22528
	ds_read_b128 v[210:213], v187 offset:23552
	global_load_lds_dwordx4 v[182:183], off
	s_add_i32 m0, s49, 0x2000
	s_add_u32 s62, s42, 0x100000
	v_lshl_add_u64 v[214:215], s[42:43], 0, v[136:137]
	s_addc_u32 s63, s43, 0
	s_add_i32 s49, s53, s2
	global_load_lds_dwordx4 v[214:215], off
	v_lshl_add_u64 v[216:217], s[62:63], 0, v[140:141]
	s_mov_b32 m0, s49
	v_lshl_add_u64 v[218:219], s[46:47], 0, v[138:139]
	global_load_lds_dwordx4 v[216:217], off
	v_lshl_add_u64 v[216:217], s[62:63], 0, v[136:137]
	s_add_i32 m0, s49, 0x2000
	s_nop 0
	global_load_lds_dwordx4 v[216:217], off
	v_lshl_add_u64 v[216:217], s[46:47], 0, v[142:143]
	s_mov_b32 m0, s3
	s_nop 0
	global_load_lds_dwordx4 v[216:217], off
	s_mov_b32 m0, s28
	s_nop 0
	global_load_lds_dwordx4 v[218:219], off
	s_waitcnt vmcnt(8)
	s_waitcnt lgkmcnt(0)
	s_barrier
; #define PG8_STAGE(bufoff, gbase, voff) do { _Pragma("unroll") for (int _i = 0; _i < 2; ++_i) \
;         __builtin_amdgcn_global_load_lds((const unsigned*)((const char*)(gbase) + (voff)[_i]), (LAS unsigned*)(lds + (bufoff) + ldsw + _i * 8192), 16, 0, 0); } while (0)
; #define PG8_LDA(dst, b, h) do { _Pragma("unroll") for (int m = 0; m < 4; ++m) _Pragma("unroll") for (int k = 0; k < 2; ++k) dst[m][k] = *(const LAS bf16x8*)(lds + PG8_SA(b, h) + aoff + m * 2048 + k * 1024); } while (0)
; #define PG8_LDB(dst, b, h) do { _Pragma("unroll") for (int n = 0; n < 2; ++n) _Pragma("unroll") for (int k = 0; k < 2; ++k) dst[n][k] = *(const LAS bf16x8*)(lds + PG8_SB(b, h) + boff + n * 2048 + k * 1024); } while (0)
; #define PG8_MMA(ai, bj, At, Bt) do { __builtin_amdgcn_s_setprio(1); _Pragma("unroll") for (int m = 0; m < 4; ++m) _Pragma("unroll") for (int n = 0; n < 2; ++n) _Pragma("unroll") for (int k = 0; k < 2; ++k) \
;         acc[ai][bj][m][n] = __builtin_amdgcn_mfma_f32_16x16x32_bf16(Bt[n][k], At[m][k], acc[ai][bj][m][n], 0, 0, 0); __builtin_amdgcn_s_setprio(0); } while (0)
; #define PG8_WAIT_V(n) asm volatile("s_waitcnt vmcnt(" #n ")" ::: "memory")
; #define PG8_WAIT_L(n) asm volatile("s_waitcnt lgkmcnt(" #n ")" ::: "memory")
; #define PG8_BAR __builtin_amdgcn_s_barrier()
; #define PG8_SCHED __builtin_amdgcn_sched_barrier(0)
; template <class Desc, class Epi>
; DI void gemm_phase(LAS unsigned char* lds, const Desc& D, const Epi& E, int wv) {
;     ...
;             PG8_WAIT_V(8); PG8_WAIT_L(0); PG8_BAR; PG8_MMA(1, 0, At, B0); PG8_MMA(1, 1, At, B1); PG8_BAR; PG8_SCHED;
;             PG8_LDB(B0, 1, 0); PG8_LDB(B1, 1, 1); PG8_SCHED; PG8_LDA(At, 1, 0); PG8_STAGE(PG8_SA(0, 1), a2 + hstepA, voffA);
;             PG8_WAIT_V(8); PG8_WAIT_L(0); PG8_BAR; PG8_MMA(0, 0, At, B0); PG8_MMA(0, 1, At, B1); PG8_BAR; PG8_SCHED;
	v_mfma_f32_16x16x32_bf16 v[60:63], v[128:131], v[174:177], v[60:63]
	v_mfma_f32_16x16x32_bf16 v[56:59], v[150:153], v[174:177], v[56:59]
	v_mfma_f32_16x16x32_bf16 v[44:47], v[128:131], v[190:193], v[44:47]
	v_mfma_f32_16x16x32_bf16 v[40:43], v[150:153], v[190:193], v[40:43]
	v_mfma_f32_16x16x32_bf16 v[28:31], v[128:131], v[198:201], v[28:31]
	v_mfma_f32_16x16x32_bf16 v[24:27], v[150:153], v[198:201], v[24:27]
	v_mfma_f32_16x16x32_bf16 v[12:15], v[128:131], v[206:209], v[12:15]
	v_mfma_f32_16x16x32_bf16 v[8:11], v[150:153], v[206:209], v[8:11]
	v_mfma_f32_16x16x32_bf16 v[60:63], v[132:135], v[178:181], v[60:63]
	v_mfma_f32_16x16x32_bf16 v[56:59], v[154:157], v[178:181], v[56:59]
	v_mfma_f32_16x16x32_bf16 v[44:47], v[132:135], v[194:197], v[44:47]
	v_mfma_f32_16x16x32_bf16 v[40:43], v[154:157], v[194:197], v[40:43]
	v_mfma_f32_16x16x32_bf16 v[28:31], v[132:135], v[202:205], v[28:31]
	v_mfma_f32_16x16x32_bf16 v[24:27], v[154:157], v[202:205], v[24:27]
	v_mfma_f32_16x16x32_bf16 v[12:15], v[132:135], v[210:213], v[12:15]
	v_mfma_f32_16x16x32_bf16 v[8:11], v[154:157], v[210:213], v[8:11]
	v_mfma_f32_16x16x32_bf16 v[52:55], v[158:161], v[174:177], v[52:55]
	v_mfma_f32_16x16x32_bf16 v[48:51], v[166:169], v[174:177], v[48:51]
	v_mfma_f32_16x16x32_bf16 v[36:39], v[158:161], v[190:193], v[36:39]
	v_mfma_f32_16x16x32_bf16 v[32:35], v[166:169], v[190:193], v[32:35]
	v_mfma_f32_16x16x32_bf16 v[20:23], v[158:161], v[198:201], v[20:23]
	v_mfma_f32_16x16x32_bf16 v[16:19], v[166:169], v[198:201], v[16:19]
	v_mfma_f32_16x16x32_bf16 v[4:7], v[158:161], v[206:209], v[4:7]
	v_mfma_f32_16x16x32_bf16 v[0:3], v[166:169], v[206:209], v[0:3]
	v_mfma_f32_16x16x32_bf16 v[52:55], v[162:165], v[178:181], v[52:55]
	v_mfma_f32_16x16x32_bf16 v[48:51], v[170:173], v[178:181], v[48:51]
	v_mfma_f32_16x16x32_bf16 v[36:39], v[162:165], v[194:197], v[36:39]
	v_mfma_f32_16x16x32_bf16 v[32:35], v[170:173], v[194:197], v[32:35]
	v_mfma_f32_16x16x32_bf16 v[20:23], v[162:165], v[202:205], v[20:23]
	v_mfma_f32_16x16x32_bf16 v[16:19], v[170:173], v[202:205], v[16:19]
	v_mfma_f32_16x16x32_bf16 v[4:7], v[162:165], v[210:213], v[4:7]
	v_mfma_f32_16x16x32_bf16 v[0:3], v[170:173], v[210:213], v[0:3]
	s_barrier
	s_add_i32 s49, 0, 0x18000
	v_add_u32_e32 v144, s49, v184
	s_add_i32 s61, 0, 0x1c000
	ds_read_b128 v[128:131], v144
	ds_read_b128 v[132:135], v144 offset:1024
	ds_read_b128 v[150:153], v144 offset:2048
	ds_read_b128 v[154:157], v144 offset:3072
	v_add_u32_e32 v144, s61, v184
	ds_read_b128 v[158:161], v144
	ds_read_b128 v[162:165], v144 offset:1024
	ds_read_b128 v[166:169], v144 offset:2048
	ds_read_b128 v[170:173], v144 offset:3072
	s_add_u32 s46, s46, 0x100000
	s_addc_u32 s47, s47, 0
	s_mov_b32 m0, s29
	v_lshl_add_u64 v[220:221], s[46:47], 0, v[142:143]
	ds_read_b128 v[174:177], v187 offset:32768
	ds_read_b128 v[178:181], v187 offset:33792
	ds_read_b128 v[190:193], v187 offset:34816
	ds_read_b128 v[194:197], v187 offset:35840
	ds_read_b128 v[198:201], v187 offset:36864
	ds_read_b128 v[202:205], v187 offset:37888
	ds_read_b128 v[206:209], v187 offset:38912
	ds_read_b128 v[210:213], v187 offset:39936
	global_load_lds_dwordx4 v[220:221], off
	v_lshl_add_u64 v[220:221], s[46:47], 0, v[138:139]
	s_mov_b32 m0, s30
	s_nop 0
	global_load_lds_dwordx4 v[220:221], off
	s_waitcnt vmcnt(8)
	s_waitcnt lgkmcnt(0)
	s_barrier
	v_mfma_f32_16x16x32_bf16 v[124:127], v[128:131], v[174:177], v[124:127]
	v_mfma_f32_16x16x32_bf16 v[120:123], v[150:153], v[174:177], v[120:123]
	v_mfma_f32_16x16x32_bf16 v[108:111], v[128:131], v[190:193], v[108:111]
	v_mfma_f32_16x16x32_bf16 v[104:107], v[150:153], v[190:193], v[104:107]
	v_mfma_f32_16x16x32_bf16 v[92:95], v[128:131], v[198:201], v[92:95]
	v_mfma_f32_16x16x32_bf16 v[88:91], v[150:153], v[198:201], v[88:91]
	v_mfma_f32_16x16x32_bf16 v[76:79], v[128:131], v[206:209], v[76:79]
	v_mfma_f32_16x16x32_bf16 v[72:75], v[150:153], v[206:209], v[72:75]
	v_mfma_f32_16x16x32_bf16 v[124:127], v[132:135], v[178:181], v[124:127]
	v_mfma_f32_16x16x32_bf16 v[120:123], v[154:157], v[178:181], v[120:123]
	v_mfma_f32_16x16x32_bf16 v[108:111], v[132:135], v[194:197], v[108:111]
	v_mfma_f32_16x16x32_bf16 v[104:107], v[154:157], v[194:197], v[104:107]
	v_mfma_f32_16x16x32_bf16 v[92:95], v[132:135], v[202:205], v[92:95]
	v_mfma_f32_16x16x32_bf16 v[88:91], v[154:157], v[202:205], v[88:91]
	v_mfma_f32_16x16x32_bf16 v[76:79], v[132:135], v[210:213], v[76:79]
	v_mfma_f32_16x16x32_bf16 v[72:75], v[154:157], v[210:213], v[72:75]
	v_mfma_f32_16x16x32_bf16 v[116:119], v[158:161], v[174:177], v[116:119]
	v_mfma_f32_16x16x32_bf16 v[112:115], v[166:169], v[174:177], v[112:115]
	v_mfma_f32_16x16x32_bf16 v[100:103], v[158:161], v[190:193], v[100:103]
	v_mfma_f32_16x16x32_bf16 v[96:99], v[166:169], v[190:193], v[96:99]
	v_mfma_f32_16x16x32_bf16 v[84:87], v[158:161], v[198:201], v[84:87]
	v_mfma_f32_16x16x32_bf16 v[80:83], v[166:169], v[198:201], v[80:83]
	v_mfma_f32_16x16x32_bf16 v[68:71], v[158:161], v[206:209], v[68:71]
	v_mfma_f32_16x16x32_bf16 v[64:67], v[166:169], v[206:209], v[64:67]
	v_mfma_f32_16x16x32_bf16 v[116:119], v[162:165], v[178:181], v[116:119]
	v_mfma_f32_16x16x32_bf16 v[112:115], v[170:173], v[178:181], v[112:115]
	v_mfma_f32_16x16x32_bf16 v[100:103], v[162:165], v[194:197], v[100:103]
	v_mfma_f32_16x16x32_bf16 v[96:99], v[170:173], v[194:197], v[96:99]
	v_mfma_f32_16x16x32_bf16 v[84:87], v[162:165], v[202:205], v[84:87]
	v_mfma_f32_16x16x32_bf16 v[80:83], v[170:173], v[202:205], v[80:83]
	v_mfma_f32_16x16x32_bf16 v[68:71], v[162:165], v[210:213], v[68:71]
	v_mfma_f32_16x16x32_bf16 v[64:67], v[170:173], v[210:213], v[64:67]
	s_barrier
; #define PG8_STAGE(bufoff, gbase, voff) do { _Pragma("unroll") for (int _i = 0; _i < 2; ++_i) \
;         __builtin_amdgcn_global_load_lds((const unsigned*)((const char*)(gbase) + (voff)[_i]), (LAS unsigned*)(lds + (bufoff) + ldsw + _i * 8192), 16, 0, 0); } while (0)
; #define PG8_LDA(dst, b, h) do { _Pragma("unroll") for (int m = 0; m < 4; ++m) _Pragma("unroll") for (int k = 0; k < 2; ++k) dst[m][k] = *(const LAS bf16x8*)(lds + PG8_SA(b, h) + aoff + m * 2048 + k * 1024); } while (0)
; #define PG8_MMA(ai, bj, At, Bt) do { __builtin_amdgcn_s_setprio(1); _Pragma("unroll") for (int m = 0; m < 4; ++m) _Pragma("unroll") for (int n = 0; n < 2; ++n) _Pragma("unroll") for (int k = 0; k < 2; ++k) \
;         acc[ai][bj][m][n] = __builtin_amdgcn_mfma_f32_16x16x32_bf16(Bt[n][k], At[m][k], acc[ai][bj][m][n], 0, 0, 0); __builtin_amdgcn_s_setprio(0); } while (0)
; #define PG8_WAIT_V(n) asm volatile("s_waitcnt vmcnt(" #n ")" ::: "memory")
; #define PG8_WAIT_L(n) asm volatile("s_waitcnt lgkmcnt(" #n ")" ::: "memory")
; #define PG8_BAR __builtin_amdgcn_s_barrier()
; #define PG8_SCHED __builtin_amdgcn_sched_barrier(0)
; template <class Desc, class Epi>
; DI void gemm_phase(LAS unsigned char* lds, const Desc& D, const Epi& E, int wv) {
;     ...
;             PG8_LDA(At, 1, 1); PG8_STAGE(PG8_SB(1, 0), b3, voffB); PG8_STAGE(PG8_SB(1, 1), b3 + hstepB, voffB); PG8_STAGE(PG8_SA(1, 0), a3, voffA);
;             PG8_WAIT_V(8); PG8_WAIT_L(0); PG8_BAR; PG8_MMA(1, 0, At, B0); PG8_MMA(1, 1, At, B1); PG8_BAR; PG8_SCHED;
;         }
;         if (wr == 0) PG8_BAR;
	s_add_i32 s46, s49, s2
	v_lshl_add_u64 v[182:183], v[182:183], 0, s[12:13]
	s_mov_b32 m0, s46
	ds_read_b128 v[174:177], v187 offset:49152
	ds_read_b128 v[178:181], v187 offset:50176
	ds_read_b128 v[190:193], v187 offset:51200
	ds_read_b128 v[194:197], v187 offset:52224
	ds_read_b128 v[198:201], v187 offset:53248
	ds_read_b128 v[202:205], v187 offset:54272
	ds_read_b128 v[206:209], v187 offset:55296
	ds_read_b128 v[210:213], v187 offset:56320
	global_load_lds_dwordx4 v[182:183], off
	s_add_i32 m0, s46, 0x2000
	s_add_u32 s42, s42, 0x100080
	v_lshl_add_u64 v[182:183], v[214:215], 0, s[12:13]
	s_addc_u32 s43, s43, 0
	s_add_i32 s46, s61, s2
	global_load_lds_dwordx4 v[182:183], off
	v_lshl_add_u64 v[182:183], s[42:43], 0, v[140:141]
	s_mov_b32 m0, s46
	s_nop 0
	global_load_lds_dwordx4 v[182:183], off
	v_lshl_add_u64 v[182:183], s[42:43], 0, v[136:137]
	s_add_i32 m0, s46, 0x2000
	s_nop 0
	global_load_lds_dwordx4 v[182:183], off
	v_lshl_add_u64 v[182:183], v[216:217], 0, s[12:13]
	s_mov_b32 m0, s50
	s_nop 0
	global_load_lds_dwordx4 v[182:183], off
	v_lshl_add_u64 v[182:183], v[218:219], 0, s[12:13]
	s_mov_b32 m0, s51
	s_nop 0
	global_load_lds_dwordx4 v[182:183], off
	s_waitcnt vmcnt(8)
	s_waitcnt lgkmcnt(0)
	s_barrier
	v_mfma_f32_16x16x32_bf16 v[60:63], v[128:131], v[174:177], v[60:63]
	v_mfma_f32_16x16x32_bf16 v[56:59], v[150:153], v[174:177], v[56:59]
	v_mfma_f32_16x16x32_bf16 v[44:47], v[128:131], v[190:193], v[44:47]
	v_mfma_f32_16x16x32_bf16 v[40:43], v[150:153], v[190:193], v[40:43]
	v_mfma_f32_16x16x32_bf16 v[28:31], v[128:131], v[198:201], v[28:31]
	v_mfma_f32_16x16x32_bf16 v[24:27], v[150:153], v[198:201], v[24:27]
	v_mfma_f32_16x16x32_bf16 v[12:15], v[128:131], v[206:209], v[12:15]
	v_mfma_f32_16x16x32_bf16 v[8:11], v[150:153], v[206:209], v[8:11]
	v_mfma_f32_16x16x32_bf16 v[60:63], v[132:135], v[178:181], v[60:63]
	v_mfma_f32_16x16x32_bf16 v[56:59], v[154:157], v[178:181], v[56:59]
	v_mfma_f32_16x16x32_bf16 v[44:47], v[132:135], v[194:197], v[44:47]
	v_mfma_f32_16x16x32_bf16 v[40:43], v[154:157], v[194:197], v[40:43]
	v_mfma_f32_16x16x32_bf16 v[28:31], v[132:135], v[202:205], v[28:31]
	v_mfma_f32_16x16x32_bf16 v[24:27], v[154:157], v[202:205], v[24:27]
	v_mfma_f32_16x16x32_bf16 v[12:15], v[132:135], v[210:213], v[12:15]
	v_mfma_f32_16x16x32_bf16 v[8:11], v[154:157], v[210:213], v[8:11]
	v_mfma_f32_16x16x32_bf16 v[52:55], v[158:161], v[174:177], v[52:55]
	v_mfma_f32_16x16x32_bf16 v[48:51], v[166:169], v[174:177], v[48:51]
	v_mfma_f32_16x16x32_bf16 v[36:39], v[158:161], v[190:193], v[36:39]
	v_mfma_f32_16x16x32_bf16 v[32:35], v[166:169], v[190:193], v[32:35]
	v_mfma_f32_16x16x32_bf16 v[20:23], v[158:161], v[198:201], v[20:23]
	v_mfma_f32_16x16x32_bf16 v[16:19], v[166:169], v[198:201], v[16:19]
	v_mfma_f32_16x16x32_bf16 v[4:7], v[158:161], v[206:209], v[4:7]
	v_mfma_f32_16x16x32_bf16 v[0:3], v[166:169], v[206:209], v[0:3]
	v_mfma_f32_16x16x32_bf16 v[52:55], v[162:165], v[178:181], v[52:55]
	v_mfma_f32_16x16x32_bf16 v[48:51], v[170:173], v[178:181], v[48:51]
	v_mfma_f32_16x16x32_bf16 v[36:39], v[162:165], v[194:197], v[36:39]
	v_mfma_f32_16x16x32_bf16 v[32:35], v[170:173], v[194:197], v[32:35]
	v_mfma_f32_16x16x32_bf16 v[20:23], v[162:165], v[202:205], v[20:23]
	v_mfma_f32_16x16x32_bf16 v[16:19], v[170:173], v[202:205], v[16:19]
	v_mfma_f32_16x16x32_bf16 v[4:7], v[162:165], v[210:213], v[4:7]
	v_mfma_f32_16x16x32_bf16 v[0:3], v[170:173], v[210:213], v[0:3]
	s_barrier
	s_add_i32 s48, s48, 2
	s_add_u32 s40, s40, 0x100
	s_addc_u32 s41, s41, 0
	s_add_u32 s5, s5, 0x100
	s_addc_u32 s23, s23, 0
	s_cmp_gt_u32 s48, 29
	s_cbranch_scc0 .LBB0_2480
	s_and_b64 vcc, exec, s[14:15]
	s_cbranch_vccz .LBB0_2483
	s_barrier

; #define PG8_STAGE(bufoff, gbase, voff) do { _Pragma("unroll") for (int _i = 0; _i < 2; ++_i) \
;         __builtin_amdgcn_global_load_lds((const unsigned*)((const char*)(gbase) + (voff)[_i]), (LAS unsigned*)(lds + (bufoff) + ldsw + _i * 8192), 16, 0, 0); } while (0)
; #define PG8_LDA(dst, b, h) do { _Pragma("unroll") for (int m = 0; m < 4; ++m) _Pragma("unroll") for (int k = 0; k < 2; ++k) dst[m][k] = *(const LAS bf16x8*)(lds + PG8_SA(b, h) + aoff + m * 2048 + k * 1024); } while (0)
; #define PG8_LDB(dst, b, h) do { _Pragma("unroll") for (int n = 0; n < 2; ++n) _Pragma("unroll") for (int k = 0; k < 2; ++k) dst[n][k] = *(const LAS bf16x8*)(lds + PG8_SB(b, h) + boff + n * 2048 + k * 1024); } while (0)
; #define PG8_MMA(ai, bj, At, Bt) do { __builtin_amdgcn_s_setprio(1); _Pragma("unroll") for (int m = 0; m < 4; ++m) _Pragma("unroll") for (int n = 0; n < 2; ++n) _Pragma("unroll") for (int k = 0; k < 2; ++k) \
;         acc[ai][bj][m][n] = __builtin_amdgcn_mfma_f32_16x16x32_bf16(Bt[n][k], At[m][k], acc[ai][bj][m][n], 0, 0, 0); __builtin_amdgcn_s_setprio(0); } while (0)
; #define PG8_WAIT_V(n) asm volatile("s_waitcnt vmcnt(" #n ")" ::: "memory")
; #define PG8_WAIT_L(n) asm volatile("s_waitcnt lgkmcnt(" #n ")" ::: "memory")
; #define PG8_BAR __builtin_amdgcn_s_barrier()
; #define PG8_SCHED __builtin_amdgcn_sched_barrier(0)
; template <class Desc, class Epi>
; DI void gemm_phase(LAS unsigned char* lds, const Desc& D, const Epi& E, int wv) {
;     ...
;             PG8_LDB(B0, 0, 0); PG8_LDB(B1, 0, 1); PG8_SCHED; PG8_LDA(At, 0, 0); PG8_STAGE(PG8_SA(1, 1), a1 + hstepA, voffA);
;             PG8_WAIT_V(8); PG8_WAIT_L(0); PG8_BAR; PG8_MMA(0, 0, At, B0); PG8_MMA(0, 1, At, B1); PG8_BAR; PG8_SCHED;
;             PG8_LDA(At, 0, 1); PG8_STAGE(PG8_SB(0, 0), b2, voffB); PG8_STAGE(PG8_SB(0, 1), b2 + hstepB, voffB); PG8_STAGE(PG8_SA(0, 0), a2, voffA);
;             PG8_WAIT_V(8); PG8_WAIT_L(0); PG8_BAR; PG8_MMA(1, 0, At, B0); PG8_MMA(1, 1, At, B1); PG8_BAR; PG8_SCHED;
.LBB0_2706:
	ds_read_b128 v[128:131], v205
	ds_read_b128 v[132:135], v205 offset:1024
	ds_read_b128 v[136:139], v205 offset:2048
	ds_read_b128 v[140:143], v205 offset:3072
	ds_read_b128 v[144:147], v206
	ds_read_b128 v[148:151], v206 offset:1024
	ds_read_b128 v[152:155], v206 offset:2048
	ds_read_b128 v[156:159], v206 offset:3072
	s_add_u32 s34, s24, 0xfff80080
	s_addc_u32 s35, s25, -1
	s_cmp_eq_u32 s66, 28
	s_cselect_b32 s41, s15, s35
	s_cselect_b32 s40, s14, s34
	s_cselect_b32 s35, s17, s21
	s_cselect_b32 s34, s16, s19
	v_lshl_add_u64 v[212:213], s[24:25], 0, v[192:193]
	s_add_i32 m0, s30, 0xc000
	ds_read_b128 v[160:163], v207
	ds_read_b128 v[164:167], v207 offset:1024
	ds_read_b128 v[168:171], v207 offset:2048
	ds_read_b128 v[172:175], v207 offset:3072
	ds_read_b128 v[176:179], v207 offset:4096
	ds_read_b128 v[180:183], v207 offset:5120
	ds_read_b128 v[200:203], v207 offset:6144
	ds_read_b128 v[208:211], v207 offset:7168
	global_load_lds_dwordx4 v[212:213], off
	v_lshl_add_u64 v[212:213], s[24:25], 0, v[194:195]
	s_add_i32 m0, s30, 0xe000
	s_nop 0
	global_load_lds_dwordx4 v[212:213], off
	s_waitcnt vmcnt(8)
	s_waitcnt lgkmcnt(0)
	s_barrier
	v_mfma_f32_16x16x32_bf16 v[124:127], v[128:131], v[160:163], v[124:127]
	v_mfma_f32_16x16x32_bf16 v[120:123], v[136:139], v[160:163], v[120:123]
	v_mfma_f32_16x16x32_bf16 v[112:115], v[128:131], v[168:171], v[112:115]
	v_mfma_f32_16x16x32_bf16 v[104:107], v[136:139], v[168:171], v[104:107]
	v_mfma_f32_16x16x32_bf16 v[96:99], v[128:131], v[176:179], v[96:99]
	v_mfma_f32_16x16x32_bf16 v[88:91], v[136:139], v[176:179], v[88:91]
	v_mfma_f32_16x16x32_bf16 v[80:83], v[128:131], v[200:203], v[80:83]
	v_mfma_f32_16x16x32_bf16 v[72:75], v[136:139], v[200:203], v[72:75]
	v_mfma_f32_16x16x32_bf16 v[124:127], v[132:135], v[164:167], v[124:127]
	v_mfma_f32_16x16x32_bf16 v[120:123], v[140:143], v[164:167], v[120:123]
	v_mfma_f32_16x16x32_bf16 v[112:115], v[132:135], v[172:175], v[112:115]
	v_mfma_f32_16x16x32_bf16 v[104:107], v[140:143], v[172:175], v[104:107]
	v_mfma_f32_16x16x32_bf16 v[96:99], v[132:135], v[180:183], v[96:99]
	v_mfma_f32_16x16x32_bf16 v[88:91], v[140:143], v[180:183], v[88:91]
	v_mfma_f32_16x16x32_bf16 v[80:83], v[132:135], v[208:211], v[80:83]
	v_mfma_f32_16x16x32_bf16 v[72:75], v[140:143], v[208:211], v[72:75]
	v_mfma_f32_16x16x32_bf16 v[116:119], v[144:147], v[160:163], v[116:119]
	v_mfma_f32_16x16x32_bf16 v[108:111], v[152:155], v[160:163], v[108:111]
	v_mfma_f32_16x16x32_bf16 v[100:103], v[144:147], v[168:171], v[100:103]
	v_mfma_f32_16x16x32_bf16 v[92:95], v[152:155], v[168:171], v[92:95]
	v_mfma_f32_16x16x32_bf16 v[84:87], v[144:147], v[176:179], v[84:87]
	v_mfma_f32_16x16x32_bf16 v[76:79], v[152:155], v[176:179], v[76:79]
	v_mfma_f32_16x16x32_bf16 v[68:71], v[144:147], v[200:203], v[68:71]
	v_mfma_f32_16x16x32_bf16 v[64:67], v[152:155], v[200:203], v[64:67]
	v_mfma_f32_16x16x32_bf16 v[116:119], v[148:151], v[164:167], v[116:119]
	v_mfma_f32_16x16x32_bf16 v[108:111], v[156:159], v[164:167], v[108:111]
	v_mfma_f32_16x16x32_bf16 v[100:103], v[148:151], v[172:175], v[100:103]
	v_mfma_f32_16x16x32_bf16 v[92:95], v[156:159], v[172:175], v[92:95]
	v_mfma_f32_16x16x32_bf16 v[84:87], v[148:151], v[180:183], v[84:87]
	v_mfma_f32_16x16x32_bf16 v[76:79], v[156:159], v[180:183], v[76:79]
	v_mfma_f32_16x16x32_bf16 v[68:71], v[148:151], v[208:211], v[68:71]
	v_mfma_f32_16x16x32_bf16 v[64:67], v[156:159], v[208:211], v[64:67]
	s_barrier
	s_add_i32 s67, s52, s28
	v_lshl_add_u64 v[212:213], s[34:35], 0, v[188:189]
	s_mov_b32 m0, s67
	ds_read_b128 v[160:163], v207 offset:16384
	ds_read_b128 v[164:167], v207 offset:17408
	ds_read_b128 v[168:171], v207 offset:18432
	ds_read_b128 v[172:175], v207 offset:19456
	ds_read_b128 v[176:179], v207 offset:20480
	ds_read_b128 v[180:183], v207 offset:21504
	ds_read_b128 v[200:203], v207 offset:22528
	ds_read_b128 v[208:211], v207 offset:23552
	global_load_lds_dwordx4 v[212:213], off
	s_add_i32 m0, s67, 0x2000
	s_add_u32 s68, s34, 0x80000
	v_lshl_add_u64 v[214:215], s[34:35], 0, v[184:185]
	s_addc_u32 s69, s35, 0
	s_add_i32 s67, s53, s28
	global_load_lds_dwordx4 v[214:215], off
	v_lshl_add_u64 v[216:217], s[68:69], 0, v[188:189]
	s_mov_b32 m0, s67
	v_lshl_add_u64 v[218:219], s[40:41], 0, v[186:187]
	global_load_lds_dwordx4 v[216:217], off
	v_lshl_add_u64 v[216:217], s[68:69], 0, v[184:185]
	s_add_i32 m0, s67, 0x2000
	s_nop 0
	global_load_lds_dwordx4 v[216:217], off
	v_lshl_add_u64 v[216:217], s[40:41], 0, v[190:191]
	s_mov_b32 m0, s30
	s_nop 0
	global_load_lds_dwordx4 v[216:217], off
	s_mov_b32 m0, s31
	s_nop 0
	global_load_lds_dwordx4 v[218:219], off
	s_waitcnt vmcnt(8)
	s_waitcnt lgkmcnt(0)
	s_barrier
; #define PG8_STAGE(bufoff, gbase, voff) do { _Pragma("unroll") for (int _i = 0; _i < 2; ++_i) \
;         __builtin_amdgcn_global_load_lds((const unsigned*)((const char*)(gbase) + (voff)[_i]), (LAS unsigned*)(lds + (bufoff) + ldsw + _i * 8192), 16, 0, 0); } while (0)
; #define PG8_LDA(dst, b, h) do { _Pragma("unroll") for (int m = 0; m < 4; ++m) _Pragma("unroll") for (int k = 0; k < 2; ++k) dst[m][k] = *(const LAS bf16x8*)(lds + PG8_SA(b, h) + aoff + m * 2048 + k * 1024); } while (0)
; #define PG8_LDB(dst, b, h) do { _Pragma("unroll") for (int n = 0; n < 2; ++n) _Pragma("unroll") for (int k = 0; k < 2; ++k) dst[n][k] = *(const LAS bf16x8*)(lds + PG8_SB(b, h) + boff + n * 2048 + k * 1024); } while (0)
; #define PG8_MMA(ai, bj, At, Bt) do { __builtin_amdgcn_s_setprio(1); _Pragma("unroll") for (int m = 0; m < 4; ++m) _Pragma("unroll") for (int n = 0; n < 2; ++n) _Pragma("unroll") for (int k = 0; k < 2; ++k) \
;         acc[ai][bj][m][n] = __builtin_amdgcn_mfma_f32_16x16x32_bf16(Bt[n][k], At[m][k], acc[ai][bj][m][n], 0, 0, 0); __builtin_amdgcn_s_setprio(0); } while (0)
; #define PG8_WAIT_V(n) asm volatile("s_waitcnt vmcnt(" #n ")" ::: "memory")
; #define PG8_WAIT_L(n) asm volatile("s_waitcnt lgkmcnt(" #n ")" ::: "memory")
; #define PG8_BAR __builtin_amdgcn_s_barrier()
; #define PG8_SCHED __builtin_amdgcn_sched_barrier(0)
; template <class Desc, class Epi>
; DI void gemm_phase(LAS unsigned char* lds, const Desc& D, const Epi& E, int wv) {
;     ...
;             PG8_WAIT_V(8); PG8_WAIT_L(0); PG8_BAR; PG8_MMA(1, 0, At, B0); PG8_MMA(1, 1, At, B1); PG8_BAR; PG8_SCHED;
;             PG8_LDB(B0, 1, 0); PG8_LDB(B1, 1, 1); PG8_SCHED; PG8_LDA(At, 1, 0); PG8_STAGE(PG8_SA(0, 1), a2 + hstepA, voffA);
;             PG8_WAIT_V(8); PG8_WAIT_L(0); PG8_BAR; PG8_MMA(0, 0, At, B0); PG8_MMA(0, 1, At, B1); PG8_BAR; PG8_SCHED;
	v_mfma_f32_16x16x32_bf16 v[60:63], v[128:131], v[160:163], v[60:63]
	v_mfma_f32_16x16x32_bf16 v[56:59], v[136:139], v[160:163], v[56:59]
	v_mfma_f32_16x16x32_bf16 v[48:51], v[128:131], v[168:171], v[48:51]
	v_mfma_f32_16x16x32_bf16 v[40:43], v[136:139], v[168:171], v[40:43]
	v_mfma_f32_16x16x32_bf16 v[32:35], v[128:131], v[176:179], v[32:35]
	v_mfma_f32_16x16x32_bf16 v[24:27], v[136:139], v[176:179], v[24:27]
	v_mfma_f32_16x16x32_bf16 v[16:19], v[128:131], v[200:203], v[16:19]
	v_mfma_f32_16x16x32_bf16 v[8:11], v[136:139], v[200:203], v[8:11]
	v_mfma_f32_16x16x32_bf16 v[60:63], v[132:135], v[164:167], v[60:63]
	v_mfma_f32_16x16x32_bf16 v[56:59], v[140:143], v[164:167], v[56:59]
	v_mfma_f32_16x16x32_bf16 v[48:51], v[132:135], v[172:175], v[48:51]
	v_mfma_f32_16x16x32_bf16 v[40:43], v[140:143], v[172:175], v[40:43]
	v_mfma_f32_16x16x32_bf16 v[32:35], v[132:135], v[180:183], v[32:35]
	v_mfma_f32_16x16x32_bf16 v[24:27], v[140:143], v[180:183], v[24:27]
	v_mfma_f32_16x16x32_bf16 v[16:19], v[132:135], v[208:211], v[16:19]
	v_mfma_f32_16x16x32_bf16 v[8:11], v[140:143], v[208:211], v[8:11]
	v_mfma_f32_16x16x32_bf16 v[52:55], v[144:147], v[160:163], v[52:55]
	v_mfma_f32_16x16x32_bf16 v[44:47], v[152:155], v[160:163], v[44:47]
	v_mfma_f32_16x16x32_bf16 v[36:39], v[144:147], v[168:171], v[36:39]
	v_mfma_f32_16x16x32_bf16 v[28:31], v[152:155], v[168:171], v[28:31]
	v_mfma_f32_16x16x32_bf16 v[20:23], v[144:147], v[176:179], v[20:23]
	v_mfma_f32_16x16x32_bf16 v[12:15], v[152:155], v[176:179], v[12:15]
	v_mfma_f32_16x16x32_bf16 v[4:7], v[144:147], v[200:203], v[4:7]
	v_mfma_f32_16x16x32_bf16 v[0:3], v[152:155], v[200:203], v[0:3]
	v_mfma_f32_16x16x32_bf16 v[52:55], v[148:151], v[164:167], v[52:55]
	v_mfma_f32_16x16x32_bf16 v[44:47], v[156:159], v[164:167], v[44:47]
	v_mfma_f32_16x16x32_bf16 v[36:39], v[148:151], v[172:175], v[36:39]
	v_mfma_f32_16x16x32_bf16 v[28:31], v[156:159], v[172:175], v[28:31]
	v_mfma_f32_16x16x32_bf16 v[20:23], v[148:151], v[180:183], v[20:23]
	v_mfma_f32_16x16x32_bf16 v[12:15], v[156:159], v[180:183], v[12:15]
	v_mfma_f32_16x16x32_bf16 v[4:7], v[148:151], v[208:211], v[4:7]
	v_mfma_f32_16x16x32_bf16 v[0:3], v[156:159], v[208:211], v[0:3]
	s_barrier
	s_add_i32 s67, 0, 0x18000
	s_add_i32 s68, 0, 0x1c000
	v_add_u32_e32 v140, s67, v204
	v_add_u32_e32 v156, s68, v204
	ds_read_b128 v[128:131], v140
	ds_read_b128 v[132:135], v140 offset:1024
	ds_read_b128 v[136:139], v140 offset:2048
	ds_read_b128 v[140:143], v140 offset:3072
	ds_read_b128 v[144:147], v156
	ds_read_b128 v[148:151], v156 offset:1024
	ds_read_b128 v[152:155], v156 offset:2048
	ds_read_b128 v[156:159], v156 offset:3072
	s_add_u32 s40, s40, 0x80000
	s_addc_u32 s41, s41, 0
	s_mov_b32 m0, s42
	v_lshl_add_u64 v[220:221], s[40:41], 0, v[190:191]
	ds_read_b128 v[160:163], v207 offset:32768
	ds_read_b128 v[164:167], v207 offset:33792
	ds_read_b128 v[168:171], v207 offset:34816
	ds_read_b128 v[172:175], v207 offset:35840
	ds_read_b128 v[176:179], v207 offset:36864
	ds_read_b128 v[180:183], v207 offset:37888
	ds_read_b128 v[200:203], v207 offset:38912
	ds_read_b128 v[208:211], v207 offset:39936
	global_load_lds_dwordx4 v[220:221], off
	v_lshl_add_u64 v[220:221], s[40:41], 0, v[186:187]
	s_mov_b32 m0, s43
	s_nop 0
	global_load_lds_dwordx4 v[220:221], off
	s_waitcnt vmcnt(8)
	s_waitcnt lgkmcnt(0)
	s_barrier
	v_mfma_f32_16x16x32_bf16 v[124:127], v[128:131], v[160:163], v[124:127]
	v_mfma_f32_16x16x32_bf16 v[120:123], v[136:139], v[160:163], v[120:123]
	v_mfma_f32_16x16x32_bf16 v[112:115], v[128:131], v[168:171], v[112:115]
	v_mfma_f32_16x16x32_bf16 v[104:107], v[136:139], v[168:171], v[104:107]
	v_mfma_f32_16x16x32_bf16 v[96:99], v[128:131], v[176:179], v[96:99]
	v_mfma_f32_16x16x32_bf16 v[88:91], v[136:139], v[176:179], v[88:91]
	v_mfma_f32_16x16x32_bf16 v[80:83], v[128:131], v[200:203], v[80:83]
	v_mfma_f32_16x16x32_bf16 v[72:75], v[136:139], v[200:203], v[72:75]
	v_mfma_f32_16x16x32_bf16 v[124:127], v[132:135], v[164:167], v[124:127]
	v_mfma_f32_16x16x32_bf16 v[120:123], v[140:143], v[164:167], v[120:123]
	v_mfma_f32_16x16x32_bf16 v[112:115], v[132:135], v[172:175], v[112:115]
	v_mfma_f32_16x16x32_bf16 v[104:107], v[140:143], v[172:175], v[104:107]
	v_mfma_f32_16x16x32_bf16 v[96:99], v[132:135], v[180:183], v[96:99]
	v_mfma_f32_16x16x32_bf16 v[88:91], v[140:143], v[180:183], v[88:91]
	v_mfma_f32_16x16x32_bf16 v[80:83], v[132:135], v[208:211], v[80:83]
	v_mfma_f32_16x16x32_bf16 v[72:75], v[140:143], v[208:211], v[72:75]
	v_mfma_f32_16x16x32_bf16 v[116:119], v[144:147], v[160:163], v[116:119]
	v_mfma_f32_16x16x32_bf16 v[108:111], v[152:155], v[160:163], v[108:111]
	v_mfma_f32_16x16x32_bf16 v[100:103], v[144:147], v[168:171], v[100:103]
	v_mfma_f32_16x16x32_bf16 v[92:95], v[152:155], v[168:171], v[92:95]
	v_mfma_f32_16x16x32_bf16 v[84:87], v[144:147], v[176:179], v[84:87]
	v_mfma_f32_16x16x32_bf16 v[76:79], v[152:155], v[176:179], v[76:79]
	v_mfma_f32_16x16x32_bf16 v[68:71], v[144:147], v[200:203], v[68:71]
	v_mfma_f32_16x16x32_bf16 v[64:67], v[152:155], v[200:203], v[64:67]
	v_mfma_f32_16x16x32_bf16 v[116:119], v[148:151], v[164:167], v[116:119]
	v_mfma_f32_16x16x32_bf16 v[108:111], v[156:159], v[164:167], v[108:111]
	v_mfma_f32_16x16x32_bf16 v[100:103], v[148:151], v[172:175], v[100:103]
	v_mfma_f32_16x16x32_bf16 v[92:95], v[156:159], v[172:175], v[92:95]
	v_mfma_f32_16x16x32_bf16 v[84:87], v[148:151], v[180:183], v[84:87]
	v_mfma_f32_16x16x32_bf16 v[76:79], v[156:159], v[180:183], v[76:79]
	v_mfma_f32_16x16x32_bf16 v[68:71], v[148:151], v[208:211], v[68:71]
	v_mfma_f32_16x16x32_bf16 v[64:67], v[156:159], v[208:211], v[64:67]
	s_barrier
; #define PG8_STAGE(bufoff, gbase, voff) do { _Pragma("unroll") for (int _i = 0; _i < 2; ++_i) \
;         __builtin_amdgcn_global_load_lds((const unsigned*)((const char*)(gbase) + (voff)[_i]), (LAS unsigned*)(lds + (bufoff) + ldsw + _i * 8192), 16, 0, 0); } while (0)
; #define PG8_LDA(dst, b, h) do { _Pragma("unroll") for (int m = 0; m < 4; ++m) _Pragma("unroll") for (int k = 0; k < 2; ++k) dst[m][k] = *(const LAS bf16x8*)(lds + PG8_SA(b, h) + aoff + m * 2048 + k * 1024); } while (0)
; #define PG8_MMA(ai, bj, At, Bt) do { __builtin_amdgcn_s_setprio(1); _Pragma("unroll") for (int m = 0; m < 4; ++m) _Pragma("unroll") for (int n = 0; n < 2; ++n) _Pragma("unroll") for (int k = 0; k < 2; ++k) \
;         acc[ai][bj][m][n] = __builtin_amdgcn_mfma_f32_16x16x32_bf16(Bt[n][k], At[m][k], acc[ai][bj][m][n], 0, 0, 0); __builtin_amdgcn_s_setprio(0); } while (0)
; #define PG8_WAIT_V(n) asm volatile("s_waitcnt vmcnt(" #n ")" ::: "memory")
; #define PG8_WAIT_L(n) asm volatile("s_waitcnt lgkmcnt(" #n ")" ::: "memory")
; #define PG8_BAR __builtin_amdgcn_s_barrier()
; #define PG8_SCHED __builtin_amdgcn_sched_barrier(0)
; template <class Desc, class Epi>
; DI void gemm_phase(LAS unsigned char* lds, const Desc& D, const Epi& E, int wv) {
;     ...
;             PG8_LDA(At, 1, 1); PG8_STAGE(PG8_SB(1, 0), b3, voffB); PG8_STAGE(PG8_SB(1, 1), b3 + hstepB, voffB); PG8_STAGE(PG8_SA(1, 0), a3, voffA);
;             PG8_WAIT_V(8); PG8_WAIT_L(0); PG8_BAR; PG8_MMA(1, 0, At, B0); PG8_MMA(1, 1, At, B1); PG8_BAR; PG8_SCHED;
;         }
;         if (wr == 0) PG8_BAR;
	s_add_i32 s40, s67, s28
	v_lshl_add_u64 v[212:213], v[212:213], 0, s[6:7]
	s_mov_b32 m0, s40
	ds_read_b128 v[160:163], v207 offset:49152
	ds_read_b128 v[164:167], v207 offset:50176
	ds_read_b128 v[168:171], v207 offset:51200
	ds_read_b128 v[172:175], v207 offset:52224
	ds_read_b128 v[176:179], v207 offset:53248
	ds_read_b128 v[180:183], v207 offset:54272
	ds_read_b128 v[200:203], v207 offset:55296
	ds_read_b128 v[208:211], v207 offset:56320
	global_load_lds_dwordx4 v[212:213], off
	s_add_i32 m0, s40, 0x2000
	s_add_u32 s34, s34, 0x80080
	v_lshl_add_u64 v[212:213], v[214:215], 0, s[6:7]
	s_addc_u32 s35, s35, 0
	s_add_i32 s40, s68, s28
	global_load_lds_dwordx4 v[212:213], off
	v_lshl_add_u64 v[212:213], s[34:35], 0, v[188:189]
	s_mov_b32 m0, s40
	s_nop 0
	global_load_lds_dwordx4 v[212:213], off
	v_lshl_add_u64 v[212:213], s[34:35], 0, v[184:185]
	s_add_i32 m0, s40, 0x2000
	s_nop 0
	global_load_lds_dwordx4 v[212:213], off
	v_lshl_add_u64 v[212:213], v[216:217], 0, s[6:7]
	s_mov_b32 m0, s49
	s_nop 0
	global_load_lds_dwordx4 v[212:213], off
	v_lshl_add_u64 v[212:213], v[218:219], 0, s[6:7]
	s_mov_b32 m0, s50
	s_nop 0
	global_load_lds_dwordx4 v[212:213], off
	s_waitcnt vmcnt(8)
	s_waitcnt lgkmcnt(0)
	s_barrier
	v_mfma_f32_16x16x32_bf16 v[60:63], v[128:131], v[160:163], v[60:63]
	v_mfma_f32_16x16x32_bf16 v[56:59], v[136:139], v[160:163], v[56:59]
	v_mfma_f32_16x16x32_bf16 v[48:51], v[128:131], v[168:171], v[48:51]
	v_mfma_f32_16x16x32_bf16 v[40:43], v[136:139], v[168:171], v[40:43]
	v_mfma_f32_16x16x32_bf16 v[32:35], v[128:131], v[176:179], v[32:35]
	v_mfma_f32_16x16x32_bf16 v[24:27], v[136:139], v[176:179], v[24:27]
	v_mfma_f32_16x16x32_bf16 v[16:19], v[128:131], v[200:203], v[16:19]
	v_mfma_f32_16x16x32_bf16 v[8:11], v[136:139], v[200:203], v[8:11]
	v_mfma_f32_16x16x32_bf16 v[60:63], v[132:135], v[164:167], v[60:63]
	v_mfma_f32_16x16x32_bf16 v[56:59], v[140:143], v[164:167], v[56:59]
	v_mfma_f32_16x16x32_bf16 v[48:51], v[132:135], v[172:175], v[48:51]
	v_mfma_f32_16x16x32_bf16 v[40:43], v[140:143], v[172:175], v[40:43]
	v_mfma_f32_16x16x32_bf16 v[32:35], v[132:135], v[180:183], v[32:35]
	v_mfma_f32_16x16x32_bf16 v[24:27], v[140:143], v[180:183], v[24:27]
	v_mfma_f32_16x16x32_bf16 v[16:19], v[132:135], v[208:211], v[16:19]
	v_mfma_f32_16x16x32_bf16 v[8:11], v[140:143], v[208:211], v[8:11]
	v_mfma_f32_16x16x32_bf16 v[52:55], v[144:147], v[160:163], v[52:55]
	v_mfma_f32_16x16x32_bf16 v[44:47], v[152:155], v[160:163], v[44:47]
	v_mfma_f32_16x16x32_bf16 v[36:39], v[144:147], v[168:171], v[36:39]
	v_mfma_f32_16x16x32_bf16 v[28:31], v[152:155], v[168:171], v[28:31]
	v_mfma_f32_16x16x32_bf16 v[20:23], v[144:147], v[176:179], v[20:23]
	v_mfma_f32_16x16x32_bf16 v[12:15], v[152:155], v[176:179], v[12:15]
	v_mfma_f32_16x16x32_bf16 v[4:7], v[144:147], v[200:203], v[4:7]
	v_mfma_f32_16x16x32_bf16 v[0:3], v[152:155], v[200:203], v[0:3]
	v_mfma_f32_16x16x32_bf16 v[52:55], v[148:151], v[164:167], v[52:55]
	v_mfma_f32_16x16x32_bf16 v[44:47], v[156:159], v[164:167], v[44:47]
	v_mfma_f32_16x16x32_bf16 v[36:39], v[148:151], v[172:175], v[36:39]
	v_mfma_f32_16x16x32_bf16 v[28:31], v[156:159], v[172:175], v[28:31]
	v_mfma_f32_16x16x32_bf16 v[20:23], v[148:151], v[180:183], v[20:23]
	v_mfma_f32_16x16x32_bf16 v[12:15], v[156:159], v[180:183], v[12:15]
	v_mfma_f32_16x16x32_bf16 v[4:7], v[148:151], v[208:211], v[4:7]
	v_mfma_f32_16x16x32_bf16 v[0:3], v[156:159], v[208:211], v[0:3]
	s_barrier
	s_add_i32 s66, s66, 2
	s_add_u32 s24, s24, 0x100
	s_addc_u32 s25, s25, 0
	s_add_u32 s19, s19, 0x100
	s_addc_u32 s21, s21, 0
	s_cmp_gt_u32 s66, 29
	s_cbranch_scc0 .LBB0_2706
	s_and_b64 vcc, exec, s[8:9]
	s_cbranch_vccz .LBB0_2709
	s_barrier
